# A+Q + peeled first K-iteration in the 12 GEMM unit loops: MFMAs start from C=0 (128 zeroing v_mov per unit removed), first vmcnt wait dropped
# speedup vs baseline: 1.0069x; 1.0069x over previous
;     __device__ __forceinline__ void operator()(const f32x4 (&acc)[2][2][4][2], const Unit& u, int wr, int wc, int fr, int fq) const {
;     ...
;         const int s = (u.pm < ML / BM) ? (u.pm >> 5) : 4;
;         const float* bp = bias + (size_t)s * BIAS_N + u.pn * BM + wc * 32 + 8 * fq;
;         const f32x4 ba0 = *(const f32x4*)bp, ba1 = *(const f32x4*)(bp + 4), bb0 = *(const f32x4*)(bp + HALF), bb1 = *(const f32x4*)(bp + HALF + 4);
;         const int lane = fq * 16 + fr;
; template <class Epi, class Sched, bool ALIGN_EPI = false, bool SP2 = false>
; __device__ __forceinline__ void gemm_phase(LAS unsigned char* lds, const Gemm g, const Sched& S, const Epi& E) {
;     ...
;         const bool has_next = S.next(ui + 1, nxt);
;         const char* nA = has_next ? (const char*)g.A + (size_t)nxt.pm * tstep + nxt.koff : cA; const char* nB = has_next ? (const char*)g.Bt + (size_t)nxt.pn * tstep + nxt.koff : cB;
;         for (int t = 0; t < nt; t += 2) {
;             const bool last = (t == nt - 2);
;             const char* a1 = cA + (size_t)(t + 1) * kstep;
;             const char* a2 = last ? nA : cA + (size_t)(t + 2) * kstep; const char* b2 = last ? nB : cB + (size_t)(t + 2) * kstep;
;             const char* a3 = a2 + kstep; const char* b3 = b2 + kstep;
;             if (last && has_next) S.a_ready(nxt);
;             if constexpr (SP2) {
;             PG8_LDB(B0, 0, 0); PG8_LDB(B1, 0, 1); PG8_SCHED; PG8_LDA(At, 0, 0); PG8_STAGE(PG8_SA(1, 1), a1 + hstep, voffA);
;             PG8_WAIT_V(8); PG8_WAIT_L(0); PG8_BAR; PG8_MMA(0, 0, At, B0); PG8_MMA(0, 1, At, B1); PG8_BAR; PG8_SCHED;
;             PG8_LDA(At, 0, 1); PG8_STAGE(PG8_SB(0, 0), b2, voffB); PG8_STAGE(PG8_SB(0, 1), b2 + hstepB, voffB); PG8_STAGE(PG8_SA(0, 0), a2, voffA);
;             PG8_WAIT_V(8); PG8_WAIT_L(0); PG8_BAR; PG8_MMA(1, 0, At, B0); PG8_MMA(1, 1, At, B1); PG8_BAR; PG8_SCHED;
;             PG8_LDB(B0, 1, 0); PG8_LDB(B1, 1, 1); PG8_SCHED; PG8_LDA(At, 1, 0); PG8_STAGE(PG8_SA(0, 1), a2 + hstep, voffA);
;             PG8_WAIT_V(8); PG8_WAIT_L(0); PG8_BAR; PG8_MMA(0, 0, At, B0); PG8_MMA(0, 1, At, B1); PG8_BAR; PG8_SCHED;
;             PG8_LDA(At, 1, 1); PG8_STAGE(PG8_SB(1, 0), b3, voffB); PG8_STAGE(PG8_SB(1, 1), b3 + hstepB, voffB); PG8_STAGE(PG8_SA(1, 0), a3, voffA);
;             PG8_WAIT_V(8); PG8_WAIT_L(0); PG8_BAR; PG8_MMA(1, 0, At, B0); PG8_MMA(1, 1, At, B1); PG8_BAR; PG8_SCHED;
.LBB0_187:
	s_ashr_i32 s45, s44, 31
	s_lshl_b64 s[12:13], s[44:45], 20
	s_add_u32 s46, s93, s12
	s_addc_u32 s47, s92, s13
	s_and_b64 s[12:13], s[38:39], exec
	s_cselect_b32 s3, s47, s17
	s_cselect_b32 s12, s46, s16
	s_ashr_i32 s43, s42, 31
	s_lshl_b64 s[14:15], s[42:43], 20
	s_add_u32 s48, s28, s14
	s_addc_u32 s49, s29, s15
	s_and_b64 s[14:15], s[38:39], exec
	s_cselect_b32 s13, s49, s51
	s_cselect_b32 s14, s48, s50
	s_add_u32 s16, s16, 0x80080
	s_addc_u32 s17, s17, 0
	s_add_u32 s15, s50, 0x100
	s_addc_u32 s18, s51, 0
	s_mov_b32 s19, -2
	s_cmpk_gt_i32 s2, 0x7f
	s_mov_b64 s[98:99], 0xb000
	s_cbranch_scc1 .Lpre_up1l0
	s_ashr_i32 s100, s2, 5
	s_mul_hi_i32 s99, s100, 0x2c00
	s_mul_i32 s98, s100, 0x2c00
.Lpre_up1l0:
	s_lshl_b64 s[98:99], s[98:99], 2
	s_add_u32 s98, s68, s98
	s_addc_u32 s99, s69, s99
	s_lshl_b32 s100, s0, 8
	s_ashr_i32 s101, s100, 31
	s_lshl_b64 s[100:101], s[100:101], 2
	s_add_u32 s98, s98, s100
	s_addc_u32 s99, s99, s101
	s_add_u32 s98, s98, s60
	s_addc_u32 s99, s99, 0
	s_lshl_b32 s100, s2, 8
	s_add_i32 s100, s100, s54
	v_or_b32_e32 v162, s100, v171
	v_ashrrev_i32_e32 v163, 31, v162
	v_lshl_add_u64 v[162:163], v[162:163], 2, s[8:9]
	v_add_u32_e32 v164, s100, v172
	v_ashrrev_i32_e32 v165, 31, v164
	v_lshl_add_u64 v[164:165], v[164:165], 2, s[8:9]
	global_load_dwordx4 v[234:237], v177, s[98:99] offset:16
	global_load_dwordx4 v[238:241], v177, s[98:99]
	global_load_dwordx4 v[242:245], v177, s[98:99] offset:528
	global_load_dwordx4 v[246:249], v177, s[98:99] offset:512
	global_load_dword v250, v[162:163], off
	global_load_dword v251, v[164:165], off
	ds_read_b128 v[66:69], v174
	ds_read_b128 v[70:73], v174 offset:1024
	ds_read_b128 v[74:77], v174 offset:2048
	ds_read_b128 v[78:81], v174 offset:3072
	ds_read_b128 v[162:165], v175
	ds_read_b128 v[182:185], v175 offset:1024
	ds_read_b128 v[186:189], v175 offset:2048
	ds_read_b128 v[190:193], v175 offset:3072
	s_add_u32 s20, s16, 0xfff80080
	s_addc_u32 s21, s17, -1
	s_cmp_eq_u32 s19, 28
	s_cselect_b32 s53, s3, s21
	s_cselect_b32 s52, s12, s20
	s_cselect_b32 s51, s13, s18
	s_cselect_b32 s50, s14, s15
	v_lshl_add_u64 v[166:167], s[16:17], 0, v[154:155]
	s_add_i32 m0, s33, 0xc000
	ds_read_b128 v[194:197], v176
	ds_read_b128 v[198:201], v176 offset:1024
	ds_read_b128 v[202:205], v176 offset:2048
	ds_read_b128 v[206:209], v176 offset:3072
	ds_read_b128 v[210:213], v176 offset:4096
	ds_read_b128 v[214:217], v176 offset:5120
	ds_read_b128 v[218:221], v176 offset:6144
	ds_read_b128 v[222:225], v176 offset:7168
	global_load_lds_dwordx4 v[166:167], off
	v_lshl_add_u64 v[166:167], s[16:17], 0, v[156:157]
	s_add_i32 m0, s33, 0xe000
	s_nop 0
	global_load_lds_dwordx4 v[166:167], off
	s_waitcnt lgkmcnt(0)
	s_barrier
	s_setprio 1
	s_waitcnt lgkmcnt(0)
	v_mfma_f32_16x16x32_bf16 v[142:145], v[66:69], v[194:197], 0
	v_mfma_f32_16x16x32_bf16 v[138:141], v[74:77], v[194:197], 0
	v_mfma_f32_16x16x32_bf16 v[126:129], v[66:69], v[202:205], 0
	v_mfma_f32_16x16x32_bf16 v[122:125], v[74:77], v[202:205], 0
	v_mfma_f32_16x16x32_bf16 v[110:113], v[66:69], v[210:213], 0
	v_mfma_f32_16x16x32_bf16 v[106:109], v[74:77], v[210:213], 0
	v_mfma_f32_16x16x32_bf16 v[94:97], v[66:69], v[218:221], 0
	v_mfma_f32_16x16x32_bf16 v[90:93], v[74:77], v[218:221], 0
	v_mfma_f32_16x16x32_bf16 v[142:145], v[70:73], v[198:201], v[142:145]
	v_mfma_f32_16x16x32_bf16 v[138:141], v[78:81], v[198:201], v[138:141]
	v_mfma_f32_16x16x32_bf16 v[126:129], v[70:73], v[206:209], v[126:129]
	v_mfma_f32_16x16x32_bf16 v[122:125], v[78:81], v[206:209], v[122:125]
	v_mfma_f32_16x16x32_bf16 v[110:113], v[70:73], v[214:217], v[110:113]
	v_mfma_f32_16x16x32_bf16 v[106:109], v[78:81], v[214:217], v[106:109]
	v_mfma_f32_16x16x32_bf16 v[94:97], v[70:73], v[222:225], v[94:97]
	v_mfma_f32_16x16x32_bf16 v[90:93], v[78:81], v[222:225], v[90:93]
	s_setprio 0
	s_setprio 1
	v_mfma_f32_16x16x32_bf16 v[134:137], v[162:165], v[194:197], 0
	v_mfma_f32_16x16x32_bf16 v[130:133], v[186:189], v[194:197], 0
	v_mfma_f32_16x16x32_bf16 v[118:121], v[162:165], v[202:205], 0
	v_mfma_f32_16x16x32_bf16 v[114:117], v[186:189], v[202:205], 0
	v_mfma_f32_16x16x32_bf16 v[102:105], v[162:165], v[210:213], 0
	v_mfma_f32_16x16x32_bf16 v[98:101], v[186:189], v[210:213], 0
	v_mfma_f32_16x16x32_bf16 v[86:89], v[162:165], v[218:221], 0
	v_mfma_f32_16x16x32_bf16 v[82:85], v[186:189], v[218:221], 0
	v_mfma_f32_16x16x32_bf16 v[134:137], v[182:185], v[198:201], v[134:137]
	v_mfma_f32_16x16x32_bf16 v[130:133], v[190:193], v[198:201], v[130:133]
	v_mfma_f32_16x16x32_bf16 v[118:121], v[182:185], v[206:209], v[118:121]
	v_mfma_f32_16x16x32_bf16 v[114:117], v[190:193], v[206:209], v[114:117]
	v_mfma_f32_16x16x32_bf16 v[102:105], v[182:185], v[214:217], v[102:105]
	v_mfma_f32_16x16x32_bf16 v[98:101], v[190:193], v[214:217], v[98:101]
	v_mfma_f32_16x16x32_bf16 v[86:89], v[182:185], v[222:225], v[86:89]
	v_mfma_f32_16x16x32_bf16 v[82:85], v[190:193], v[222:225], v[82:85]
	s_setprio 0
	s_barrier
	s_add_i32 s20, s57, s27
	v_lshl_add_u64 v[166:167], s[50:51], 0, v[150:151]
	s_mov_b32 m0, s20
	ds_read_b128 v[194:197], v176 offset:16384
	ds_read_b128 v[198:201], v176 offset:17408
	ds_read_b128 v[202:205], v176 offset:18432
	ds_read_b128 v[206:209], v176 offset:19456
	ds_read_b128 v[210:213], v176 offset:20480
	ds_read_b128 v[214:217], v176 offset:21504
	ds_read_b128 v[218:221], v176 offset:22528
	ds_read_b128 v[222:225], v176 offset:23552
	global_load_lds_dwordx4 v[166:167], off
	s_add_i32 m0, s20, 0x2000
	s_add_u32 s20, s50, 0x80000
	v_lshl_add_u64 v[226:227], s[50:51], 0, v[146:147]
	s_addc_u32 s21, s51, 0
	s_add_i32 s22, s58, s27
	global_load_lds_dwordx4 v[226:227], off
	v_lshl_add_u64 v[228:229], s[20:21], 0, v[150:151]
	s_mov_b32 m0, s22
	v_lshl_add_u64 v[230:231], s[52:53], 0, v[148:149]
	global_load_lds_dwordx4 v[228:229], off
	v_lshl_add_u64 v[228:229], s[20:21], 0, v[146:147]
	s_add_i32 m0, s22, 0x2000
	s_nop 0
	global_load_lds_dwordx4 v[228:229], off
	v_lshl_add_u64 v[228:229], s[52:53], 0, v[152:153]
	s_mov_b32 m0, s33
	s_nop 0
	global_load_lds_dwordx4 v[228:229], off
	s_mov_b32 m0, s34
	s_nop 0
	global_load_lds_dwordx4 v[230:231], off
	s_waitcnt vmcnt(8)
	s_waitcnt lgkmcnt(0)
	s_barrier
; #define PG8_STAGE(bufoff, gbase, voff) do { _Pragma("unroll") for (int _i = 0; _i < 2; ++_i) \
;         __builtin_amdgcn_global_load_lds((const unsigned*)((const char*)(gbase) + (voff)[_i]), (LAS unsigned*)(lds + (bufoff) + ldsw + _i * 8192), 16, 0, 0); } while (0)
; #define PG8_LDA(dst, b, h) do { _Pragma("unroll") for (int m = 0; m < 4; ++m) _Pragma("unroll") for (int k = 0; k < 2; ++k) dst[m][k] = *(const LAS bf16x8*)(lds + PG8_SA(b, h) + aoff + m * 2048 + k * 1024); } while (0)
; #define PG8_LDB(dst, b, h) do { _Pragma("unroll") for (int n = 0; n < 2; ++n) _Pragma("unroll") for (int k = 0; k < 2; ++k) dst[n][k] = *(const LAS bf16x8*)(lds + PG8_SB(b, h) + boff + n * 2048 + k * 1024); } while (0)
; #define PG8_MMA(ai, bj, At, Bt) do { __builtin_amdgcn_s_setprio(1); _Pragma("unroll") for (int m = 0; m < 4; ++m) _Pragma("unroll") for (int n = 0; n < 2; ++n) _Pragma("unroll") for (int k = 0; k < 2; ++k) \
;         acc[ai][bj][m][n] = __builtin_amdgcn_mfma_f32_16x16x32_bf16(Bt[n][k], At[m][k], acc[ai][bj][m][n], 0, 0, 0); __builtin_amdgcn_s_setprio(0); } while (0)
; #define PG8_WAIT_V(n) asm volatile("s_waitcnt vmcnt(" #n ")" ::: "memory")
; template <class Epi, class Sched, bool ALIGN_EPI = false, bool SP2 = false>
; __device__ __forceinline__ void gemm_phase(LAS unsigned char* lds, const Gemm g, const Sched& S, const Epi& E) {
;     ...
;             PG8_LDB(B0, 0, 0); PG8_LDB(B1, 0, 1); PG8_SCHED; PG8_LDA(At, 0, 0); PG8_STAGE(PG8_SA(1, 1), a1 + hstep, voffA);
;             PG8_WAIT_V(8); PG8_WAIT_L(0); PG8_BAR; PG8_MMA(0, 0, At, B0); PG8_MMA(0, 1, At, B1); PG8_BAR; PG8_SCHED;
;             PG8_LDA(At, 0, 1); PG8_STAGE(PG8_SB(0, 0), b2, voffB); PG8_STAGE(PG8_SB(0, 1), b2 + hstepB, voffB); PG8_STAGE(PG8_SA(0, 0), a2, voffA);
;             PG8_WAIT_V(8); PG8_WAIT_L(0); PG8_BAR; PG8_MMA(1, 0, At, B0); PG8_MMA(1, 1, At, B1); PG8_BAR; PG8_SCHED;
;             PG8_LDB(B0, 1, 0); PG8_LDB(B1, 1, 1); PG8_SCHED; PG8_LDA(At, 1, 0); PG8_STAGE(PG8_SA(0, 1), a2 + hstep, voffA);
;             PG8_WAIT_V(8); PG8_WAIT_L(0); PG8_BAR; PG8_MMA(0, 0, At, B0); PG8_MMA(0, 1, At, B1); PG8_BAR; PG8_SCHED;
;             PG8_LDA(At, 1, 1); PG8_STAGE(PG8_SB(1, 0), b3, voffB); PG8_STAGE(PG8_SB(1, 1), b3 + hstepB, voffB); PG8_STAGE(PG8_SA(1, 0), a3, voffA);
;             PG8_WAIT_V(8); PG8_WAIT_L(0); PG8_BAR; PG8_MMA(1, 0, At, B0); PG8_MMA(1, 1, At, B1); PG8_BAR; PG8_SCHED;
	s_setprio 1
	s_waitcnt lgkmcnt(0)
	v_mfma_f32_16x16x32_bf16 v[62:65], v[66:69], v[194:197], 0
	v_mfma_f32_16x16x32_bf16 v[58:61], v[74:77], v[194:197], 0
	v_mfma_f32_16x16x32_bf16 v[46:49], v[66:69], v[202:205], 0
	v_mfma_f32_16x16x32_bf16 v[42:45], v[74:77], v[202:205], 0
	v_mfma_f32_16x16x32_bf16 v[30:33], v[66:69], v[210:213], 0
	v_mfma_f32_16x16x32_bf16 v[26:29], v[74:77], v[210:213], 0
	v_mfma_f32_16x16x32_bf16 v[14:17], v[66:69], v[218:221], 0
	v_mfma_f32_16x16x32_bf16 v[10:13], v[74:77], v[218:221], 0
	v_mfma_f32_16x16x32_bf16 v[62:65], v[70:73], v[198:201], v[62:65]
	v_mfma_f32_16x16x32_bf16 v[58:61], v[78:81], v[198:201], v[58:61]
	v_mfma_f32_16x16x32_bf16 v[46:49], v[70:73], v[206:209], v[46:49]
	v_mfma_f32_16x16x32_bf16 v[42:45], v[78:81], v[206:209], v[42:45]
	v_mfma_f32_16x16x32_bf16 v[30:33], v[70:73], v[214:217], v[30:33]
	v_mfma_f32_16x16x32_bf16 v[26:29], v[78:81], v[214:217], v[26:29]
	v_mfma_f32_16x16x32_bf16 v[14:17], v[70:73], v[222:225], v[14:17]
	v_mfma_f32_16x16x32_bf16 v[10:13], v[78:81], v[222:225], v[10:13]
	s_setprio 0
	s_setprio 1
	v_mfma_f32_16x16x32_bf16 v[54:57], v[162:165], v[194:197], 0
	v_mfma_f32_16x16x32_bf16 v[50:53], v[186:189], v[194:197], 0
	v_mfma_f32_16x16x32_bf16 v[38:41], v[162:165], v[202:205], 0
	v_mfma_f32_16x16x32_bf16 v[34:37], v[186:189], v[202:205], 0
	v_mfma_f32_16x16x32_bf16 v[22:25], v[162:165], v[210:213], 0
	v_mfma_f32_16x16x32_bf16 v[18:21], v[186:189], v[210:213], 0
	v_mfma_f32_16x16x32_bf16 v[6:9], v[162:165], v[218:221], 0
	v_mfma_f32_16x16x32_bf16 v[2:5], v[186:189], v[218:221], 0
	v_mfma_f32_16x16x32_bf16 v[54:57], v[182:185], v[198:201], v[54:57]
	v_mfma_f32_16x16x32_bf16 v[50:53], v[190:193], v[198:201], v[50:53]
	v_mfma_f32_16x16x32_bf16 v[38:41], v[182:185], v[206:209], v[38:41]
	v_mfma_f32_16x16x32_bf16 v[34:37], v[190:193], v[206:209], v[34:37]
	v_mfma_f32_16x16x32_bf16 v[22:25], v[182:185], v[214:217], v[22:25]
	v_mfma_f32_16x16x32_bf16 v[18:21], v[190:193], v[214:217], v[18:21]
	v_mfma_f32_16x16x32_bf16 v[6:9], v[182:185], v[222:225], v[6:9]
	v_mfma_f32_16x16x32_bf16 v[2:5], v[190:193], v[222:225], v[2:5]
	s_setprio 0
	s_barrier
	s_add_i32 s22, 0, 0x18000
	s_add_i32 s23, 0, 0x1c000
	v_add_u32_e32 v78, s22, v170
	v_add_u32_e32 v168, s23, v170
	ds_read_b128 v[66:69], v78
	ds_read_b128 v[70:73], v78 offset:1024
	ds_read_b128 v[74:77], v78 offset:2048
	ds_read_b128 v[78:81], v78 offset:3072
	ds_read_b128 v[162:165], v168
	ds_read_b128 v[182:185], v168 offset:1024
	ds_read_b128 v[186:189], v168 offset:2048
	ds_read_b128 v[190:193], v168 offset:3072
	s_add_u32 s20, s52, 0x80000
	s_addc_u32 s21, s53, 0
	s_mov_b32 m0, s35
	v_lshl_add_u64 v[232:233], s[20:21], 0, v[152:153]
	ds_read_b128 v[194:197], v176 offset:32768
	ds_read_b128 v[198:201], v176 offset:33792
	ds_read_b128 v[202:205], v176 offset:34816
	ds_read_b128 v[206:209], v176 offset:35840
	ds_read_b128 v[210:213], v176 offset:36864
	ds_read_b128 v[214:217], v176 offset:37888
	ds_read_b128 v[218:221], v176 offset:38912
	ds_read_b128 v[222:225], v176 offset:39936
	global_load_lds_dwordx4 v[232:233], off
	v_lshl_add_u64 v[232:233], s[20:21], 0, v[148:149]
	s_mov_b32 m0, s36
	s_nop 0
	global_load_lds_dwordx4 v[232:233], off
	s_waitcnt vmcnt(8)
	s_waitcnt lgkmcnt(0)
	s_barrier
	s_setprio 1
	s_waitcnt lgkmcnt(0)
	v_mfma_f32_16x16x32_bf16 v[142:145], v[66:69], v[194:197], v[142:145]
	v_mfma_f32_16x16x32_bf16 v[138:141], v[74:77], v[194:197], v[138:141]
	v_mfma_f32_16x16x32_bf16 v[126:129], v[66:69], v[202:205], v[126:129]
	v_mfma_f32_16x16x32_bf16 v[122:125], v[74:77], v[202:205], v[122:125]
	v_mfma_f32_16x16x32_bf16 v[110:113], v[66:69], v[210:213], v[110:113]
	v_mfma_f32_16x16x32_bf16 v[106:109], v[74:77], v[210:213], v[106:109]
	v_mfma_f32_16x16x32_bf16 v[94:97], v[66:69], v[218:221], v[94:97]
	v_mfma_f32_16x16x32_bf16 v[90:93], v[74:77], v[218:221], v[90:93]
	v_mfma_f32_16x16x32_bf16 v[142:145], v[70:73], v[198:201], v[142:145]
	v_mfma_f32_16x16x32_bf16 v[138:141], v[78:81], v[198:201], v[138:141]
	v_mfma_f32_16x16x32_bf16 v[126:129], v[70:73], v[206:209], v[126:129]
	v_mfma_f32_16x16x32_bf16 v[122:125], v[78:81], v[206:209], v[122:125]
	v_mfma_f32_16x16x32_bf16 v[110:113], v[70:73], v[214:217], v[110:113]
	v_mfma_f32_16x16x32_bf16 v[106:109], v[78:81], v[214:217], v[106:109]
	v_mfma_f32_16x16x32_bf16 v[94:97], v[70:73], v[222:225], v[94:97]
	v_mfma_f32_16x16x32_bf16 v[90:93], v[78:81], v[222:225], v[90:93]
	s_setprio 0
	s_setprio 1
	v_mfma_f32_16x16x32_bf16 v[134:137], v[162:165], v[194:197], v[134:137]
	v_mfma_f32_16x16x32_bf16 v[130:133], v[186:189], v[194:197], v[130:133]
	v_mfma_f32_16x16x32_bf16 v[118:121], v[162:165], v[202:205], v[118:121]
	v_mfma_f32_16x16x32_bf16 v[114:117], v[186:189], v[202:205], v[114:117]
	v_mfma_f32_16x16x32_bf16 v[102:105], v[162:165], v[210:213], v[102:105]
	v_mfma_f32_16x16x32_bf16 v[98:101], v[186:189], v[210:213], v[98:101]
	v_mfma_f32_16x16x32_bf16 v[86:89], v[162:165], v[218:221], v[86:89]
	v_mfma_f32_16x16x32_bf16 v[82:85], v[186:189], v[218:221], v[82:85]
	v_mfma_f32_16x16x32_bf16 v[134:137], v[182:185], v[198:201], v[134:137]
	v_mfma_f32_16x16x32_bf16 v[130:133], v[190:193], v[198:201], v[130:133]
	v_mfma_f32_16x16x32_bf16 v[118:121], v[182:185], v[206:209], v[118:121]
	v_mfma_f32_16x16x32_bf16 v[114:117], v[190:193], v[206:209], v[114:117]
	v_mfma_f32_16x16x32_bf16 v[102:105], v[182:185], v[214:217], v[102:105]
	v_mfma_f32_16x16x32_bf16 v[98:101], v[190:193], v[214:217], v[98:101]
	v_mfma_f32_16x16x32_bf16 v[86:89], v[182:185], v[222:225], v[86:89]
	v_mfma_f32_16x16x32_bf16 v[82:85], v[190:193], v[222:225], v[82:85]
	s_setprio 0
	s_barrier
; #define PG8_STAGE(bufoff, gbase, voff) do { _Pragma("unroll") for (int _i = 0; _i < 2; ++_i) \
;         __builtin_amdgcn_global_load_lds((const unsigned*)((const char*)(gbase) + (voff)[_i]), (LAS unsigned*)(lds + (bufoff) + ldsw + _i * 8192), 16, 0, 0); } while (0)
; #define PG8_LDA(dst, b, h) do { _Pragma("unroll") for (int m = 0; m < 4; ++m) _Pragma("unroll") for (int k = 0; k < 2; ++k) dst[m][k] = *(const LAS bf16x8*)(lds + PG8_SA(b, h) + aoff + m * 2048 + k * 1024); } while (0)
; #define PG8_LDB(dst, b, h) do { _Pragma("unroll") for (int n = 0; n < 2; ++n) _Pragma("unroll") for (int k = 0; k < 2; ++k) dst[n][k] = *(const LAS bf16x8*)(lds + PG8_SB(b, h) + boff + n * 2048 + k * 1024); } while (0)
; template <class Epi, class Sched, bool ALIGN_EPI = false, bool SP2 = false>
; __device__ __forceinline__ void gemm_phase(LAS unsigned char* lds, const Gemm g, const Sched& S, const Epi& E) {
;     ...
;         for (int t = 0; t < nt; t += 2) {
;             const bool last = (t == nt - 2);
;             const char* a1 = cA + (size_t)(t + 1) * kstep;
;             const char* a2 = last ? nA : cA + (size_t)(t + 2) * kstep; const char* b2 = last ? nB : cB + (size_t)(t + 2) * kstep;
;             const char* a3 = a2 + kstep; const char* b3 = b2 + kstep;
;             if (last && has_next) S.a_ready(nxt);
;             if constexpr (SP2) {
;             PG8_LDB(B0, 0, 0); PG8_LDB(B1, 0, 1); PG8_SCHED; PG8_LDA(At, 0, 0); PG8_STAGE(PG8_SA(1, 1), a1 + hstep, voffA);
;             PG8_WAIT_V(8); PG8_WAIT_L(0); PG8_BAR; PG8_MMA(0, 0, At, B0); PG8_MMA(0, 1, At, B1); PG8_BAR; PG8_SCHED;
;             PG8_LDA(At, 0, 1); PG8_STAGE(PG8_SB(0, 0), b2, voffB); PG8_STAGE(PG8_SB(0, 1), b2 + hstepB, voffB); PG8_STAGE(PG8_SA(0, 0), a2, voffA);
;             PG8_WAIT_V(8); PG8_WAIT_L(0); PG8_BAR; PG8_MMA(1, 0, At, B0); PG8_MMA(1, 1, At, B1); PG8_BAR; PG8_SCHED;
;             PG8_LDB(B0, 1, 0); PG8_LDB(B1, 1, 1); PG8_SCHED; PG8_LDA(At, 1, 0); PG8_STAGE(PG8_SA(0, 1), a2 + hstep, voffA);
;             PG8_WAIT_V(8); PG8_WAIT_L(0); PG8_BAR; PG8_MMA(0, 0, At, B0); PG8_MMA(0, 1, At, B1); PG8_BAR; PG8_SCHED;
;             PG8_LDA(At, 1, 1); PG8_STAGE(PG8_SB(1, 0), b3, voffB); PG8_STAGE(PG8_SB(1, 1), b3 + hstepB, voffB); PG8_STAGE(PG8_SA(1, 0), a3, voffA);
;             PG8_WAIT_V(8); PG8_WAIT_L(0); PG8_BAR; PG8_MMA(1, 0, At, B0); PG8_MMA(1, 1, At, B1); PG8_BAR; PG8_SCHED;
	s_add_i32 s20, s22, s27
	v_lshl_add_u64 v[166:167], v[166:167], 0, s[10:11]
	s_mov_b32 m0, s20
	ds_read_b128 v[194:197], v176 offset:49152
	ds_read_b128 v[198:201], v176 offset:50176
	ds_read_b128 v[202:205], v176 offset:51200
	ds_read_b128 v[206:209], v176 offset:52224
	ds_read_b128 v[210:213], v176 offset:53248
	ds_read_b128 v[214:217], v176 offset:54272
	ds_read_b128 v[218:221], v176 offset:55296
	ds_read_b128 v[222:225], v176 offset:56320
	global_load_lds_dwordx4 v[166:167], off
	s_add_i32 m0, s20, 0x2000
	s_add_u32 s20, s50, 0x80080
	v_lshl_add_u64 v[166:167], v[226:227], 0, s[10:11]
	s_addc_u32 s21, s51, 0
	s_add_i32 s22, s23, s27
	global_load_lds_dwordx4 v[166:167], off
	v_lshl_add_u64 v[166:167], s[20:21], 0, v[150:151]
	s_mov_b32 m0, s22
	s_nop 0
	global_load_lds_dwordx4 v[166:167], off
	v_lshl_add_u64 v[166:167], s[20:21], 0, v[146:147]
	s_add_i32 m0, s22, 0x2000
	s_nop 0
	global_load_lds_dwordx4 v[166:167], off
	v_lshl_add_u64 v[166:167], v[228:229], 0, s[10:11]
	s_mov_b32 m0, s55
	s_nop 0
	global_load_lds_dwordx4 v[166:167], off
	v_lshl_add_u64 v[166:167], v[230:231], 0, s[10:11]
	s_mov_b32 m0, s56
	s_nop 0
	global_load_lds_dwordx4 v[166:167], off
	s_waitcnt vmcnt(8)
	s_waitcnt lgkmcnt(0)
	s_barrier
	s_setprio 1
	s_waitcnt lgkmcnt(0)
	v_mfma_f32_16x16x32_bf16 v[62:65], v[66:69], v[194:197], v[62:65]
	v_mfma_f32_16x16x32_bf16 v[58:61], v[74:77], v[194:197], v[58:61]
	v_mfma_f32_16x16x32_bf16 v[46:49], v[66:69], v[202:205], v[46:49]
	v_mfma_f32_16x16x32_bf16 v[42:45], v[74:77], v[202:205], v[42:45]
	v_mfma_f32_16x16x32_bf16 v[30:33], v[66:69], v[210:213], v[30:33]
	v_mfma_f32_16x16x32_bf16 v[26:29], v[74:77], v[210:213], v[26:29]
	v_mfma_f32_16x16x32_bf16 v[14:17], v[66:69], v[218:221], v[14:17]
	v_mfma_f32_16x16x32_bf16 v[10:13], v[74:77], v[218:221], v[10:13]
	v_mfma_f32_16x16x32_bf16 v[62:65], v[70:73], v[198:201], v[62:65]
	v_mfma_f32_16x16x32_bf16 v[58:61], v[78:81], v[198:201], v[58:61]
	v_mfma_f32_16x16x32_bf16 v[46:49], v[70:73], v[206:209], v[46:49]
	v_mfma_f32_16x16x32_bf16 v[42:45], v[78:81], v[206:209], v[42:45]
	v_mfma_f32_16x16x32_bf16 v[30:33], v[70:73], v[214:217], v[30:33]
	v_mfma_f32_16x16x32_bf16 v[26:29], v[78:81], v[214:217], v[26:29]
	v_mfma_f32_16x16x32_bf16 v[14:17], v[70:73], v[222:225], v[14:17]
	v_mfma_f32_16x16x32_bf16 v[10:13], v[78:81], v[222:225], v[10:13]
	s_setprio 0
	s_setprio 1
	v_mfma_f32_16x16x32_bf16 v[54:57], v[162:165], v[194:197], v[54:57]
	v_mfma_f32_16x16x32_bf16 v[50:53], v[186:189], v[194:197], v[50:53]
	v_mfma_f32_16x16x32_bf16 v[38:41], v[162:165], v[202:205], v[38:41]
	v_mfma_f32_16x16x32_bf16 v[34:37], v[186:189], v[202:205], v[34:37]
	v_mfma_f32_16x16x32_bf16 v[22:25], v[162:165], v[210:213], v[22:25]
	v_mfma_f32_16x16x32_bf16 v[18:21], v[186:189], v[210:213], v[18:21]
	v_mfma_f32_16x16x32_bf16 v[6:9], v[162:165], v[218:221], v[6:9]
	v_mfma_f32_16x16x32_bf16 v[2:5], v[186:189], v[218:221], v[2:5]
	v_mfma_f32_16x16x32_bf16 v[54:57], v[182:185], v[198:201], v[54:57]
	v_mfma_f32_16x16x32_bf16 v[50:53], v[190:193], v[198:201], v[50:53]
	v_mfma_f32_16x16x32_bf16 v[38:41], v[182:185], v[206:209], v[38:41]
	v_mfma_f32_16x16x32_bf16 v[34:37], v[190:193], v[206:209], v[34:37]
	v_mfma_f32_16x16x32_bf16 v[22:25], v[182:185], v[214:217], v[22:25]
	v_mfma_f32_16x16x32_bf16 v[18:21], v[190:193], v[214:217], v[18:21]
	v_mfma_f32_16x16x32_bf16 v[6:9], v[182:185], v[222:225], v[6:9]
	v_mfma_f32_16x16x32_bf16 v[2:5], v[190:193], v[222:225], v[2:5]
	s_setprio 0
	s_barrier
	s_add_i32 s19, s19, 2
	s_add_u32 s16, s16, 0x100
	s_addc_u32 s17, s17, 0
	s_add_u32 s15, s15, 0x100
	s_addc_u32 s18, s18, 0
	s_cmp_gt_u32 s19, 29

; __device__ __forceinline__ unsigned cvt_pk_bf16(float lo, float hi) { unsigned r; asm volatile("v_cvt_pk_bf16_f32 %0, %1, %2" : "=v"(r) : "v"(lo), "v"(hi)); return r; }
; __device__ __forceinline__ float silu_mul(float a, float b) { return a * b * __builtin_amdgcn_rcpf(1.0f + __builtin_amdgcn_exp2f(-a * LOG2E)); }
; __device__ __forceinline__ float row_rstd(const float* ss, int row) { return 1.0f / sqrtf(ss[row] * (1.0f / DM) + 1e-6f); }
;     __device__ __forceinline__ void operator()(const f32x4 (&acc)[2][2][4][2], const Unit& u, int wr, int wc, int fr, int fq) const {
;     ...
;         const float rsl0 = row_rstd(ss, u.pm * BM + wr * 64 + lane), rsl1 = row_rstd(ss, u.pm * BM + HALF + wr * 64 + lane);
; #pragma unroll
;         for (int ai = 0; ai < 2; ++ai)
; #pragma unroll
;             for (int m = 0; m < 4; ++m) { const int row = row0 + ai * HALF + m * 16; const float rs = __shfl(ai ? rsl1 : rsl0, m * 16 + fr); bf16_t* rowp = O + (size_t)row * DFF + col0;
;                 const f32x4 a0 = acc[ai][0][m][0] * rs + ba0, a1 = acc[ai][0][m][1] * rs + ba1, b0 = acc[ai][1][m][0] * rs + bb0, b1 = acc[ai][1][m][1] * rs + bb1;
;                 u32x4 w; w.x = cvt_pk_bf16(silu_mul(a0[0], b0[0]), silu_mul(a0[1], b0[1])); w.y = cvt_pk_bf16(silu_mul(a0[2], b0[2]), silu_mul(a0[3], b0[3]));
;                 w.z = cvt_pk_bf16(silu_mul(a1[0], b1[0]), silu_mul(a1[1], b1[1])); w.w = cvt_pk_bf16(silu_mul(a1[2], b1[2]), silu_mul(a1[3], b1[3]));
;                 *(u32x4*)rowp = w; }
.LBB0_193:
	s_lshl_b32 s2, s2, 8
	s_add_i32 s12, s2, s54
	s_lshl_b64 s[2:3], s[16:17], 2
	s_add_u32 s13, s68, s2
	s_addc_u32 s14, s69, s3
	s_lshl_b32 s2, s0, 8
	s_ashr_i32 s3, s2, 31
	s_lshl_b64 s[2:3], s[2:3], 2
	v_lshl_or_b32 v164, s0, 7, v173
	s_add_u32 s0, s13, s2
	s_addc_u32 s3, s14, s3
	v_or_b32_e32 v162, s12, v171
	s_add_u32 s2, s0, s60
	v_ashrrev_i32_e32 v163, 31, v162
	s_addc_u32 s3, s3, 0
	v_lshl_add_u64 v[162:163], v[162:163], 2, s[8:9]
	v_mov_b32_e32 v74, v234
	v_mov_b32_e32 v75, v235
	v_mov_b32_e32 v76, v236
	v_mov_b32_e32 v77, v237
	v_mov_b32_e32 v78, v238
	v_mov_b32_e32 v79, v239
	v_mov_b32_e32 v80, v240
	v_mov_b32_e32 v81, v241
	v_mov_b32_e32 v66, v242
	v_mov_b32_e32 v67, v243
	v_mov_b32_e32 v68, v244
	v_mov_b32_e32 v69, v245
	v_mov_b32_e32 v70, v246
	v_mov_b32_e32 v71, v247
	v_mov_b32_e32 v72, v248
	v_mov_b32_e32 v73, v249
	v_or_b32_e32 v181, s12, v169
	v_mov_b32_e32 v162, v250
	s_waitcnt vmcnt(0)
	v_fmamk_f32 v162, v162, 0x3a000000, v178
	v_cmp_gt_f32_e32 vcc, s61, v162
	v_mul_f32_e32 v163, 0x4f800000, v162
	s_nop 0
	v_cndmask_b32_e32 v162, v162, v163, vcc
	v_sqrt_f32_e32 v163, v162
	s_nop 0
	v_add_u32_e32 v165, -1, v163
	v_fma_f32 v166, -v165, v163, v162
	v_cmp_ge_f32_e64 s[2:3], 0, v166
	v_add_u32_e32 v166, 1, v163
	s_nop 0
	v_cndmask_b32_e64 v165, v163, v165, s[2:3]
	v_fma_f32 v163, -v166, v163, v162
	v_cmp_lt_f32_e64 s[2:3], 0, v163
	s_nop 1
	v_cndmask_b32_e64 v163, v165, v166, s[2:3]
	v_mul_f32_e32 v165, 0x37800000, v163
	v_cndmask_b32_e32 v163, v163, v165, vcc
	v_cmp_class_f32_e32 vcc, v162, v179
	s_nop 1
	v_cndmask_b32_e32 v166, v163, v162, vcc
	v_add_u32_e32 v162, s12, v172
	v_ashrrev_i32_e32 v163, 31, v162
	v_lshl_add_u64 v[162:163], v[162:163], 2, s[8:9]
	v_mov_b32_e32 v162, v251
	v_fmamk_f32 v162, v162, 0x3a000000, v178
	v_cmp_gt_f32_e32 vcc, s61, v162
	v_mul_f32_e32 v163, 0x4f800000, v162
	s_nop 0
	v_cndmask_b32_e32 v162, v162, v163, vcc
	v_sqrt_f32_e32 v163, v162
	s_nop 0
	v_add_u32_e32 v165, -1, v163
	v_fma_f32 v167, -v165, v163, v162
	v_cmp_ge_f32_e64 s[2:3], 0, v167
	v_add_u32_e32 v167, 1, v163
	s_nop 0
	v_cndmask_b32_e64 v165, v163, v165, s[2:3]
	v_fma_f32 v163, -v167, v163, v162
	v_cmp_lt_f32_e64 s[2:3], 0, v163
	s_nop 1
	v_cndmask_b32_e64 v163, v165, v167, s[2:3]
	v_mul_f32_e32 v165, 0x37800000, v163
	v_cndmask_b32_e32 v163, v163, v165, vcc
	v_cmp_class_f32_e32 vcc, v162, v179
	v_ashrrev_i32_e32 v165, 31, v164
	v_lshlrev_b64 v[164:165], 1, v[164:165]
	v_cndmask_b32_e32 v182, v163, v162, vcc
	v_div_scale_f32 v162, s[2:3], v166, v166, 1.0
	v_rcp_f32_e32 v163, v162
	s_nop 0
	v_fma_f32 v167, -v162, v163, 1.0
	v_fmac_f32_e32 v163, v167, v163
	v_div_scale_f32 v167, vcc, 1.0, v166, 1.0
	v_mul_f32_e32 v168, v167, v163
	v_fma_f32 v183, -v162, v168, v167
	v_fmac_f32_e32 v168, v183, v163
	v_fma_f32 v162, -v162, v168, v167
	v_div_fmas_f32 v162, v162, v163, v168
	v_div_fixup_f32 v183, v162, v166, 1.0
	ds_bpermute_b32 v168, v180, v183
	v_mov_b64_e32 v[162:163], s[96:97]
	v_mad_i64_i32 v[166:167], s[2:3], v181, s59, v[162:163]
	v_lshl_add_u64 v[166:167], v[166:167], 0, v[164:165]
	s_waitcnt lgkmcnt(0)
	v_pk_fma_f32 v[142:143], v[142:143], v[168:169], v[78:79] op_sel_hi:[1,0,1]
	v_pk_fma_f32 v[134:135], v[134:135], v[168:169], v[70:71] op_sel_hi:[1,0,1]
	v_pk_fma_f32 v[184:185], v[132:133], v[168:169], v[68:69] op_sel_hi:[1,0,1]
	v_pk_fma_f32 v[132:133], v[130:131], v[168:169], v[66:67] op_sel_hi:[1,0,1]
	v_mul_f32_e32 v131, 0xbfb8aa3b, v142
	v_mul_f32_e32 v130, v142, v134
	v_exp_f32_e32 v131, v131
	v_mul_f32_e32 v134, 0xbfb8aa3b, v143
	v_exp_f32_e32 v134, v134
	v_pk_fma_f32 v[144:145], v[144:145], v[168:169], v[80:81] op_sel_hi:[1,0,1]
	v_add_f32_e32 v131, 1.0, v131
	v_rcp_f32_e32 v131, v131
	v_add_f32_e32 v134, 1.0, v134
	v_rcp_f32_e32 v134, v134
	v_pk_fma_f32 v[136:137], v[136:137], v[168:169], v[72:73] op_sel_hi:[1,0,1]
	v_mul_f32_e32 v130, v130, v131
	v_mul_f32_e32 v131, v143, v135
	v_mul_f32_e32 v131, v131, v134
	v_mul_f32_e32 v134, 0xbfb8aa3b, v144
	v_exp_f32_e32 v134, v134
	v_mul_f32_e32 v135, 0xbfb8aa3b, v145
	v_exp_f32_e32 v135, v135
	v_cvt_pk_bf16_f32 v130, v130, v131
	v_add_f32_e32 v134, 1.0, v134
	v_rcp_f32_e32 v134, v134
	v_add_f32_e32 v135, 1.0, v135
	v_rcp_f32_e32 v135, v135
	v_mul_f32_e32 v131, v144, v136
	v_mul_f32_e32 v131, v131, v134
	v_mul_f32_e32 v134, v145, v137
	v_pk_fma_f32 v[138:139], v[138:139], v[168:169], v[74:75] op_sel_hi:[1,0,1]
	v_mul_f32_e32 v134, v134, v135
	v_cvt_pk_bf16_f32 v131, v131, v134
	v_mul_f32_e32 v134, 0xbfb8aa3b, v138
	v_exp_f32_e32 v134, v134
	v_mul_f32_e32 v132, v138, v132
	v_pk_fma_f32 v[140:141], v[140:141], v[168:169], v[76:77] op_sel_hi:[1,0,1]
	v_mul_f32_e32 v133, v139, v133
	v_add_f32_e32 v134, 1.0, v134
	v_rcp_f32_e32 v134, v134
	v_mul_f32_e32 v135, 0xbfb8aa3b, v141
	v_exp_f32_e32 v135, v135
	v_mul_f32_e32 v132, v132, v134
	v_mul_f32_e32 v134, 0xbfb8aa3b, v139
	v_exp_f32_e32 v134, v134
	v_add_f32_e32 v135, 1.0, v135
	v_rcp_f32_e32 v135, v135
	v_add_f32_e32 v134, 1.0, v134
	v_rcp_f32_e32 v134, v134
	s_nop 0
	v_mul_f32_e32 v133, v133, v134
	v_mul_f32_e32 v134, 0xbfb8aa3b, v140
	v_exp_f32_e32 v134, v134
	v_cvt_pk_bf16_f32 v132, v132, v133
	v_mul_f32_e32 v133, v140, v184
	v_add_f32_e32 v134, 1.0, v134
	v_rcp_f32_e32 v134, v134
	s_nop 0
	v_mul_f32_e32 v133, v133, v134
	v_mul_f32_e32 v134, v141, v185
	v_mul_f32_e32 v134, v134, v135
	v_cvt_pk_bf16_f32 v133, v133, v134
	global_store_dwordx4 v[166:167], v[130:133], off
	ds_bpermute_b32 v130, v180, v183 offset:64
	s_nop 0
	v_or_b32_e32 v131, 16, v181
	v_mad_i64_i32 v[132:133], s[2:3], v131, s59, v[162:163]
	s_waitcnt lgkmcnt(0)
; __device__ __forceinline__ unsigned cvt_pk_bf16(float lo, float hi) { unsigned r; asm volatile("v_cvt_pk_bf16_f32 %0, %1, %2" : "=v"(r) : "v"(lo), "v"(hi)); return r; }
; __device__ __forceinline__ float silu_mul(float a, float b) { return a * b * __builtin_amdgcn_rcpf(1.0f + __builtin_amdgcn_exp2f(-a * LOG2E)); }
;     __device__ __forceinline__ void operator()(const f32x4 (&acc)[2][2][4][2], const Unit& u, int wr, int wc, int fr, int fq) const {
;     ...
;             for (int m = 0; m < 4; ++m) { const int row = row0 + ai * HALF + m * 16; const float rs = __shfl(ai ? rsl1 : rsl0, m * 16 + fr); bf16_t* rowp = O + (size_t)row * DFF + col0;
;                 const f32x4 a0 = acc[ai][0][m][0] * rs + ba0, a1 = acc[ai][0][m][1] * rs + ba1, b0 = acc[ai][1][m][0] * rs + bb0, b1 = acc[ai][1][m][1] * rs + bb1;
;                 u32x4 w; w.x = cvt_pk_bf16(silu_mul(a0[0], b0[0]), silu_mul(a0[1], b0[1])); w.y = cvt_pk_bf16(silu_mul(a0[2], b0[2]), silu_mul(a0[3], b0[3]));
;                 w.z = cvt_pk_bf16(silu_mul(a1[0], b1[0]), silu_mul(a1[1], b1[1])); w.w = cvt_pk_bf16(silu_mul(a1[2], b1[2]), silu_mul(a1[3], b1[3]));
;                 *(u32x4*)rowp = w; }
	v_pk_fma_f32 v[126:127], v[126:127], v[130:131], v[78:79] op_sel_hi:[1,0,1]
	v_pk_fma_f32 v[118:119], v[118:119], v[130:131], v[70:71] op_sel_hi:[1,0,1]
	v_pk_fma_f32 v[134:135], v[116:117], v[130:131], v[68:69] op_sel_hi:[1,0,1]
	v_pk_fma_f32 v[116:117], v[114:115], v[130:131], v[66:67] op_sel_hi:[1,0,1]
	v_mul_f32_e32 v115, 0xbfb8aa3b, v126
	v_mul_f32_e32 v114, v126, v118
	v_exp_f32_e32 v115, v115
	v_mul_f32_e32 v118, 0xbfb8aa3b, v127
	v_exp_f32_e32 v118, v118
	v_pk_fma_f32 v[128:129], v[128:129], v[130:131], v[80:81] op_sel_hi:[1,0,1]
	v_add_f32_e32 v115, 1.0, v115
	v_rcp_f32_e32 v115, v115
	v_add_f32_e32 v118, 1.0, v118
	v_rcp_f32_e32 v118, v118
	v_pk_fma_f32 v[120:121], v[120:121], v[130:131], v[72:73] op_sel_hi:[1,0,1]
	v_mul_f32_e32 v114, v114, v115
	v_mul_f32_e32 v115, v127, v119
	v_mul_f32_e32 v115, v115, v118
	v_mul_f32_e32 v118, 0xbfb8aa3b, v128
	v_exp_f32_e32 v118, v118
	v_mul_f32_e32 v119, 0xbfb8aa3b, v129
	v_exp_f32_e32 v119, v119
	v_cvt_pk_bf16_f32 v114, v114, v115
	v_add_f32_e32 v118, 1.0, v118
	v_rcp_f32_e32 v118, v118
	v_add_f32_e32 v119, 1.0, v119
	v_rcp_f32_e32 v119, v119
	v_mul_f32_e32 v115, v128, v120
	v_mul_f32_e32 v115, v115, v118
	v_mul_f32_e32 v118, v129, v121
	v_pk_fma_f32 v[122:123], v[122:123], v[130:131], v[74:75] op_sel_hi:[1,0,1]
	v_mul_f32_e32 v118, v118, v119
	v_cvt_pk_bf16_f32 v115, v115, v118
	v_mul_f32_e32 v118, 0xbfb8aa3b, v122
	v_exp_f32_e32 v118, v118
	v_mul_f32_e32 v116, v122, v116
	v_pk_fma_f32 v[124:125], v[124:125], v[130:131], v[76:77] op_sel_hi:[1,0,1]
	v_mul_f32_e32 v117, v123, v117
	v_add_f32_e32 v118, 1.0, v118
	v_rcp_f32_e32 v118, v118
	v_mul_f32_e32 v119, 0xbfb8aa3b, v125
	v_exp_f32_e32 v119, v119
	v_lshl_add_u64 v[132:133], v[132:133], 0, v[164:165]
	v_mul_f32_e32 v116, v116, v118
	v_mul_f32_e32 v118, 0xbfb8aa3b, v123
	v_exp_f32_e32 v118, v118
	v_add_f32_e32 v119, 1.0, v119
	v_rcp_f32_e32 v119, v119
	v_add_f32_e32 v118, 1.0, v118
	v_rcp_f32_e32 v118, v118
	s_nop 0
	v_mul_f32_e32 v117, v117, v118
	v_mul_f32_e32 v118, 0xbfb8aa3b, v124
	v_exp_f32_e32 v118, v118
	v_cvt_pk_bf16_f32 v116, v116, v117
	v_mul_f32_e32 v117, v124, v134
	v_add_f32_e32 v118, 1.0, v118
	v_rcp_f32_e32 v118, v118
	s_nop 0
	v_mul_f32_e32 v117, v117, v118
	v_mul_f32_e32 v118, v125, v135
	v_mul_f32_e32 v118, v118, v119
	v_cvt_pk_bf16_f32 v117, v117, v118
	global_store_dwordx4 v[132:133], v[114:117], off
	ds_bpermute_b32 v114, v180, v183 offset:128
	s_nop 0
	v_or_b32_e32 v115, 32, v181
	v_mad_i64_i32 v[116:117], s[2:3], v115, s59, v[162:163]
	s_waitcnt lgkmcnt(0)
	v_pk_fma_f32 v[110:111], v[110:111], v[114:115], v[78:79] op_sel_hi:[1,0,1]
	v_pk_fma_f32 v[102:103], v[102:103], v[114:115], v[70:71] op_sel_hi:[1,0,1]
	v_pk_fma_f32 v[118:119], v[100:101], v[114:115], v[68:69] op_sel_hi:[1,0,1]
	v_pk_fma_f32 v[100:101], v[98:99], v[114:115], v[66:67] op_sel_hi:[1,0,1]
	v_mul_f32_e32 v99, 0xbfb8aa3b, v110
	v_mul_f32_e32 v98, v110, v102
	v_exp_f32_e32 v99, v99
	v_mul_f32_e32 v102, 0xbfb8aa3b, v111
	v_exp_f32_e32 v102, v102
	v_pk_fma_f32 v[112:113], v[112:113], v[114:115], v[80:81] op_sel_hi:[1,0,1]
	v_add_f32_e32 v99, 1.0, v99
	v_rcp_f32_e32 v99, v99
	v_add_f32_e32 v102, 1.0, v102
	v_rcp_f32_e32 v102, v102
	v_pk_fma_f32 v[104:105], v[104:105], v[114:115], v[72:73] op_sel_hi:[1,0,1]
	v_mul_f32_e32 v98, v98, v99
	v_mul_f32_e32 v99, v111, v103
	v_mul_f32_e32 v99, v99, v102
	v_mul_f32_e32 v102, 0xbfb8aa3b, v112
	v_exp_f32_e32 v102, v102
	v_mul_f32_e32 v103, 0xbfb8aa3b, v113
	v_exp_f32_e32 v103, v103
	v_cvt_pk_bf16_f32 v98, v98, v99
	v_add_f32_e32 v102, 1.0, v102
	v_rcp_f32_e32 v102, v102
	v_add_f32_e32 v103, 1.0, v103
	v_rcp_f32_e32 v103, v103
	v_mul_f32_e32 v99, v112, v104
	v_mul_f32_e32 v99, v99, v102
	v_mul_f32_e32 v102, v113, v105
	v_pk_fma_f32 v[106:107], v[106:107], v[114:115], v[74:75] op_sel_hi:[1,0,1]
	v_mul_f32_e32 v102, v102, v103
	v_cvt_pk_bf16_f32 v99, v99, v102
	v_mul_f32_e32 v102, 0xbfb8aa3b, v106
	v_exp_f32_e32 v102, v102
	v_mul_f32_e32 v100, v106, v100
	v_pk_fma_f32 v[108:109], v[108:109], v[114:115], v[76:77] op_sel_hi:[1,0,1]
	v_mul_f32_e32 v101, v107, v101
	v_add_f32_e32 v102, 1.0, v102
	v_rcp_f32_e32 v102, v102
	v_mul_f32_e32 v103, 0xbfb8aa3b, v109
	v_exp_f32_e32 v103, v103
	v_lshl_add_u64 v[116:117], v[116:117], 0, v[164:165]
	v_mul_f32_e32 v100, v100, v102
	v_mul_f32_e32 v102, 0xbfb8aa3b, v107
	v_exp_f32_e32 v102, v102
	v_add_f32_e32 v103, 1.0, v103
	v_rcp_f32_e32 v103, v103
	v_add_f32_e32 v102, 1.0, v102
	v_rcp_f32_e32 v102, v102
	s_nop 0
	v_mul_f32_e32 v101, v101, v102
	v_mul_f32_e32 v102, 0xbfb8aa3b, v108
	v_exp_f32_e32 v102, v102
	v_cvt_pk_bf16_f32 v100, v100, v101
	v_mul_f32_e32 v101, v108, v118
	v_add_f32_e32 v102, 1.0, v102
	v_rcp_f32_e32 v102, v102
	s_nop 0
	v_mul_f32_e32 v101, v101, v102
	v_mul_f32_e32 v102, v109, v119
	v_mul_f32_e32 v102, v102, v103
	v_cvt_pk_bf16_f32 v101, v101, v102
	global_store_dwordx4 v[116:117], v[98:101], off
	ds_bpermute_b32 v98, v180, v183 offset:192
	s_nop 0
	v_or_b32_e32 v99, 48, v181
	v_mad_i64_i32 v[100:101], s[2:3], v99, s59, v[162:163]
	s_waitcnt lgkmcnt(0)
; __device__ __forceinline__ unsigned cvt_pk_bf16(float lo, float hi) { unsigned r; asm volatile("v_cvt_pk_bf16_f32 %0, %1, %2" : "=v"(r) : "v"(lo), "v"(hi)); return r; }
; __device__ __forceinline__ float row_rstd(const float* ss, int row) { return 1.0f / sqrtf(ss[row] * (1.0f / DM) + 1e-6f); }
; __device__ __forceinline__ float silu_mul(float a, float b) { return a * b * __builtin_amdgcn_rcpf(1.0f + __builtin_amdgcn_exp2f(-a * LOG2E)); }
;     __device__ __forceinline__ void operator()(const f32x4 (&acc)[2][2][4][2], const Unit& u, int wr, int wc, int fr, int fq) const {
;     ...
;         const float rsl0 = row_rstd(ss, u.pm * BM + wr * 64 + lane), rsl1 = row_rstd(ss, u.pm * BM + HALF + wr * 64 + lane);
; #pragma unroll
;         for (int ai = 0; ai < 2; ++ai)
; #pragma unroll
;             for (int m = 0; m < 4; ++m) { const int row = row0 + ai * HALF + m * 16; const float rs = __shfl(ai ? rsl1 : rsl0, m * 16 + fr); bf16_t* rowp = O + (size_t)row * DFF + col0;
;                 const f32x4 a0 = acc[ai][0][m][0] * rs + ba0, a1 = acc[ai][0][m][1] * rs + ba1, b0 = acc[ai][1][m][0] * rs + bb0, b1 = acc[ai][1][m][1] * rs + bb1;
;                 u32x4 w; w.x = cvt_pk_bf16(silu_mul(a0[0], b0[0]), silu_mul(a0[1], b0[1])); w.y = cvt_pk_bf16(silu_mul(a0[2], b0[2]), silu_mul(a0[3], b0[3]));
;                 w.z = cvt_pk_bf16(silu_mul(a1[0], b1[0]), silu_mul(a1[1], b1[1])); w.w = cvt_pk_bf16(silu_mul(a1[2], b1[2]), silu_mul(a1[3], b1[3]));
;                 *(u32x4*)rowp = w; }
	v_pk_fma_f32 v[94:95], v[94:95], v[98:99], v[78:79] op_sel_hi:[1,0,1]
	v_pk_fma_f32 v[86:87], v[86:87], v[98:99], v[70:71] op_sel_hi:[1,0,1]
	v_pk_fma_f32 v[102:103], v[84:85], v[98:99], v[68:69] op_sel_hi:[1,0,1]
	v_pk_fma_f32 v[84:85], v[82:83], v[98:99], v[66:67] op_sel_hi:[1,0,1]
	v_mul_f32_e32 v83, 0xbfb8aa3b, v94
	v_mul_f32_e32 v82, v94, v86
	v_exp_f32_e32 v83, v83
	v_mul_f32_e32 v86, 0xbfb8aa3b, v95
	v_exp_f32_e32 v86, v86
	v_pk_fma_f32 v[96:97], v[96:97], v[98:99], v[80:81] op_sel_hi:[1,0,1]
	v_add_f32_e32 v83, 1.0, v83
	v_rcp_f32_e32 v83, v83
	v_add_f32_e32 v86, 1.0, v86
	v_rcp_f32_e32 v86, v86
	v_pk_fma_f32 v[88:89], v[88:89], v[98:99], v[72:73] op_sel_hi:[1,0,1]
	v_mul_f32_e32 v82, v82, v83
	v_mul_f32_e32 v83, v95, v87
	v_mul_f32_e32 v83, v83, v86
	v_mul_f32_e32 v86, 0xbfb8aa3b, v96
	v_exp_f32_e32 v86, v86
	v_mul_f32_e32 v87, 0xbfb8aa3b, v97
	v_exp_f32_e32 v87, v87
	v_cvt_pk_bf16_f32 v82, v82, v83
	v_add_f32_e32 v86, 1.0, v86
	v_rcp_f32_e32 v86, v86
	v_add_f32_e32 v87, 1.0, v87
	v_rcp_f32_e32 v87, v87
	v_mul_f32_e32 v83, v96, v88
	v_mul_f32_e32 v83, v83, v86
	v_mul_f32_e32 v86, v97, v89
	v_pk_fma_f32 v[90:91], v[90:91], v[98:99], v[74:75] op_sel_hi:[1,0,1]
	v_mul_f32_e32 v86, v86, v87
	v_cvt_pk_bf16_f32 v83, v83, v86
	v_mul_f32_e32 v86, 0xbfb8aa3b, v90
	v_exp_f32_e32 v86, v86
	v_mul_f32_e32 v84, v90, v84
	v_pk_fma_f32 v[92:93], v[92:93], v[98:99], v[76:77] op_sel_hi:[1,0,1]
	v_mul_f32_e32 v85, v91, v85
	v_add_f32_e32 v86, 1.0, v86
	v_rcp_f32_e32 v86, v86
	v_mul_f32_e32 v87, 0xbfb8aa3b, v93
	v_exp_f32_e32 v87, v87
	v_lshl_add_u64 v[100:101], v[100:101], 0, v[164:165]
	v_mul_f32_e32 v84, v84, v86
	v_mul_f32_e32 v86, 0xbfb8aa3b, v91
	v_exp_f32_e32 v86, v86
	v_add_f32_e32 v87, 1.0, v87
	v_rcp_f32_e32 v87, v87
	v_add_f32_e32 v86, 1.0, v86
	v_rcp_f32_e32 v86, v86
	s_nop 0
	v_mul_f32_e32 v85, v85, v86
	v_mul_f32_e32 v86, 0xbfb8aa3b, v92
	v_exp_f32_e32 v86, v86
	v_cvt_pk_bf16_f32 v84, v84, v85
	v_mul_f32_e32 v85, v92, v102
	v_add_f32_e32 v86, 1.0, v86
	v_rcp_f32_e32 v86, v86
	s_nop 0
	v_mul_f32_e32 v85, v85, v86
	v_mul_f32_e32 v86, v93, v103
	v_mul_f32_e32 v86, v86, v87
	v_cvt_pk_bf16_f32 v85, v85, v86
	global_store_dwordx4 v[100:101], v[82:85], off
	s_nop 1
	v_div_scale_f32 v82, s[2:3], v182, v182, 1.0
	v_rcp_f32_e32 v84, v82
	v_add_u32_e32 v83, 0x80, v181
	v_fma_f32 v85, -v82, v84, 1.0
	v_fmac_f32_e32 v84, v85, v84
	v_div_scale_f32 v85, vcc, 1.0, v182, 1.0
	v_mul_f32_e32 v86, v85, v84
	v_fma_f32 v87, -v82, v86, v85
	v_fmac_f32_e32 v86, v87, v84
	v_fma_f32 v82, -v82, v86, v85
	v_div_fmas_f32 v82, v82, v84, v86
	v_div_fixup_f32 v82, v82, v182, 1.0
	ds_bpermute_b32 v84, v180, v82
	v_mad_i64_i32 v[86:87], s[2:3], v83, s59, v[162:163]
	v_lshl_add_u64 v[86:87], v[86:87], 0, v[164:165]
	s_andn2_b64 vcc, exec, s[38:39]
	s_waitcnt lgkmcnt(0)
	v_pk_fma_f32 v[62:63], v[62:63], v[84:85], v[78:79] op_sel_hi:[1,0,1]
	v_pk_fma_f32 v[54:55], v[54:55], v[84:85], v[70:71] op_sel_hi:[1,0,1]
	v_pk_fma_f32 v[88:89], v[52:53], v[84:85], v[68:69] op_sel_hi:[1,0,1]
	v_pk_fma_f32 v[52:53], v[50:51], v[84:85], v[66:67] op_sel_hi:[1,0,1]
	v_mul_f32_e32 v51, 0xbfb8aa3b, v62
	v_mul_f32_e32 v50, v62, v54
	v_exp_f32_e32 v51, v51
	v_mul_f32_e32 v54, 0xbfb8aa3b, v63
	v_exp_f32_e32 v54, v54
	v_pk_fma_f32 v[64:65], v[64:65], v[84:85], v[80:81] op_sel_hi:[1,0,1]
	v_add_f32_e32 v51, 1.0, v51
	v_rcp_f32_e32 v51, v51
	v_add_f32_e32 v54, 1.0, v54
	v_rcp_f32_e32 v54, v54
	v_pk_fma_f32 v[56:57], v[56:57], v[84:85], v[72:73] op_sel_hi:[1,0,1]
	v_mul_f32_e32 v50, v50, v51
	v_mul_f32_e32 v51, v63, v55
	v_mul_f32_e32 v51, v51, v54
	v_mul_f32_e32 v54, 0xbfb8aa3b, v64
	v_exp_f32_e32 v54, v54
	v_mul_f32_e32 v55, 0xbfb8aa3b, v65
	v_exp_f32_e32 v55, v55
	v_cvt_pk_bf16_f32 v50, v50, v51
	v_add_f32_e32 v54, 1.0, v54
	v_rcp_f32_e32 v54, v54
	v_add_f32_e32 v55, 1.0, v55
	v_rcp_f32_e32 v55, v55
	v_mul_f32_e32 v51, v64, v56
	v_mul_f32_e32 v51, v51, v54
	v_mul_f32_e32 v54, v65, v57
	v_pk_fma_f32 v[58:59], v[58:59], v[84:85], v[74:75] op_sel_hi:[1,0,1]
	v_mul_f32_e32 v54, v54, v55
	v_cvt_pk_bf16_f32 v51, v51, v54
	v_mul_f32_e32 v54, 0xbfb8aa3b, v58
	v_exp_f32_e32 v54, v54
	v_mul_f32_e32 v52, v58, v52
	v_pk_fma_f32 v[60:61], v[60:61], v[84:85], v[76:77] op_sel_hi:[1,0,1]
	v_mul_f32_e32 v53, v59, v53
	v_add_f32_e32 v54, 1.0, v54
	v_rcp_f32_e32 v54, v54
	v_mul_f32_e32 v55, 0xbfb8aa3b, v61
	v_exp_f32_e32 v55, v55
	v_mul_f32_e32 v52, v52, v54
	v_mul_f32_e32 v54, 0xbfb8aa3b, v59
	v_exp_f32_e32 v54, v54
	v_add_f32_e32 v55, 1.0, v55
	v_rcp_f32_e32 v55, v55
	v_add_f32_e32 v54, 1.0, v54
	v_rcp_f32_e32 v54, v54
	s_nop 0
	v_mul_f32_e32 v53, v53, v54
	v_mul_f32_e32 v54, 0xbfb8aa3b, v60
	v_exp_f32_e32 v54, v54
	v_cvt_pk_bf16_f32 v52, v52, v53
	v_mul_f32_e32 v53, v60, v88
	v_add_f32_e32 v54, 1.0, v54
	v_rcp_f32_e32 v54, v54
	s_nop 0
	v_mul_f32_e32 v53, v53, v54
	v_mul_f32_e32 v54, v61, v89
	v_mul_f32_e32 v54, v54, v55
	v_cvt_pk_bf16_f32 v53, v53, v54
	global_store_dwordx4 v[86:87], v[50:53], off
	ds_bpermute_b32 v50, v180, v82 offset:64
	s_nop 0
	v_add_u32_e32 v51, 0x90, v181
	v_mad_i64_i32 v[52:53], s[2:3], v51, s59, v[162:163]
	s_waitcnt lgkmcnt(0)
; __device__ __forceinline__ unsigned cvt_pk_bf16(float lo, float hi) { unsigned r; asm volatile("v_cvt_pk_bf16_f32 %0, %1, %2" : "=v"(r) : "v"(lo), "v"(hi)); return r; }
; __device__ __forceinline__ float silu_mul(float a, float b) { return a * b * __builtin_amdgcn_rcpf(1.0f + __builtin_amdgcn_exp2f(-a * LOG2E)); }
; #define PG8_BAR __builtin_amdgcn_s_barrier()
;     __device__ __forceinline__ void operator()(const f32x4 (&acc)[2][2][4][2], const Unit& u, int wr, int wc, int fr, int fq) const {
;     ...
;             for (int m = 0; m < 4; ++m) { const int row = row0 + ai * HALF + m * 16; const float rs = __shfl(ai ? rsl1 : rsl0, m * 16 + fr); bf16_t* rowp = O + (size_t)row * DFF + col0;
;                 const f32x4 a0 = acc[ai][0][m][0] * rs + ba0, a1 = acc[ai][0][m][1] * rs + ba1, b0 = acc[ai][1][m][0] * rs + bb0, b1 = acc[ai][1][m][1] * rs + bb1;
;                 u32x4 w; w.x = cvt_pk_bf16(silu_mul(a0[0], b0[0]), silu_mul(a0[1], b0[1])); w.y = cvt_pk_bf16(silu_mul(a0[2], b0[2]), silu_mul(a0[3], b0[3]));
;                 w.z = cvt_pk_bf16(silu_mul(a1[0], b1[0]), silu_mul(a1[1], b1[1])); w.w = cvt_pk_bf16(silu_mul(a1[2], b1[2]), silu_mul(a1[3], b1[3]));
;                 *(u32x4*)rowp = w; }
; template <class Epi, class Sched, bool ALIGN_EPI = false, bool SP2 = false>
; __device__ __forceinline__ void gemm_phase(LAS unsigned char* lds, const Gemm g, const Sched& S, const Epi& E) {
;     ...
;         if constexpr (!Epi::AFTER_DRAIN) { E(acc, cur, wr, wc, fr, fq); S.done(cur); }
;         if (!has_next) break;
; #pragma unroll
;         for (int a = 0; a < 2; ++a)
; #pragma unroll
;             for (int b = 0; b < 2; ++b)
; #pragma unroll
;                 for (int m = 0; m < 4; ++m)
; #pragma unroll
;                     for (int n = 0; n < 2; ++n) acc[a][b][m][n] = (f32x4){0.f, 0.f, 0.f, 0.f};
;         cur = nxt; cA = nA; cB = nB; ++ui;
;         if constexpr (ALIGN_EPI) { if (wr == 1) PG8_BAR; }
;     }
	v_pk_fma_f32 v[46:47], v[46:47], v[50:51], v[78:79] op_sel_hi:[1,0,1]
	v_pk_fma_f32 v[38:39], v[38:39], v[50:51], v[70:71] op_sel_hi:[1,0,1]
	v_pk_fma_f32 v[54:55], v[36:37], v[50:51], v[68:69] op_sel_hi:[1,0,1]
	v_pk_fma_f32 v[36:37], v[34:35], v[50:51], v[66:67] op_sel_hi:[1,0,1]
	v_mul_f32_e32 v35, 0xbfb8aa3b, v46
	v_mul_f32_e32 v34, v46, v38
	v_exp_f32_e32 v35, v35
	v_mul_f32_e32 v38, 0xbfb8aa3b, v47
	v_exp_f32_e32 v38, v38
	v_pk_fma_f32 v[48:49], v[48:49], v[50:51], v[80:81] op_sel_hi:[1,0,1]
	v_add_f32_e32 v35, 1.0, v35
	v_rcp_f32_e32 v35, v35
	v_add_f32_e32 v38, 1.0, v38
	v_rcp_f32_e32 v38, v38
	v_pk_fma_f32 v[40:41], v[40:41], v[50:51], v[72:73] op_sel_hi:[1,0,1]
	v_mul_f32_e32 v34, v34, v35
	v_mul_f32_e32 v35, v47, v39
	v_mul_f32_e32 v35, v35, v38
	v_mul_f32_e32 v38, 0xbfb8aa3b, v48
	v_exp_f32_e32 v38, v38
	v_mul_f32_e32 v39, 0xbfb8aa3b, v49
	v_exp_f32_e32 v39, v39
	v_cvt_pk_bf16_f32 v34, v34, v35
	v_add_f32_e32 v38, 1.0, v38
	v_rcp_f32_e32 v38, v38
	v_add_f32_e32 v39, 1.0, v39
	v_rcp_f32_e32 v39, v39
	v_mul_f32_e32 v35, v48, v40
	v_mul_f32_e32 v35, v35, v38
	v_mul_f32_e32 v38, v49, v41
	v_pk_fma_f32 v[42:43], v[42:43], v[50:51], v[74:75] op_sel_hi:[1,0,1]
	v_mul_f32_e32 v38, v38, v39
	v_cvt_pk_bf16_f32 v35, v35, v38
	v_mul_f32_e32 v38, 0xbfb8aa3b, v42
	v_exp_f32_e32 v38, v38
	v_mul_f32_e32 v36, v42, v36
	v_pk_fma_f32 v[44:45], v[44:45], v[50:51], v[76:77] op_sel_hi:[1,0,1]
	v_mul_f32_e32 v37, v43, v37
	v_add_f32_e32 v38, 1.0, v38
	v_rcp_f32_e32 v38, v38
	v_mul_f32_e32 v39, 0xbfb8aa3b, v45
	v_exp_f32_e32 v39, v39
	v_lshl_add_u64 v[52:53], v[52:53], 0, v[164:165]
	v_mul_f32_e32 v36, v36, v38
	v_mul_f32_e32 v38, 0xbfb8aa3b, v43
	v_exp_f32_e32 v38, v38
	v_add_f32_e32 v39, 1.0, v39
	v_rcp_f32_e32 v39, v39
	v_add_f32_e32 v38, 1.0, v38
	v_rcp_f32_e32 v38, v38
	s_nop 0
	v_mul_f32_e32 v37, v37, v38
	v_mul_f32_e32 v38, 0xbfb8aa3b, v44
	v_exp_f32_e32 v38, v38
	v_cvt_pk_bf16_f32 v36, v36, v37
	v_mul_f32_e32 v37, v44, v54
	v_add_f32_e32 v38, 1.0, v38
	v_rcp_f32_e32 v38, v38
	s_nop 0
	v_mul_f32_e32 v37, v37, v38
	v_mul_f32_e32 v38, v45, v55
	v_mul_f32_e32 v38, v38, v39
	v_cvt_pk_bf16_f32 v37, v37, v38
	global_store_dwordx4 v[52:53], v[34:37], off
	ds_bpermute_b32 v34, v180, v82 offset:128
	s_nop 0
	v_add_u32_e32 v35, 0xa0, v181
	v_mad_i64_i32 v[36:37], s[2:3], v35, s59, v[162:163]
	s_waitcnt lgkmcnt(0)
	v_pk_fma_f32 v[30:31], v[30:31], v[34:35], v[78:79] op_sel_hi:[1,0,1]
	v_pk_fma_f32 v[22:23], v[22:23], v[34:35], v[70:71] op_sel_hi:[1,0,1]
	v_pk_fma_f32 v[38:39], v[20:21], v[34:35], v[68:69] op_sel_hi:[1,0,1]
	v_pk_fma_f32 v[20:21], v[18:19], v[34:35], v[66:67] op_sel_hi:[1,0,1]
	v_mul_f32_e32 v19, 0xbfb8aa3b, v30
	v_mul_f32_e32 v18, v30, v22
	v_exp_f32_e32 v19, v19
	v_mul_f32_e32 v22, 0xbfb8aa3b, v31
	v_exp_f32_e32 v22, v22
	v_pk_fma_f32 v[32:33], v[32:33], v[34:35], v[80:81] op_sel_hi:[1,0,1]
	v_add_f32_e32 v19, 1.0, v19
	v_rcp_f32_e32 v19, v19
	v_add_f32_e32 v22, 1.0, v22
	v_rcp_f32_e32 v22, v22
	v_pk_fma_f32 v[24:25], v[24:25], v[34:35], v[72:73] op_sel_hi:[1,0,1]
	v_mul_f32_e32 v18, v18, v19
	v_mul_f32_e32 v19, v31, v23
	v_mul_f32_e32 v19, v19, v22
	v_mul_f32_e32 v22, 0xbfb8aa3b, v32
	v_exp_f32_e32 v22, v22
	v_mul_f32_e32 v23, 0xbfb8aa3b, v33
	v_exp_f32_e32 v23, v23
	v_cvt_pk_bf16_f32 v18, v18, v19
	v_add_f32_e32 v22, 1.0, v22
	v_rcp_f32_e32 v22, v22
	v_add_f32_e32 v23, 1.0, v23
	v_rcp_f32_e32 v23, v23
	v_mul_f32_e32 v19, v32, v24
	v_mul_f32_e32 v19, v19, v22
	v_mul_f32_e32 v22, v33, v25
	v_pk_fma_f32 v[26:27], v[26:27], v[34:35], v[74:75] op_sel_hi:[1,0,1]
	v_mul_f32_e32 v22, v22, v23
	v_cvt_pk_bf16_f32 v19, v19, v22
	v_mul_f32_e32 v22, 0xbfb8aa3b, v26
	v_exp_f32_e32 v22, v22
	v_mul_f32_e32 v20, v26, v20
	v_pk_fma_f32 v[28:29], v[28:29], v[34:35], v[76:77] op_sel_hi:[1,0,1]
	v_mul_f32_e32 v21, v27, v21
	v_add_f32_e32 v22, 1.0, v22
	v_rcp_f32_e32 v22, v22
	v_mul_f32_e32 v23, 0xbfb8aa3b, v29
	v_exp_f32_e32 v23, v23
	v_lshl_add_u64 v[36:37], v[36:37], 0, v[164:165]
	v_mul_f32_e32 v20, v20, v22
	v_mul_f32_e32 v22, 0xbfb8aa3b, v27
	v_exp_f32_e32 v22, v22
	v_add_f32_e32 v23, 1.0, v23
	v_rcp_f32_e32 v23, v23
	v_add_f32_e32 v22, 1.0, v22
	v_rcp_f32_e32 v22, v22
	s_nop 0
	v_mul_f32_e32 v21, v21, v22
	v_mul_f32_e32 v22, 0xbfb8aa3b, v28
	v_exp_f32_e32 v22, v22
	v_cvt_pk_bf16_f32 v20, v20, v21
	v_mul_f32_e32 v21, v28, v38
	v_add_f32_e32 v22, 1.0, v22
	v_rcp_f32_e32 v22, v22
	s_nop 0
	v_mul_f32_e32 v21, v21, v22
	v_mul_f32_e32 v22, v29, v39
	v_mul_f32_e32 v22, v22, v23
	v_cvt_pk_bf16_f32 v21, v21, v22
	global_store_dwordx4 v[36:37], v[18:21], off
	ds_bpermute_b32 v18, v180, v82 offset:192
	s_nop 0
	v_add_u32_e32 v19, 0xb0, v181
	v_mad_i64_i32 v[20:21], s[2:3], v19, s59, v[162:163]
	s_waitcnt lgkmcnt(0)
	v_pk_fma_f32 v[14:15], v[14:15], v[18:19], v[78:79] op_sel_hi:[1,0,1]
	v_pk_fma_f32 v[6:7], v[6:7], v[18:19], v[70:71] op_sel_hi:[1,0,1]
	v_pk_fma_f32 v[22:23], v[4:5], v[18:19], v[68:69] op_sel_hi:[1,0,1]
	v_pk_fma_f32 v[4:5], v[2:3], v[18:19], v[66:67] op_sel_hi:[1,0,1]
	v_mul_f32_e32 v3, 0xbfb8aa3b, v14
	v_mul_f32_e32 v2, v14, v6
	v_exp_f32_e32 v3, v3
	v_mul_f32_e32 v6, 0xbfb8aa3b, v15
	v_exp_f32_e32 v6, v6
	v_pk_fma_f32 v[16:17], v[16:17], v[18:19], v[80:81] op_sel_hi:[1,0,1]
	v_add_f32_e32 v3, 1.0, v3
	v_rcp_f32_e32 v3, v3
	v_add_f32_e32 v6, 1.0, v6
	v_rcp_f32_e32 v6, v6
	v_pk_fma_f32 v[8:9], v[8:9], v[18:19], v[72:73] op_sel_hi:[1,0,1]
	v_mul_f32_e32 v2, v2, v3
	v_mul_f32_e32 v3, v15, v7
	v_mul_f32_e32 v3, v3, v6
	v_mul_f32_e32 v6, 0xbfb8aa3b, v16
	v_exp_f32_e32 v6, v6
	v_mul_f32_e32 v7, 0xbfb8aa3b, v17
	v_exp_f32_e32 v7, v7
	v_cvt_pk_bf16_f32 v2, v2, v3
	v_add_f32_e32 v6, 1.0, v6
	v_rcp_f32_e32 v6, v6
	v_add_f32_e32 v7, 1.0, v7
	v_rcp_f32_e32 v7, v7
	v_mul_f32_e32 v3, v16, v8
	v_mul_f32_e32 v3, v3, v6
	v_mul_f32_e32 v6, v17, v9
	v_pk_fma_f32 v[10:11], v[10:11], v[18:19], v[74:75] op_sel_hi:[1,0,1]
	v_mul_f32_e32 v6, v6, v7
	v_cvt_pk_bf16_f32 v3, v3, v6
	v_mul_f32_e32 v6, 0xbfb8aa3b, v10
	v_exp_f32_e32 v6, v6
	v_mul_f32_e32 v4, v10, v4
	v_pk_fma_f32 v[12:13], v[12:13], v[18:19], v[76:77] op_sel_hi:[1,0,1]
	v_mul_f32_e32 v5, v11, v5
	v_add_f32_e32 v6, 1.0, v6
	v_rcp_f32_e32 v6, v6
	v_mul_f32_e32 v7, 0xbfb8aa3b, v13
	v_exp_f32_e32 v7, v7
	v_lshl_add_u64 v[20:21], v[20:21], 0, v[164:165]
	v_mul_f32_e32 v4, v4, v6
	v_mul_f32_e32 v6, 0xbfb8aa3b, v11
	v_exp_f32_e32 v6, v6
	v_add_f32_e32 v7, 1.0, v7
	v_rcp_f32_e32 v7, v7
	s_mov_b64 s[2:3], -1
	v_add_f32_e32 v6, 1.0, v6
	v_rcp_f32_e32 v6, v6
	s_nop 0
	v_mul_f32_e32 v5, v5, v6
	v_mul_f32_e32 v6, 0xbfb8aa3b, v12
	v_exp_f32_e32 v6, v6
	v_cvt_pk_bf16_f32 v4, v4, v5
	v_mul_f32_e32 v5, v12, v22
	v_add_f32_e32 v6, 1.0, v6
	v_rcp_f32_e32 v6, v6
	s_nop 0
	v_mul_f32_e32 v5, v5, v6
	v_mul_f32_e32 v6, v13, v23
	v_mul_f32_e32 v6, v6, v7
	v_cvt_pk_bf16_f32 v5, v5, v6
	global_store_dwordx4 v[20:21], v[2:5], off
	s_cbranch_vccnz .LBB0_184
	s_andn2_b64 vcc, exec, s[4:5]
	s_cbranch_vccnz .LBB0_183
	s_barrier
	s_branch .LBB0_183

;     __device__ bool next(int i, Unit& u) const { if (i != 0 || c >= 128) return false; const int t = c >> 2; u.pm = t & 3; u.pn = t >> 2; u.koff = koff_bytes; u.q = c & 3; return true; }
; #define PG8_STAGE(bufoff, gbase, voff) do { _Pragma("unroll") for (int _i = 0; _i < 2; ++_i) \
;         __builtin_amdgcn_global_load_lds((const unsigned*)((const char*)(gbase) + (voff)[_i]), (LAS unsigned*)(lds + (bufoff) + ldsw + _i * 8192), 16, 0, 0); } while (0)
; template <class Epi, class Sched, bool ALIGN_EPI = false, bool SP2 = false>
; __device__ __forceinline__ void gemm_phase(LAS unsigned char* lds, const Gemm g, const Sched& S, const Epi& E) {
;     ...
;         const bool has_next = S.next(ui + 1, nxt);
;         const char* nA = has_next ? (const char*)g.A + (size_t)nxt.pm * tstep + nxt.koff : cA; const char* nB = has_next ? (const char*)g.Bt + (size_t)nxt.pn * tstep + nxt.koff : cB;
;         for (int t = 0; t < nt; t += 2) {
;             const bool last = (t == nt - 2);
;             const char* a1 = cA + (size_t)(t + 1) * kstep;
;             const char* a2 = last ? nA : cA + (size_t)(t + 2) * kstep; const char* b2 = last ? nB : cB + (size_t)(t + 2) * kstep;
;             const char* a3 = a2 + kstep; const char* b3 = b2 + kstep;
;             if (last && has_next) S.a_ready(nxt);
;             if constexpr (SP2) {
;             PG8_LDB(B0, 0, 0); PG8_LDB(B1, 0, 1); PG8_SCHED; PG8_LDA(At, 0, 0); PG8_STAGE(PG8_SA(1, 1), a1 + hstep, voffA);
;             PG8_WAIT_V(8); PG8_WAIT_L(0); PG8_BAR; PG8_MMA(0, 0, At, B0); PG8_MMA(0, 1, At, B1); PG8_BAR; PG8_SCHED;
;             PG8_LDA(At, 0, 1); PG8_STAGE(PG8_SB(0, 0), b2, voffB); PG8_STAGE(PG8_SB(0, 1), b2 + hstepB, voffB); PG8_STAGE(PG8_SA(0, 0), a2, voffA);
;             PG8_WAIT_V(8); PG8_WAIT_L(0); PG8_BAR; PG8_MMA(1, 0, At, B0); PG8_MMA(1, 1, At, B1); PG8_BAR; PG8_SCHED;
;             PG8_LDB(B0, 1, 0); PG8_LDB(B1, 1, 1); PG8_SCHED; PG8_LDA(At, 1, 0); PG8_STAGE(PG8_SA(0, 1), a2 + hstep, voffA);
;             PG8_WAIT_V(8); PG8_WAIT_L(0); PG8_BAR; PG8_MMA(0, 0, At, B0); PG8_MMA(0, 1, At, B1); PG8_BAR; PG8_SCHED;
;             PG8_LDA(At, 1, 1); PG8_STAGE(PG8_SB(1, 0), b3, voffB); PG8_STAGE(PG8_SB(1, 1), b3 + hstepB, voffB); PG8_STAGE(PG8_SA(1, 0), a3, voffA);
;             PG8_WAIT_V(8); PG8_WAIT_L(0); PG8_BAR; PG8_MMA(1, 0, At, B0); PG8_MMA(1, 1, At, B1); PG8_BAR; PG8_SCHED;
.LBB0_316:
	s_add_u32 s5, s22, 0x100
	s_addc_u32 s12, s23, 0
	s_mov_b32 s13, -2
	ds_read_b128 v[130:133], v196
	ds_read_b128 v[134:137], v196 offset:1024
	ds_read_b128 v[138:141], v196 offset:2048
	ds_read_b128 v[142:145], v196 offset:3072
	ds_read_b128 v[166:169], v197
	ds_read_b128 v[170:173], v197 offset:1024
	ds_read_b128 v[174:177], v197 offset:2048
	ds_read_b128 v[178:181], v197 offset:3072
	s_add_u32 s54, s16, 0x100
	s_addc_u32 s55, s17, 0
	s_cmpk_eq_i32 s13, 0x54
	s_cselect_b32 s59, s3, s55
	s_cselect_b32 s58, s2, s54
	s_cselect_b32 s57, s53, s12
	s_cselect_b32 s56, s52, s5
	v_lshl_add_u64 v[190:191], s[16:17], 0, v[158:159]
	s_add_i32 m0, s29, 0xc000
	ds_read_b128 v[182:185], v198
	ds_read_b128 v[186:189], v198 offset:1024
	ds_read_b128 v[202:205], v198 offset:2048
	ds_read_b128 v[206:209], v198 offset:3072
	ds_read_b128 v[210:213], v198 offset:4096
	ds_read_b128 v[214:217], v198 offset:5120
	ds_read_b128 v[218:221], v198 offset:6144
	ds_read_b128 v[222:225], v198 offset:7168
	global_load_lds_dwordx4 v[190:191], off
	v_lshl_add_u64 v[190:191], s[16:17], 0, v[160:161]
	s_add_i32 m0, s29, 0xe000
	s_nop 0
	global_load_lds_dwordx4 v[190:191], off
	s_waitcnt lgkmcnt(0)
	s_barrier
	s_setprio 1
	s_waitcnt lgkmcnt(0)
	v_mfma_f32_16x16x32_bf16 v[126:129], v[130:133], v[182:185], 0
	v_mfma_f32_16x16x32_bf16 v[122:125], v[138:141], v[182:185], 0
	v_mfma_f32_16x16x32_bf16 v[110:113], v[130:133], v[202:205], 0
	v_mfma_f32_16x16x32_bf16 v[106:109], v[138:141], v[202:205], 0
	v_mfma_f32_16x16x32_bf16 v[94:97], v[130:133], v[210:213], 0
	v_mfma_f32_16x16x32_bf16 v[90:93], v[138:141], v[210:213], 0
	v_mfma_f32_16x16x32_bf16 v[78:81], v[130:133], v[218:221], 0
	v_mfma_f32_16x16x32_bf16 v[74:77], v[138:141], v[218:221], 0
	v_mfma_f32_16x16x32_bf16 v[126:129], v[134:137], v[186:189], v[126:129]
	v_mfma_f32_16x16x32_bf16 v[122:125], v[142:145], v[186:189], v[122:125]
	v_mfma_f32_16x16x32_bf16 v[110:113], v[134:137], v[206:209], v[110:113]
	v_mfma_f32_16x16x32_bf16 v[106:109], v[142:145], v[206:209], v[106:109]
	v_mfma_f32_16x16x32_bf16 v[94:97], v[134:137], v[214:217], v[94:97]
	v_mfma_f32_16x16x32_bf16 v[90:93], v[142:145], v[214:217], v[90:93]
	v_mfma_f32_16x16x32_bf16 v[78:81], v[134:137], v[222:225], v[78:81]
	v_mfma_f32_16x16x32_bf16 v[74:77], v[142:145], v[222:225], v[74:77]
	s_setprio 0
	s_setprio 1
	v_mfma_f32_16x16x32_bf16 v[118:121], v[166:169], v[182:185], 0
	v_mfma_f32_16x16x32_bf16 v[114:117], v[174:177], v[182:185], 0
	v_mfma_f32_16x16x32_bf16 v[102:105], v[166:169], v[202:205], 0
	v_mfma_f32_16x16x32_bf16 v[98:101], v[174:177], v[202:205], 0
	v_mfma_f32_16x16x32_bf16 v[86:89], v[166:169], v[210:213], 0
	v_mfma_f32_16x16x32_bf16 v[82:85], v[174:177], v[210:213], 0
	v_mfma_f32_16x16x32_bf16 v[70:73], v[166:169], v[218:221], 0
	v_mfma_f32_16x16x32_bf16 v[66:69], v[174:177], v[218:221], 0
	v_mfma_f32_16x16x32_bf16 v[118:121], v[170:173], v[186:189], v[118:121]
	v_mfma_f32_16x16x32_bf16 v[114:117], v[178:181], v[186:189], v[114:117]
	v_mfma_f32_16x16x32_bf16 v[102:105], v[170:173], v[206:209], v[102:105]
	v_mfma_f32_16x16x32_bf16 v[98:101], v[178:181], v[206:209], v[98:101]
	v_mfma_f32_16x16x32_bf16 v[86:89], v[170:173], v[214:217], v[86:89]
	v_mfma_f32_16x16x32_bf16 v[82:85], v[178:181], v[214:217], v[82:85]
	v_mfma_f32_16x16x32_bf16 v[70:73], v[170:173], v[222:225], v[70:73]
	v_mfma_f32_16x16x32_bf16 v[66:69], v[178:181], v[222:225], v[66:69]
	s_setprio 0
	s_barrier
	s_add_i32 s14, s64, s28
	v_lshl_add_u64 v[190:191], s[56:57], 0, v[148:149]
	s_mov_b32 m0, s14
	ds_read_b128 v[182:185], v198 offset:16384
	ds_read_b128 v[186:189], v198 offset:17408
	ds_read_b128 v[202:205], v198 offset:18432
	ds_read_b128 v[206:209], v198 offset:19456
	ds_read_b128 v[210:213], v198 offset:20480
	ds_read_b128 v[214:217], v198 offset:21504
	ds_read_b128 v[218:221], v198 offset:22528
	ds_read_b128 v[222:225], v198 offset:23552
	global_load_lds_dwordx4 v[190:191], off
	s_add_i32 m0, s14, 0x2000
	s_add_u32 s14, s56, 0x58000
	v_lshl_add_u64 v[226:227], s[56:57], 0, v[152:153]
	s_addc_u32 s15, s57, 0
	s_add_i32 s16, s65, s28
	global_load_lds_dwordx4 v[226:227], off
	v_lshl_add_u64 v[228:229], s[14:15], 0, v[148:149]
	s_mov_b32 m0, s16
	v_lshl_add_u64 v[230:231], s[58:59], 0, v[150:151]
	global_load_lds_dwordx4 v[228:229], off
	v_lshl_add_u64 v[228:229], s[14:15], 0, v[152:153]
	s_add_i32 m0, s16, 0x2000
	s_nop 0
	global_load_lds_dwordx4 v[228:229], off
	v_lshl_add_u64 v[228:229], s[58:59], 0, v[146:147]
	s_mov_b32 m0, s29
	s_nop 0
	global_load_lds_dwordx4 v[228:229], off
	s_mov_b32 m0, s30
	s_nop 0
	global_load_lds_dwordx4 v[230:231], off
	s_waitcnt vmcnt(8)
	s_waitcnt lgkmcnt(0)
	s_barrier
; #define PG8_STAGE(bufoff, gbase, voff) do { _Pragma("unroll") for (int _i = 0; _i < 2; ++_i) \
;         __builtin_amdgcn_global_load_lds((const unsigned*)((const char*)(gbase) + (voff)[_i]), (LAS unsigned*)(lds + (bufoff) + ldsw + _i * 8192), 16, 0, 0); } while (0)
; #define PG8_LDA(dst, b, h) do { _Pragma("unroll") for (int m = 0; m < 4; ++m) _Pragma("unroll") for (int k = 0; k < 2; ++k) dst[m][k] = *(const LAS bf16x8*)(lds + PG8_SA(b, h) + aoff + m * 2048 + k * 1024); } while (0)
; #define PG8_LDB(dst, b, h) do { _Pragma("unroll") for (int n = 0; n < 2; ++n) _Pragma("unroll") for (int k = 0; k < 2; ++k) dst[n][k] = *(const LAS bf16x8*)(lds + PG8_SB(b, h) + boff + n * 2048 + k * 1024); } while (0)
; #define PG8_MMA(ai, bj, At, Bt) do { __builtin_amdgcn_s_setprio(1); _Pragma("unroll") for (int m = 0; m < 4; ++m) _Pragma("unroll") for (int n = 0; n < 2; ++n) _Pragma("unroll") for (int k = 0; k < 2; ++k) \
;         acc[ai][bj][m][n] = __builtin_amdgcn_mfma_f32_16x16x32_bf16(Bt[n][k], At[m][k], acc[ai][bj][m][n], 0, 0, 0); __builtin_amdgcn_s_setprio(0); } while (0)
; #define PG8_WAIT_V(n) asm volatile("s_waitcnt vmcnt(" #n ")" ::: "memory")
; template <class Epi, class Sched, bool ALIGN_EPI = false, bool SP2 = false>
; __device__ __forceinline__ void gemm_phase(LAS unsigned char* lds, const Gemm g, const Sched& S, const Epi& E) {
;     ...
;             PG8_LDB(B0, 0, 0); PG8_LDB(B1, 0, 1); PG8_SCHED; PG8_LDA(At, 0, 0); PG8_STAGE(PG8_SA(1, 1), a1 + hstep, voffA);
;             PG8_WAIT_V(8); PG8_WAIT_L(0); PG8_BAR; PG8_MMA(0, 0, At, B0); PG8_MMA(0, 1, At, B1); PG8_BAR; PG8_SCHED;
;             PG8_LDA(At, 0, 1); PG8_STAGE(PG8_SB(0, 0), b2, voffB); PG8_STAGE(PG8_SB(0, 1), b2 + hstepB, voffB); PG8_STAGE(PG8_SA(0, 0), a2, voffA);
;             PG8_WAIT_V(8); PG8_WAIT_L(0); PG8_BAR; PG8_MMA(1, 0, At, B0); PG8_MMA(1, 1, At, B1); PG8_BAR; PG8_SCHED;
;             PG8_LDB(B0, 1, 0); PG8_LDB(B1, 1, 1); PG8_SCHED; PG8_LDA(At, 1, 0); PG8_STAGE(PG8_SA(0, 1), a2 + hstep, voffA);
;             PG8_WAIT_V(8); PG8_WAIT_L(0); PG8_BAR; PG8_MMA(0, 0, At, B0); PG8_MMA(0, 1, At, B1); PG8_BAR; PG8_SCHED;
;             PG8_LDA(At, 1, 1); PG8_STAGE(PG8_SB(1, 0), b3, voffB); PG8_STAGE(PG8_SB(1, 1), b3 + hstepB, voffB); PG8_STAGE(PG8_SA(1, 0), a3, voffA);
;             PG8_WAIT_V(8); PG8_WAIT_L(0); PG8_BAR; PG8_MMA(1, 0, At, B0); PG8_MMA(1, 1, At, B1); PG8_BAR; PG8_SCHED;
	s_setprio 1
	s_waitcnt lgkmcnt(0)
	v_mfma_f32_16x16x32_bf16 v[62:65], v[130:133], v[182:185], 0
	v_mfma_f32_16x16x32_bf16 v[58:61], v[138:141], v[182:185], 0
	v_mfma_f32_16x16x32_bf16 v[46:49], v[130:133], v[202:205], 0
	v_mfma_f32_16x16x32_bf16 v[42:45], v[138:141], v[202:205], 0
	v_mfma_f32_16x16x32_bf16 v[30:33], v[130:133], v[210:213], 0
	v_mfma_f32_16x16x32_bf16 v[26:29], v[138:141], v[210:213], 0
	v_mfma_f32_16x16x32_bf16 v[14:17], v[130:133], v[218:221], 0
	v_mfma_f32_16x16x32_bf16 v[10:13], v[138:141], v[218:221], 0
	v_mfma_f32_16x16x32_bf16 v[62:65], v[134:137], v[186:189], v[62:65]
	v_mfma_f32_16x16x32_bf16 v[58:61], v[142:145], v[186:189], v[58:61]
	v_mfma_f32_16x16x32_bf16 v[46:49], v[134:137], v[206:209], v[46:49]
	v_mfma_f32_16x16x32_bf16 v[42:45], v[142:145], v[206:209], v[42:45]
	v_mfma_f32_16x16x32_bf16 v[30:33], v[134:137], v[214:217], v[30:33]
	v_mfma_f32_16x16x32_bf16 v[26:29], v[142:145], v[214:217], v[26:29]
	v_mfma_f32_16x16x32_bf16 v[14:17], v[134:137], v[222:225], v[14:17]
	v_mfma_f32_16x16x32_bf16 v[10:13], v[142:145], v[222:225], v[10:13]
	s_setprio 0
	s_setprio 1
	v_mfma_f32_16x16x32_bf16 v[54:57], v[166:169], v[182:185], 0
	v_mfma_f32_16x16x32_bf16 v[50:53], v[174:177], v[182:185], 0
	v_mfma_f32_16x16x32_bf16 v[38:41], v[166:169], v[202:205], 0
	v_mfma_f32_16x16x32_bf16 v[34:37], v[174:177], v[202:205], 0
	v_mfma_f32_16x16x32_bf16 v[22:25], v[166:169], v[210:213], 0
	v_mfma_f32_16x16x32_bf16 v[18:21], v[174:177], v[210:213], 0
	v_mfma_f32_16x16x32_bf16 v[6:9], v[166:169], v[218:221], 0
	v_mfma_f32_16x16x32_bf16 v[2:5], v[174:177], v[218:221], 0
	v_mfma_f32_16x16x32_bf16 v[54:57], v[170:173], v[186:189], v[54:57]
	v_mfma_f32_16x16x32_bf16 v[50:53], v[178:181], v[186:189], v[50:53]
	v_mfma_f32_16x16x32_bf16 v[38:41], v[170:173], v[206:209], v[38:41]
	v_mfma_f32_16x16x32_bf16 v[34:37], v[178:181], v[206:209], v[34:37]
	v_mfma_f32_16x16x32_bf16 v[22:25], v[170:173], v[214:217], v[22:25]
	v_mfma_f32_16x16x32_bf16 v[18:21], v[178:181], v[214:217], v[18:21]
	v_mfma_f32_16x16x32_bf16 v[6:9], v[170:173], v[222:225], v[6:9]
	v_mfma_f32_16x16x32_bf16 v[2:5], v[178:181], v[222:225], v[2:5]
	s_setprio 0
	s_barrier
	s_add_i32 s16, 0, 0x18000
	s_add_i32 s17, 0, 0x1c000
	v_add_u32_e32 v142, s16, v1
	v_add_u32_e32 v154, s17, v1
	ds_read_b128 v[130:133], v142
	ds_read_b128 v[134:137], v142 offset:1024
	ds_read_b128 v[138:141], v142 offset:2048
	ds_read_b128 v[142:145], v142 offset:3072
	ds_read_b128 v[166:169], v154
	ds_read_b128 v[170:173], v154 offset:1024
	ds_read_b128 v[174:177], v154 offset:2048
	ds_read_b128 v[178:181], v154 offset:3072
	s_add_u32 s14, s58, 0x160000
	s_addc_u32 s15, s59, 0
	s_mov_b32 m0, s31
	v_lshl_add_u64 v[232:233], s[14:15], 0, v[146:147]
	ds_read_b128 v[182:185], v198 offset:32768
	ds_read_b128 v[186:189], v198 offset:33792
	ds_read_b128 v[202:205], v198 offset:34816
	ds_read_b128 v[206:209], v198 offset:35840
	ds_read_b128 v[210:213], v198 offset:36864
	ds_read_b128 v[214:217], v198 offset:37888
	ds_read_b128 v[218:221], v198 offset:38912
	ds_read_b128 v[222:225], v198 offset:39936
	global_load_lds_dwordx4 v[232:233], off
	v_lshl_add_u64 v[232:233], s[14:15], 0, v[150:151]
	s_mov_b32 m0, s33
	s_nop 0
	global_load_lds_dwordx4 v[232:233], off
	s_waitcnt vmcnt(8)
	s_waitcnt lgkmcnt(0)
	s_barrier
	s_setprio 1
	s_waitcnt lgkmcnt(0)
	v_mfma_f32_16x16x32_bf16 v[126:129], v[130:133], v[182:185], v[126:129]
	v_mfma_f32_16x16x32_bf16 v[122:125], v[138:141], v[182:185], v[122:125]
	v_mfma_f32_16x16x32_bf16 v[110:113], v[130:133], v[202:205], v[110:113]
	v_mfma_f32_16x16x32_bf16 v[106:109], v[138:141], v[202:205], v[106:109]
	v_mfma_f32_16x16x32_bf16 v[94:97], v[130:133], v[210:213], v[94:97]
	v_mfma_f32_16x16x32_bf16 v[90:93], v[138:141], v[210:213], v[90:93]
	v_mfma_f32_16x16x32_bf16 v[78:81], v[130:133], v[218:221], v[78:81]
	v_mfma_f32_16x16x32_bf16 v[74:77], v[138:141], v[218:221], v[74:77]
	v_mfma_f32_16x16x32_bf16 v[126:129], v[134:137], v[186:189], v[126:129]
	v_mfma_f32_16x16x32_bf16 v[122:125], v[142:145], v[186:189], v[122:125]
	v_mfma_f32_16x16x32_bf16 v[110:113], v[134:137], v[206:209], v[110:113]
	v_mfma_f32_16x16x32_bf16 v[106:109], v[142:145], v[206:209], v[106:109]
	v_mfma_f32_16x16x32_bf16 v[94:97], v[134:137], v[214:217], v[94:97]
	v_mfma_f32_16x16x32_bf16 v[90:93], v[142:145], v[214:217], v[90:93]
	v_mfma_f32_16x16x32_bf16 v[78:81], v[134:137], v[222:225], v[78:81]
	v_mfma_f32_16x16x32_bf16 v[74:77], v[142:145], v[222:225], v[74:77]
	s_setprio 0
	s_setprio 1
	v_mfma_f32_16x16x32_bf16 v[118:121], v[166:169], v[182:185], v[118:121]
	v_mfma_f32_16x16x32_bf16 v[114:117], v[174:177], v[182:185], v[114:117]
	v_mfma_f32_16x16x32_bf16 v[102:105], v[166:169], v[202:205], v[102:105]
	v_mfma_f32_16x16x32_bf16 v[98:101], v[174:177], v[202:205], v[98:101]
	v_mfma_f32_16x16x32_bf16 v[86:89], v[166:169], v[210:213], v[86:89]
	v_mfma_f32_16x16x32_bf16 v[82:85], v[174:177], v[210:213], v[82:85]
	v_mfma_f32_16x16x32_bf16 v[70:73], v[166:169], v[218:221], v[70:73]
	v_mfma_f32_16x16x32_bf16 v[66:69], v[174:177], v[218:221], v[66:69]
	v_mfma_f32_16x16x32_bf16 v[118:121], v[170:173], v[186:189], v[118:121]
	v_mfma_f32_16x16x32_bf16 v[114:117], v[178:181], v[186:189], v[114:117]
	v_mfma_f32_16x16x32_bf16 v[102:105], v[170:173], v[206:209], v[102:105]
	v_mfma_f32_16x16x32_bf16 v[98:101], v[178:181], v[206:209], v[98:101]
	v_mfma_f32_16x16x32_bf16 v[86:89], v[170:173], v[214:217], v[86:89]
	v_mfma_f32_16x16x32_bf16 v[82:85], v[178:181], v[214:217], v[82:85]
	v_mfma_f32_16x16x32_bf16 v[70:73], v[170:173], v[222:225], v[70:73]
	v_mfma_f32_16x16x32_bf16 v[66:69], v[178:181], v[222:225], v[66:69]
	s_setprio 0
	s_barrier
; #define PG8_STAGE(bufoff, gbase, voff) do { _Pragma("unroll") for (int _i = 0; _i < 2; ++_i) \
;         __builtin_amdgcn_global_load_lds((const unsigned*)((const char*)(gbase) + (voff)[_i]), (LAS unsigned*)(lds + (bufoff) + ldsw + _i * 8192), 16, 0, 0); } while (0)
; #define PG8_LDA(dst, b, h) do { _Pragma("unroll") for (int m = 0; m < 4; ++m) _Pragma("unroll") for (int k = 0; k < 2; ++k) dst[m][k] = *(const LAS bf16x8*)(lds + PG8_SA(b, h) + aoff + m * 2048 + k * 1024); } while (0)
; #define PG8_LDB(dst, b, h) do { _Pragma("unroll") for (int n = 0; n < 2; ++n) _Pragma("unroll") for (int k = 0; k < 2; ++k) dst[n][k] = *(const LAS bf16x8*)(lds + PG8_SB(b, h) + boff + n * 2048 + k * 1024); } while (0)
; template <class Epi, class Sched, bool ALIGN_EPI = false, bool SP2 = false>
; __device__ __forceinline__ void gemm_phase(LAS unsigned char* lds, const Gemm g, const Sched& S, const Epi& E) {
;     ...
;         for (int t = 0; t < nt; t += 2) {
;             const bool last = (t == nt - 2);
;             const char* a1 = cA + (size_t)(t + 1) * kstep;
;             const char* a2 = last ? nA : cA + (size_t)(t + 2) * kstep; const char* b2 = last ? nB : cB + (size_t)(t + 2) * kstep;
;             const char* a3 = a2 + kstep; const char* b3 = b2 + kstep;
;             if (last && has_next) S.a_ready(nxt);
;             if constexpr (SP2) {
;             PG8_LDB(B0, 0, 0); PG8_LDB(B1, 0, 1); PG8_SCHED; PG8_LDA(At, 0, 0); PG8_STAGE(PG8_SA(1, 1), a1 + hstep, voffA);
;             PG8_WAIT_V(8); PG8_WAIT_L(0); PG8_BAR; PG8_MMA(0, 0, At, B0); PG8_MMA(0, 1, At, B1); PG8_BAR; PG8_SCHED;
;             PG8_LDA(At, 0, 1); PG8_STAGE(PG8_SB(0, 0), b2, voffB); PG8_STAGE(PG8_SB(0, 1), b2 + hstepB, voffB); PG8_STAGE(PG8_SA(0, 0), a2, voffA);
;             PG8_WAIT_V(8); PG8_WAIT_L(0); PG8_BAR; PG8_MMA(1, 0, At, B0); PG8_MMA(1, 1, At, B1); PG8_BAR; PG8_SCHED;
;             PG8_LDB(B0, 1, 0); PG8_LDB(B1, 1, 1); PG8_SCHED; PG8_LDA(At, 1, 0); PG8_STAGE(PG8_SA(0, 1), a2 + hstep, voffA);
;             PG8_WAIT_V(8); PG8_WAIT_L(0); PG8_BAR; PG8_MMA(0, 0, At, B0); PG8_MMA(0, 1, At, B1); PG8_BAR; PG8_SCHED;
;             PG8_LDA(At, 1, 1); PG8_STAGE(PG8_SB(1, 0), b3, voffB); PG8_STAGE(PG8_SB(1, 1), b3 + hstepB, voffB); PG8_STAGE(PG8_SA(1, 0), a3, voffA);
;             PG8_WAIT_V(8); PG8_WAIT_L(0); PG8_BAR; PG8_MMA(1, 0, At, B0); PG8_MMA(1, 1, At, B1); PG8_BAR; PG8_SCHED;
	s_add_i32 s14, s16, s28
	v_lshl_add_u64 v[190:191], v[190:191], 0, s[48:49]
	s_mov_b32 m0, s14
	ds_read_b128 v[182:185], v198 offset:49152
	ds_read_b128 v[186:189], v198 offset:50176
	ds_read_b128 v[202:205], v198 offset:51200
	ds_read_b128 v[206:209], v198 offset:52224
	ds_read_b128 v[210:213], v198 offset:53248
	ds_read_b128 v[214:217], v198 offset:54272
	ds_read_b128 v[218:221], v198 offset:55296
	ds_read_b128 v[222:225], v198 offset:56320
	global_load_lds_dwordx4 v[190:191], off
	s_add_i32 m0, s14, 0x2000
	s_add_u32 s14, s56, 0x58080
	v_lshl_add_u64 v[190:191], v[226:227], 0, s[48:49]
	s_addc_u32 s15, s57, 0
	s_add_i32 s16, s17, s28
	global_load_lds_dwordx4 v[190:191], off
	v_lshl_add_u64 v[190:191], s[14:15], 0, v[148:149]
	s_mov_b32 m0, s16
	s_nop 0
	global_load_lds_dwordx4 v[190:191], off
	v_lshl_add_u64 v[190:191], s[14:15], 0, v[152:153]
	s_add_i32 m0, s16, 0x2000
	s_nop 0
	global_load_lds_dwordx4 v[190:191], off
	v_lshl_add_u64 v[190:191], v[228:229], 0, s[48:49]
	s_mov_b32 m0, s61
	s_nop 0
	global_load_lds_dwordx4 v[190:191], off
	v_lshl_add_u64 v[190:191], v[230:231], 0, s[48:49]
	s_mov_b32 m0, s62
	s_nop 0
	global_load_lds_dwordx4 v[190:191], off
	s_waitcnt vmcnt(8)
	s_waitcnt lgkmcnt(0)
	s_barrier
	s_setprio 1
	s_waitcnt lgkmcnt(0)
	v_mfma_f32_16x16x32_bf16 v[62:65], v[130:133], v[182:185], v[62:65]
	v_mfma_f32_16x16x32_bf16 v[58:61], v[138:141], v[182:185], v[58:61]
	v_mfma_f32_16x16x32_bf16 v[46:49], v[130:133], v[202:205], v[46:49]
	v_mfma_f32_16x16x32_bf16 v[42:45], v[138:141], v[202:205], v[42:45]
	v_mfma_f32_16x16x32_bf16 v[30:33], v[130:133], v[210:213], v[30:33]
	v_mfma_f32_16x16x32_bf16 v[26:29], v[138:141], v[210:213], v[26:29]
	v_mfma_f32_16x16x32_bf16 v[14:17], v[130:133], v[218:221], v[14:17]
	v_mfma_f32_16x16x32_bf16 v[10:13], v[138:141], v[218:221], v[10:13]
	v_mfma_f32_16x16x32_bf16 v[62:65], v[134:137], v[186:189], v[62:65]
	v_mfma_f32_16x16x32_bf16 v[58:61], v[142:145], v[186:189], v[58:61]
	v_mfma_f32_16x16x32_bf16 v[46:49], v[134:137], v[206:209], v[46:49]
	v_mfma_f32_16x16x32_bf16 v[42:45], v[142:145], v[206:209], v[42:45]
	v_mfma_f32_16x16x32_bf16 v[30:33], v[134:137], v[214:217], v[30:33]
	v_mfma_f32_16x16x32_bf16 v[26:29], v[142:145], v[214:217], v[26:29]
	v_mfma_f32_16x16x32_bf16 v[14:17], v[134:137], v[222:225], v[14:17]
	v_mfma_f32_16x16x32_bf16 v[10:13], v[142:145], v[222:225], v[10:13]
	s_setprio 0
	s_setprio 1
	v_mfma_f32_16x16x32_bf16 v[54:57], v[166:169], v[182:185], v[54:57]
	v_mfma_f32_16x16x32_bf16 v[50:53], v[174:177], v[182:185], v[50:53]
	v_mfma_f32_16x16x32_bf16 v[38:41], v[166:169], v[202:205], v[38:41]
	v_mfma_f32_16x16x32_bf16 v[34:37], v[174:177], v[202:205], v[34:37]
	v_mfma_f32_16x16x32_bf16 v[22:25], v[166:169], v[210:213], v[22:25]
	v_mfma_f32_16x16x32_bf16 v[18:21], v[174:177], v[210:213], v[18:21]
	v_mfma_f32_16x16x32_bf16 v[6:9], v[166:169], v[218:221], v[6:9]
	v_mfma_f32_16x16x32_bf16 v[2:5], v[174:177], v[218:221], v[2:5]
	v_mfma_f32_16x16x32_bf16 v[54:57], v[170:173], v[186:189], v[54:57]
	v_mfma_f32_16x16x32_bf16 v[50:53], v[178:181], v[186:189], v[50:53]
	v_mfma_f32_16x16x32_bf16 v[38:41], v[170:173], v[206:209], v[38:41]
	v_mfma_f32_16x16x32_bf16 v[34:37], v[178:181], v[206:209], v[34:37]
	v_mfma_f32_16x16x32_bf16 v[22:25], v[170:173], v[214:217], v[22:25]
	v_mfma_f32_16x16x32_bf16 v[18:21], v[178:181], v[214:217], v[18:21]
	v_mfma_f32_16x16x32_bf16 v[6:9], v[170:173], v[222:225], v[6:9]
	v_mfma_f32_16x16x32_bf16 v[2:5], v[178:181], v[222:225], v[2:5]
	s_setprio 0
	s_barrier
	s_add_i32 s13, s13, 2
	s_add_u32 s5, s5, 0x100
	s_addc_u32 s12, s12, 0
	s_cmpk_gt_u32 s13, 0x55
	s_mov_b64 s[16:17], s[54:55]

;     __device__ bool next(int i, Unit& u) const { if (i != 0 || c >= 128) return false; const int t = c >> 2; u.pm = t & 3; u.pn = t >> 2; u.koff = koff_bytes; u.q = c & 3; return true; }
; #define PG8_STAGE(bufoff, gbase, voff) do { _Pragma("unroll") for (int _i = 0; _i < 2; ++_i) \
;         __builtin_amdgcn_global_load_lds((const unsigned*)((const char*)(gbase) + (voff)[_i]), (LAS unsigned*)(lds + (bufoff) + ldsw + _i * 8192), 16, 0, 0); } while (0)
; template <class Epi, class Sched, bool ALIGN_EPI = false, bool SP2 = false>
; __device__ __forceinline__ void gemm_phase(LAS unsigned char* lds, const Gemm g, const Sched& S, const Epi& E) {
;     ...
;         const bool has_next = S.next(ui + 1, nxt);
;         const char* nA = has_next ? (const char*)g.A + (size_t)nxt.pm * tstep + nxt.koff : cA; const char* nB = has_next ? (const char*)g.Bt + (size_t)nxt.pn * tstep + nxt.koff : cB;
;         for (int t = 0; t < nt; t += 2) {
;             const bool last = (t == nt - 2);
;             const char* a1 = cA + (size_t)(t + 1) * kstep;
;             const char* a2 = last ? nA : cA + (size_t)(t + 2) * kstep; const char* b2 = last ? nB : cB + (size_t)(t + 2) * kstep;
;             const char* a3 = a2 + kstep; const char* b3 = b2 + kstep;
;             if (last && has_next) S.a_ready(nxt);
;             if constexpr (SP2) {
;             PG8_LDB(B0, 0, 0); PG8_LDB(B1, 0, 1); PG8_SCHED; PG8_LDA(At, 0, 0); PG8_STAGE(PG8_SA(1, 1), a1 + hstep, voffA);
;             PG8_WAIT_V(8); PG8_WAIT_L(0); PG8_BAR; PG8_MMA(0, 0, At, B0); PG8_MMA(0, 1, At, B1); PG8_BAR; PG8_SCHED;
;             PG8_LDA(At, 0, 1); PG8_STAGE(PG8_SB(0, 0), b2, voffB); PG8_STAGE(PG8_SB(0, 1), b2 + hstepB, voffB); PG8_STAGE(PG8_SA(0, 0), a2, voffA);
;             PG8_WAIT_V(8); PG8_WAIT_L(0); PG8_BAR; PG8_MMA(1, 0, At, B0); PG8_MMA(1, 1, At, B1); PG8_BAR; PG8_SCHED;
;             PG8_LDB(B0, 1, 0); PG8_LDB(B1, 1, 1); PG8_SCHED; PG8_LDA(At, 1, 0); PG8_STAGE(PG8_SA(0, 1), a2 + hstep, voffA);
;             PG8_WAIT_V(8); PG8_WAIT_L(0); PG8_BAR; PG8_MMA(0, 0, At, B0); PG8_MMA(0, 1, At, B1); PG8_BAR; PG8_SCHED;
;             PG8_LDA(At, 1, 1); PG8_STAGE(PG8_SB(1, 0), b3, voffB); PG8_STAGE(PG8_SB(1, 1), b3 + hstepB, voffB); PG8_STAGE(PG8_SA(1, 0), a3, voffA);
;             PG8_WAIT_V(8); PG8_WAIT_L(0); PG8_BAR; PG8_MMA(1, 0, At, B0); PG8_MMA(1, 1, At, B1); PG8_BAR; PG8_SCHED;
.LBB0_534:
	s_ashr_i32 s53, s52, 31
	s_lshl_b64 s[14:15], s[52:53], 20
	s_add_u32 s54, s93, s14
	s_addc_u32 s55, s92, s15
	s_and_b64 s[14:15], s[44:45], exec
	s_cselect_b32 s0, s55, s17
	s_cselect_b32 s3, s54, s16
	s_ashr_i32 s51, s50, 31
	s_lshl_b64 s[14:15], s[50:51], 20
	s_add_u32 s56, s27, s14
	s_addc_u32 s57, s28, s15
	s_and_b64 s[14:15], s[44:45], exec
	s_cselect_b32 s14, s57, s49
	s_cselect_b32 s15, s56, s48
	s_add_u32 s16, s16, 0x80080
	s_addc_u32 s17, s17, 0
	s_add_u32 s18, s48, 0x100
	s_addc_u32 s19, s49, 0
	s_mov_b32 s20, -2
	ds_read_b128 v[34:37], v203
	ds_read_b128 v[38:41], v203 offset:1024
	ds_read_b128 v[42:45], v203 offset:2048
	ds_read_b128 v[46:49], v203 offset:3072
	s_waitcnt vmcnt(0)
	ds_read_b128 v[98:101], v204
	ds_read_b128 v[102:105], v204 offset:1024
	ds_read_b128 v[106:109], v204 offset:2048
	ds_read_b128 v[110:113], v204 offset:3072
	s_add_u32 s21, s16, 0xfff80080
	s_addc_u32 s22, s17, -1
	s_cmp_eq_u32 s20, 28
	s_cselect_b32 s59, s0, s22
	s_cselect_b32 s58, s3, s21
	s_cselect_b32 s49, s14, s19
	s_cselect_b32 s48, s15, s18
	v_lshl_add_u64 v[182:183], s[16:17], 0, v[172:173]
	s_add_i32 m0, s30, 0xc000
	ds_read_b128 v[212:215], v205
	ds_read_b128 v[216:219], v205 offset:1024
	ds_read_b128 v[220:223], v205 offset:2048
	ds_read_b128 v[224:227], v205 offset:3072
	ds_read_b128 v[228:231], v205 offset:4096
	ds_read_b128 v[232:235], v205 offset:5120
	ds_read_b128 v[236:239], v205 offset:6144
	ds_read_b128 v[240:243], v205 offset:7168
	global_load_lds_dwordx4 v[182:183], off
	v_lshl_add_u64 v[182:183], s[16:17], 0, v[174:175]
	s_add_i32 m0, s30, 0xe000
	s_nop 0
	global_load_lds_dwordx4 v[182:183], off
	s_waitcnt lgkmcnt(0)
	s_barrier
	s_setprio 1
	s_waitcnt lgkmcnt(0)
	v_mfma_f32_16x16x32_bf16 v[158:161], v[34:37], v[212:215], 0
	v_mfma_f32_16x16x32_bf16 v[154:157], v[42:45], v[212:215], 0
	v_mfma_f32_16x16x32_bf16 v[142:145], v[34:37], v[220:223], 0
	v_mfma_f32_16x16x32_bf16 v[138:141], v[42:45], v[220:223], 0
	v_mfma_f32_16x16x32_bf16 v[126:129], v[34:37], v[228:231], 0
	v_mfma_f32_16x16x32_bf16 v[122:125], v[42:45], v[228:231], 0
	v_mfma_f32_16x16x32_bf16 v[94:97], v[34:37], v[236:239], 0
	v_mfma_f32_16x16x32_bf16 v[90:93], v[42:45], v[236:239], 0
	v_mfma_f32_16x16x32_bf16 v[158:161], v[38:41], v[216:219], v[158:161]
	v_mfma_f32_16x16x32_bf16 v[154:157], v[46:49], v[216:219], v[154:157]
	v_mfma_f32_16x16x32_bf16 v[142:145], v[38:41], v[224:227], v[142:145]
	v_mfma_f32_16x16x32_bf16 v[138:141], v[46:49], v[224:227], v[138:141]
	v_mfma_f32_16x16x32_bf16 v[126:129], v[38:41], v[232:235], v[126:129]
	v_mfma_f32_16x16x32_bf16 v[122:125], v[46:49], v[232:235], v[122:125]
	v_mfma_f32_16x16x32_bf16 v[94:97], v[38:41], v[240:243], v[94:97]
	v_mfma_f32_16x16x32_bf16 v[90:93], v[46:49], v[240:243], v[90:93]
	s_setprio 0
	s_setprio 1
	v_mfma_f32_16x16x32_bf16 v[150:153], v[98:101], v[212:215], 0
	v_mfma_f32_16x16x32_bf16 v[146:149], v[106:109], v[212:215], 0
	v_mfma_f32_16x16x32_bf16 v[134:137], v[98:101], v[220:223], 0
	v_mfma_f32_16x16x32_bf16 v[130:133], v[106:109], v[220:223], 0
	v_mfma_f32_16x16x32_bf16 v[118:121], v[98:101], v[228:231], 0
	v_mfma_f32_16x16x32_bf16 v[114:117], v[106:109], v[228:231], 0
	v_mfma_f32_16x16x32_bf16 v[86:89], v[98:101], v[236:239], 0
	v_mfma_f32_16x16x32_bf16 v[82:85], v[106:109], v[236:239], 0
	v_mfma_f32_16x16x32_bf16 v[150:153], v[102:105], v[216:219], v[150:153]
	v_mfma_f32_16x16x32_bf16 v[146:149], v[110:113], v[216:219], v[146:149]
	v_mfma_f32_16x16x32_bf16 v[134:137], v[102:105], v[224:227], v[134:137]
	v_mfma_f32_16x16x32_bf16 v[130:133], v[110:113], v[224:227], v[130:133]
	v_mfma_f32_16x16x32_bf16 v[118:121], v[102:105], v[232:235], v[118:121]
	v_mfma_f32_16x16x32_bf16 v[114:117], v[110:113], v[232:235], v[114:117]
	v_mfma_f32_16x16x32_bf16 v[86:89], v[102:105], v[240:243], v[86:89]
	v_mfma_f32_16x16x32_bf16 v[82:85], v[110:113], v[240:243], v[82:85]
	s_setprio 0
	s_barrier
	s_add_i32 s21, s68, s29
	v_lshl_add_u64 v[182:183], s[48:49], 0, v[164:165]
	s_mov_b32 m0, s21
	ds_read_b128 v[212:215], v205 offset:16384
	ds_read_b128 v[216:219], v205 offset:17408
	ds_read_b128 v[220:223], v205 offset:18432
	ds_read_b128 v[224:227], v205 offset:19456
	ds_read_b128 v[228:231], v205 offset:20480
	ds_read_b128 v[232:235], v205 offset:21504
	ds_read_b128 v[236:239], v205 offset:22528
	ds_read_b128 v[240:243], v205 offset:23552
	global_load_lds_dwordx4 v[182:183], off
	s_add_i32 m0, s21, 0x2000
	s_add_u32 s22, s48, 0x20000
	v_lshl_add_u64 v[244:245], s[48:49], 0, v[168:169]
	s_addc_u32 s23, s49, 0
	s_add_i32 s21, s69, s29
	global_load_lds_dwordx4 v[244:245], off
	v_lshl_add_u64 v[246:247], s[22:23], 0, v[164:165]
	s_mov_b32 m0, s21
	v_lshl_add_u64 v[248:249], s[58:59], 0, v[166:167]
	global_load_lds_dwordx4 v[246:247], off
	v_lshl_add_u64 v[246:247], s[22:23], 0, v[168:169]
	s_add_i32 m0, s21, 0x2000
	s_nop 0
	global_load_lds_dwordx4 v[246:247], off
	v_lshl_add_u64 v[246:247], s[58:59], 0, v[162:163]
	s_mov_b32 m0, s30
	s_nop 0
	global_load_lds_dwordx4 v[246:247], off
	s_mov_b32 m0, s31
	s_nop 0
	global_load_lds_dwordx4 v[248:249], off
	s_waitcnt vmcnt(8)
	s_waitcnt lgkmcnt(0)
	s_barrier
; #define PG8_STAGE(bufoff, gbase, voff) do { _Pragma("unroll") for (int _i = 0; _i < 2; ++_i) \
;         __builtin_amdgcn_global_load_lds((const unsigned*)((const char*)(gbase) + (voff)[_i]), (LAS unsigned*)(lds + (bufoff) + ldsw + _i * 8192), 16, 0, 0); } while (0)
; #define PG8_LDA(dst, b, h) do { _Pragma("unroll") for (int m = 0; m < 4; ++m) _Pragma("unroll") for (int k = 0; k < 2; ++k) dst[m][k] = *(const LAS bf16x8*)(lds + PG8_SA(b, h) + aoff + m * 2048 + k * 1024); } while (0)
; #define PG8_LDB(dst, b, h) do { _Pragma("unroll") for (int n = 0; n < 2; ++n) _Pragma("unroll") for (int k = 0; k < 2; ++k) dst[n][k] = *(const LAS bf16x8*)(lds + PG8_SB(b, h) + boff + n * 2048 + k * 1024); } while (0)
; #define PG8_MMA(ai, bj, At, Bt) do { __builtin_amdgcn_s_setprio(1); _Pragma("unroll") for (int m = 0; m < 4; ++m) _Pragma("unroll") for (int n = 0; n < 2; ++n) _Pragma("unroll") for (int k = 0; k < 2; ++k) \
;         acc[ai][bj][m][n] = __builtin_amdgcn_mfma_f32_16x16x32_bf16(Bt[n][k], At[m][k], acc[ai][bj][m][n], 0, 0, 0); __builtin_amdgcn_s_setprio(0); } while (0)
; #define PG8_WAIT_V(n) asm volatile("s_waitcnt vmcnt(" #n ")" ::: "memory")
; template <class Epi, class Sched, bool ALIGN_EPI = false, bool SP2 = false>
; __device__ __forceinline__ void gemm_phase(LAS unsigned char* lds, const Gemm g, const Sched& S, const Epi& E) {
;     ...
;             PG8_LDB(B0, 0, 0); PG8_LDB(B1, 0, 1); PG8_SCHED; PG8_LDA(At, 0, 0); PG8_STAGE(PG8_SA(1, 1), a1 + hstep, voffA);
;             PG8_WAIT_V(8); PG8_WAIT_L(0); PG8_BAR; PG8_MMA(0, 0, At, B0); PG8_MMA(0, 1, At, B1); PG8_BAR; PG8_SCHED;
;             PG8_LDA(At, 0, 1); PG8_STAGE(PG8_SB(0, 0), b2, voffB); PG8_STAGE(PG8_SB(0, 1), b2 + hstepB, voffB); PG8_STAGE(PG8_SA(0, 0), a2, voffA);
;             PG8_WAIT_V(8); PG8_WAIT_L(0); PG8_BAR; PG8_MMA(1, 0, At, B0); PG8_MMA(1, 1, At, B1); PG8_BAR; PG8_SCHED;
;             PG8_LDB(B0, 1, 0); PG8_LDB(B1, 1, 1); PG8_SCHED; PG8_LDA(At, 1, 0); PG8_STAGE(PG8_SA(0, 1), a2 + hstep, voffA);
;             PG8_WAIT_V(8); PG8_WAIT_L(0); PG8_BAR; PG8_MMA(0, 0, At, B0); PG8_MMA(0, 1, At, B1); PG8_BAR; PG8_SCHED;
;             PG8_LDA(At, 1, 1); PG8_STAGE(PG8_SB(1, 0), b3, voffB); PG8_STAGE(PG8_SB(1, 1), b3 + hstepB, voffB); PG8_STAGE(PG8_SA(1, 0), a3, voffA);
;             PG8_WAIT_V(8); PG8_WAIT_L(0); PG8_BAR; PG8_MMA(1, 0, At, B0); PG8_MMA(1, 1, At, B1); PG8_BAR; PG8_SCHED;
	s_setprio 1
	s_waitcnt lgkmcnt(0)
	v_mfma_f32_16x16x32_bf16 v[78:81], v[34:37], v[212:215], 0
	v_mfma_f32_16x16x32_bf16 v[74:77], v[42:45], v[212:215], 0
	v_mfma_f32_16x16x32_bf16 v[62:65], v[34:37], v[220:223], 0
	v_mfma_f32_16x16x32_bf16 v[58:61], v[42:45], v[220:223], 0
	v_mfma_f32_16x16x32_bf16 v[30:33], v[34:37], v[228:231], 0
	v_mfma_f32_16x16x32_bf16 v[26:29], v[42:45], v[228:231], 0
	v_mfma_f32_16x16x32_bf16 v[14:17], v[34:37], v[236:239], 0
	v_mfma_f32_16x16x32_bf16 v[10:13], v[42:45], v[236:239], 0
	v_mfma_f32_16x16x32_bf16 v[78:81], v[38:41], v[216:219], v[78:81]
	v_mfma_f32_16x16x32_bf16 v[74:77], v[46:49], v[216:219], v[74:77]
	v_mfma_f32_16x16x32_bf16 v[62:65], v[38:41], v[224:227], v[62:65]
	v_mfma_f32_16x16x32_bf16 v[58:61], v[46:49], v[224:227], v[58:61]
	v_mfma_f32_16x16x32_bf16 v[30:33], v[38:41], v[232:235], v[30:33]
	v_mfma_f32_16x16x32_bf16 v[26:29], v[46:49], v[232:235], v[26:29]
	v_mfma_f32_16x16x32_bf16 v[14:17], v[38:41], v[240:243], v[14:17]
	v_mfma_f32_16x16x32_bf16 v[10:13], v[46:49], v[240:243], v[10:13]
	s_setprio 0
	s_setprio 1
	v_mfma_f32_16x16x32_bf16 v[22:25], v[98:101], v[228:231], 0
	v_mfma_f32_16x16x32_bf16 v[18:21], v[106:109], v[228:231], 0
	v_mfma_f32_16x16x32_bf16 v[6:9], v[98:101], v[236:239], 0
	v_mfma_f32_16x16x32_bf16 v[2:5], v[106:109], v[236:239], 0
	v_mfma_f32_16x16x32_bf16 v[34:37], v[98:101], v[212:215], 0
	v_mfma_f32_16x16x32_bf16 v[38:41], v[106:109], v[212:215], 0
	v_mfma_f32_16x16x32_bf16 v[42:45], v[98:101], v[220:223], 0
	v_mfma_f32_16x16x32_bf16 v[46:49], v[106:109], v[220:223], 0
	v_mfma_f32_16x16x32_bf16 v[22:25], v[102:105], v[232:235], v[22:25]
	v_mfma_f32_16x16x32_bf16 v[18:21], v[110:113], v[232:235], v[18:21]
	v_mfma_f32_16x16x32_bf16 v[6:9], v[102:105], v[240:243], v[6:9]
	v_mfma_f32_16x16x32_bf16 v[2:5], v[110:113], v[240:243], v[2:5]
	v_mfma_f32_16x16x32_bf16 v[34:37], v[102:105], v[216:219], v[34:37]
	v_mfma_f32_16x16x32_bf16 v[38:41], v[110:113], v[216:219], v[38:41]
	v_mfma_f32_16x16x32_bf16 v[42:45], v[102:105], v[224:227], v[42:45]
	v_mfma_f32_16x16x32_bf16 v[46:49], v[110:113], v[224:227], v[46:49]
	s_setprio 0
	s_barrier
	s_add_i32 s21, 0, 0x18000
	s_add_i32 s24, 0, 0x1c000
	v_add_u32_e32 v70, s21, v186
	v_add_u32_e32 v110, s24, v186
	ds_read_b128 v[50:53], v70
	ds_read_b128 v[54:57], v70 offset:1024
	ds_read_b128 v[66:69], v70 offset:2048
	ds_read_b128 v[70:73], v70 offset:3072
	ds_read_b128 v[98:101], v110
	ds_read_b128 v[102:105], v110 offset:1024
	ds_read_b128 v[106:109], v110 offset:2048
	ds_read_b128 v[110:113], v110 offset:3072
	s_add_u32 s22, s58, 0x80000
	s_addc_u32 s23, s59, 0
	s_mov_b32 m0, s33
	v_lshl_add_u64 v[250:251], s[22:23], 0, v[162:163]
	ds_read_b128 v[212:215], v205 offset:32768
	ds_read_b128 v[216:219], v205 offset:33792
	ds_read_b128 v[220:223], v205 offset:34816
	ds_read_b128 v[224:227], v205 offset:35840
	ds_read_b128 v[228:231], v205 offset:36864
	ds_read_b128 v[232:235], v205 offset:37888
	ds_read_b128 v[236:239], v205 offset:38912
	ds_read_b128 v[240:243], v205 offset:39936
	global_load_lds_dwordx4 v[250:251], off
	v_lshl_add_u64 v[250:251], s[22:23], 0, v[166:167]
	s_mov_b32 m0, s60
	s_nop 0
	global_load_lds_dwordx4 v[250:251], off
	s_waitcnt vmcnt(8)
	s_waitcnt lgkmcnt(0)
	s_barrier
	s_setprio 1
	s_waitcnt lgkmcnt(0)
	v_mfma_f32_16x16x32_bf16 v[158:161], v[50:53], v[212:215], v[158:161]
	v_mfma_f32_16x16x32_bf16 v[154:157], v[66:69], v[212:215], v[154:157]
	v_mfma_f32_16x16x32_bf16 v[142:145], v[50:53], v[220:223], v[142:145]
	v_mfma_f32_16x16x32_bf16 v[138:141], v[66:69], v[220:223], v[138:141]
	v_mfma_f32_16x16x32_bf16 v[126:129], v[50:53], v[228:231], v[126:129]
	v_mfma_f32_16x16x32_bf16 v[122:125], v[66:69], v[228:231], v[122:125]
	v_mfma_f32_16x16x32_bf16 v[94:97], v[50:53], v[236:239], v[94:97]
	v_mfma_f32_16x16x32_bf16 v[90:93], v[66:69], v[236:239], v[90:93]
	v_mfma_f32_16x16x32_bf16 v[158:161], v[54:57], v[216:219], v[158:161]
	v_mfma_f32_16x16x32_bf16 v[154:157], v[70:73], v[216:219], v[154:157]
	v_mfma_f32_16x16x32_bf16 v[142:145], v[54:57], v[224:227], v[142:145]
	v_mfma_f32_16x16x32_bf16 v[138:141], v[70:73], v[224:227], v[138:141]
	v_mfma_f32_16x16x32_bf16 v[126:129], v[54:57], v[232:235], v[126:129]
	v_mfma_f32_16x16x32_bf16 v[122:125], v[70:73], v[232:235], v[122:125]
	v_mfma_f32_16x16x32_bf16 v[94:97], v[54:57], v[240:243], v[94:97]
	v_mfma_f32_16x16x32_bf16 v[90:93], v[70:73], v[240:243], v[90:93]
	s_setprio 0
	s_setprio 1
	v_mfma_f32_16x16x32_bf16 v[150:153], v[98:101], v[212:215], v[150:153]
	v_mfma_f32_16x16x32_bf16 v[146:149], v[106:109], v[212:215], v[146:149]
	v_mfma_f32_16x16x32_bf16 v[134:137], v[98:101], v[220:223], v[134:137]
	v_mfma_f32_16x16x32_bf16 v[130:133], v[106:109], v[220:223], v[130:133]
	v_mfma_f32_16x16x32_bf16 v[118:121], v[98:101], v[228:231], v[118:121]
	v_mfma_f32_16x16x32_bf16 v[114:117], v[106:109], v[228:231], v[114:117]
	v_mfma_f32_16x16x32_bf16 v[86:89], v[98:101], v[236:239], v[86:89]
	v_mfma_f32_16x16x32_bf16 v[82:85], v[106:109], v[236:239], v[82:85]
	v_mfma_f32_16x16x32_bf16 v[150:153], v[102:105], v[216:219], v[150:153]
	v_mfma_f32_16x16x32_bf16 v[146:149], v[110:113], v[216:219], v[146:149]
	v_mfma_f32_16x16x32_bf16 v[134:137], v[102:105], v[224:227], v[134:137]
	v_mfma_f32_16x16x32_bf16 v[130:133], v[110:113], v[224:227], v[130:133]
	v_mfma_f32_16x16x32_bf16 v[118:121], v[102:105], v[232:235], v[118:121]
	v_mfma_f32_16x16x32_bf16 v[114:117], v[110:113], v[232:235], v[114:117]
	v_mfma_f32_16x16x32_bf16 v[86:89], v[102:105], v[240:243], v[86:89]
	v_mfma_f32_16x16x32_bf16 v[82:85], v[110:113], v[240:243], v[82:85]
	s_setprio 0
	s_barrier
; #define PG8_STAGE(bufoff, gbase, voff) do { _Pragma("unroll") for (int _i = 0; _i < 2; ++_i) \
;         __builtin_amdgcn_global_load_lds((const unsigned*)((const char*)(gbase) + (voff)[_i]), (LAS unsigned*)(lds + (bufoff) + ldsw + _i * 8192), 16, 0, 0); } while (0)
; #define PG8_LDA(dst, b, h) do { _Pragma("unroll") for (int m = 0; m < 4; ++m) _Pragma("unroll") for (int k = 0; k < 2; ++k) dst[m][k] = *(const LAS bf16x8*)(lds + PG8_SA(b, h) + aoff + m * 2048 + k * 1024); } while (0)
; #define PG8_LDB(dst, b, h) do { _Pragma("unroll") for (int n = 0; n < 2; ++n) _Pragma("unroll") for (int k = 0; k < 2; ++k) dst[n][k] = *(const LAS bf16x8*)(lds + PG8_SB(b, h) + boff + n * 2048 + k * 1024); } while (0)
; template <class Epi, class Sched, bool ALIGN_EPI = false, bool SP2 = false>
; __device__ __forceinline__ void gemm_phase(LAS unsigned char* lds, const Gemm g, const Sched& S, const Epi& E) {
;     ...
;         for (int t = 0; t < nt; t += 2) {
;             const bool last = (t == nt - 2);
;             const char* a1 = cA + (size_t)(t + 1) * kstep;
;             const char* a2 = last ? nA : cA + (size_t)(t + 2) * kstep; const char* b2 = last ? nB : cB + (size_t)(t + 2) * kstep;
;             const char* a3 = a2 + kstep; const char* b3 = b2 + kstep;
;             if (last && has_next) S.a_ready(nxt);
;             if constexpr (SP2) {
;             PG8_LDB(B0, 0, 0); PG8_LDB(B1, 0, 1); PG8_SCHED; PG8_LDA(At, 0, 0); PG8_STAGE(PG8_SA(1, 1), a1 + hstep, voffA);
;             PG8_WAIT_V(8); PG8_WAIT_L(0); PG8_BAR; PG8_MMA(0, 0, At, B0); PG8_MMA(0, 1, At, B1); PG8_BAR; PG8_SCHED;
;             PG8_LDA(At, 0, 1); PG8_STAGE(PG8_SB(0, 0), b2, voffB); PG8_STAGE(PG8_SB(0, 1), b2 + hstepB, voffB); PG8_STAGE(PG8_SA(0, 0), a2, voffA);
;             PG8_WAIT_V(8); PG8_WAIT_L(0); PG8_BAR; PG8_MMA(1, 0, At, B0); PG8_MMA(1, 1, At, B1); PG8_BAR; PG8_SCHED;
;             PG8_LDB(B0, 1, 0); PG8_LDB(B1, 1, 1); PG8_SCHED; PG8_LDA(At, 1, 0); PG8_STAGE(PG8_SA(0, 1), a2 + hstep, voffA);
;             PG8_WAIT_V(8); PG8_WAIT_L(0); PG8_BAR; PG8_MMA(0, 0, At, B0); PG8_MMA(0, 1, At, B1); PG8_BAR; PG8_SCHED;
;             PG8_LDA(At, 1, 1); PG8_STAGE(PG8_SB(1, 0), b3, voffB); PG8_STAGE(PG8_SB(1, 1), b3 + hstepB, voffB); PG8_STAGE(PG8_SA(1, 0), a3, voffA);
;             PG8_WAIT_V(8); PG8_WAIT_L(0); PG8_BAR; PG8_MMA(1, 0, At, B0); PG8_MMA(1, 1, At, B1); PG8_BAR; PG8_SCHED;
	s_add_i32 s21, s21, s29
	v_lshl_add_u64 v[182:183], v[182:183], 0, s[34:35]
	s_mov_b32 m0, s21
	ds_read_b128 v[212:215], v205 offset:49152
	ds_read_b128 v[216:219], v205 offset:50176
	ds_read_b128 v[220:223], v205 offset:51200
	ds_read_b128 v[224:227], v205 offset:52224
	ds_read_b128 v[228:231], v205 offset:53248
	ds_read_b128 v[232:235], v205 offset:54272
	ds_read_b128 v[236:239], v205 offset:55296
	ds_read_b128 v[240:243], v205 offset:56320
	global_load_lds_dwordx4 v[182:183], off
	s_add_i32 m0, s21, 0x2000
	s_add_u32 s22, s48, 0x20080
	v_lshl_add_u64 v[182:183], v[244:245], 0, s[34:35]
	s_addc_u32 s23, s49, 0
	s_add_i32 s21, s24, s29
	global_load_lds_dwordx4 v[182:183], off
	v_lshl_add_u64 v[182:183], s[22:23], 0, v[164:165]
	s_mov_b32 m0, s21
	s_nop 0
	global_load_lds_dwordx4 v[182:183], off
	v_lshl_add_u64 v[182:183], s[22:23], 0, v[168:169]
	s_add_i32 m0, s21, 0x2000
	s_nop 0
	global_load_lds_dwordx4 v[182:183], off
	v_lshl_add_u64 v[182:183], v[246:247], 0, s[34:35]
	s_mov_b32 m0, s65
	s_nop 0
	global_load_lds_dwordx4 v[182:183], off
	v_lshl_add_u64 v[182:183], v[248:249], 0, s[34:35]
	s_mov_b32 m0, s66
	s_nop 0
	global_load_lds_dwordx4 v[182:183], off
	s_waitcnt vmcnt(8)
	s_waitcnt lgkmcnt(0)
	s_barrier
	s_setprio 1
	s_waitcnt lgkmcnt(0)
	v_mfma_f32_16x16x32_bf16 v[78:81], v[50:53], v[212:215], v[78:81]
	v_mfma_f32_16x16x32_bf16 v[74:77], v[66:69], v[212:215], v[74:77]
	v_mfma_f32_16x16x32_bf16 v[62:65], v[50:53], v[220:223], v[62:65]
	v_mfma_f32_16x16x32_bf16 v[58:61], v[66:69], v[220:223], v[58:61]
	v_mfma_f32_16x16x32_bf16 v[30:33], v[50:53], v[228:231], v[30:33]
	v_mfma_f32_16x16x32_bf16 v[26:29], v[66:69], v[228:231], v[26:29]
	v_mfma_f32_16x16x32_bf16 v[14:17], v[50:53], v[236:239], v[14:17]
	v_mfma_f32_16x16x32_bf16 v[10:13], v[66:69], v[236:239], v[10:13]
	v_mfma_f32_16x16x32_bf16 v[78:81], v[54:57], v[216:219], v[78:81]
	v_mfma_f32_16x16x32_bf16 v[74:77], v[70:73], v[216:219], v[74:77]
	v_mfma_f32_16x16x32_bf16 v[62:65], v[54:57], v[224:227], v[62:65]
	v_mfma_f32_16x16x32_bf16 v[58:61], v[70:73], v[224:227], v[58:61]
	v_mfma_f32_16x16x32_bf16 v[30:33], v[54:57], v[232:235], v[30:33]
	v_mfma_f32_16x16x32_bf16 v[26:29], v[70:73], v[232:235], v[26:29]
	v_mfma_f32_16x16x32_bf16 v[14:17], v[54:57], v[240:243], v[14:17]
	v_mfma_f32_16x16x32_bf16 v[10:13], v[70:73], v[240:243], v[10:13]
	s_setprio 0
	s_setprio 1
	v_mfma_f32_16x16x32_bf16 v[34:37], v[98:101], v[212:215], v[34:37]
	v_mfma_f32_16x16x32_bf16 v[70:73], v[102:105], v[216:219], v[34:37]
	v_mfma_f32_16x16x32_bf16 v[34:37], v[106:109], v[212:215], v[38:41]
	v_mfma_f32_16x16x32_bf16 v[66:69], v[110:113], v[216:219], v[34:37]
	v_mfma_f32_16x16x32_bf16 v[34:37], v[98:101], v[220:223], v[42:45]
	v_mfma_f32_16x16x32_bf16 v[54:57], v[102:105], v[224:227], v[34:37]
	v_mfma_f32_16x16x32_bf16 v[34:37], v[106:109], v[220:223], v[46:49]
	v_mfma_f32_16x16x32_bf16 v[22:25], v[98:101], v[228:231], v[22:25]
	v_mfma_f32_16x16x32_bf16 v[18:21], v[106:109], v[228:231], v[18:21]
	v_mfma_f32_16x16x32_bf16 v[6:9], v[98:101], v[236:239], v[6:9]
	v_mfma_f32_16x16x32_bf16 v[2:5], v[106:109], v[236:239], v[2:5]
	v_mfma_f32_16x16x32_bf16 v[50:53], v[110:113], v[224:227], v[34:37]
	v_mfma_f32_16x16x32_bf16 v[22:25], v[102:105], v[232:235], v[22:25]
	v_mfma_f32_16x16x32_bf16 v[18:21], v[110:113], v[232:235], v[18:21]
	v_mfma_f32_16x16x32_bf16 v[6:9], v[102:105], v[240:243], v[6:9]
	v_mfma_f32_16x16x32_bf16 v[2:5], v[110:113], v[240:243], v[2:5]
	s_setprio 0
	s_barrier
	s_add_i32 s20, s20, 2
	s_add_u32 s16, s16, 0x100
	s_addc_u32 s17, s17, 0
	s_add_u32 s18, s18, 0x100
	s_addc_u32 s19, s19, 0
	s_cmp_gt_u32 s20, 29

;     __device__ bool next(int i, Unit& u) const { if (i != 0 || c >= 128) return false; const int t = c >> 2; u.pm = t & 3; u.pn = t >> 2; u.koff = koff_bytes; u.q = c & 3; return true; }
; #define PG8_STAGE(bufoff, gbase, voff) do { _Pragma("unroll") for (int _i = 0; _i < 2; ++_i) \
;         __builtin_amdgcn_global_load_lds((const unsigned*)((const char*)(gbase) + (voff)[_i]), (LAS unsigned*)(lds + (bufoff) + ldsw + _i * 8192), 16, 0, 0); } while (0)
; template <class Epi, class Sched, bool ALIGN_EPI = false, bool SP2 = false>
; __device__ __forceinline__ void gemm_phase(LAS unsigned char* lds, const Gemm g, const Sched& S, const Epi& E) {
;     ...
;         const bool has_next = S.next(ui + 1, nxt);
;         const char* nA = has_next ? (const char*)g.A + (size_t)nxt.pm * tstep + nxt.koff : cA; const char* nB = has_next ? (const char*)g.Bt + (size_t)nxt.pn * tstep + nxt.koff : cB;
;         for (int t = 0; t < nt; t += 2) {
;             const bool last = (t == nt - 2);
;             const char* a1 = cA + (size_t)(t + 1) * kstep;
;             const char* a2 = last ? nA : cA + (size_t)(t + 2) * kstep; const char* b2 = last ? nB : cB + (size_t)(t + 2) * kstep;
;             const char* a3 = a2 + kstep; const char* b3 = b2 + kstep;
;             if (last && has_next) S.a_ready(nxt);
;             if constexpr (SP2) {
;             PG8_LDB(B0, 0, 0); PG8_LDB(B1, 0, 1); PG8_SCHED; PG8_LDA(At, 0, 0); PG8_STAGE(PG8_SA(1, 1), a1 + hstep, voffA);
;             PG8_WAIT_V(8); PG8_WAIT_L(0); PG8_BAR; PG8_MMA(0, 0, At, B0); PG8_MMA(0, 1, At, B1); PG8_BAR; PG8_SCHED;
;             PG8_LDA(At, 0, 1); PG8_STAGE(PG8_SB(0, 0), b2, voffB); PG8_STAGE(PG8_SB(0, 1), b2 + hstepB, voffB); PG8_STAGE(PG8_SA(0, 0), a2, voffA);
;             PG8_WAIT_V(8); PG8_WAIT_L(0); PG8_BAR; PG8_MMA(1, 0, At, B0); PG8_MMA(1, 1, At, B1); PG8_BAR; PG8_SCHED;
;             PG8_LDB(B0, 1, 0); PG8_LDB(B1, 1, 1); PG8_SCHED; PG8_LDA(At, 1, 0); PG8_STAGE(PG8_SA(0, 1), a2 + hstep, voffA);
;             PG8_WAIT_V(8); PG8_WAIT_L(0); PG8_BAR; PG8_MMA(0, 0, At, B0); PG8_MMA(0, 1, At, B1); PG8_BAR; PG8_SCHED;
;             PG8_LDA(At, 1, 1); PG8_STAGE(PG8_SB(1, 0), b3, voffB); PG8_STAGE(PG8_SB(1, 1), b3 + hstepB, voffB); PG8_STAGE(PG8_SA(1, 0), a3, voffA);
;             PG8_WAIT_V(8); PG8_WAIT_L(0); PG8_BAR; PG8_MMA(1, 0, At, B0); PG8_MMA(1, 1, At, B1); PG8_BAR; PG8_SCHED;
.LBB0_1249:
	s_ashr_i32 s19, s18, 31
	s_lshl_b64 s[20:21], s[18:19], 20
	v_readlane_b32 s0, v252, 25
	s_add_u32 s20, s0, s20
	v_readlane_b32 s0, v252, 26
	s_addc_u32 s21, s0, s21
	s_and_b64 s[22:23], s[44:45], exec
	s_cselect_b32 s0, s21, s17
	s_cselect_b32 s3, s20, s16
	s_ashr_i32 s15, s14, 31
	s_lshl_b64 s[22:23], s[14:15], 20
	s_add_u32 s22, s26, s22
	s_addc_u32 s23, s27, s23
	s_and_b64 s[24:25], s[44:45], exec
	s_cselect_b32 s15, s23, s49
	s_cselect_b32 s19, s22, s48
	s_add_u32 s16, s16, 0x80080
	s_addc_u32 s17, s17, 0
	s_add_u32 s24, s48, 0x100
	s_addc_u32 s25, s49, 0
	s_mov_b32 s47, -2
	s_waitcnt vmcnt(0)
	ds_read_b128 v[50:53], v196
	ds_read_b128 v[54:57], v196 offset:1024
	ds_read_b128 v[138:141], v196 offset:2048
	ds_read_b128 v[142:145], v196 offset:3072
	ds_read_b128 v[146:149], v197
	ds_read_b128 v[150:153], v197 offset:1024
	ds_read_b128 v[174:177], v197 offset:2048
	ds_read_b128 v[178:181], v197 offset:3072
	s_add_u32 s48, s16, 0xfff80080
	s_addc_u32 s49, s17, -1
	s_cmp_eq_u32 s47, 28
	s_cselect_b32 s51, s0, s49
	s_cselect_b32 s50, s3, s48
	s_cselect_b32 s49, s15, s25
	s_cselect_b32 s48, s19, s24
	v_lshl_add_u64 v[190:191], s[16:17], 0, v[166:167]
	s_add_i32 m0, s29, 0xc000
	ds_read_b128 v[182:185], v198
	ds_read_b128 v[186:189], v198 offset:1024
	ds_read_b128 v[202:205], v198 offset:2048
	ds_read_b128 v[206:209], v198 offset:3072
	ds_read_b128 v[210:213], v198 offset:4096
	ds_read_b128 v[214:217], v198 offset:5120
	ds_read_b128 v[218:221], v198 offset:6144
	ds_read_b128 v[222:225], v198 offset:7168
	global_load_lds_dwordx4 v[190:191], off
	v_lshl_add_u64 v[190:191], s[16:17], 0, v[168:169]
	s_add_i32 m0, s29, 0xe000
	s_nop 0
	global_load_lds_dwordx4 v[190:191], off
	s_waitcnt lgkmcnt(0)
	s_barrier
	s_setprio 1
	s_waitcnt lgkmcnt(0)
	v_mfma_f32_16x16x32_bf16 v[134:137], v[50:53], v[182:185], 0
	v_mfma_f32_16x16x32_bf16 v[130:133], v[138:141], v[182:185], 0
	v_mfma_f32_16x16x32_bf16 v[118:121], v[50:53], v[202:205], 0
	v_mfma_f32_16x16x32_bf16 v[114:117], v[138:141], v[202:205], 0
	v_mfma_f32_16x16x32_bf16 v[102:105], v[50:53], v[210:213], 0
	v_mfma_f32_16x16x32_bf16 v[98:101], v[138:141], v[210:213], 0
	v_mfma_f32_16x16x32_bf16 v[86:89], v[50:53], v[218:221], 0
	v_mfma_f32_16x16x32_bf16 v[82:85], v[138:141], v[218:221], 0
	v_mfma_f32_16x16x32_bf16 v[134:137], v[54:57], v[186:189], v[134:137]
	v_mfma_f32_16x16x32_bf16 v[130:133], v[142:145], v[186:189], v[130:133]
	v_mfma_f32_16x16x32_bf16 v[118:121], v[54:57], v[206:209], v[118:121]
	v_mfma_f32_16x16x32_bf16 v[114:117], v[142:145], v[206:209], v[114:117]
	v_mfma_f32_16x16x32_bf16 v[102:105], v[54:57], v[214:217], v[102:105]
	v_mfma_f32_16x16x32_bf16 v[98:101], v[142:145], v[214:217], v[98:101]
	v_mfma_f32_16x16x32_bf16 v[86:89], v[54:57], v[222:225], v[86:89]
	v_mfma_f32_16x16x32_bf16 v[82:85], v[142:145], v[222:225], v[82:85]
	s_setprio 0
	s_setprio 1
	v_mfma_f32_16x16x32_bf16 v[126:129], v[146:149], v[182:185], 0
	v_mfma_f32_16x16x32_bf16 v[122:125], v[174:177], v[182:185], 0
	v_mfma_f32_16x16x32_bf16 v[110:113], v[146:149], v[202:205], 0
	v_mfma_f32_16x16x32_bf16 v[106:109], v[174:177], v[202:205], 0
	v_mfma_f32_16x16x32_bf16 v[94:97], v[146:149], v[210:213], 0
	v_mfma_f32_16x16x32_bf16 v[90:93], v[174:177], v[210:213], 0
	v_mfma_f32_16x16x32_bf16 v[78:81], v[146:149], v[218:221], 0
	v_mfma_f32_16x16x32_bf16 v[74:77], v[174:177], v[218:221], 0
	v_mfma_f32_16x16x32_bf16 v[126:129], v[150:153], v[186:189], v[126:129]
	v_mfma_f32_16x16x32_bf16 v[122:125], v[178:181], v[186:189], v[122:125]
	v_mfma_f32_16x16x32_bf16 v[110:113], v[150:153], v[206:209], v[110:113]
	v_mfma_f32_16x16x32_bf16 v[106:109], v[178:181], v[206:209], v[106:109]
	v_mfma_f32_16x16x32_bf16 v[94:97], v[150:153], v[214:217], v[94:97]
	v_mfma_f32_16x16x32_bf16 v[90:93], v[178:181], v[214:217], v[90:93]
	v_mfma_f32_16x16x32_bf16 v[78:81], v[150:153], v[222:225], v[78:81]
	v_mfma_f32_16x16x32_bf16 v[74:77], v[178:181], v[222:225], v[74:77]
	s_setprio 0
	s_barrier
	s_add_i32 s58, s56, s28
	v_lshl_add_u64 v[190:191], s[48:49], 0, v[156:157]
	s_mov_b32 m0, s58
	ds_read_b128 v[182:185], v198 offset:16384
	ds_read_b128 v[186:189], v198 offset:17408
	ds_read_b128 v[202:205], v198 offset:18432
	ds_read_b128 v[206:209], v198 offset:19456
	ds_read_b128 v[210:213], v198 offset:20480
	ds_read_b128 v[214:217], v198 offset:21504
	ds_read_b128 v[218:221], v198 offset:22528
	ds_read_b128 v[222:225], v198 offset:23552
	global_load_lds_dwordx4 v[190:191], off
	s_add_i32 m0, s58, 0x2000
	s_add_u32 s58, s48, 0x20000
	v_lshl_add_u64 v[226:227], s[48:49], 0, v[160:161]
	s_addc_u32 s59, s49, 0
	s_add_i32 s60, s57, s28
	global_load_lds_dwordx4 v[226:227], off
	v_lshl_add_u64 v[228:229], s[58:59], 0, v[156:157]
	s_mov_b32 m0, s60
	v_lshl_add_u64 v[230:231], s[50:51], 0, v[158:159]
	global_load_lds_dwordx4 v[228:229], off
	v_lshl_add_u64 v[228:229], s[58:59], 0, v[160:161]
	s_add_i32 m0, s60, 0x2000
	s_nop 0
	global_load_lds_dwordx4 v[228:229], off
	v_lshl_add_u64 v[228:229], s[50:51], 0, v[154:155]
	s_mov_b32 m0, s29
	s_nop 0
	global_load_lds_dwordx4 v[228:229], off
	s_mov_b32 m0, s30
	s_nop 0
	global_load_lds_dwordx4 v[230:231], off
	s_waitcnt vmcnt(8)
	s_waitcnt lgkmcnt(0)
	s_barrier
; #define PG8_STAGE(bufoff, gbase, voff) do { _Pragma("unroll") for (int _i = 0; _i < 2; ++_i) \
;         __builtin_amdgcn_global_load_lds((const unsigned*)((const char*)(gbase) + (voff)[_i]), (LAS unsigned*)(lds + (bufoff) + ldsw + _i * 8192), 16, 0, 0); } while (0)
; #define PG8_LDA(dst, b, h) do { _Pragma("unroll") for (int m = 0; m < 4; ++m) _Pragma("unroll") for (int k = 0; k < 2; ++k) dst[m][k] = *(const LAS bf16x8*)(lds + PG8_SA(b, h) + aoff + m * 2048 + k * 1024); } while (0)
; #define PG8_LDB(dst, b, h) do { _Pragma("unroll") for (int n = 0; n < 2; ++n) _Pragma("unroll") for (int k = 0; k < 2; ++k) dst[n][k] = *(const LAS bf16x8*)(lds + PG8_SB(b, h) + boff + n * 2048 + k * 1024); } while (0)
; #define PG8_MMA(ai, bj, At, Bt) do { __builtin_amdgcn_s_setprio(1); _Pragma("unroll") for (int m = 0; m < 4; ++m) _Pragma("unroll") for (int n = 0; n < 2; ++n) _Pragma("unroll") for (int k = 0; k < 2; ++k) \
;         acc[ai][bj][m][n] = __builtin_amdgcn_mfma_f32_16x16x32_bf16(Bt[n][k], At[m][k], acc[ai][bj][m][n], 0, 0, 0); __builtin_amdgcn_s_setprio(0); } while (0)
; #define PG8_WAIT_V(n) asm volatile("s_waitcnt vmcnt(" #n ")" ::: "memory")
; template <class Epi, class Sched, bool ALIGN_EPI = false, bool SP2 = false>
; __device__ __forceinline__ void gemm_phase(LAS unsigned char* lds, const Gemm g, const Sched& S, const Epi& E) {
;     ...
;             PG8_LDB(B0, 0, 0); PG8_LDB(B1, 0, 1); PG8_SCHED; PG8_LDA(At, 0, 0); PG8_STAGE(PG8_SA(1, 1), a1 + hstep, voffA);
;             PG8_WAIT_V(8); PG8_WAIT_L(0); PG8_BAR; PG8_MMA(0, 0, At, B0); PG8_MMA(0, 1, At, B1); PG8_BAR; PG8_SCHED;
;             PG8_LDA(At, 0, 1); PG8_STAGE(PG8_SB(0, 0), b2, voffB); PG8_STAGE(PG8_SB(0, 1), b2 + hstepB, voffB); PG8_STAGE(PG8_SA(0, 0), a2, voffA);
;             PG8_WAIT_V(8); PG8_WAIT_L(0); PG8_BAR; PG8_MMA(1, 0, At, B0); PG8_MMA(1, 1, At, B1); PG8_BAR; PG8_SCHED;
;             PG8_LDB(B0, 1, 0); PG8_LDB(B1, 1, 1); PG8_SCHED; PG8_LDA(At, 1, 0); PG8_STAGE(PG8_SA(0, 1), a2 + hstep, voffA);
;             PG8_WAIT_V(8); PG8_WAIT_L(0); PG8_BAR; PG8_MMA(0, 0, At, B0); PG8_MMA(0, 1, At, B1); PG8_BAR; PG8_SCHED;
;             PG8_LDA(At, 1, 1); PG8_STAGE(PG8_SB(1, 0), b3, voffB); PG8_STAGE(PG8_SB(1, 1), b3 + hstepB, voffB); PG8_STAGE(PG8_SA(1, 0), a3, voffA);
;             PG8_WAIT_V(8); PG8_WAIT_L(0); PG8_BAR; PG8_MMA(1, 0, At, B0); PG8_MMA(1, 1, At, B1); PG8_BAR; PG8_SCHED;
	s_setprio 1
	s_waitcnt lgkmcnt(0)
	v_mfma_f32_16x16x32_bf16 v[70:73], v[50:53], v[182:185], 0
	v_mfma_f32_16x16x32_bf16 v[66:69], v[138:141], v[182:185], 0
	v_mfma_f32_16x16x32_bf16 v[46:49], v[50:53], v[202:205], 0
	v_mfma_f32_16x16x32_bf16 v[42:45], v[138:141], v[202:205], 0
	v_mfma_f32_16x16x32_bf16 v[30:33], v[50:53], v[210:213], 0
	v_mfma_f32_16x16x32_bf16 v[26:29], v[138:141], v[210:213], 0
	v_mfma_f32_16x16x32_bf16 v[14:17], v[50:53], v[218:221], 0
	v_mfma_f32_16x16x32_bf16 v[10:13], v[138:141], v[218:221], 0
	v_mfma_f32_16x16x32_bf16 v[70:73], v[54:57], v[186:189], v[70:73]
	v_mfma_f32_16x16x32_bf16 v[66:69], v[142:145], v[186:189], v[66:69]
	v_mfma_f32_16x16x32_bf16 v[46:49], v[54:57], v[206:209], v[46:49]
	v_mfma_f32_16x16x32_bf16 v[42:45], v[142:145], v[206:209], v[42:45]
	v_mfma_f32_16x16x32_bf16 v[30:33], v[54:57], v[214:217], v[30:33]
	v_mfma_f32_16x16x32_bf16 v[26:29], v[142:145], v[214:217], v[26:29]
	v_mfma_f32_16x16x32_bf16 v[14:17], v[54:57], v[222:225], v[14:17]
	v_mfma_f32_16x16x32_bf16 v[10:13], v[142:145], v[222:225], v[10:13]
	s_setprio 0
	s_setprio 1
	v_mfma_f32_16x16x32_bf16 v[38:41], v[146:149], v[202:205], 0
	v_mfma_f32_16x16x32_bf16 v[34:37], v[174:177], v[202:205], 0
	v_mfma_f32_16x16x32_bf16 v[22:25], v[146:149], v[210:213], 0
	v_mfma_f32_16x16x32_bf16 v[18:21], v[174:177], v[210:213], 0
	v_mfma_f32_16x16x32_bf16 v[6:9], v[146:149], v[218:221], 0
	v_mfma_f32_16x16x32_bf16 v[2:5], v[174:177], v[218:221], 0
	v_mfma_f32_16x16x32_bf16 v[50:53], v[146:149], v[182:185], 0
	v_mfma_f32_16x16x32_bf16 v[54:57], v[174:177], v[182:185], 0
	v_mfma_f32_16x16x32_bf16 v[38:41], v[150:153], v[206:209], v[38:41]
	v_mfma_f32_16x16x32_bf16 v[34:37], v[178:181], v[206:209], v[34:37]
	v_mfma_f32_16x16x32_bf16 v[22:25], v[150:153], v[214:217], v[22:25]
	v_mfma_f32_16x16x32_bf16 v[18:21], v[178:181], v[214:217], v[18:21]
	v_mfma_f32_16x16x32_bf16 v[6:9], v[150:153], v[222:225], v[6:9]
	v_mfma_f32_16x16x32_bf16 v[2:5], v[178:181], v[222:225], v[2:5]
	v_mfma_f32_16x16x32_bf16 v[50:53], v[150:153], v[186:189], v[50:53]
	v_mfma_f32_16x16x32_bf16 v[54:57], v[178:181], v[186:189], v[54:57]
	s_setprio 0
	s_barrier
	s_add_i32 s58, 0, 0x18000
	s_add_i32 s59, 0, 0x1c000
	v_add_u32_e32 v142, s58, v1
	v_add_u32_e32 v162, s59, v1
	ds_read_b128 v[58:61], v142
	ds_read_b128 v[62:65], v142 offset:1024
	ds_read_b128 v[138:141], v142 offset:2048
	ds_read_b128 v[142:145], v142 offset:3072
	ds_read_b128 v[146:149], v162
	ds_read_b128 v[150:153], v162 offset:1024
	ds_read_b128 v[174:177], v162 offset:2048
	ds_read_b128 v[178:181], v162 offset:3072
	s_add_u32 s50, s50, 0x80000
	s_addc_u32 s51, s51, 0
	s_mov_b32 m0, s31
	v_lshl_add_u64 v[232:233], s[50:51], 0, v[154:155]
	ds_read_b128 v[182:185], v198 offset:32768
	ds_read_b128 v[186:189], v198 offset:33792
	ds_read_b128 v[202:205], v198 offset:34816
	ds_read_b128 v[206:209], v198 offset:35840
	ds_read_b128 v[210:213], v198 offset:36864
	ds_read_b128 v[214:217], v198 offset:37888
	ds_read_b128 v[218:221], v198 offset:38912
	ds_read_b128 v[222:225], v198 offset:39936
	global_load_lds_dwordx4 v[232:233], off
	v_lshl_add_u64 v[232:233], s[50:51], 0, v[158:159]
	s_mov_b32 m0, s33
	s_nop 0
	global_load_lds_dwordx4 v[232:233], off
	s_waitcnt vmcnt(8)
	s_waitcnt lgkmcnt(0)
	s_barrier
	s_setprio 1
	s_waitcnt lgkmcnt(0)
	v_mfma_f32_16x16x32_bf16 v[134:137], v[58:61], v[182:185], v[134:137]
	v_mfma_f32_16x16x32_bf16 v[130:133], v[138:141], v[182:185], v[130:133]
	v_mfma_f32_16x16x32_bf16 v[118:121], v[58:61], v[202:205], v[118:121]
	v_mfma_f32_16x16x32_bf16 v[114:117], v[138:141], v[202:205], v[114:117]
	v_mfma_f32_16x16x32_bf16 v[102:105], v[58:61], v[210:213], v[102:105]
	v_mfma_f32_16x16x32_bf16 v[98:101], v[138:141], v[210:213], v[98:101]
	v_mfma_f32_16x16x32_bf16 v[86:89], v[58:61], v[218:221], v[86:89]
	v_mfma_f32_16x16x32_bf16 v[82:85], v[138:141], v[218:221], v[82:85]
	v_mfma_f32_16x16x32_bf16 v[134:137], v[62:65], v[186:189], v[134:137]
	v_mfma_f32_16x16x32_bf16 v[130:133], v[142:145], v[186:189], v[130:133]
	v_mfma_f32_16x16x32_bf16 v[118:121], v[62:65], v[206:209], v[118:121]
	v_mfma_f32_16x16x32_bf16 v[114:117], v[142:145], v[206:209], v[114:117]
	v_mfma_f32_16x16x32_bf16 v[102:105], v[62:65], v[214:217], v[102:105]
	v_mfma_f32_16x16x32_bf16 v[98:101], v[142:145], v[214:217], v[98:101]
	v_mfma_f32_16x16x32_bf16 v[86:89], v[62:65], v[222:225], v[86:89]
	v_mfma_f32_16x16x32_bf16 v[82:85], v[142:145], v[222:225], v[82:85]
	s_setprio 0
	s_setprio 1
	v_mfma_f32_16x16x32_bf16 v[126:129], v[146:149], v[182:185], v[126:129]
	v_mfma_f32_16x16x32_bf16 v[122:125], v[174:177], v[182:185], v[122:125]
	v_mfma_f32_16x16x32_bf16 v[110:113], v[146:149], v[202:205], v[110:113]
	v_mfma_f32_16x16x32_bf16 v[106:109], v[174:177], v[202:205], v[106:109]
	v_mfma_f32_16x16x32_bf16 v[94:97], v[146:149], v[210:213], v[94:97]
	v_mfma_f32_16x16x32_bf16 v[90:93], v[174:177], v[210:213], v[90:93]
	v_mfma_f32_16x16x32_bf16 v[78:81], v[146:149], v[218:221], v[78:81]
	v_mfma_f32_16x16x32_bf16 v[74:77], v[174:177], v[218:221], v[74:77]
	v_mfma_f32_16x16x32_bf16 v[126:129], v[150:153], v[186:189], v[126:129]
	v_mfma_f32_16x16x32_bf16 v[122:125], v[178:181], v[186:189], v[122:125]
	v_mfma_f32_16x16x32_bf16 v[110:113], v[150:153], v[206:209], v[110:113]
	v_mfma_f32_16x16x32_bf16 v[106:109], v[178:181], v[206:209], v[106:109]
	v_mfma_f32_16x16x32_bf16 v[94:97], v[150:153], v[214:217], v[94:97]
	v_mfma_f32_16x16x32_bf16 v[90:93], v[178:181], v[214:217], v[90:93]
	v_mfma_f32_16x16x32_bf16 v[78:81], v[150:153], v[222:225], v[78:81]
	v_mfma_f32_16x16x32_bf16 v[74:77], v[178:181], v[222:225], v[74:77]
	s_setprio 0
	s_barrier
; #define PG8_STAGE(bufoff, gbase, voff) do { _Pragma("unroll") for (int _i = 0; _i < 2; ++_i) \
;         __builtin_amdgcn_global_load_lds((const unsigned*)((const char*)(gbase) + (voff)[_i]), (LAS unsigned*)(lds + (bufoff) + ldsw + _i * 8192), 16, 0, 0); } while (0)
; #define PG8_LDA(dst, b, h) do { _Pragma("unroll") for (int m = 0; m < 4; ++m) _Pragma("unroll") for (int k = 0; k < 2; ++k) dst[m][k] = *(const LAS bf16x8*)(lds + PG8_SA(b, h) + aoff + m * 2048 + k * 1024); } while (0)
; #define PG8_LDB(dst, b, h) do { _Pragma("unroll") for (int n = 0; n < 2; ++n) _Pragma("unroll") for (int k = 0; k < 2; ++k) dst[n][k] = *(const LAS bf16x8*)(lds + PG8_SB(b, h) + boff + n * 2048 + k * 1024); } while (0)
; template <class Epi, class Sched, bool ALIGN_EPI = false, bool SP2 = false>
; __device__ __forceinline__ void gemm_phase(LAS unsigned char* lds, const Gemm g, const Sched& S, const Epi& E) {
;     ...
;         for (int t = 0; t < nt; t += 2) {
;             const bool last = (t == nt - 2);
;             const char* a1 = cA + (size_t)(t + 1) * kstep;
;             const char* a2 = last ? nA : cA + (size_t)(t + 2) * kstep; const char* b2 = last ? nB : cB + (size_t)(t + 2) * kstep;
;             const char* a3 = a2 + kstep; const char* b3 = b2 + kstep;
;             if (last && has_next) S.a_ready(nxt);
;             if constexpr (SP2) {
;             PG8_LDB(B0, 0, 0); PG8_LDB(B1, 0, 1); PG8_SCHED; PG8_LDA(At, 0, 0); PG8_STAGE(PG8_SA(1, 1), a1 + hstep, voffA);
;             PG8_WAIT_V(8); PG8_WAIT_L(0); PG8_BAR; PG8_MMA(0, 0, At, B0); PG8_MMA(0, 1, At, B1); PG8_BAR; PG8_SCHED;
;             PG8_LDA(At, 0, 1); PG8_STAGE(PG8_SB(0, 0), b2, voffB); PG8_STAGE(PG8_SB(0, 1), b2 + hstepB, voffB); PG8_STAGE(PG8_SA(0, 0), a2, voffA);
;             PG8_WAIT_V(8); PG8_WAIT_L(0); PG8_BAR; PG8_MMA(1, 0, At, B0); PG8_MMA(1, 1, At, B1); PG8_BAR; PG8_SCHED;
;             PG8_LDB(B0, 1, 0); PG8_LDB(B1, 1, 1); PG8_SCHED; PG8_LDA(At, 1, 0); PG8_STAGE(PG8_SA(0, 1), a2 + hstep, voffA);
;             PG8_WAIT_V(8); PG8_WAIT_L(0); PG8_BAR; PG8_MMA(0, 0, At, B0); PG8_MMA(0, 1, At, B1); PG8_BAR; PG8_SCHED;
;             PG8_LDA(At, 1, 1); PG8_STAGE(PG8_SB(1, 0), b3, voffB); PG8_STAGE(PG8_SB(1, 1), b3 + hstepB, voffB); PG8_STAGE(PG8_SA(1, 0), a3, voffA);
;             PG8_WAIT_V(8); PG8_WAIT_L(0); PG8_BAR; PG8_MMA(1, 0, At, B0); PG8_MMA(1, 1, At, B1); PG8_BAR; PG8_SCHED;
	s_add_i32 s50, s58, s28
	v_lshl_add_u64 v[190:191], v[190:191], 0, s[10:11]
	s_mov_b32 m0, s50
	ds_read_b128 v[182:185], v198 offset:49152
	ds_read_b128 v[186:189], v198 offset:50176
	ds_read_b128 v[202:205], v198 offset:51200
	ds_read_b128 v[206:209], v198 offset:52224
	ds_read_b128 v[210:213], v198 offset:53248
	ds_read_b128 v[214:217], v198 offset:54272
	ds_read_b128 v[218:221], v198 offset:55296
	ds_read_b128 v[222:225], v198 offset:56320
	global_load_lds_dwordx4 v[190:191], off
	s_add_i32 m0, s50, 0x2000
	s_add_u32 s48, s48, 0x20080
	v_lshl_add_u64 v[190:191], v[226:227], 0, s[10:11]
	s_addc_u32 s49, s49, 0
	s_add_i32 s50, s59, s28
	global_load_lds_dwordx4 v[190:191], off
	v_lshl_add_u64 v[190:191], s[48:49], 0, v[156:157]
	s_mov_b32 m0, s50
	s_nop 0
	global_load_lds_dwordx4 v[190:191], off
	v_lshl_add_u64 v[190:191], s[48:49], 0, v[160:161]
	s_add_i32 m0, s50, 0x2000
	s_nop 0
	global_load_lds_dwordx4 v[190:191], off
	v_lshl_add_u64 v[190:191], v[228:229], 0, s[10:11]
	s_mov_b32 m0, s53
	s_nop 0
	global_load_lds_dwordx4 v[190:191], off
	v_lshl_add_u64 v[190:191], v[230:231], 0, s[10:11]
	s_mov_b32 m0, s54
	s_nop 0
	global_load_lds_dwordx4 v[190:191], off
	s_waitcnt vmcnt(8)
	s_waitcnt lgkmcnt(0)
	s_barrier
	s_setprio 1
	s_waitcnt lgkmcnt(0)
	v_mfma_f32_16x16x32_bf16 v[70:73], v[58:61], v[182:185], v[70:73]
	v_mfma_f32_16x16x32_bf16 v[66:69], v[138:141], v[182:185], v[66:69]
	v_mfma_f32_16x16x32_bf16 v[46:49], v[58:61], v[202:205], v[46:49]
	v_mfma_f32_16x16x32_bf16 v[42:45], v[138:141], v[202:205], v[42:45]
	v_mfma_f32_16x16x32_bf16 v[30:33], v[58:61], v[210:213], v[30:33]
	v_mfma_f32_16x16x32_bf16 v[26:29], v[138:141], v[210:213], v[26:29]
	v_mfma_f32_16x16x32_bf16 v[14:17], v[58:61], v[218:221], v[14:17]
	v_mfma_f32_16x16x32_bf16 v[10:13], v[138:141], v[218:221], v[10:13]
	v_mfma_f32_16x16x32_bf16 v[70:73], v[62:65], v[186:189], v[70:73]
	v_mfma_f32_16x16x32_bf16 v[66:69], v[142:145], v[186:189], v[66:69]
	v_mfma_f32_16x16x32_bf16 v[46:49], v[62:65], v[206:209], v[46:49]
	v_mfma_f32_16x16x32_bf16 v[42:45], v[142:145], v[206:209], v[42:45]
	v_mfma_f32_16x16x32_bf16 v[30:33], v[62:65], v[214:217], v[30:33]
	v_mfma_f32_16x16x32_bf16 v[26:29], v[142:145], v[214:217], v[26:29]
	v_mfma_f32_16x16x32_bf16 v[14:17], v[62:65], v[222:225], v[14:17]
	v_mfma_f32_16x16x32_bf16 v[10:13], v[142:145], v[222:225], v[10:13]
	s_setprio 0
	s_setprio 1
	v_mfma_f32_16x16x32_bf16 v[50:53], v[146:149], v[182:185], v[50:53]
	v_mfma_f32_16x16x32_bf16 v[62:65], v[150:153], v[186:189], v[50:53]
	v_mfma_f32_16x16x32_bf16 v[50:53], v[174:177], v[182:185], v[54:57]
	v_mfma_f32_16x16x32_bf16 v[38:41], v[146:149], v[202:205], v[38:41]
	v_mfma_f32_16x16x32_bf16 v[34:37], v[174:177], v[202:205], v[34:37]
	v_mfma_f32_16x16x32_bf16 v[22:25], v[146:149], v[210:213], v[22:25]
	v_mfma_f32_16x16x32_bf16 v[18:21], v[174:177], v[210:213], v[18:21]
	v_mfma_f32_16x16x32_bf16 v[6:9], v[146:149], v[218:221], v[6:9]
	v_mfma_f32_16x16x32_bf16 v[2:5], v[174:177], v[218:221], v[2:5]
	v_mfma_f32_16x16x32_bf16 v[58:61], v[178:181], v[186:189], v[50:53]
	v_mfma_f32_16x16x32_bf16 v[38:41], v[150:153], v[206:209], v[38:41]
	v_mfma_f32_16x16x32_bf16 v[34:37], v[178:181], v[206:209], v[34:37]
	v_mfma_f32_16x16x32_bf16 v[22:25], v[150:153], v[214:217], v[22:25]
	v_mfma_f32_16x16x32_bf16 v[18:21], v[178:181], v[214:217], v[18:21]
	v_mfma_f32_16x16x32_bf16 v[6:9], v[150:153], v[222:225], v[6:9]
	v_mfma_f32_16x16x32_bf16 v[2:5], v[178:181], v[222:225], v[2:5]
	s_setprio 0
	s_barrier
	s_add_i32 s47, s47, 2
	s_add_u32 s16, s16, 0x100
	s_addc_u32 s17, s17, 0
	s_add_u32 s24, s24, 0x100
	s_addc_u32 s25, s25, 0
	s_cmp_gt_u32 s47, 29

;     __device__ __forceinline__ void operator()(const f32x4 (&acc)[2][2][4][2], const Unit& u, int wr, int wc, int fr, int fq) const {
;     ...
;         const int s = (u.pm < ML / BM) ? (u.pm >> 5) : 4;
;         const float* bp = bias + (size_t)s * BIAS_N + u.pn * BM + wc * 32 + 8 * fq;
;         const f32x4 ba0 = *(const f32x4*)bp, ba1 = *(const f32x4*)(bp + 4), bb0 = *(const f32x4*)(bp + HALF), bb1 = *(const f32x4*)(bp + HALF + 4);
;         const int lane = fq * 16 + fr;
; template <class Epi, class Sched, bool ALIGN_EPI = false, bool SP2 = false>
; __device__ __forceinline__ void gemm_phase(LAS unsigned char* lds, const Gemm g, const Sched& S, const Epi& E) {
;     ...
;         const bool has_next = S.next(ui + 1, nxt);
;         const char* nA = has_next ? (const char*)g.A + (size_t)nxt.pm * tstep + nxt.koff : cA; const char* nB = has_next ? (const char*)g.Bt + (size_t)nxt.pn * tstep + nxt.koff : cB;
;         for (int t = 0; t < nt; t += 2) {
;             const bool last = (t == nt - 2);
;             const char* a1 = cA + (size_t)(t + 1) * kstep;
;             const char* a2 = last ? nA : cA + (size_t)(t + 2) * kstep; const char* b2 = last ? nB : cB + (size_t)(t + 2) * kstep;
;             const char* a3 = a2 + kstep; const char* b3 = b2 + kstep;
;             if (last && has_next) S.a_ready(nxt);
;             if constexpr (SP2) {
;             PG8_LDB(B0, 0, 0); PG8_LDB(B1, 0, 1); PG8_SCHED; PG8_LDA(At, 0, 0); PG8_STAGE(PG8_SA(1, 1), a1 + hstep, voffA);
;             PG8_WAIT_V(8); PG8_WAIT_L(0); PG8_BAR; PG8_MMA(0, 0, At, B0); PG8_MMA(0, 1, At, B1); PG8_BAR; PG8_SCHED;
;             PG8_LDA(At, 0, 1); PG8_STAGE(PG8_SB(0, 0), b2, voffB); PG8_STAGE(PG8_SB(0, 1), b2 + hstepB, voffB); PG8_STAGE(PG8_SA(0, 0), a2, voffA);
;             PG8_WAIT_V(8); PG8_WAIT_L(0); PG8_BAR; PG8_MMA(1, 0, At, B0); PG8_MMA(1, 1, At, B1); PG8_BAR; PG8_SCHED;
;             PG8_LDB(B0, 1, 0); PG8_LDB(B1, 1, 1); PG8_SCHED; PG8_LDA(At, 1, 0); PG8_STAGE(PG8_SA(0, 1), a2 + hstep, voffA);
;             PG8_WAIT_V(8); PG8_WAIT_L(0); PG8_BAR; PG8_MMA(0, 0, At, B0); PG8_MMA(0, 1, At, B1); PG8_BAR; PG8_SCHED;
;             PG8_LDA(At, 1, 1); PG8_STAGE(PG8_SB(1, 0), b3, voffB); PG8_STAGE(PG8_SB(1, 1), b3 + hstepB, voffB); PG8_STAGE(PG8_SA(1, 0), a3, voffA);
;             PG8_WAIT_V(8); PG8_WAIT_L(0); PG8_BAR; PG8_MMA(1, 0, At, B0); PG8_MMA(1, 1, At, B1); PG8_BAR; PG8_SCHED;
.LBB0_1464:
	s_ashr_i32 s15, s14, 31
	s_lshl_b64 s[18:19], s[14:15], 20
	s_add_u32 s18, s93, s18
	s_addc_u32 s19, s92, s19
	s_and_b64 s[20:21], s[38:39], exec
	s_cselect_b32 s3, s19, s17
	s_cselect_b32 s15, s18, s16
	s_ashr_i32 s13, s12, 31
	s_lshl_b64 s[20:21], s[12:13], 20
	s_add_u32 s20, s27, s20
	s_addc_u32 s21, s28, s21
	s_and_b64 s[24:25], s[38:39], exec
	s_cselect_b32 s13, s21, s23
	s_cselect_b32 s24, s20, s22
	s_add_u32 s16, s16, 0x80080
	s_addc_u32 s17, s17, 0
	s_add_u32 s25, s22, 0x100
	s_addc_u32 s52, s23, 0
	s_mov_b32 s53, -2
	s_waitcnt vmcnt(0)
	s_cmpk_gt_i32 s2, 0x7f
	s_mov_b64 s[98:99], 0xb000
	s_cbranch_scc1 .Lpre_up2l0
	s_ashr_i32 s100, s2, 5
	s_mul_hi_i32 s99, s100, 0x2c00
	s_mul_i32 s98, s100, 0x2c00
.Lpre_up2l0:
	s_lshl_b64 s[98:99], s[98:99], 2
	s_add_u32 s98, s43, s98
	s_addc_u32 s99, s44, s99
	s_lshl_b32 s100, s0, 8
	s_ashr_i32 s101, s100, 31
	s_lshl_b64 s[100:101], s[100:101], 2
	s_add_u32 s98, s98, s100
	s_addc_u32 s99, s99, s101
	s_add_u32 s98, s98, s50
	s_addc_u32 s99, s99, 0
	s_lshl_b32 s100, s2, 8
	s_add_i32 s100, s100, s42
	v_or_b32_e32 v162, s100, v171
	v_ashrrev_i32_e32 v163, 31, v162
	v_lshl_add_u64 v[162:163], v[162:163], 2, s[64:65]
	v_add_u32_e32 v164, s100, v172
	v_ashrrev_i32_e32 v165, 31, v164
	v_lshl_add_u64 v[164:165], v[164:165], 2, s[64:65]
	global_load_dwordx4 v[234:237], v177, s[98:99] offset:16
	global_load_dwordx4 v[238:241], v177, s[98:99]
	global_load_dwordx4 v[242:245], v177, s[98:99] offset:528
	global_load_dwordx4 v[246:249], v177, s[98:99] offset:512
	global_load_dword v250, v[162:163], off
	global_load_dword v251, v[164:165], off
	ds_read_b128 v[66:69], v174
	ds_read_b128 v[70:73], v174 offset:1024
	ds_read_b128 v[74:77], v174 offset:2048
	ds_read_b128 v[78:81], v174 offset:3072
	ds_read_b128 v[162:165], v175
	ds_read_b128 v[182:185], v175 offset:1024
	ds_read_b128 v[186:189], v175 offset:2048
	ds_read_b128 v[190:193], v175 offset:3072
	s_add_u32 s22, s16, 0xfff80080
	s_addc_u32 s23, s17, -1
	s_cmp_eq_u32 s53, 28
	s_cselect_b32 s41, s3, s23
	s_cselect_b32 s40, s15, s22
	s_cselect_b32 s23, s13, s52
	s_cselect_b32 s22, s24, s25
	v_lshl_add_u64 v[166:167], s[16:17], 0, v[154:155]
	s_add_i32 m0, s33, 0xc000
	ds_read_b128 v[194:197], v176
	ds_read_b128 v[198:201], v176 offset:1024
	ds_read_b128 v[202:205], v176 offset:2048
	ds_read_b128 v[206:209], v176 offset:3072
	ds_read_b128 v[210:213], v176 offset:4096
	ds_read_b128 v[214:217], v176 offset:5120
	ds_read_b128 v[218:221], v176 offset:6144
	ds_read_b128 v[222:225], v176 offset:7168
	global_load_lds_dwordx4 v[166:167], off
	v_lshl_add_u64 v[166:167], s[16:17], 0, v[156:157]
	s_add_i32 m0, s33, 0xe000
	s_nop 0
	global_load_lds_dwordx4 v[166:167], off
	s_waitcnt lgkmcnt(0)
	s_barrier
	s_setprio 1
	s_waitcnt lgkmcnt(0)
	v_mfma_f32_16x16x32_bf16 v[142:145], v[66:69], v[194:197], 0
	v_mfma_f32_16x16x32_bf16 v[138:141], v[74:77], v[194:197], 0
	v_mfma_f32_16x16x32_bf16 v[126:129], v[66:69], v[202:205], 0
	v_mfma_f32_16x16x32_bf16 v[122:125], v[74:77], v[202:205], 0
	v_mfma_f32_16x16x32_bf16 v[110:113], v[66:69], v[210:213], 0
	v_mfma_f32_16x16x32_bf16 v[106:109], v[74:77], v[210:213], 0
	v_mfma_f32_16x16x32_bf16 v[94:97], v[66:69], v[218:221], 0
	v_mfma_f32_16x16x32_bf16 v[90:93], v[74:77], v[218:221], 0
	v_mfma_f32_16x16x32_bf16 v[142:145], v[70:73], v[198:201], v[142:145]
	v_mfma_f32_16x16x32_bf16 v[138:141], v[78:81], v[198:201], v[138:141]
	v_mfma_f32_16x16x32_bf16 v[126:129], v[70:73], v[206:209], v[126:129]
	v_mfma_f32_16x16x32_bf16 v[122:125], v[78:81], v[206:209], v[122:125]
	v_mfma_f32_16x16x32_bf16 v[110:113], v[70:73], v[214:217], v[110:113]
	v_mfma_f32_16x16x32_bf16 v[106:109], v[78:81], v[214:217], v[106:109]
	v_mfma_f32_16x16x32_bf16 v[94:97], v[70:73], v[222:225], v[94:97]
	v_mfma_f32_16x16x32_bf16 v[90:93], v[78:81], v[222:225], v[90:93]
	s_setprio 0
	s_setprio 1
	v_mfma_f32_16x16x32_bf16 v[134:137], v[162:165], v[194:197], 0
	v_mfma_f32_16x16x32_bf16 v[130:133], v[186:189], v[194:197], 0
	v_mfma_f32_16x16x32_bf16 v[118:121], v[162:165], v[202:205], 0
	v_mfma_f32_16x16x32_bf16 v[114:117], v[186:189], v[202:205], 0
	v_mfma_f32_16x16x32_bf16 v[102:105], v[162:165], v[210:213], 0
	v_mfma_f32_16x16x32_bf16 v[98:101], v[186:189], v[210:213], 0
	v_mfma_f32_16x16x32_bf16 v[86:89], v[162:165], v[218:221], 0
	v_mfma_f32_16x16x32_bf16 v[82:85], v[186:189], v[218:221], 0
	v_mfma_f32_16x16x32_bf16 v[134:137], v[182:185], v[198:201], v[134:137]
	v_mfma_f32_16x16x32_bf16 v[130:133], v[190:193], v[198:201], v[130:133]
	v_mfma_f32_16x16x32_bf16 v[118:121], v[182:185], v[206:209], v[118:121]
	v_mfma_f32_16x16x32_bf16 v[114:117], v[190:193], v[206:209], v[114:117]
	v_mfma_f32_16x16x32_bf16 v[102:105], v[182:185], v[214:217], v[102:105]
	v_mfma_f32_16x16x32_bf16 v[98:101], v[190:193], v[214:217], v[98:101]
	v_mfma_f32_16x16x32_bf16 v[86:89], v[182:185], v[222:225], v[86:89]
	v_mfma_f32_16x16x32_bf16 v[82:85], v[190:193], v[222:225], v[82:85]
	s_setprio 0
	s_barrier
	s_add_i32 s54, s47, s29
	v_lshl_add_u64 v[166:167], s[22:23], 0, v[150:151]
	s_mov_b32 m0, s54
	ds_read_b128 v[194:197], v176 offset:16384
	ds_read_b128 v[198:201], v176 offset:17408
	ds_read_b128 v[202:205], v176 offset:18432
	ds_read_b128 v[206:209], v176 offset:19456
	ds_read_b128 v[210:213], v176 offset:20480
	ds_read_b128 v[214:217], v176 offset:21504
	ds_read_b128 v[218:221], v176 offset:22528
	ds_read_b128 v[222:225], v176 offset:23552
	global_load_lds_dwordx4 v[166:167], off
	s_add_i32 m0, s54, 0x2000
	s_add_u32 s54, s22, 0x80000
	v_lshl_add_u64 v[226:227], s[22:23], 0, v[146:147]
	s_addc_u32 s55, s23, 0
	s_add_i32 s56, s48, s29
	global_load_lds_dwordx4 v[226:227], off
	v_lshl_add_u64 v[228:229], s[54:55], 0, v[150:151]
	s_mov_b32 m0, s56
	v_lshl_add_u64 v[230:231], s[40:41], 0, v[148:149]
	global_load_lds_dwordx4 v[228:229], off
	v_lshl_add_u64 v[228:229], s[54:55], 0, v[146:147]
	s_add_i32 m0, s56, 0x2000
	s_nop 0
	global_load_lds_dwordx4 v[228:229], off
	v_lshl_add_u64 v[228:229], s[40:41], 0, v[152:153]
	s_mov_b32 m0, s33
	s_nop 0
	global_load_lds_dwordx4 v[228:229], off
	s_mov_b32 m0, s34
	s_nop 0
	global_load_lds_dwordx4 v[230:231], off
	s_waitcnt vmcnt(8)
	s_waitcnt lgkmcnt(0)
	s_barrier
; #define PG8_STAGE(bufoff, gbase, voff) do { _Pragma("unroll") for (int _i = 0; _i < 2; ++_i) \
;         __builtin_amdgcn_global_load_lds((const unsigned*)((const char*)(gbase) + (voff)[_i]), (LAS unsigned*)(lds + (bufoff) + ldsw + _i * 8192), 16, 0, 0); } while (0)
; #define PG8_LDA(dst, b, h) do { _Pragma("unroll") for (int m = 0; m < 4; ++m) _Pragma("unroll") for (int k = 0; k < 2; ++k) dst[m][k] = *(const LAS bf16x8*)(lds + PG8_SA(b, h) + aoff + m * 2048 + k * 1024); } while (0)
; #define PG8_LDB(dst, b, h) do { _Pragma("unroll") for (int n = 0; n < 2; ++n) _Pragma("unroll") for (int k = 0; k < 2; ++k) dst[n][k] = *(const LAS bf16x8*)(lds + PG8_SB(b, h) + boff + n * 2048 + k * 1024); } while (0)
; #define PG8_MMA(ai, bj, At, Bt) do { __builtin_amdgcn_s_setprio(1); _Pragma("unroll") for (int m = 0; m < 4; ++m) _Pragma("unroll") for (int n = 0; n < 2; ++n) _Pragma("unroll") for (int k = 0; k < 2; ++k) \
;         acc[ai][bj][m][n] = __builtin_amdgcn_mfma_f32_16x16x32_bf16(Bt[n][k], At[m][k], acc[ai][bj][m][n], 0, 0, 0); __builtin_amdgcn_s_setprio(0); } while (0)
; #define PG8_WAIT_V(n) asm volatile("s_waitcnt vmcnt(" #n ")" ::: "memory")
; template <class Epi, class Sched, bool ALIGN_EPI = false, bool SP2 = false>
; __device__ __forceinline__ void gemm_phase(LAS unsigned char* lds, const Gemm g, const Sched& S, const Epi& E) {
;     ...
;             PG8_LDB(B0, 0, 0); PG8_LDB(B1, 0, 1); PG8_SCHED; PG8_LDA(At, 0, 0); PG8_STAGE(PG8_SA(1, 1), a1 + hstep, voffA);
;             PG8_WAIT_V(8); PG8_WAIT_L(0); PG8_BAR; PG8_MMA(0, 0, At, B0); PG8_MMA(0, 1, At, B1); PG8_BAR; PG8_SCHED;
;             PG8_LDA(At, 0, 1); PG8_STAGE(PG8_SB(0, 0), b2, voffB); PG8_STAGE(PG8_SB(0, 1), b2 + hstepB, voffB); PG8_STAGE(PG8_SA(0, 0), a2, voffA);
;             PG8_WAIT_V(8); PG8_WAIT_L(0); PG8_BAR; PG8_MMA(1, 0, At, B0); PG8_MMA(1, 1, At, B1); PG8_BAR; PG8_SCHED;
;             PG8_LDB(B0, 1, 0); PG8_LDB(B1, 1, 1); PG8_SCHED; PG8_LDA(At, 1, 0); PG8_STAGE(PG8_SA(0, 1), a2 + hstep, voffA);
;             PG8_WAIT_V(8); PG8_WAIT_L(0); PG8_BAR; PG8_MMA(0, 0, At, B0); PG8_MMA(0, 1, At, B1); PG8_BAR; PG8_SCHED;
;             PG8_LDA(At, 1, 1); PG8_STAGE(PG8_SB(1, 0), b3, voffB); PG8_STAGE(PG8_SB(1, 1), b3 + hstepB, voffB); PG8_STAGE(PG8_SA(1, 0), a3, voffA);
;             PG8_WAIT_V(8); PG8_WAIT_L(0); PG8_BAR; PG8_MMA(1, 0, At, B0); PG8_MMA(1, 1, At, B1); PG8_BAR; PG8_SCHED;
	s_setprio 1
	s_waitcnt lgkmcnt(0)
	v_mfma_f32_16x16x32_bf16 v[62:65], v[66:69], v[194:197], 0
	v_mfma_f32_16x16x32_bf16 v[58:61], v[74:77], v[194:197], 0
	v_mfma_f32_16x16x32_bf16 v[46:49], v[66:69], v[202:205], 0
	v_mfma_f32_16x16x32_bf16 v[42:45], v[74:77], v[202:205], 0
	v_mfma_f32_16x16x32_bf16 v[30:33], v[66:69], v[210:213], 0
	v_mfma_f32_16x16x32_bf16 v[26:29], v[74:77], v[210:213], 0
	v_mfma_f32_16x16x32_bf16 v[14:17], v[66:69], v[218:221], 0
	v_mfma_f32_16x16x32_bf16 v[10:13], v[74:77], v[218:221], 0
	v_mfma_f32_16x16x32_bf16 v[62:65], v[70:73], v[198:201], v[62:65]
	v_mfma_f32_16x16x32_bf16 v[58:61], v[78:81], v[198:201], v[58:61]
	v_mfma_f32_16x16x32_bf16 v[46:49], v[70:73], v[206:209], v[46:49]
	v_mfma_f32_16x16x32_bf16 v[42:45], v[78:81], v[206:209], v[42:45]
	v_mfma_f32_16x16x32_bf16 v[30:33], v[70:73], v[214:217], v[30:33]
	v_mfma_f32_16x16x32_bf16 v[26:29], v[78:81], v[214:217], v[26:29]
	v_mfma_f32_16x16x32_bf16 v[14:17], v[70:73], v[222:225], v[14:17]
	v_mfma_f32_16x16x32_bf16 v[10:13], v[78:81], v[222:225], v[10:13]
	s_setprio 0
	s_setprio 1
	v_mfma_f32_16x16x32_bf16 v[54:57], v[162:165], v[194:197], 0
	v_mfma_f32_16x16x32_bf16 v[50:53], v[186:189], v[194:197], 0
	v_mfma_f32_16x16x32_bf16 v[38:41], v[162:165], v[202:205], 0
	v_mfma_f32_16x16x32_bf16 v[34:37], v[186:189], v[202:205], 0
	v_mfma_f32_16x16x32_bf16 v[22:25], v[162:165], v[210:213], 0
	v_mfma_f32_16x16x32_bf16 v[18:21], v[186:189], v[210:213], 0
	v_mfma_f32_16x16x32_bf16 v[6:9], v[162:165], v[218:221], 0
	v_mfma_f32_16x16x32_bf16 v[2:5], v[186:189], v[218:221], 0
	v_mfma_f32_16x16x32_bf16 v[54:57], v[182:185], v[198:201], v[54:57]
	v_mfma_f32_16x16x32_bf16 v[50:53], v[190:193], v[198:201], v[50:53]
	v_mfma_f32_16x16x32_bf16 v[38:41], v[182:185], v[206:209], v[38:41]
	v_mfma_f32_16x16x32_bf16 v[34:37], v[190:193], v[206:209], v[34:37]
	v_mfma_f32_16x16x32_bf16 v[22:25], v[182:185], v[214:217], v[22:25]
	v_mfma_f32_16x16x32_bf16 v[18:21], v[190:193], v[214:217], v[18:21]
	v_mfma_f32_16x16x32_bf16 v[6:9], v[182:185], v[222:225], v[6:9]
	v_mfma_f32_16x16x32_bf16 v[2:5], v[190:193], v[222:225], v[2:5]
	s_setprio 0
	s_barrier
	s_add_i32 s54, 0, 0x18000
	s_add_i32 s55, 0, 0x1c000
	v_add_u32_e32 v78, s54, v170
	v_add_u32_e32 v168, s55, v170
	ds_read_b128 v[66:69], v78
	ds_read_b128 v[70:73], v78 offset:1024
	ds_read_b128 v[74:77], v78 offset:2048
	ds_read_b128 v[78:81], v78 offset:3072
	ds_read_b128 v[162:165], v168
	ds_read_b128 v[182:185], v168 offset:1024
	ds_read_b128 v[186:189], v168 offset:2048
	ds_read_b128 v[190:193], v168 offset:3072
	s_add_u32 s40, s40, 0x80000
	s_addc_u32 s41, s41, 0
	s_mov_b32 m0, s35
	v_lshl_add_u64 v[232:233], s[40:41], 0, v[152:153]
	ds_read_b128 v[194:197], v176 offset:32768
	ds_read_b128 v[198:201], v176 offset:33792
	ds_read_b128 v[202:205], v176 offset:34816
	ds_read_b128 v[206:209], v176 offset:35840
	ds_read_b128 v[210:213], v176 offset:36864
	ds_read_b128 v[214:217], v176 offset:37888
	ds_read_b128 v[218:221], v176 offset:38912
	ds_read_b128 v[222:225], v176 offset:39936
	global_load_lds_dwordx4 v[232:233], off
	v_lshl_add_u64 v[232:233], s[40:41], 0, v[148:149]
	s_mov_b32 m0, s36
	s_nop 0
	global_load_lds_dwordx4 v[232:233], off
	s_waitcnt vmcnt(8)
	s_waitcnt lgkmcnt(0)
	s_barrier
	s_setprio 1
	s_waitcnt lgkmcnt(0)
	v_mfma_f32_16x16x32_bf16 v[142:145], v[66:69], v[194:197], v[142:145]
	v_mfma_f32_16x16x32_bf16 v[138:141], v[74:77], v[194:197], v[138:141]
	v_mfma_f32_16x16x32_bf16 v[126:129], v[66:69], v[202:205], v[126:129]
	v_mfma_f32_16x16x32_bf16 v[122:125], v[74:77], v[202:205], v[122:125]
	v_mfma_f32_16x16x32_bf16 v[110:113], v[66:69], v[210:213], v[110:113]
	v_mfma_f32_16x16x32_bf16 v[106:109], v[74:77], v[210:213], v[106:109]
	v_mfma_f32_16x16x32_bf16 v[94:97], v[66:69], v[218:221], v[94:97]
	v_mfma_f32_16x16x32_bf16 v[90:93], v[74:77], v[218:221], v[90:93]
	v_mfma_f32_16x16x32_bf16 v[142:145], v[70:73], v[198:201], v[142:145]
	v_mfma_f32_16x16x32_bf16 v[138:141], v[78:81], v[198:201], v[138:141]
	v_mfma_f32_16x16x32_bf16 v[126:129], v[70:73], v[206:209], v[126:129]
	v_mfma_f32_16x16x32_bf16 v[122:125], v[78:81], v[206:209], v[122:125]
	v_mfma_f32_16x16x32_bf16 v[110:113], v[70:73], v[214:217], v[110:113]
	v_mfma_f32_16x16x32_bf16 v[106:109], v[78:81], v[214:217], v[106:109]
	v_mfma_f32_16x16x32_bf16 v[94:97], v[70:73], v[222:225], v[94:97]
	v_mfma_f32_16x16x32_bf16 v[90:93], v[78:81], v[222:225], v[90:93]
	s_setprio 0
	s_setprio 1
	v_mfma_f32_16x16x32_bf16 v[134:137], v[162:165], v[194:197], v[134:137]
	v_mfma_f32_16x16x32_bf16 v[130:133], v[186:189], v[194:197], v[130:133]
	v_mfma_f32_16x16x32_bf16 v[118:121], v[162:165], v[202:205], v[118:121]
	v_mfma_f32_16x16x32_bf16 v[114:117], v[186:189], v[202:205], v[114:117]
	v_mfma_f32_16x16x32_bf16 v[102:105], v[162:165], v[210:213], v[102:105]
	v_mfma_f32_16x16x32_bf16 v[98:101], v[186:189], v[210:213], v[98:101]
	v_mfma_f32_16x16x32_bf16 v[86:89], v[162:165], v[218:221], v[86:89]
	v_mfma_f32_16x16x32_bf16 v[82:85], v[186:189], v[218:221], v[82:85]
	v_mfma_f32_16x16x32_bf16 v[134:137], v[182:185], v[198:201], v[134:137]
	v_mfma_f32_16x16x32_bf16 v[130:133], v[190:193], v[198:201], v[130:133]
	v_mfma_f32_16x16x32_bf16 v[118:121], v[182:185], v[206:209], v[118:121]
	v_mfma_f32_16x16x32_bf16 v[114:117], v[190:193], v[206:209], v[114:117]
	v_mfma_f32_16x16x32_bf16 v[102:105], v[182:185], v[214:217], v[102:105]
	v_mfma_f32_16x16x32_bf16 v[98:101], v[190:193], v[214:217], v[98:101]
	v_mfma_f32_16x16x32_bf16 v[86:89], v[182:185], v[222:225], v[86:89]
	v_mfma_f32_16x16x32_bf16 v[82:85], v[190:193], v[222:225], v[82:85]
	s_setprio 0
	s_barrier
; #define PG8_STAGE(bufoff, gbase, voff) do { _Pragma("unroll") for (int _i = 0; _i < 2; ++_i) \
;         __builtin_amdgcn_global_load_lds((const unsigned*)((const char*)(gbase) + (voff)[_i]), (LAS unsigned*)(lds + (bufoff) + ldsw + _i * 8192), 16, 0, 0); } while (0)
; #define PG8_LDA(dst, b, h) do { _Pragma("unroll") for (int m = 0; m < 4; ++m) _Pragma("unroll") for (int k = 0; k < 2; ++k) dst[m][k] = *(const LAS bf16x8*)(lds + PG8_SA(b, h) + aoff + m * 2048 + k * 1024); } while (0)
; #define PG8_LDB(dst, b, h) do { _Pragma("unroll") for (int n = 0; n < 2; ++n) _Pragma("unroll") for (int k = 0; k < 2; ++k) dst[n][k] = *(const LAS bf16x8*)(lds + PG8_SB(b, h) + boff + n * 2048 + k * 1024); } while (0)
; template <class Epi, class Sched, bool ALIGN_EPI = false, bool SP2 = false>
; __device__ __forceinline__ void gemm_phase(LAS unsigned char* lds, const Gemm g, const Sched& S, const Epi& E) {
;     ...
;         for (int t = 0; t < nt; t += 2) {
;             const bool last = (t == nt - 2);
;             const char* a1 = cA + (size_t)(t + 1) * kstep;
;             const char* a2 = last ? nA : cA + (size_t)(t + 2) * kstep; const char* b2 = last ? nB : cB + (size_t)(t + 2) * kstep;
;             const char* a3 = a2 + kstep; const char* b3 = b2 + kstep;
;             if (last && has_next) S.a_ready(nxt);
;             if constexpr (SP2) {
;             PG8_LDB(B0, 0, 0); PG8_LDB(B1, 0, 1); PG8_SCHED; PG8_LDA(At, 0, 0); PG8_STAGE(PG8_SA(1, 1), a1 + hstep, voffA);
;             PG8_WAIT_V(8); PG8_WAIT_L(0); PG8_BAR; PG8_MMA(0, 0, At, B0); PG8_MMA(0, 1, At, B1); PG8_BAR; PG8_SCHED;
;             PG8_LDA(At, 0, 1); PG8_STAGE(PG8_SB(0, 0), b2, voffB); PG8_STAGE(PG8_SB(0, 1), b2 + hstepB, voffB); PG8_STAGE(PG8_SA(0, 0), a2, voffA);
;             PG8_WAIT_V(8); PG8_WAIT_L(0); PG8_BAR; PG8_MMA(1, 0, At, B0); PG8_MMA(1, 1, At, B1); PG8_BAR; PG8_SCHED;
;             PG8_LDB(B0, 1, 0); PG8_LDB(B1, 1, 1); PG8_SCHED; PG8_LDA(At, 1, 0); PG8_STAGE(PG8_SA(0, 1), a2 + hstep, voffA);
;             PG8_WAIT_V(8); PG8_WAIT_L(0); PG8_BAR; PG8_MMA(0, 0, At, B0); PG8_MMA(0, 1, At, B1); PG8_BAR; PG8_SCHED;
;             PG8_LDA(At, 1, 1); PG8_STAGE(PG8_SB(1, 0), b3, voffB); PG8_STAGE(PG8_SB(1, 1), b3 + hstepB, voffB); PG8_STAGE(PG8_SA(1, 0), a3, voffA);
;             PG8_WAIT_V(8); PG8_WAIT_L(0); PG8_BAR; PG8_MMA(1, 0, At, B0); PG8_MMA(1, 1, At, B1); PG8_BAR; PG8_SCHED;
	s_add_i32 s40, s54, s29
	v_lshl_add_u64 v[166:167], v[166:167], 0, s[8:9]
	s_mov_b32 m0, s40
	ds_read_b128 v[194:197], v176 offset:49152
	ds_read_b128 v[198:201], v176 offset:50176
	ds_read_b128 v[202:205], v176 offset:51200
	ds_read_b128 v[206:209], v176 offset:52224
	ds_read_b128 v[210:213], v176 offset:53248
	ds_read_b128 v[214:217], v176 offset:54272
	ds_read_b128 v[218:221], v176 offset:55296
	ds_read_b128 v[222:225], v176 offset:56320
	global_load_lds_dwordx4 v[166:167], off
	s_add_i32 m0, s40, 0x2000
	s_add_u32 s22, s22, 0x80080
	v_lshl_add_u64 v[166:167], v[226:227], 0, s[8:9]
	s_addc_u32 s23, s23, 0
	s_add_i32 s40, s55, s29
	global_load_lds_dwordx4 v[166:167], off
	v_lshl_add_u64 v[166:167], s[22:23], 0, v[150:151]
	s_mov_b32 m0, s40
	s_nop 0
	global_load_lds_dwordx4 v[166:167], off
	v_lshl_add_u64 v[166:167], s[22:23], 0, v[146:147]
	s_add_i32 m0, s40, 0x2000
	s_nop 0
	global_load_lds_dwordx4 v[166:167], off
	v_lshl_add_u64 v[166:167], v[228:229], 0, s[8:9]
	s_mov_b32 m0, s45
	s_nop 0
	global_load_lds_dwordx4 v[166:167], off
	v_lshl_add_u64 v[166:167], v[230:231], 0, s[8:9]
	s_mov_b32 m0, s46
	s_nop 0
	global_load_lds_dwordx4 v[166:167], off
	s_waitcnt vmcnt(8)
	s_waitcnt lgkmcnt(0)
	s_barrier
	s_setprio 1
	s_waitcnt lgkmcnt(0)
	v_mfma_f32_16x16x32_bf16 v[62:65], v[66:69], v[194:197], v[62:65]
	v_mfma_f32_16x16x32_bf16 v[58:61], v[74:77], v[194:197], v[58:61]
	v_mfma_f32_16x16x32_bf16 v[46:49], v[66:69], v[202:205], v[46:49]
	v_mfma_f32_16x16x32_bf16 v[42:45], v[74:77], v[202:205], v[42:45]
	v_mfma_f32_16x16x32_bf16 v[30:33], v[66:69], v[210:213], v[30:33]
	v_mfma_f32_16x16x32_bf16 v[26:29], v[74:77], v[210:213], v[26:29]
	v_mfma_f32_16x16x32_bf16 v[14:17], v[66:69], v[218:221], v[14:17]
	v_mfma_f32_16x16x32_bf16 v[10:13], v[74:77], v[218:221], v[10:13]
	v_mfma_f32_16x16x32_bf16 v[62:65], v[70:73], v[198:201], v[62:65]
	v_mfma_f32_16x16x32_bf16 v[58:61], v[78:81], v[198:201], v[58:61]
	v_mfma_f32_16x16x32_bf16 v[46:49], v[70:73], v[206:209], v[46:49]
	v_mfma_f32_16x16x32_bf16 v[42:45], v[78:81], v[206:209], v[42:45]
	v_mfma_f32_16x16x32_bf16 v[30:33], v[70:73], v[214:217], v[30:33]
	v_mfma_f32_16x16x32_bf16 v[26:29], v[78:81], v[214:217], v[26:29]
	v_mfma_f32_16x16x32_bf16 v[14:17], v[70:73], v[222:225], v[14:17]
	v_mfma_f32_16x16x32_bf16 v[10:13], v[78:81], v[222:225], v[10:13]
	s_setprio 0
	s_setprio 1
	v_mfma_f32_16x16x32_bf16 v[54:57], v[162:165], v[194:197], v[54:57]
	v_mfma_f32_16x16x32_bf16 v[50:53], v[186:189], v[194:197], v[50:53]
	v_mfma_f32_16x16x32_bf16 v[38:41], v[162:165], v[202:205], v[38:41]
	v_mfma_f32_16x16x32_bf16 v[34:37], v[186:189], v[202:205], v[34:37]
	v_mfma_f32_16x16x32_bf16 v[22:25], v[162:165], v[210:213], v[22:25]
	v_mfma_f32_16x16x32_bf16 v[18:21], v[186:189], v[210:213], v[18:21]
	v_mfma_f32_16x16x32_bf16 v[6:9], v[162:165], v[218:221], v[6:9]
	v_mfma_f32_16x16x32_bf16 v[2:5], v[186:189], v[218:221], v[2:5]
	v_mfma_f32_16x16x32_bf16 v[54:57], v[182:185], v[198:201], v[54:57]
	v_mfma_f32_16x16x32_bf16 v[50:53], v[190:193], v[198:201], v[50:53]
	v_mfma_f32_16x16x32_bf16 v[38:41], v[182:185], v[206:209], v[38:41]
	v_mfma_f32_16x16x32_bf16 v[34:37], v[190:193], v[206:209], v[34:37]
	v_mfma_f32_16x16x32_bf16 v[22:25], v[182:185], v[214:217], v[22:25]
	v_mfma_f32_16x16x32_bf16 v[18:21], v[190:193], v[214:217], v[18:21]
	v_mfma_f32_16x16x32_bf16 v[6:9], v[182:185], v[222:225], v[6:9]
	v_mfma_f32_16x16x32_bf16 v[2:5], v[190:193], v[222:225], v[2:5]
	s_setprio 0
	s_barrier
	s_add_i32 s53, s53, 2
	s_add_u32 s16, s16, 0x100
	s_addc_u32 s17, s17, 0
	s_add_u32 s25, s25, 0x100
	s_addc_u32 s52, s52, 0
	s_cmp_gt_u32 s53, 29

; __device__ __forceinline__ unsigned cvt_pk_bf16(float lo, float hi) { unsigned r; asm volatile("v_cvt_pk_bf16_f32 %0, %1, %2" : "=v"(r) : "v"(lo), "v"(hi)); return r; }
; __device__ __forceinline__ float silu_mul(float a, float b) { return a * b * __builtin_amdgcn_rcpf(1.0f + __builtin_amdgcn_exp2f(-a * LOG2E)); }
; __device__ __forceinline__ float row_rstd(const float* ss, int row) { return 1.0f / sqrtf(ss[row] * (1.0f / DM) + 1e-6f); }
;     __device__ __forceinline__ void operator()(const f32x4 (&acc)[2][2][4][2], const Unit& u, int wr, int wc, int fr, int fq) const {
;     ...
;         const float rsl0 = row_rstd(ss, u.pm * BM + wr * 64 + lane), rsl1 = row_rstd(ss, u.pm * BM + HALF + wr * 64 + lane);
; #pragma unroll
;         for (int ai = 0; ai < 2; ++ai)
; #pragma unroll
;             for (int m = 0; m < 4; ++m) { const int row = row0 + ai * HALF + m * 16; const float rs = __shfl(ai ? rsl1 : rsl0, m * 16 + fr); bf16_t* rowp = O + (size_t)row * DFF + col0;
;                 const f32x4 a0 = acc[ai][0][m][0] * rs + ba0, a1 = acc[ai][0][m][1] * rs + ba1, b0 = acc[ai][1][m][0] * rs + bb0, b1 = acc[ai][1][m][1] * rs + bb1;
;                 u32x4 w; w.x = cvt_pk_bf16(silu_mul(a0[0], b0[0]), silu_mul(a0[1], b0[1])); w.y = cvt_pk_bf16(silu_mul(a0[2], b0[2]), silu_mul(a0[3], b0[3]));
;                 w.z = cvt_pk_bf16(silu_mul(a1[0], b1[0]), silu_mul(a1[1], b1[1])); w.w = cvt_pk_bf16(silu_mul(a1[2], b1[2]), silu_mul(a1[3], b1[3]));
;                 *(u32x4*)rowp = w; }
.LBB0_1470:
	s_lshl_b32 s2, s2, 8
	s_add_i32 s13, s2, s42
	s_lshl_b64 s[2:3], s[16:17], 2
	s_add_u32 s15, s43, s2
	s_addc_u32 s16, s44, s3
	s_lshl_b32 s2, s0, 8
	s_ashr_i32 s3, s2, 31
	s_lshl_b64 s[2:3], s[2:3], 2
	v_lshl_or_b32 v164, s0, 7, v173
	s_add_u32 s0, s15, s2
	s_addc_u32 s3, s16, s3
	v_or_b32_e32 v162, s13, v171
	s_add_u32 s2, s0, s50
	v_ashrrev_i32_e32 v163, 31, v162
	s_addc_u32 s3, s3, 0
	v_lshl_add_u64 v[162:163], v[162:163], 2, s[64:65]
	v_mov_b32_e32 v74, v234
	v_mov_b32_e32 v75, v235
	v_mov_b32_e32 v76, v236
	v_mov_b32_e32 v77, v237
	v_mov_b32_e32 v78, v238
	v_mov_b32_e32 v79, v239
	v_mov_b32_e32 v80, v240
	v_mov_b32_e32 v81, v241
	v_mov_b32_e32 v66, v242
	v_mov_b32_e32 v67, v243
	v_mov_b32_e32 v68, v244
	v_mov_b32_e32 v69, v245
	v_mov_b32_e32 v70, v246
	v_mov_b32_e32 v71, v247
	v_mov_b32_e32 v72, v248
	v_mov_b32_e32 v73, v249
	v_or_b32_e32 v181, s13, v169
	v_mov_b32_e32 v162, v250
	s_waitcnt vmcnt(0)
	v_fmamk_f32 v162, v162, 0x3a000000, v178
	v_cmp_gt_f32_e32 vcc, s51, v162
	v_mul_f32_e32 v163, 0x4f800000, v162
	s_nop 0
	v_cndmask_b32_e32 v162, v162, v163, vcc
	v_sqrt_f32_e32 v163, v162
	s_nop 0
	v_add_u32_e32 v165, -1, v163
	v_fma_f32 v166, -v165, v163, v162
	v_cmp_ge_f32_e64 s[2:3], 0, v166
	v_add_u32_e32 v166, 1, v163
	s_nop 0
	v_cndmask_b32_e64 v165, v163, v165, s[2:3]
	v_fma_f32 v163, -v166, v163, v162
	v_cmp_lt_f32_e64 s[2:3], 0, v163
	s_nop 1
	v_cndmask_b32_e64 v163, v165, v166, s[2:3]
	v_mul_f32_e32 v165, 0x37800000, v163
	v_cndmask_b32_e32 v163, v163, v165, vcc
	v_cmp_class_f32_e32 vcc, v162, v179
	s_nop 1
	v_cndmask_b32_e32 v166, v163, v162, vcc
	v_add_u32_e32 v162, s13, v172
	v_ashrrev_i32_e32 v163, 31, v162
	v_lshl_add_u64 v[162:163], v[162:163], 2, s[64:65]
	v_mov_b32_e32 v162, v251
	v_fmamk_f32 v162, v162, 0x3a000000, v178
	v_cmp_gt_f32_e32 vcc, s51, v162
	v_mul_f32_e32 v163, 0x4f800000, v162
	s_nop 0
	v_cndmask_b32_e32 v162, v162, v163, vcc
	v_sqrt_f32_e32 v163, v162
	s_nop 0
	v_add_u32_e32 v165, -1, v163
	v_fma_f32 v167, -v165, v163, v162
	v_cmp_ge_f32_e64 s[2:3], 0, v167
	v_add_u32_e32 v167, 1, v163
	s_nop 0
	v_cndmask_b32_e64 v165, v163, v165, s[2:3]
	v_fma_f32 v163, -v167, v163, v162
	v_cmp_lt_f32_e64 s[2:3], 0, v163
	s_nop 1
	v_cndmask_b32_e64 v163, v165, v167, s[2:3]
	v_mul_f32_e32 v165, 0x37800000, v163
	v_cndmask_b32_e32 v163, v163, v165, vcc
	v_cmp_class_f32_e32 vcc, v162, v179
	v_ashrrev_i32_e32 v165, 31, v164
	v_lshlrev_b64 v[164:165], 1, v[164:165]
	v_cndmask_b32_e32 v182, v163, v162, vcc
	v_div_scale_f32 v162, s[2:3], v166, v166, 1.0
	v_rcp_f32_e32 v163, v162
	s_nop 0
	v_fma_f32 v167, -v162, v163, 1.0
	v_fmac_f32_e32 v163, v167, v163
	v_div_scale_f32 v167, vcc, 1.0, v166, 1.0
	v_mul_f32_e32 v168, v167, v163
	v_fma_f32 v183, -v162, v168, v167
	v_fmac_f32_e32 v168, v183, v163
	v_fma_f32 v162, -v162, v168, v167
	v_div_fmas_f32 v162, v162, v163, v168
	v_div_fixup_f32 v183, v162, v166, 1.0
	ds_bpermute_b32 v168, v180, v183
	v_mov_b64_e32 v[162:163], s[96:97]
	v_mad_i64_i32 v[166:167], s[2:3], v181, s49, v[162:163]
	v_lshl_add_u64 v[166:167], v[166:167], 0, v[164:165]
	s_waitcnt lgkmcnt(0)
	v_pk_fma_f32 v[142:143], v[142:143], v[168:169], v[78:79] op_sel_hi:[1,0,1]
	v_pk_fma_f32 v[134:135], v[134:135], v[168:169], v[70:71] op_sel_hi:[1,0,1]
	v_pk_fma_f32 v[184:185], v[132:133], v[168:169], v[68:69] op_sel_hi:[1,0,1]
	v_pk_fma_f32 v[132:133], v[130:131], v[168:169], v[66:67] op_sel_hi:[1,0,1]
	v_mul_f32_e32 v131, 0xbfb8aa3b, v142
	v_mul_f32_e32 v130, v142, v134
	v_exp_f32_e32 v131, v131
	v_mul_f32_e32 v134, 0xbfb8aa3b, v143
	v_exp_f32_e32 v134, v134
	v_pk_fma_f32 v[144:145], v[144:145], v[168:169], v[80:81] op_sel_hi:[1,0,1]
	v_add_f32_e32 v131, 1.0, v131
	v_rcp_f32_e32 v131, v131
	v_add_f32_e32 v134, 1.0, v134
	v_rcp_f32_e32 v134, v134
	v_pk_fma_f32 v[136:137], v[136:137], v[168:169], v[72:73] op_sel_hi:[1,0,1]
	v_mul_f32_e32 v130, v130, v131
	v_mul_f32_e32 v131, v143, v135
	v_mul_f32_e32 v131, v131, v134
	v_mul_f32_e32 v134, 0xbfb8aa3b, v144
	v_exp_f32_e32 v134, v134
	v_mul_f32_e32 v135, 0xbfb8aa3b, v145
	v_exp_f32_e32 v135, v135
	v_cvt_pk_bf16_f32 v130, v130, v131
	v_add_f32_e32 v134, 1.0, v134
	v_rcp_f32_e32 v134, v134
	v_add_f32_e32 v135, 1.0, v135
	v_rcp_f32_e32 v135, v135
	v_mul_f32_e32 v131, v144, v136
	v_mul_f32_e32 v131, v131, v134
	v_mul_f32_e32 v134, v145, v137
	v_pk_fma_f32 v[138:139], v[138:139], v[168:169], v[74:75] op_sel_hi:[1,0,1]
	v_mul_f32_e32 v134, v134, v135
	v_cvt_pk_bf16_f32 v131, v131, v134
	v_mul_f32_e32 v134, 0xbfb8aa3b, v138
	v_exp_f32_e32 v134, v134
	v_mul_f32_e32 v132, v138, v132
	v_pk_fma_f32 v[140:141], v[140:141], v[168:169], v[76:77] op_sel_hi:[1,0,1]
	v_mul_f32_e32 v133, v139, v133
	v_add_f32_e32 v134, 1.0, v134
	v_rcp_f32_e32 v134, v134
	v_mul_f32_e32 v135, 0xbfb8aa3b, v141
	v_exp_f32_e32 v135, v135
	v_mul_f32_e32 v132, v132, v134
	v_mul_f32_e32 v134, 0xbfb8aa3b, v139
	v_exp_f32_e32 v134, v134
	v_add_f32_e32 v135, 1.0, v135
	v_rcp_f32_e32 v135, v135
	v_add_f32_e32 v134, 1.0, v134
	v_rcp_f32_e32 v134, v134
	s_nop 0
	v_mul_f32_e32 v133, v133, v134
	v_mul_f32_e32 v134, 0xbfb8aa3b, v140
	v_exp_f32_e32 v134, v134
	v_cvt_pk_bf16_f32 v132, v132, v133
	v_mul_f32_e32 v133, v140, v184
	v_add_f32_e32 v134, 1.0, v134
	v_rcp_f32_e32 v134, v134
	s_nop 0
	v_mul_f32_e32 v133, v133, v134
	v_mul_f32_e32 v134, v141, v185
	v_mul_f32_e32 v134, v134, v135
	v_cvt_pk_bf16_f32 v133, v133, v134
	global_store_dwordx4 v[166:167], v[130:133], off
	ds_bpermute_b32 v130, v180, v183 offset:64
	s_nop 0
	v_or_b32_e32 v131, 16, v181
	v_mad_i64_i32 v[132:133], s[2:3], v131, s49, v[162:163]
	s_waitcnt lgkmcnt(0)
; __device__ __forceinline__ unsigned cvt_pk_bf16(float lo, float hi) { unsigned r; asm volatile("v_cvt_pk_bf16_f32 %0, %1, %2" : "=v"(r) : "v"(lo), "v"(hi)); return r; }
; __device__ __forceinline__ float silu_mul(float a, float b) { return a * b * __builtin_amdgcn_rcpf(1.0f + __builtin_amdgcn_exp2f(-a * LOG2E)); }
;     __device__ __forceinline__ void operator()(const f32x4 (&acc)[2][2][4][2], const Unit& u, int wr, int wc, int fr, int fq) const {
;     ...
;             for (int m = 0; m < 4; ++m) { const int row = row0 + ai * HALF + m * 16; const float rs = __shfl(ai ? rsl1 : rsl0, m * 16 + fr); bf16_t* rowp = O + (size_t)row * DFF + col0;
;                 const f32x4 a0 = acc[ai][0][m][0] * rs + ba0, a1 = acc[ai][0][m][1] * rs + ba1, b0 = acc[ai][1][m][0] * rs + bb0, b1 = acc[ai][1][m][1] * rs + bb1;
;                 u32x4 w; w.x = cvt_pk_bf16(silu_mul(a0[0], b0[0]), silu_mul(a0[1], b0[1])); w.y = cvt_pk_bf16(silu_mul(a0[2], b0[2]), silu_mul(a0[3], b0[3]));
;                 w.z = cvt_pk_bf16(silu_mul(a1[0], b1[0]), silu_mul(a1[1], b1[1])); w.w = cvt_pk_bf16(silu_mul(a1[2], b1[2]), silu_mul(a1[3], b1[3]));
;                 *(u32x4*)rowp = w; }
	v_pk_fma_f32 v[126:127], v[126:127], v[130:131], v[78:79] op_sel_hi:[1,0,1]
	v_pk_fma_f32 v[118:119], v[118:119], v[130:131], v[70:71] op_sel_hi:[1,0,1]
	v_pk_fma_f32 v[134:135], v[116:117], v[130:131], v[68:69] op_sel_hi:[1,0,1]
	v_pk_fma_f32 v[116:117], v[114:115], v[130:131], v[66:67] op_sel_hi:[1,0,1]
	v_mul_f32_e32 v115, 0xbfb8aa3b, v126
	v_mul_f32_e32 v114, v126, v118
	v_exp_f32_e32 v115, v115
	v_mul_f32_e32 v118, 0xbfb8aa3b, v127
	v_exp_f32_e32 v118, v118
	v_pk_fma_f32 v[128:129], v[128:129], v[130:131], v[80:81] op_sel_hi:[1,0,1]
	v_add_f32_e32 v115, 1.0, v115
	v_rcp_f32_e32 v115, v115
	v_add_f32_e32 v118, 1.0, v118
	v_rcp_f32_e32 v118, v118
	v_pk_fma_f32 v[120:121], v[120:121], v[130:131], v[72:73] op_sel_hi:[1,0,1]
	v_mul_f32_e32 v114, v114, v115
	v_mul_f32_e32 v115, v127, v119
	v_mul_f32_e32 v115, v115, v118
	v_mul_f32_e32 v118, 0xbfb8aa3b, v128
	v_exp_f32_e32 v118, v118
	v_mul_f32_e32 v119, 0xbfb8aa3b, v129
	v_exp_f32_e32 v119, v119
	v_cvt_pk_bf16_f32 v114, v114, v115
	v_add_f32_e32 v118, 1.0, v118
	v_rcp_f32_e32 v118, v118
	v_add_f32_e32 v119, 1.0, v119
	v_rcp_f32_e32 v119, v119
	v_mul_f32_e32 v115, v128, v120
	v_mul_f32_e32 v115, v115, v118
	v_mul_f32_e32 v118, v129, v121
	v_pk_fma_f32 v[122:123], v[122:123], v[130:131], v[74:75] op_sel_hi:[1,0,1]
	v_mul_f32_e32 v118, v118, v119
	v_cvt_pk_bf16_f32 v115, v115, v118
	v_mul_f32_e32 v118, 0xbfb8aa3b, v122
	v_exp_f32_e32 v118, v118
	v_mul_f32_e32 v116, v122, v116
	v_pk_fma_f32 v[124:125], v[124:125], v[130:131], v[76:77] op_sel_hi:[1,0,1]
	v_mul_f32_e32 v117, v123, v117
	v_add_f32_e32 v118, 1.0, v118
	v_rcp_f32_e32 v118, v118
	v_mul_f32_e32 v119, 0xbfb8aa3b, v125
	v_exp_f32_e32 v119, v119
	v_lshl_add_u64 v[132:133], v[132:133], 0, v[164:165]
	v_mul_f32_e32 v116, v116, v118
	v_mul_f32_e32 v118, 0xbfb8aa3b, v123
	v_exp_f32_e32 v118, v118
	v_add_f32_e32 v119, 1.0, v119
	v_rcp_f32_e32 v119, v119
	v_add_f32_e32 v118, 1.0, v118
	v_rcp_f32_e32 v118, v118
	s_nop 0
	v_mul_f32_e32 v117, v117, v118
	v_mul_f32_e32 v118, 0xbfb8aa3b, v124
	v_exp_f32_e32 v118, v118
	v_cvt_pk_bf16_f32 v116, v116, v117
	v_mul_f32_e32 v117, v124, v134
	v_add_f32_e32 v118, 1.0, v118
	v_rcp_f32_e32 v118, v118
	s_nop 0
	v_mul_f32_e32 v117, v117, v118
	v_mul_f32_e32 v118, v125, v135
	v_mul_f32_e32 v118, v118, v119
	v_cvt_pk_bf16_f32 v117, v117, v118
	global_store_dwordx4 v[132:133], v[114:117], off
	ds_bpermute_b32 v114, v180, v183 offset:128
	s_nop 0
	v_or_b32_e32 v115, 32, v181
	v_mad_i64_i32 v[116:117], s[2:3], v115, s49, v[162:163]
	s_waitcnt lgkmcnt(0)
	v_pk_fma_f32 v[110:111], v[110:111], v[114:115], v[78:79] op_sel_hi:[1,0,1]
	v_pk_fma_f32 v[102:103], v[102:103], v[114:115], v[70:71] op_sel_hi:[1,0,1]
	v_pk_fma_f32 v[118:119], v[100:101], v[114:115], v[68:69] op_sel_hi:[1,0,1]
	v_pk_fma_f32 v[100:101], v[98:99], v[114:115], v[66:67] op_sel_hi:[1,0,1]
	v_mul_f32_e32 v99, 0xbfb8aa3b, v110
	v_mul_f32_e32 v98, v110, v102
	v_exp_f32_e32 v99, v99
	v_mul_f32_e32 v102, 0xbfb8aa3b, v111
	v_exp_f32_e32 v102, v102
	v_pk_fma_f32 v[112:113], v[112:113], v[114:115], v[80:81] op_sel_hi:[1,0,1]
	v_add_f32_e32 v99, 1.0, v99
	v_rcp_f32_e32 v99, v99
	v_add_f32_e32 v102, 1.0, v102
	v_rcp_f32_e32 v102, v102
	v_pk_fma_f32 v[104:105], v[104:105], v[114:115], v[72:73] op_sel_hi:[1,0,1]
	v_mul_f32_e32 v98, v98, v99
	v_mul_f32_e32 v99, v111, v103
	v_mul_f32_e32 v99, v99, v102
	v_mul_f32_e32 v102, 0xbfb8aa3b, v112
	v_exp_f32_e32 v102, v102
	v_mul_f32_e32 v103, 0xbfb8aa3b, v113
	v_exp_f32_e32 v103, v103
	v_cvt_pk_bf16_f32 v98, v98, v99
	v_add_f32_e32 v102, 1.0, v102
	v_rcp_f32_e32 v102, v102
	v_add_f32_e32 v103, 1.0, v103
	v_rcp_f32_e32 v103, v103
	v_mul_f32_e32 v99, v112, v104
	v_mul_f32_e32 v99, v99, v102
	v_mul_f32_e32 v102, v113, v105
	v_pk_fma_f32 v[106:107], v[106:107], v[114:115], v[74:75] op_sel_hi:[1,0,1]
	v_mul_f32_e32 v102, v102, v103
	v_cvt_pk_bf16_f32 v99, v99, v102
	v_mul_f32_e32 v102, 0xbfb8aa3b, v106
	v_exp_f32_e32 v102, v102
	v_mul_f32_e32 v100, v106, v100
	v_pk_fma_f32 v[108:109], v[108:109], v[114:115], v[76:77] op_sel_hi:[1,0,1]
	v_mul_f32_e32 v101, v107, v101
	v_add_f32_e32 v102, 1.0, v102
	v_rcp_f32_e32 v102, v102
	v_mul_f32_e32 v103, 0xbfb8aa3b, v109
	v_exp_f32_e32 v103, v103
	v_lshl_add_u64 v[116:117], v[116:117], 0, v[164:165]
	v_mul_f32_e32 v100, v100, v102
	v_mul_f32_e32 v102, 0xbfb8aa3b, v107
	v_exp_f32_e32 v102, v102
	v_add_f32_e32 v103, 1.0, v103
	v_rcp_f32_e32 v103, v103
	v_add_f32_e32 v102, 1.0, v102
	v_rcp_f32_e32 v102, v102
	s_nop 0
	v_mul_f32_e32 v101, v101, v102
	v_mul_f32_e32 v102, 0xbfb8aa3b, v108
	v_exp_f32_e32 v102, v102
	v_cvt_pk_bf16_f32 v100, v100, v101
	v_mul_f32_e32 v101, v108, v118
	v_add_f32_e32 v102, 1.0, v102
	v_rcp_f32_e32 v102, v102
	s_nop 0
	v_mul_f32_e32 v101, v101, v102
	v_mul_f32_e32 v102, v109, v119
	v_mul_f32_e32 v102, v102, v103
	v_cvt_pk_bf16_f32 v101, v101, v102
	global_store_dwordx4 v[116:117], v[98:101], off
	ds_bpermute_b32 v98, v180, v183 offset:192
	s_nop 0
	v_or_b32_e32 v99, 48, v181
	v_mad_i64_i32 v[100:101], s[2:3], v99, s49, v[162:163]
	s_waitcnt lgkmcnt(0)
; __device__ __forceinline__ unsigned cvt_pk_bf16(float lo, float hi) { unsigned r; asm volatile("v_cvt_pk_bf16_f32 %0, %1, %2" : "=v"(r) : "v"(lo), "v"(hi)); return r; }
; __device__ __forceinline__ float silu_mul(float a, float b) { return a * b * __builtin_amdgcn_rcpf(1.0f + __builtin_amdgcn_exp2f(-a * LOG2E)); }
; __device__ __forceinline__ float row_rstd(const float* ss, int row) { return 1.0f / sqrtf(ss[row] * (1.0f / DM) + 1e-6f); }
;     __device__ __forceinline__ void operator()(const f32x4 (&acc)[2][2][4][2], const Unit& u, int wr, int wc, int fr, int fq) const {
;     ...
;             for (int m = 0; m < 4; ++m) { const int row = row0 + ai * HALF + m * 16; const float rs = __shfl(ai ? rsl1 : rsl0, m * 16 + fr); bf16_t* rowp = O + (size_t)row * DFF + col0;
;                 const f32x4 a0 = acc[ai][0][m][0] * rs + ba0, a1 = acc[ai][0][m][1] * rs + ba1, b0 = acc[ai][1][m][0] * rs + bb0, b1 = acc[ai][1][m][1] * rs + bb1;
;                 u32x4 w; w.x = cvt_pk_bf16(silu_mul(a0[0], b0[0]), silu_mul(a0[1], b0[1])); w.y = cvt_pk_bf16(silu_mul(a0[2], b0[2]), silu_mul(a0[3], b0[3]));
;                 w.z = cvt_pk_bf16(silu_mul(a1[0], b1[0]), silu_mul(a1[1], b1[1])); w.w = cvt_pk_bf16(silu_mul(a1[2], b1[2]), silu_mul(a1[3], b1[3]));
;                 *(u32x4*)rowp = w; }
	v_pk_fma_f32 v[94:95], v[94:95], v[98:99], v[78:79] op_sel_hi:[1,0,1]
	v_pk_fma_f32 v[86:87], v[86:87], v[98:99], v[70:71] op_sel_hi:[1,0,1]
	v_pk_fma_f32 v[102:103], v[84:85], v[98:99], v[68:69] op_sel_hi:[1,0,1]
	v_pk_fma_f32 v[84:85], v[82:83], v[98:99], v[66:67] op_sel_hi:[1,0,1]
	v_mul_f32_e32 v83, 0xbfb8aa3b, v94
	v_mul_f32_e32 v82, v94, v86
	v_exp_f32_e32 v83, v83
	v_mul_f32_e32 v86, 0xbfb8aa3b, v95
	v_exp_f32_e32 v86, v86
	v_pk_fma_f32 v[96:97], v[96:97], v[98:99], v[80:81] op_sel_hi:[1,0,1]
	v_add_f32_e32 v83, 1.0, v83
	v_rcp_f32_e32 v83, v83
	v_add_f32_e32 v86, 1.0, v86
	v_rcp_f32_e32 v86, v86
	v_pk_fma_f32 v[88:89], v[88:89], v[98:99], v[72:73] op_sel_hi:[1,0,1]
	v_mul_f32_e32 v82, v82, v83
	v_mul_f32_e32 v83, v95, v87
	v_mul_f32_e32 v83, v83, v86
	v_mul_f32_e32 v86, 0xbfb8aa3b, v96
	v_exp_f32_e32 v86, v86
	v_mul_f32_e32 v87, 0xbfb8aa3b, v97
	v_exp_f32_e32 v87, v87
	v_cvt_pk_bf16_f32 v82, v82, v83
	v_add_f32_e32 v86, 1.0, v86
	v_rcp_f32_e32 v86, v86
	v_add_f32_e32 v87, 1.0, v87
	v_rcp_f32_e32 v87, v87
	v_mul_f32_e32 v83, v96, v88
	v_mul_f32_e32 v83, v83, v86
	v_mul_f32_e32 v86, v97, v89
	v_pk_fma_f32 v[90:91], v[90:91], v[98:99], v[74:75] op_sel_hi:[1,0,1]
	v_mul_f32_e32 v86, v86, v87
	v_cvt_pk_bf16_f32 v83, v83, v86
	v_mul_f32_e32 v86, 0xbfb8aa3b, v90
	v_exp_f32_e32 v86, v86
	v_mul_f32_e32 v84, v90, v84
	v_pk_fma_f32 v[92:93], v[92:93], v[98:99], v[76:77] op_sel_hi:[1,0,1]
	v_mul_f32_e32 v85, v91, v85
	v_add_f32_e32 v86, 1.0, v86
	v_rcp_f32_e32 v86, v86
	v_mul_f32_e32 v87, 0xbfb8aa3b, v93
	v_exp_f32_e32 v87, v87
	v_lshl_add_u64 v[100:101], v[100:101], 0, v[164:165]
	v_mul_f32_e32 v84, v84, v86
	v_mul_f32_e32 v86, 0xbfb8aa3b, v91
	v_exp_f32_e32 v86, v86
	v_add_f32_e32 v87, 1.0, v87
	v_rcp_f32_e32 v87, v87
	v_add_f32_e32 v86, 1.0, v86
	v_rcp_f32_e32 v86, v86
	s_nop 0
	v_mul_f32_e32 v85, v85, v86
	v_mul_f32_e32 v86, 0xbfb8aa3b, v92
	v_exp_f32_e32 v86, v86
	v_cvt_pk_bf16_f32 v84, v84, v85
	v_mul_f32_e32 v85, v92, v102
	v_add_f32_e32 v86, 1.0, v86
	v_rcp_f32_e32 v86, v86
	s_nop 0
	v_mul_f32_e32 v85, v85, v86
	v_mul_f32_e32 v86, v93, v103
	v_mul_f32_e32 v86, v86, v87
	v_cvt_pk_bf16_f32 v85, v85, v86
	global_store_dwordx4 v[100:101], v[82:85], off
	s_nop 1
	v_div_scale_f32 v82, s[2:3], v182, v182, 1.0
	v_rcp_f32_e32 v84, v82
	v_add_u32_e32 v83, 0x80, v181
	v_fma_f32 v85, -v82, v84, 1.0
	v_fmac_f32_e32 v84, v85, v84
	v_div_scale_f32 v85, vcc, 1.0, v182, 1.0
	v_mul_f32_e32 v86, v85, v84
	v_fma_f32 v87, -v82, v86, v85
	v_fmac_f32_e32 v86, v87, v84
	v_fma_f32 v82, -v82, v86, v85
	v_div_fmas_f32 v82, v82, v84, v86
	v_div_fixup_f32 v82, v82, v182, 1.0
	ds_bpermute_b32 v84, v180, v82
	v_mad_i64_i32 v[86:87], s[2:3], v83, s49, v[162:163]
	v_lshl_add_u64 v[86:87], v[86:87], 0, v[164:165]
	s_andn2_b64 vcc, exec, s[38:39]
	s_waitcnt lgkmcnt(0)
	v_pk_fma_f32 v[62:63], v[62:63], v[84:85], v[78:79] op_sel_hi:[1,0,1]
	v_pk_fma_f32 v[54:55], v[54:55], v[84:85], v[70:71] op_sel_hi:[1,0,1]
	v_pk_fma_f32 v[88:89], v[52:53], v[84:85], v[68:69] op_sel_hi:[1,0,1]
	v_pk_fma_f32 v[52:53], v[50:51], v[84:85], v[66:67] op_sel_hi:[1,0,1]
	v_mul_f32_e32 v51, 0xbfb8aa3b, v62
	v_mul_f32_e32 v50, v62, v54
	v_exp_f32_e32 v51, v51
	v_mul_f32_e32 v54, 0xbfb8aa3b, v63
	v_exp_f32_e32 v54, v54
	v_pk_fma_f32 v[64:65], v[64:65], v[84:85], v[80:81] op_sel_hi:[1,0,1]
	v_add_f32_e32 v51, 1.0, v51
	v_rcp_f32_e32 v51, v51
	v_add_f32_e32 v54, 1.0, v54
	v_rcp_f32_e32 v54, v54
	v_pk_fma_f32 v[56:57], v[56:57], v[84:85], v[72:73] op_sel_hi:[1,0,1]
	v_mul_f32_e32 v50, v50, v51
	v_mul_f32_e32 v51, v63, v55
	v_mul_f32_e32 v51, v51, v54
	v_mul_f32_e32 v54, 0xbfb8aa3b, v64
	v_exp_f32_e32 v54, v54
	v_mul_f32_e32 v55, 0xbfb8aa3b, v65
	v_exp_f32_e32 v55, v55
	v_cvt_pk_bf16_f32 v50, v50, v51
	v_add_f32_e32 v54, 1.0, v54
	v_rcp_f32_e32 v54, v54
	v_add_f32_e32 v55, 1.0, v55
	v_rcp_f32_e32 v55, v55
	v_mul_f32_e32 v51, v64, v56
	v_mul_f32_e32 v51, v51, v54
	v_mul_f32_e32 v54, v65, v57
	v_pk_fma_f32 v[58:59], v[58:59], v[84:85], v[74:75] op_sel_hi:[1,0,1]
	v_mul_f32_e32 v54, v54, v55
	v_cvt_pk_bf16_f32 v51, v51, v54
	v_mul_f32_e32 v54, 0xbfb8aa3b, v58
	v_exp_f32_e32 v54, v54
	v_mul_f32_e32 v52, v58, v52
	v_pk_fma_f32 v[60:61], v[60:61], v[84:85], v[76:77] op_sel_hi:[1,0,1]
	v_mul_f32_e32 v53, v59, v53
	v_add_f32_e32 v54, 1.0, v54
	v_rcp_f32_e32 v54, v54
	v_mul_f32_e32 v55, 0xbfb8aa3b, v61
	v_exp_f32_e32 v55, v55
	v_mul_f32_e32 v52, v52, v54
	v_mul_f32_e32 v54, 0xbfb8aa3b, v59
	v_exp_f32_e32 v54, v54
	v_add_f32_e32 v55, 1.0, v55
	v_rcp_f32_e32 v55, v55
	v_add_f32_e32 v54, 1.0, v54
	v_rcp_f32_e32 v54, v54
	s_nop 0
	v_mul_f32_e32 v53, v53, v54
	v_mul_f32_e32 v54, 0xbfb8aa3b, v60
	v_exp_f32_e32 v54, v54
	v_cvt_pk_bf16_f32 v52, v52, v53
	v_mul_f32_e32 v53, v60, v88
	v_add_f32_e32 v54, 1.0, v54
	v_rcp_f32_e32 v54, v54
	s_nop 0
	v_mul_f32_e32 v53, v53, v54
	v_mul_f32_e32 v54, v61, v89
	v_mul_f32_e32 v54, v54, v55
	v_cvt_pk_bf16_f32 v53, v53, v54
	global_store_dwordx4 v[86:87], v[50:53], off
	ds_bpermute_b32 v50, v180, v82 offset:64
	s_nop 0
	v_add_u32_e32 v51, 0x90, v181
	v_mad_i64_i32 v[52:53], s[2:3], v51, s49, v[162:163]
	s_waitcnt lgkmcnt(0)
; __device__ __forceinline__ unsigned cvt_pk_bf16(float lo, float hi) { unsigned r; asm volatile("v_cvt_pk_bf16_f32 %0, %1, %2" : "=v"(r) : "v"(lo), "v"(hi)); return r; }
; __device__ __forceinline__ float silu_mul(float a, float b) { return a * b * __builtin_amdgcn_rcpf(1.0f + __builtin_amdgcn_exp2f(-a * LOG2E)); }
; #define PG8_BAR __builtin_amdgcn_s_barrier()
;     __device__ __forceinline__ void operator()(const f32x4 (&acc)[2][2][4][2], const Unit& u, int wr, int wc, int fr, int fq) const {
;     ...
;             for (int m = 0; m < 4; ++m) { const int row = row0 + ai * HALF + m * 16; const float rs = __shfl(ai ? rsl1 : rsl0, m * 16 + fr); bf16_t* rowp = O + (size_t)row * DFF + col0;
;                 const f32x4 a0 = acc[ai][0][m][0] * rs + ba0, a1 = acc[ai][0][m][1] * rs + ba1, b0 = acc[ai][1][m][0] * rs + bb0, b1 = acc[ai][1][m][1] * rs + bb1;
;                 u32x4 w; w.x = cvt_pk_bf16(silu_mul(a0[0], b0[0]), silu_mul(a0[1], b0[1])); w.y = cvt_pk_bf16(silu_mul(a0[2], b0[2]), silu_mul(a0[3], b0[3]));
;                 w.z = cvt_pk_bf16(silu_mul(a1[0], b1[0]), silu_mul(a1[1], b1[1])); w.w = cvt_pk_bf16(silu_mul(a1[2], b1[2]), silu_mul(a1[3], b1[3]));
;                 *(u32x4*)rowp = w; }
; template <class Epi, class Sched, bool ALIGN_EPI = false, bool SP2 = false>
; __device__ __forceinline__ void gemm_phase(LAS unsigned char* lds, const Gemm g, const Sched& S, const Epi& E) {
;     ...
;         if (!has_next) break;
; #pragma unroll
;         for (int a = 0; a < 2; ++a)
; #pragma unroll
;             for (int b = 0; b < 2; ++b)
; #pragma unroll
;                 for (int m = 0; m < 4; ++m)
; #pragma unroll
;                     for (int n = 0; n < 2; ++n) acc[a][b][m][n] = (f32x4){0.f, 0.f, 0.f, 0.f};
;         cur = nxt; cA = nA; cB = nB; ++ui;
;         if constexpr (ALIGN_EPI) { if (wr == 1) PG8_BAR; }
	v_pk_fma_f32 v[46:47], v[46:47], v[50:51], v[78:79] op_sel_hi:[1,0,1]
	v_pk_fma_f32 v[38:39], v[38:39], v[50:51], v[70:71] op_sel_hi:[1,0,1]
	v_pk_fma_f32 v[54:55], v[36:37], v[50:51], v[68:69] op_sel_hi:[1,0,1]
	v_pk_fma_f32 v[36:37], v[34:35], v[50:51], v[66:67] op_sel_hi:[1,0,1]
	v_mul_f32_e32 v35, 0xbfb8aa3b, v46
	v_mul_f32_e32 v34, v46, v38
	v_exp_f32_e32 v35, v35
	v_mul_f32_e32 v38, 0xbfb8aa3b, v47
	v_exp_f32_e32 v38, v38
	v_pk_fma_f32 v[48:49], v[48:49], v[50:51], v[80:81] op_sel_hi:[1,0,1]
	v_add_f32_e32 v35, 1.0, v35
	v_rcp_f32_e32 v35, v35
	v_add_f32_e32 v38, 1.0, v38
	v_rcp_f32_e32 v38, v38
	v_pk_fma_f32 v[40:41], v[40:41], v[50:51], v[72:73] op_sel_hi:[1,0,1]
	v_mul_f32_e32 v34, v34, v35
	v_mul_f32_e32 v35, v47, v39
	v_mul_f32_e32 v35, v35, v38
	v_mul_f32_e32 v38, 0xbfb8aa3b, v48
	v_exp_f32_e32 v38, v38
	v_mul_f32_e32 v39, 0xbfb8aa3b, v49
	v_exp_f32_e32 v39, v39
	v_cvt_pk_bf16_f32 v34, v34, v35
	v_add_f32_e32 v38, 1.0, v38
	v_rcp_f32_e32 v38, v38
	v_add_f32_e32 v39, 1.0, v39
	v_rcp_f32_e32 v39, v39
	v_mul_f32_e32 v35, v48, v40
	v_mul_f32_e32 v35, v35, v38
	v_mul_f32_e32 v38, v49, v41
	v_pk_fma_f32 v[42:43], v[42:43], v[50:51], v[74:75] op_sel_hi:[1,0,1]
	v_mul_f32_e32 v38, v38, v39
	v_cvt_pk_bf16_f32 v35, v35, v38
	v_mul_f32_e32 v38, 0xbfb8aa3b, v42
	v_exp_f32_e32 v38, v38
	v_mul_f32_e32 v36, v42, v36
	v_pk_fma_f32 v[44:45], v[44:45], v[50:51], v[76:77] op_sel_hi:[1,0,1]
	v_mul_f32_e32 v37, v43, v37
	v_add_f32_e32 v38, 1.0, v38
	v_rcp_f32_e32 v38, v38
	v_mul_f32_e32 v39, 0xbfb8aa3b, v45
	v_exp_f32_e32 v39, v39
	v_lshl_add_u64 v[52:53], v[52:53], 0, v[164:165]
	v_mul_f32_e32 v36, v36, v38
	v_mul_f32_e32 v38, 0xbfb8aa3b, v43
	v_exp_f32_e32 v38, v38
	v_add_f32_e32 v39, 1.0, v39
	v_rcp_f32_e32 v39, v39
	v_add_f32_e32 v38, 1.0, v38
	v_rcp_f32_e32 v38, v38
	s_nop 0
	v_mul_f32_e32 v37, v37, v38
	v_mul_f32_e32 v38, 0xbfb8aa3b, v44
	v_exp_f32_e32 v38, v38
	v_cvt_pk_bf16_f32 v36, v36, v37
	v_mul_f32_e32 v37, v44, v54
	v_add_f32_e32 v38, 1.0, v38
	v_rcp_f32_e32 v38, v38
	s_nop 0
	v_mul_f32_e32 v37, v37, v38
	v_mul_f32_e32 v38, v45, v55
	v_mul_f32_e32 v38, v38, v39
	v_cvt_pk_bf16_f32 v37, v37, v38
	global_store_dwordx4 v[52:53], v[34:37], off
	ds_bpermute_b32 v34, v180, v82 offset:128
	s_nop 0
	v_add_u32_e32 v35, 0xa0, v181
	v_mad_i64_i32 v[36:37], s[2:3], v35, s49, v[162:163]
	s_waitcnt lgkmcnt(0)
	v_pk_fma_f32 v[30:31], v[30:31], v[34:35], v[78:79] op_sel_hi:[1,0,1]
	v_pk_fma_f32 v[22:23], v[22:23], v[34:35], v[70:71] op_sel_hi:[1,0,1]
	v_pk_fma_f32 v[38:39], v[20:21], v[34:35], v[68:69] op_sel_hi:[1,0,1]
	v_pk_fma_f32 v[20:21], v[18:19], v[34:35], v[66:67] op_sel_hi:[1,0,1]
	v_mul_f32_e32 v19, 0xbfb8aa3b, v30
	v_mul_f32_e32 v18, v30, v22
	v_exp_f32_e32 v19, v19
	v_mul_f32_e32 v22, 0xbfb8aa3b, v31
	v_exp_f32_e32 v22, v22
	v_pk_fma_f32 v[32:33], v[32:33], v[34:35], v[80:81] op_sel_hi:[1,0,1]
	v_add_f32_e32 v19, 1.0, v19
	v_rcp_f32_e32 v19, v19
	v_add_f32_e32 v22, 1.0, v22
	v_rcp_f32_e32 v22, v22
	v_pk_fma_f32 v[24:25], v[24:25], v[34:35], v[72:73] op_sel_hi:[1,0,1]
	v_mul_f32_e32 v18, v18, v19
	v_mul_f32_e32 v19, v31, v23
	v_mul_f32_e32 v19, v19, v22
	v_mul_f32_e32 v22, 0xbfb8aa3b, v32
	v_exp_f32_e32 v22, v22
	v_mul_f32_e32 v23, 0xbfb8aa3b, v33
	v_exp_f32_e32 v23, v23
	v_cvt_pk_bf16_f32 v18, v18, v19
	v_add_f32_e32 v22, 1.0, v22
	v_rcp_f32_e32 v22, v22
	v_add_f32_e32 v23, 1.0, v23
	v_rcp_f32_e32 v23, v23
	v_mul_f32_e32 v19, v32, v24
	v_mul_f32_e32 v19, v19, v22
	v_mul_f32_e32 v22, v33, v25
	v_pk_fma_f32 v[26:27], v[26:27], v[34:35], v[74:75] op_sel_hi:[1,0,1]
	v_mul_f32_e32 v22, v22, v23
	v_cvt_pk_bf16_f32 v19, v19, v22
	v_mul_f32_e32 v22, 0xbfb8aa3b, v26
	v_exp_f32_e32 v22, v22
	v_mul_f32_e32 v20, v26, v20
	v_pk_fma_f32 v[28:29], v[28:29], v[34:35], v[76:77] op_sel_hi:[1,0,1]
	v_mul_f32_e32 v21, v27, v21
	v_add_f32_e32 v22, 1.0, v22
	v_rcp_f32_e32 v22, v22
	v_mul_f32_e32 v23, 0xbfb8aa3b, v29
	v_exp_f32_e32 v23, v23
	v_lshl_add_u64 v[36:37], v[36:37], 0, v[164:165]
	v_mul_f32_e32 v20, v20, v22
	v_mul_f32_e32 v22, 0xbfb8aa3b, v27
	v_exp_f32_e32 v22, v22
	v_add_f32_e32 v23, 1.0, v23
	v_rcp_f32_e32 v23, v23
	v_add_f32_e32 v22, 1.0, v22
	v_rcp_f32_e32 v22, v22
	s_nop 0
	v_mul_f32_e32 v21, v21, v22
	v_mul_f32_e32 v22, 0xbfb8aa3b, v28
	v_exp_f32_e32 v22, v22
	v_cvt_pk_bf16_f32 v20, v20, v21
	v_mul_f32_e32 v21, v28, v38
	v_add_f32_e32 v22, 1.0, v22
	v_rcp_f32_e32 v22, v22
	s_nop 0
	v_mul_f32_e32 v21, v21, v22
	v_mul_f32_e32 v22, v29, v39
	v_mul_f32_e32 v22, v22, v23
	v_cvt_pk_bf16_f32 v21, v21, v22
	global_store_dwordx4 v[36:37], v[18:21], off
	ds_bpermute_b32 v18, v180, v82 offset:192
	s_nop 0
	v_add_u32_e32 v19, 0xb0, v181
	v_mad_i64_i32 v[20:21], s[2:3], v19, s49, v[162:163]
	s_waitcnt lgkmcnt(0)
	v_pk_fma_f32 v[14:15], v[14:15], v[18:19], v[78:79] op_sel_hi:[1,0,1]
	v_pk_fma_f32 v[6:7], v[6:7], v[18:19], v[70:71] op_sel_hi:[1,0,1]
	v_pk_fma_f32 v[22:23], v[4:5], v[18:19], v[68:69] op_sel_hi:[1,0,1]
	v_pk_fma_f32 v[4:5], v[2:3], v[18:19], v[66:67] op_sel_hi:[1,0,1]
	v_mul_f32_e32 v3, 0xbfb8aa3b, v14
	v_mul_f32_e32 v2, v14, v6
	v_exp_f32_e32 v3, v3
	v_mul_f32_e32 v6, 0xbfb8aa3b, v15
	v_exp_f32_e32 v6, v6
	v_pk_fma_f32 v[16:17], v[16:17], v[18:19], v[80:81] op_sel_hi:[1,0,1]
	v_add_f32_e32 v3, 1.0, v3
	v_rcp_f32_e32 v3, v3
	v_add_f32_e32 v6, 1.0, v6
	v_rcp_f32_e32 v6, v6
	v_pk_fma_f32 v[8:9], v[8:9], v[18:19], v[72:73] op_sel_hi:[1,0,1]
	v_mul_f32_e32 v2, v2, v3
	v_mul_f32_e32 v3, v15, v7
	v_mul_f32_e32 v3, v3, v6
	v_mul_f32_e32 v6, 0xbfb8aa3b, v16
	v_exp_f32_e32 v6, v6
	v_mul_f32_e32 v7, 0xbfb8aa3b, v17
	v_exp_f32_e32 v7, v7
	v_cvt_pk_bf16_f32 v2, v2, v3
	v_add_f32_e32 v6, 1.0, v6
	v_rcp_f32_e32 v6, v6
	v_add_f32_e32 v7, 1.0, v7
	v_rcp_f32_e32 v7, v7
	v_mul_f32_e32 v3, v16, v8
	v_mul_f32_e32 v3, v3, v6
	v_mul_f32_e32 v6, v17, v9
	v_pk_fma_f32 v[10:11], v[10:11], v[18:19], v[74:75] op_sel_hi:[1,0,1]
	v_mul_f32_e32 v6, v6, v7
	v_cvt_pk_bf16_f32 v3, v3, v6
	v_mul_f32_e32 v6, 0xbfb8aa3b, v10
	v_exp_f32_e32 v6, v6
	v_mul_f32_e32 v4, v10, v4
	v_pk_fma_f32 v[12:13], v[12:13], v[18:19], v[76:77] op_sel_hi:[1,0,1]
	v_mul_f32_e32 v5, v11, v5
	v_add_f32_e32 v6, 1.0, v6
	v_rcp_f32_e32 v6, v6
	v_mul_f32_e32 v7, 0xbfb8aa3b, v13
	v_exp_f32_e32 v7, v7
	v_lshl_add_u64 v[20:21], v[20:21], 0, v[164:165]
	v_mul_f32_e32 v4, v4, v6
	v_mul_f32_e32 v6, 0xbfb8aa3b, v11
	v_exp_f32_e32 v6, v6
	v_add_f32_e32 v7, 1.0, v7
	v_rcp_f32_e32 v7, v7
	s_mov_b64 s[2:3], -1
	v_add_f32_e32 v6, 1.0, v6
	v_rcp_f32_e32 v6, v6
	s_nop 0
	v_mul_f32_e32 v5, v5, v6
	v_mul_f32_e32 v6, 0xbfb8aa3b, v12
	v_exp_f32_e32 v6, v6
	v_cvt_pk_bf16_f32 v4, v4, v5
	v_mul_f32_e32 v5, v12, v22
	v_add_f32_e32 v6, 1.0, v6
	v_rcp_f32_e32 v6, v6
	s_nop 0
	v_mul_f32_e32 v5, v5, v6
	v_mul_f32_e32 v6, v13, v23
	v_mul_f32_e32 v6, v6, v7
	v_cvt_pk_bf16_f32 v5, v5, v6
	global_store_dwordx4 v[20:21], v[2:5], off
	s_cbranch_vccnz .LBB0_1461
	s_andn2_b64 vcc, exec, s[4:5]
	s_cbranch_vccnz .LBB0_1460
	s_barrier
	s_branch .LBB0_1460

;     __device__ bool next(int i, Unit& u) const { if (i != 0 || c >= 128) return false; const int t = c >> 2; u.pm = t & 3; u.pn = t >> 2; u.koff = koff_bytes; u.q = c & 3; return true; }
; #define PG8_STAGE(bufoff, gbase, voff) do { _Pragma("unroll") for (int _i = 0; _i < 2; ++_i) \
;         __builtin_amdgcn_global_load_lds((const unsigned*)((const char*)(gbase) + (voff)[_i]), (LAS unsigned*)(lds + (bufoff) + ldsw + _i * 8192), 16, 0, 0); } while (0)
; #define PG8_LDA(dst, b, h) do { _Pragma("unroll") for (int m = 0; m < 4; ++m) _Pragma("unroll") for (int k = 0; k < 2; ++k) dst[m][k] = *(const LAS bf16x8*)(lds + PG8_SA(b, h) + aoff + m * 2048 + k * 1024); } while (0)
; #define PG8_LDB(dst, b, h) do { _Pragma("unroll") for (int n = 0; n < 2; ++n) _Pragma("unroll") for (int k = 0; k < 2; ++k) dst[n][k] = *(const LAS bf16x8*)(lds + PG8_SB(b, h) + boff + n * 2048 + k * 1024); } while (0)
; template <class Epi, class Sched, bool ALIGN_EPI = false, bool SP2 = false>
; __device__ __forceinline__ void gemm_phase(LAS unsigned char* lds, const Gemm g, const Sched& S, const Epi& E) {
;     ...
;     Unit cur, nxt; int ui = 0;
;     if (!S.next(0, cur)) return;
;     f32x4 acc[2][2][4][2];
; #pragma unroll
;     for (int a = 0; a < 2; ++a)
; #pragma unroll
;         for (int b = 0; b < 2; ++b)
; #pragma unroll
;             for (int m = 0; m < 4; ++m)
; #pragma unroll
;                 for (int n = 0; n < 2; ++n) acc[a][b][m][n] = (f32x4){0.f, 0.f, 0.f, 0.f};
;     ...
;         const bool has_next = S.next(ui + 1, nxt);
;         const char* nA = has_next ? (const char*)g.A + (size_t)nxt.pm * tstep + nxt.koff : cA; const char* nB = has_next ? (const char*)g.Bt + (size_t)nxt.pn * tstep + nxt.koff : cB;
;         for (int t = 0; t < nt; t += 2) {
;             const bool last = (t == nt - 2);
;             const char* a1 = cA + (size_t)(t + 1) * kstep;
;             const char* a2 = last ? nA : cA + (size_t)(t + 2) * kstep; const char* b2 = last ? nB : cB + (size_t)(t + 2) * kstep;
;             const char* a3 = a2 + kstep; const char* b3 = b2 + kstep;
;             if (last && has_next) S.a_ready(nxt);
;             if constexpr (SP2) {
;             PG8_LDB(B0, 0, 0); PG8_LDB(B1, 0, 1); PG8_SCHED; PG8_LDA(At, 0, 0); PG8_STAGE(PG8_SA(1, 1), a1 + hstep, voffA);
;             PG8_WAIT_V(8); PG8_WAIT_L(0); PG8_BAR; PG8_MMA(0, 0, At, B0); PG8_MMA(0, 1, At, B1); PG8_BAR; PG8_SCHED;
.LBB0_1594:
	s_add_u32 s9, s20, 0x100
	s_addc_u32 s24, s21, 0
	s_mov_b32 s25, -2
	s_waitcnt vmcnt(0)
	ds_read_b128 v[130:133], v196
	ds_read_b128 v[134:137], v196 offset:1024
	ds_read_b128 v[138:141], v196 offset:2048
	ds_read_b128 v[142:145], v196 offset:3072
	ds_read_b128 v[166:169], v197
	ds_read_b128 v[170:173], v197 offset:1024
	ds_read_b128 v[174:177], v197 offset:2048
	ds_read_b128 v[178:181], v197 offset:3072
	s_add_u32 s20, s16, 0x100
	s_addc_u32 s21, s17, 0
	s_cmpk_eq_i32 s25, 0x54
	s_cselect_b32 s47, s3, s21
	s_cselect_b32 s46, s2, s20
	s_cselect_b32 s23, s19, s24
	s_cselect_b32 s22, s18, s9
	v_lshl_add_u64 v[190:191], s[16:17], 0, v[158:159]
	s_add_i32 m0, s31, 0xc000
	ds_read_b128 v[182:185], v198
	ds_read_b128 v[186:189], v198 offset:1024
	ds_read_b128 v[202:205], v198 offset:2048
	ds_read_b128 v[206:209], v198 offset:3072
	ds_read_b128 v[210:213], v198 offset:4096
	ds_read_b128 v[214:217], v198 offset:5120
	ds_read_b128 v[218:221], v198 offset:6144
	ds_read_b128 v[222:225], v198 offset:7168
	global_load_lds_dwordx4 v[190:191], off
	v_lshl_add_u64 v[190:191], s[16:17], 0, v[160:161]
	s_add_i32 m0, s31, 0xe000
	s_nop 0
	global_load_lds_dwordx4 v[190:191], off
	s_waitcnt lgkmcnt(0)
	s_barrier
	s_setprio 1
	s_waitcnt lgkmcnt(0)
	v_mfma_f32_16x16x32_bf16 v[126:129], v[130:133], v[182:185], 0
	v_mfma_f32_16x16x32_bf16 v[122:125], v[138:141], v[182:185], 0
	v_mfma_f32_16x16x32_bf16 v[110:113], v[130:133], v[202:205], 0
	v_mfma_f32_16x16x32_bf16 v[106:109], v[138:141], v[202:205], 0
	v_mfma_f32_16x16x32_bf16 v[94:97], v[130:133], v[210:213], 0
	v_mfma_f32_16x16x32_bf16 v[90:93], v[138:141], v[210:213], 0
	v_mfma_f32_16x16x32_bf16 v[78:81], v[130:133], v[218:221], 0
	v_mfma_f32_16x16x32_bf16 v[74:77], v[138:141], v[218:221], 0
	v_mfma_f32_16x16x32_bf16 v[126:129], v[134:137], v[186:189], v[126:129]
	v_mfma_f32_16x16x32_bf16 v[122:125], v[142:145], v[186:189], v[122:125]
	v_mfma_f32_16x16x32_bf16 v[110:113], v[134:137], v[206:209], v[110:113]
	v_mfma_f32_16x16x32_bf16 v[106:109], v[142:145], v[206:209], v[106:109]
	v_mfma_f32_16x16x32_bf16 v[94:97], v[134:137], v[214:217], v[94:97]
	v_mfma_f32_16x16x32_bf16 v[90:93], v[142:145], v[214:217], v[90:93]
	v_mfma_f32_16x16x32_bf16 v[78:81], v[134:137], v[222:225], v[78:81]
	v_mfma_f32_16x16x32_bf16 v[74:77], v[142:145], v[222:225], v[74:77]
	s_setprio 0
	s_setprio 1
	v_mfma_f32_16x16x32_bf16 v[118:121], v[166:169], v[182:185], 0
	v_mfma_f32_16x16x32_bf16 v[114:117], v[174:177], v[182:185], 0
	v_mfma_f32_16x16x32_bf16 v[102:105], v[166:169], v[202:205], 0
	v_mfma_f32_16x16x32_bf16 v[98:101], v[174:177], v[202:205], 0
	v_mfma_f32_16x16x32_bf16 v[86:89], v[166:169], v[210:213], 0
	v_mfma_f32_16x16x32_bf16 v[82:85], v[174:177], v[210:213], 0
	v_mfma_f32_16x16x32_bf16 v[70:73], v[166:169], v[218:221], 0
	v_mfma_f32_16x16x32_bf16 v[66:69], v[174:177], v[218:221], 0
	v_mfma_f32_16x16x32_bf16 v[118:121], v[170:173], v[186:189], v[118:121]
	v_mfma_f32_16x16x32_bf16 v[114:117], v[178:181], v[186:189], v[114:117]
	v_mfma_f32_16x16x32_bf16 v[102:105], v[170:173], v[206:209], v[102:105]
	v_mfma_f32_16x16x32_bf16 v[98:101], v[178:181], v[206:209], v[98:101]
	v_mfma_f32_16x16x32_bf16 v[86:89], v[170:173], v[214:217], v[86:89]
	v_mfma_f32_16x16x32_bf16 v[82:85], v[178:181], v[214:217], v[82:85]
	v_mfma_f32_16x16x32_bf16 v[70:73], v[170:173], v[222:225], v[70:73]
	v_mfma_f32_16x16x32_bf16 v[66:69], v[178:181], v[222:225], v[66:69]
	s_setprio 0
	s_barrier
	s_add_i32 s16, s52, s30
	v_lshl_add_u64 v[190:191], s[22:23], 0, v[148:149]
	s_mov_b32 m0, s16
	ds_read_b128 v[182:185], v198 offset:16384
	ds_read_b128 v[186:189], v198 offset:17408
	ds_read_b128 v[202:205], v198 offset:18432
	ds_read_b128 v[206:209], v198 offset:19456
	ds_read_b128 v[210:213], v198 offset:20480
	ds_read_b128 v[214:217], v198 offset:21504
	ds_read_b128 v[218:221], v198 offset:22528
	ds_read_b128 v[222:225], v198 offset:23552
	global_load_lds_dwordx4 v[190:191], off
	s_add_i32 m0, s16, 0x2000
	s_add_u32 s16, s22, 0x58000
	v_lshl_add_u64 v[226:227], s[22:23], 0, v[152:153]
	s_addc_u32 s17, s23, 0
	s_add_i32 s56, s53, s30
	global_load_lds_dwordx4 v[226:227], off
	v_lshl_add_u64 v[228:229], s[16:17], 0, v[148:149]
	s_mov_b32 m0, s56
	v_lshl_add_u64 v[230:231], s[46:47], 0, v[150:151]
	global_load_lds_dwordx4 v[228:229], off
	v_lshl_add_u64 v[228:229], s[16:17], 0, v[152:153]
	s_add_i32 m0, s56, 0x2000
	s_nop 0
	global_load_lds_dwordx4 v[228:229], off
	v_lshl_add_u64 v[228:229], s[46:47], 0, v[146:147]
	s_mov_b32 m0, s31
	s_nop 0
	global_load_lds_dwordx4 v[228:229], off
	s_mov_b32 m0, s33
	s_nop 0
	global_load_lds_dwordx4 v[230:231], off
	s_waitcnt vmcnt(8)
	s_waitcnt lgkmcnt(0)
	s_barrier
; #define PG8_STAGE(bufoff, gbase, voff) do { _Pragma("unroll") for (int _i = 0; _i < 2; ++_i) \
;         __builtin_amdgcn_global_load_lds((const unsigned*)((const char*)(gbase) + (voff)[_i]), (LAS unsigned*)(lds + (bufoff) + ldsw + _i * 8192), 16, 0, 0); } while (0)
; #define PG8_LDA(dst, b, h) do { _Pragma("unroll") for (int m = 0; m < 4; ++m) _Pragma("unroll") for (int k = 0; k < 2; ++k) dst[m][k] = *(const LAS bf16x8*)(lds + PG8_SA(b, h) + aoff + m * 2048 + k * 1024); } while (0)
; #define PG8_LDB(dst, b, h) do { _Pragma("unroll") for (int n = 0; n < 2; ++n) _Pragma("unroll") for (int k = 0; k < 2; ++k) dst[n][k] = *(const LAS bf16x8*)(lds + PG8_SB(b, h) + boff + n * 2048 + k * 1024); } while (0)
; #define PG8_MMA(ai, bj, At, Bt) do { __builtin_amdgcn_s_setprio(1); _Pragma("unroll") for (int m = 0; m < 4; ++m) _Pragma("unroll") for (int n = 0; n < 2; ++n) _Pragma("unroll") for (int k = 0; k < 2; ++k) \
;         acc[ai][bj][m][n] = __builtin_amdgcn_mfma_f32_16x16x32_bf16(Bt[n][k], At[m][k], acc[ai][bj][m][n], 0, 0, 0); __builtin_amdgcn_s_setprio(0); } while (0)
; #define PG8_WAIT_V(n) asm volatile("s_waitcnt vmcnt(" #n ")" ::: "memory")
; #define PG8_WAIT_L(n) asm volatile("s_waitcnt lgkmcnt(" #n ")" ::: "memory")
; #define PG8_BAR __builtin_amdgcn_s_barrier()
; #define PG8_SCHED __builtin_amdgcn_sched_barrier(0)
; template <class Epi, class Sched, bool ALIGN_EPI = false, bool SP2 = false>
; __device__ __forceinline__ void gemm_phase(LAS unsigned char* lds, const Gemm g, const Sched& S, const Epi& E) {
;     ...
;             PG8_WAIT_V(8); PG8_WAIT_L(0); PG8_BAR; PG8_MMA(1, 0, At, B0); PG8_MMA(1, 1, At, B1); PG8_BAR; PG8_SCHED;
;             PG8_LDB(B0, 1, 0); PG8_LDB(B1, 1, 1); PG8_SCHED; PG8_LDA(At, 1, 0); PG8_STAGE(PG8_SA(0, 1), a2 + hstep, voffA);
;             PG8_WAIT_V(8); PG8_WAIT_L(0); PG8_BAR; PG8_MMA(0, 0, At, B0); PG8_MMA(0, 1, At, B1); PG8_BAR; PG8_SCHED;
	s_setprio 1
	s_waitcnt lgkmcnt(0)
	v_mfma_f32_16x16x32_bf16 v[62:65], v[130:133], v[182:185], 0
	v_mfma_f32_16x16x32_bf16 v[58:61], v[138:141], v[182:185], 0
	v_mfma_f32_16x16x32_bf16 v[46:49], v[130:133], v[202:205], 0
	v_mfma_f32_16x16x32_bf16 v[42:45], v[138:141], v[202:205], 0
	v_mfma_f32_16x16x32_bf16 v[30:33], v[130:133], v[210:213], 0
	v_mfma_f32_16x16x32_bf16 v[26:29], v[138:141], v[210:213], 0
	v_mfma_f32_16x16x32_bf16 v[14:17], v[130:133], v[218:221], 0
	v_mfma_f32_16x16x32_bf16 v[10:13], v[138:141], v[218:221], 0
	v_mfma_f32_16x16x32_bf16 v[62:65], v[134:137], v[186:189], v[62:65]
	v_mfma_f32_16x16x32_bf16 v[58:61], v[142:145], v[186:189], v[58:61]
	v_mfma_f32_16x16x32_bf16 v[46:49], v[134:137], v[206:209], v[46:49]
	v_mfma_f32_16x16x32_bf16 v[42:45], v[142:145], v[206:209], v[42:45]
	v_mfma_f32_16x16x32_bf16 v[30:33], v[134:137], v[214:217], v[30:33]
	v_mfma_f32_16x16x32_bf16 v[26:29], v[142:145], v[214:217], v[26:29]
	v_mfma_f32_16x16x32_bf16 v[14:17], v[134:137], v[222:225], v[14:17]
	v_mfma_f32_16x16x32_bf16 v[10:13], v[142:145], v[222:225], v[10:13]
	s_setprio 0
	s_setprio 1
	v_mfma_f32_16x16x32_bf16 v[54:57], v[166:169], v[182:185], 0
	v_mfma_f32_16x16x32_bf16 v[50:53], v[174:177], v[182:185], 0
	v_mfma_f32_16x16x32_bf16 v[38:41], v[166:169], v[202:205], 0
	v_mfma_f32_16x16x32_bf16 v[34:37], v[174:177], v[202:205], 0
	v_mfma_f32_16x16x32_bf16 v[22:25], v[166:169], v[210:213], 0
	v_mfma_f32_16x16x32_bf16 v[18:21], v[174:177], v[210:213], 0
	v_mfma_f32_16x16x32_bf16 v[6:9], v[166:169], v[218:221], 0
	v_mfma_f32_16x16x32_bf16 v[2:5], v[174:177], v[218:221], 0
	v_mfma_f32_16x16x32_bf16 v[54:57], v[170:173], v[186:189], v[54:57]
	v_mfma_f32_16x16x32_bf16 v[50:53], v[178:181], v[186:189], v[50:53]
	v_mfma_f32_16x16x32_bf16 v[38:41], v[170:173], v[206:209], v[38:41]
	v_mfma_f32_16x16x32_bf16 v[34:37], v[178:181], v[206:209], v[34:37]
	v_mfma_f32_16x16x32_bf16 v[22:25], v[170:173], v[214:217], v[22:25]
	v_mfma_f32_16x16x32_bf16 v[18:21], v[178:181], v[214:217], v[18:21]
	v_mfma_f32_16x16x32_bf16 v[6:9], v[170:173], v[222:225], v[6:9]
	v_mfma_f32_16x16x32_bf16 v[2:5], v[178:181], v[222:225], v[2:5]
	s_setprio 0
	s_barrier
	s_add_i32 s56, 0, 0x18000
	s_add_i32 s57, 0, 0x1c000
	v_add_u32_e32 v142, s56, v1
	v_add_u32_e32 v154, s57, v1
	ds_read_b128 v[130:133], v142
	ds_read_b128 v[134:137], v142 offset:1024
	ds_read_b128 v[138:141], v142 offset:2048
	ds_read_b128 v[142:145], v142 offset:3072
	ds_read_b128 v[166:169], v154
	ds_read_b128 v[170:173], v154 offset:1024
	ds_read_b128 v[174:177], v154 offset:2048
	ds_read_b128 v[178:181], v154 offset:3072
	s_add_u32 s16, s46, 0x160000
	s_addc_u32 s17, s47, 0
	s_mov_b32 m0, s34
	v_lshl_add_u64 v[232:233], s[16:17], 0, v[146:147]
	ds_read_b128 v[182:185], v198 offset:32768
	ds_read_b128 v[186:189], v198 offset:33792
	ds_read_b128 v[202:205], v198 offset:34816
	ds_read_b128 v[206:209], v198 offset:35840
	ds_read_b128 v[210:213], v198 offset:36864
	ds_read_b128 v[214:217], v198 offset:37888
	ds_read_b128 v[218:221], v198 offset:38912
	ds_read_b128 v[222:225], v198 offset:39936
	global_load_lds_dwordx4 v[232:233], off
	v_lshl_add_u64 v[232:233], s[16:17], 0, v[150:151]
	s_mov_b32 m0, s35
	s_nop 0
	global_load_lds_dwordx4 v[232:233], off
	s_waitcnt vmcnt(8)
	s_waitcnt lgkmcnt(0)
	s_barrier
	s_setprio 1
	s_waitcnt lgkmcnt(0)
	v_mfma_f32_16x16x32_bf16 v[126:129], v[130:133], v[182:185], v[126:129]
	v_mfma_f32_16x16x32_bf16 v[122:125], v[138:141], v[182:185], v[122:125]
	v_mfma_f32_16x16x32_bf16 v[110:113], v[130:133], v[202:205], v[110:113]
	v_mfma_f32_16x16x32_bf16 v[106:109], v[138:141], v[202:205], v[106:109]
	v_mfma_f32_16x16x32_bf16 v[94:97], v[130:133], v[210:213], v[94:97]
	v_mfma_f32_16x16x32_bf16 v[90:93], v[138:141], v[210:213], v[90:93]
	v_mfma_f32_16x16x32_bf16 v[78:81], v[130:133], v[218:221], v[78:81]
	v_mfma_f32_16x16x32_bf16 v[74:77], v[138:141], v[218:221], v[74:77]
	v_mfma_f32_16x16x32_bf16 v[126:129], v[134:137], v[186:189], v[126:129]
	v_mfma_f32_16x16x32_bf16 v[122:125], v[142:145], v[186:189], v[122:125]
	v_mfma_f32_16x16x32_bf16 v[110:113], v[134:137], v[206:209], v[110:113]
	v_mfma_f32_16x16x32_bf16 v[106:109], v[142:145], v[206:209], v[106:109]
	v_mfma_f32_16x16x32_bf16 v[94:97], v[134:137], v[214:217], v[94:97]
	v_mfma_f32_16x16x32_bf16 v[90:93], v[142:145], v[214:217], v[90:93]
	v_mfma_f32_16x16x32_bf16 v[78:81], v[134:137], v[222:225], v[78:81]
	v_mfma_f32_16x16x32_bf16 v[74:77], v[142:145], v[222:225], v[74:77]
	s_setprio 0
	s_setprio 1
	v_mfma_f32_16x16x32_bf16 v[118:121], v[166:169], v[182:185], v[118:121]
	v_mfma_f32_16x16x32_bf16 v[114:117], v[174:177], v[182:185], v[114:117]
	v_mfma_f32_16x16x32_bf16 v[102:105], v[166:169], v[202:205], v[102:105]
	v_mfma_f32_16x16x32_bf16 v[98:101], v[174:177], v[202:205], v[98:101]
	v_mfma_f32_16x16x32_bf16 v[86:89], v[166:169], v[210:213], v[86:89]
	v_mfma_f32_16x16x32_bf16 v[82:85], v[174:177], v[210:213], v[82:85]
	v_mfma_f32_16x16x32_bf16 v[70:73], v[166:169], v[218:221], v[70:73]
	v_mfma_f32_16x16x32_bf16 v[66:69], v[174:177], v[218:221], v[66:69]
	v_mfma_f32_16x16x32_bf16 v[118:121], v[170:173], v[186:189], v[118:121]
	v_mfma_f32_16x16x32_bf16 v[114:117], v[178:181], v[186:189], v[114:117]
	v_mfma_f32_16x16x32_bf16 v[102:105], v[170:173], v[206:209], v[102:105]
	v_mfma_f32_16x16x32_bf16 v[98:101], v[178:181], v[206:209], v[98:101]
	v_mfma_f32_16x16x32_bf16 v[86:89], v[170:173], v[214:217], v[86:89]
	v_mfma_f32_16x16x32_bf16 v[82:85], v[178:181], v[214:217], v[82:85]
	v_mfma_f32_16x16x32_bf16 v[70:73], v[170:173], v[222:225], v[70:73]
	v_mfma_f32_16x16x32_bf16 v[66:69], v[178:181], v[222:225], v[66:69]
	s_setprio 0
	s_barrier
; #define PG8_STAGE(bufoff, gbase, voff) do { _Pragma("unroll") for (int _i = 0; _i < 2; ++_i) \
;         __builtin_amdgcn_global_load_lds((const unsigned*)((const char*)(gbase) + (voff)[_i]), (LAS unsigned*)(lds + (bufoff) + ldsw + _i * 8192), 16, 0, 0); } while (0)
; #define PG8_LDA(dst, b, h) do { _Pragma("unroll") for (int m = 0; m < 4; ++m) _Pragma("unroll") for (int k = 0; k < 2; ++k) dst[m][k] = *(const LAS bf16x8*)(lds + PG8_SA(b, h) + aoff + m * 2048 + k * 1024); } while (0)
; #define PG8_MMA(ai, bj, At, Bt) do { __builtin_amdgcn_s_setprio(1); _Pragma("unroll") for (int m = 0; m < 4; ++m) _Pragma("unroll") for (int n = 0; n < 2; ++n) _Pragma("unroll") for (int k = 0; k < 2; ++k) \
;         acc[ai][bj][m][n] = __builtin_amdgcn_mfma_f32_16x16x32_bf16(Bt[n][k], At[m][k], acc[ai][bj][m][n], 0, 0, 0); __builtin_amdgcn_s_setprio(0); } while (0)
; #define PG8_WAIT_V(n) asm volatile("s_waitcnt vmcnt(" #n ")" ::: "memory")
; #define PG8_WAIT_L(n) asm volatile("s_waitcnt lgkmcnt(" #n ")" ::: "memory")
; #define PG8_BAR __builtin_amdgcn_s_barrier()
; #define PG8_SCHED __builtin_amdgcn_sched_barrier(0)
; template <class Epi, class Sched, bool ALIGN_EPI = false, bool SP2 = false>
; __device__ __forceinline__ void gemm_phase(LAS unsigned char* lds, const Gemm g, const Sched& S, const Epi& E) {
;     ...
;         for (int t = 0; t < nt; t += 2) {
;             const bool last = (t == nt - 2);
;     ...
;             PG8_LDA(At, 1, 1); PG8_STAGE(PG8_SB(1, 0), b3, voffB); PG8_STAGE(PG8_SB(1, 1), b3 + hstepB, voffB); PG8_STAGE(PG8_SA(1, 0), a3, voffA);
;             PG8_WAIT_V(8); PG8_WAIT_L(0); PG8_BAR; PG8_MMA(1, 0, At, B0); PG8_MMA(1, 1, At, B1); PG8_BAR; PG8_SCHED;
	s_add_i32 s16, s56, s30
	v_lshl_add_u64 v[190:191], v[190:191], 0, s[12:13]
	s_mov_b32 m0, s16
	ds_read_b128 v[182:185], v198 offset:49152
	ds_read_b128 v[186:189], v198 offset:50176
	ds_read_b128 v[202:205], v198 offset:51200
	ds_read_b128 v[206:209], v198 offset:52224
	ds_read_b128 v[210:213], v198 offset:53248
	ds_read_b128 v[214:217], v198 offset:54272
	ds_read_b128 v[218:221], v198 offset:55296
	ds_read_b128 v[222:225], v198 offset:56320
	global_load_lds_dwordx4 v[190:191], off
	s_add_i32 m0, s16, 0x2000
	s_add_u32 s16, s22, 0x58080
	v_lshl_add_u64 v[190:191], v[226:227], 0, s[12:13]
	s_addc_u32 s17, s23, 0
	s_add_i32 s22, s57, s30
	global_load_lds_dwordx4 v[190:191], off
	v_lshl_add_u64 v[190:191], s[16:17], 0, v[148:149]
	s_mov_b32 m0, s22
	s_nop 0
	global_load_lds_dwordx4 v[190:191], off
	v_lshl_add_u64 v[190:191], s[16:17], 0, v[152:153]
	s_add_i32 m0, s22, 0x2000
	s_nop 0
	global_load_lds_dwordx4 v[190:191], off
	v_lshl_add_u64 v[190:191], v[228:229], 0, s[12:13]
	s_mov_b32 m0, s49
	s_nop 0
	global_load_lds_dwordx4 v[190:191], off
	v_lshl_add_u64 v[190:191], v[230:231], 0, s[12:13]
	s_mov_b32 m0, s50
	s_nop 0
	global_load_lds_dwordx4 v[190:191], off
	s_waitcnt vmcnt(8)
	s_waitcnt lgkmcnt(0)
	s_barrier
	s_setprio 1
	s_waitcnt lgkmcnt(0)
	v_mfma_f32_16x16x32_bf16 v[62:65], v[130:133], v[182:185], v[62:65]
	v_mfma_f32_16x16x32_bf16 v[58:61], v[138:141], v[182:185], v[58:61]
	v_mfma_f32_16x16x32_bf16 v[46:49], v[130:133], v[202:205], v[46:49]
	v_mfma_f32_16x16x32_bf16 v[42:45], v[138:141], v[202:205], v[42:45]
	v_mfma_f32_16x16x32_bf16 v[30:33], v[130:133], v[210:213], v[30:33]
	v_mfma_f32_16x16x32_bf16 v[26:29], v[138:141], v[210:213], v[26:29]
	v_mfma_f32_16x16x32_bf16 v[14:17], v[130:133], v[218:221], v[14:17]
	v_mfma_f32_16x16x32_bf16 v[10:13], v[138:141], v[218:221], v[10:13]
	v_mfma_f32_16x16x32_bf16 v[62:65], v[134:137], v[186:189], v[62:65]
	v_mfma_f32_16x16x32_bf16 v[58:61], v[142:145], v[186:189], v[58:61]
	v_mfma_f32_16x16x32_bf16 v[46:49], v[134:137], v[206:209], v[46:49]
	v_mfma_f32_16x16x32_bf16 v[42:45], v[142:145], v[206:209], v[42:45]
	v_mfma_f32_16x16x32_bf16 v[30:33], v[134:137], v[214:217], v[30:33]
	v_mfma_f32_16x16x32_bf16 v[26:29], v[142:145], v[214:217], v[26:29]
	v_mfma_f32_16x16x32_bf16 v[14:17], v[134:137], v[222:225], v[14:17]
	v_mfma_f32_16x16x32_bf16 v[10:13], v[142:145], v[222:225], v[10:13]
	s_setprio 0
	s_setprio 1
	v_mfma_f32_16x16x32_bf16 v[54:57], v[166:169], v[182:185], v[54:57]
	v_mfma_f32_16x16x32_bf16 v[50:53], v[174:177], v[182:185], v[50:53]
	v_mfma_f32_16x16x32_bf16 v[38:41], v[166:169], v[202:205], v[38:41]
	v_mfma_f32_16x16x32_bf16 v[34:37], v[174:177], v[202:205], v[34:37]
	v_mfma_f32_16x16x32_bf16 v[22:25], v[166:169], v[210:213], v[22:25]
	v_mfma_f32_16x16x32_bf16 v[18:21], v[174:177], v[210:213], v[18:21]
	v_mfma_f32_16x16x32_bf16 v[6:9], v[166:169], v[218:221], v[6:9]
	v_mfma_f32_16x16x32_bf16 v[2:5], v[174:177], v[218:221], v[2:5]
	v_mfma_f32_16x16x32_bf16 v[54:57], v[170:173], v[186:189], v[54:57]
	v_mfma_f32_16x16x32_bf16 v[50:53], v[178:181], v[186:189], v[50:53]
	v_mfma_f32_16x16x32_bf16 v[38:41], v[170:173], v[206:209], v[38:41]
	v_mfma_f32_16x16x32_bf16 v[34:37], v[178:181], v[206:209], v[34:37]
	v_mfma_f32_16x16x32_bf16 v[22:25], v[170:173], v[214:217], v[22:25]
	v_mfma_f32_16x16x32_bf16 v[18:21], v[178:181], v[214:217], v[18:21]
	v_mfma_f32_16x16x32_bf16 v[6:9], v[170:173], v[222:225], v[6:9]
	v_mfma_f32_16x16x32_bf16 v[2:5], v[178:181], v[222:225], v[2:5]
	s_setprio 0
	s_barrier
	s_add_i32 s25, s25, 2
	s_add_u32 s9, s9, 0x100
	s_addc_u32 s24, s24, 0
	s_cmpk_gt_u32 s25, 0x55
	s_mov_b64 s[16:17], s[20:21]

;     __device__ bool next(int i, Unit& u) const { if (i != 0 || c >= 128) return false; const int t = c >> 2; u.pm = t & 3; u.pn = t >> 2; u.koff = koff_bytes; u.q = c & 3; return true; }
; #define PG8_STAGE(bufoff, gbase, voff) do { _Pragma("unroll") for (int _i = 0; _i < 2; ++_i) \
;         __builtin_amdgcn_global_load_lds((const unsigned*)((const char*)(gbase) + (voff)[_i]), (LAS unsigned*)(lds + (bufoff) + ldsw + _i * 8192), 16, 0, 0); } while (0)
; #define PG8_LDA(dst, b, h) do { _Pragma("unroll") for (int m = 0; m < 4; ++m) _Pragma("unroll") for (int k = 0; k < 2; ++k) dst[m][k] = *(const LAS bf16x8*)(lds + PG8_SA(b, h) + aoff + m * 2048 + k * 1024); } while (0)
; #define PG8_LDB(dst, b, h) do { _Pragma("unroll") for (int n = 0; n < 2; ++n) _Pragma("unroll") for (int k = 0; k < 2; ++k) dst[n][k] = *(const LAS bf16x8*)(lds + PG8_SB(b, h) + boff + n * 2048 + k * 1024); } while (0)
; template <class Epi, class Sched, bool ALIGN_EPI = false, bool SP2 = false>
; __device__ __forceinline__ void gemm_phase(LAS unsigned char* lds, const Gemm g, const Sched& S, const Epi& E) {
;     ...
;     Unit cur, nxt; int ui = 0;
;     if (!S.next(0, cur)) return;
;     f32x4 acc[2][2][4][2];
; #pragma unroll
;     for (int a = 0; a < 2; ++a)
; #pragma unroll
;         for (int b = 0; b < 2; ++b)
; #pragma unroll
;             for (int m = 0; m < 4; ++m)
; #pragma unroll
;                 for (int n = 0; n < 2; ++n) acc[a][b][m][n] = (f32x4){0.f, 0.f, 0.f, 0.f};
;     ...
;         const bool has_next = S.next(ui + 1, nxt);
;         const char* nA = has_next ? (const char*)g.A + (size_t)nxt.pm * tstep + nxt.koff : cA; const char* nB = has_next ? (const char*)g.Bt + (size_t)nxt.pn * tstep + nxt.koff : cB;
;         for (int t = 0; t < nt; t += 2) {
;             const bool last = (t == nt - 2);
;             const char* a1 = cA + (size_t)(t + 1) * kstep;
;             const char* a2 = last ? nA : cA + (size_t)(t + 2) * kstep; const char* b2 = last ? nB : cB + (size_t)(t + 2) * kstep;
;             const char* a3 = a2 + kstep; const char* b3 = b2 + kstep;
;             if (last && has_next) S.a_ready(nxt);
;             if constexpr (SP2) {
;             PG8_LDB(B0, 0, 0); PG8_LDB(B1, 0, 1); PG8_SCHED; PG8_LDA(At, 0, 0); PG8_STAGE(PG8_SA(1, 1), a1 + hstep, voffA);
;             PG8_WAIT_V(8); PG8_WAIT_L(0); PG8_BAR; PG8_MMA(0, 0, At, B0); PG8_MMA(0, 1, At, B1); PG8_BAR; PG8_SCHED;
.LBB0_1821:
	s_ashr_i32 s15, s14, 31
	v_cmp_lt_i64_e64 s[38:39], s[18:19], v[158:159]
	s_lshl_b64 s[18:19], s[14:15], 20
	s_add_u32 s18, s93, s18
	s_addc_u32 s19, s92, s19
	s_and_b64 s[20:21], s[38:39], exec
	s_cselect_b32 s3, s19, s23
	s_cselect_b32 s15, s18, s22
	s_ashr_i32 s13, s12, 31
	s_lshl_b64 s[20:21], s[12:13], 20
	s_add_u32 s20, s54, s20
	s_addc_u32 s21, s55, s21
	s_and_b64 s[24:25], s[38:39], exec
	s_cselect_b32 s13, s21, s17
	s_cselect_b32 s24, s20, s16
	s_add_u32 s25, s16, 0x100
	s_addc_u32 s49, s17, 0
	s_add_u32 s16, s22, 0x80080
	s_addc_u32 s17, s23, 0
	s_mov_b32 s50, -2
	s_waitcnt vmcnt(0)
	s_cmpk_gt_i32 s2, 0x7f
	s_mov_b64 s[98:99], 0xb000
	s_cbranch_scc1 .Lpre_up1l1
	s_ashr_i32 s100, s2, 5
	s_mul_hi_i32 s99, s100, 0x2c00
	s_mul_i32 s98, s100, 0x2c00
.Lpre_up1l1:
	s_lshl_b64 s[98:99], s[98:99], 2
	s_add_u32 s98, s36, s98
	s_addc_u32 s99, s37, s99
	s_lshl_b32 s100, s0, 8
	s_ashr_i32 s101, s100, 31
	s_lshl_b64 s[100:101], s[100:101], 2
	s_add_u32 s98, s98, s100
	s_addc_u32 s99, s99, s101
	s_add_u32 s98, s98, s47
	s_addc_u32 s99, s99, 0
	s_lshl_b32 s100, s2, 8
	s_add_i32 s100, s100, s35
	v_or_b32_e32 v162, s100, v170
	v_ashrrev_i32_e32 v163, 31, v162
	v_lshl_add_u64 v[162:163], v[162:163], 2, s[6:7]
	v_add_u32_e32 v164, s100, v171
	v_ashrrev_i32_e32 v165, 31, v164
	v_lshl_add_u64 v[164:165], v[164:165], 2, s[6:7]
	global_load_dwordx4 v[234:237], v176, s[98:99] offset:16
	global_load_dwordx4 v[238:241], v176, s[98:99]
	global_load_dwordx4 v[242:245], v176, s[98:99] offset:528
	global_load_dwordx4 v[246:249], v176, s[98:99] offset:512
	global_load_dword v250, v[162:163], off
	global_load_dword v251, v[164:165], off
	ds_read_b128 v[66:69], v173
	ds_read_b128 v[70:73], v173 offset:1024
	ds_read_b128 v[74:77], v173 offset:2048
	ds_read_b128 v[78:81], v173 offset:3072
	ds_read_b128 v[162:165], v174
	ds_read_b128 v[180:183], v174 offset:1024
	ds_read_b128 v[184:187], v174 offset:2048
	ds_read_b128 v[188:191], v174 offset:3072
	s_add_u32 s22, s16, 0xfff80080
	s_addc_u32 s23, s17, -1
	s_cmp_eq_u32 s50, 28
	s_cselect_b32 s41, s3, s23
	s_cselect_b32 s40, s15, s22
	s_cselect_b32 s23, s13, s49
	s_cselect_b32 s22, s24, s25
	v_lshl_add_u64 v[166:167], s[16:17], 0, v[156:157]
	s_add_i32 m0, s29, 0xc000
	ds_read_b128 v[192:195], v175
	ds_read_b128 v[196:199], v175 offset:1024
	ds_read_b128 v[200:203], v175 offset:2048
	ds_read_b128 v[204:207], v175 offset:3072
	ds_read_b128 v[208:211], v175 offset:4096
	ds_read_b128 v[212:215], v175 offset:5120
	ds_read_b128 v[216:219], v175 offset:6144
	ds_read_b128 v[220:223], v175 offset:7168
	global_load_lds_dwordx4 v[166:167], off
	v_lshl_add_u64 v[166:167], s[16:17], 0, v[154:155]
	s_add_i32 m0, s29, 0xe000
	s_nop 0
	global_load_lds_dwordx4 v[166:167], off
	s_waitcnt lgkmcnt(0)
	s_barrier
	s_setprio 1
	s_waitcnt lgkmcnt(0)
	v_mfma_f32_16x16x32_bf16 v[142:145], v[66:69], v[192:195], 0
	v_mfma_f32_16x16x32_bf16 v[138:141], v[74:77], v[192:195], 0
	v_mfma_f32_16x16x32_bf16 v[126:129], v[66:69], v[200:203], 0
	v_mfma_f32_16x16x32_bf16 v[122:125], v[74:77], v[200:203], 0
	v_mfma_f32_16x16x32_bf16 v[110:113], v[66:69], v[208:211], 0
	v_mfma_f32_16x16x32_bf16 v[106:109], v[74:77], v[208:211], 0
	v_mfma_f32_16x16x32_bf16 v[94:97], v[66:69], v[216:219], 0
	v_mfma_f32_16x16x32_bf16 v[90:93], v[74:77], v[216:219], 0
	v_mfma_f32_16x16x32_bf16 v[142:145], v[70:73], v[196:199], v[142:145]
	v_mfma_f32_16x16x32_bf16 v[138:141], v[78:81], v[196:199], v[138:141]
	v_mfma_f32_16x16x32_bf16 v[126:129], v[70:73], v[204:207], v[126:129]
	v_mfma_f32_16x16x32_bf16 v[122:125], v[78:81], v[204:207], v[122:125]
	v_mfma_f32_16x16x32_bf16 v[110:113], v[70:73], v[212:215], v[110:113]
	v_mfma_f32_16x16x32_bf16 v[106:109], v[78:81], v[212:215], v[106:109]
	v_mfma_f32_16x16x32_bf16 v[94:97], v[70:73], v[220:223], v[94:97]
	v_mfma_f32_16x16x32_bf16 v[90:93], v[78:81], v[220:223], v[90:93]
	s_setprio 0
	s_setprio 1
	v_mfma_f32_16x16x32_bf16 v[134:137], v[162:165], v[192:195], 0
	v_mfma_f32_16x16x32_bf16 v[130:133], v[184:187], v[192:195], 0
	v_mfma_f32_16x16x32_bf16 v[118:121], v[162:165], v[200:203], 0
	v_mfma_f32_16x16x32_bf16 v[114:117], v[184:187], v[200:203], 0
	v_mfma_f32_16x16x32_bf16 v[102:105], v[162:165], v[208:211], 0
	v_mfma_f32_16x16x32_bf16 v[98:101], v[184:187], v[208:211], 0
	v_mfma_f32_16x16x32_bf16 v[86:89], v[162:165], v[216:219], 0
	v_mfma_f32_16x16x32_bf16 v[82:85], v[184:187], v[216:219], 0
	v_mfma_f32_16x16x32_bf16 v[134:137], v[180:183], v[196:199], v[134:137]
	v_mfma_f32_16x16x32_bf16 v[130:133], v[188:191], v[196:199], v[130:133]
	v_mfma_f32_16x16x32_bf16 v[118:121], v[180:183], v[204:207], v[118:121]
	v_mfma_f32_16x16x32_bf16 v[114:117], v[188:191], v[204:207], v[114:117]
	v_mfma_f32_16x16x32_bf16 v[102:105], v[180:183], v[212:215], v[102:105]
	v_mfma_f32_16x16x32_bf16 v[98:101], v[188:191], v[212:215], v[98:101]
	v_mfma_f32_16x16x32_bf16 v[86:89], v[180:183], v[220:223], v[86:89]
	v_mfma_f32_16x16x32_bf16 v[82:85], v[188:191], v[220:223], v[82:85]
	s_setprio 0
	s_barrier
	s_add_i32 s51, s44, s26
	v_lshl_add_u64 v[166:167], s[22:23], 0, v[150:151]
	s_mov_b32 m0, s51
	ds_read_b128 v[192:195], v175 offset:16384
	ds_read_b128 v[196:199], v175 offset:17408
	ds_read_b128 v[200:203], v175 offset:18432
	ds_read_b128 v[204:207], v175 offset:19456
	ds_read_b128 v[208:211], v175 offset:20480
	ds_read_b128 v[212:215], v175 offset:21504
	ds_read_b128 v[216:219], v175 offset:22528
	ds_read_b128 v[220:223], v175 offset:23552
	global_load_lds_dwordx4 v[166:167], off
	s_add_i32 m0, s51, 0x2000
	s_add_u32 s52, s22, 0x80000
	v_lshl_add_u64 v[224:225], s[22:23], 0, v[146:147]
	s_addc_u32 s53, s23, 0
	s_add_i32 s51, s45, s26
	global_load_lds_dwordx4 v[224:225], off
	v_lshl_add_u64 v[226:227], s[52:53], 0, v[150:151]
	s_mov_b32 m0, s51
	v_lshl_add_u64 v[228:229], s[40:41], 0, v[148:149]
	global_load_lds_dwordx4 v[226:227], off
	v_lshl_add_u64 v[226:227], s[52:53], 0, v[146:147]
	s_add_i32 m0, s51, 0x2000
	s_nop 0
	global_load_lds_dwordx4 v[226:227], off
	v_lshl_add_u64 v[226:227], s[40:41], 0, v[152:153]
	s_mov_b32 m0, s29
	s_nop 0
	global_load_lds_dwordx4 v[226:227], off
	s_mov_b32 m0, s30
	s_nop 0
	global_load_lds_dwordx4 v[228:229], off
	s_waitcnt vmcnt(8)
	s_waitcnt lgkmcnt(0)
	s_barrier
; #define PG8_STAGE(bufoff, gbase, voff) do { _Pragma("unroll") for (int _i = 0; _i < 2; ++_i) \
;         __builtin_amdgcn_global_load_lds((const unsigned*)((const char*)(gbase) + (voff)[_i]), (LAS unsigned*)(lds + (bufoff) + ldsw + _i * 8192), 16, 0, 0); } while (0)
; #define PG8_LDA(dst, b, h) do { _Pragma("unroll") for (int m = 0; m < 4; ++m) _Pragma("unroll") for (int k = 0; k < 2; ++k) dst[m][k] = *(const LAS bf16x8*)(lds + PG8_SA(b, h) + aoff + m * 2048 + k * 1024); } while (0)
; #define PG8_LDB(dst, b, h) do { _Pragma("unroll") for (int n = 0; n < 2; ++n) _Pragma("unroll") for (int k = 0; k < 2; ++k) dst[n][k] = *(const LAS bf16x8*)(lds + PG8_SB(b, h) + boff + n * 2048 + k * 1024); } while (0)
; #define PG8_MMA(ai, bj, At, Bt) do { __builtin_amdgcn_s_setprio(1); _Pragma("unroll") for (int m = 0; m < 4; ++m) _Pragma("unroll") for (int n = 0; n < 2; ++n) _Pragma("unroll") for (int k = 0; k < 2; ++k) \
;         acc[ai][bj][m][n] = __builtin_amdgcn_mfma_f32_16x16x32_bf16(Bt[n][k], At[m][k], acc[ai][bj][m][n], 0, 0, 0); __builtin_amdgcn_s_setprio(0); } while (0)
; #define PG8_WAIT_V(n) asm volatile("s_waitcnt vmcnt(" #n ")" ::: "memory")
; #define PG8_WAIT_L(n) asm volatile("s_waitcnt lgkmcnt(" #n ")" ::: "memory")
; #define PG8_BAR __builtin_amdgcn_s_barrier()
; #define PG8_SCHED __builtin_amdgcn_sched_barrier(0)
; template <class Epi, class Sched, bool ALIGN_EPI = false, bool SP2 = false>
; __device__ __forceinline__ void gemm_phase(LAS unsigned char* lds, const Gemm g, const Sched& S, const Epi& E) {
;     ...
;             PG8_WAIT_V(8); PG8_WAIT_L(0); PG8_BAR; PG8_MMA(1, 0, At, B0); PG8_MMA(1, 1, At, B1); PG8_BAR; PG8_SCHED;
;             PG8_LDB(B0, 1, 0); PG8_LDB(B1, 1, 1); PG8_SCHED; PG8_LDA(At, 1, 0); PG8_STAGE(PG8_SA(0, 1), a2 + hstep, voffA);
;             PG8_WAIT_V(8); PG8_WAIT_L(0); PG8_BAR; PG8_MMA(0, 0, At, B0); PG8_MMA(0, 1, At, B1); PG8_BAR; PG8_SCHED;
	s_setprio 1
	s_waitcnt lgkmcnt(0)
	v_mfma_f32_16x16x32_bf16 v[62:65], v[66:69], v[192:195], 0
	v_mfma_f32_16x16x32_bf16 v[58:61], v[74:77], v[192:195], 0
	v_mfma_f32_16x16x32_bf16 v[46:49], v[66:69], v[200:203], 0
	v_mfma_f32_16x16x32_bf16 v[42:45], v[74:77], v[200:203], 0
	v_mfma_f32_16x16x32_bf16 v[30:33], v[66:69], v[208:211], 0
	v_mfma_f32_16x16x32_bf16 v[26:29], v[74:77], v[208:211], 0
	v_mfma_f32_16x16x32_bf16 v[14:17], v[66:69], v[216:219], 0
	v_mfma_f32_16x16x32_bf16 v[10:13], v[74:77], v[216:219], 0
	v_mfma_f32_16x16x32_bf16 v[62:65], v[70:73], v[196:199], v[62:65]
	v_mfma_f32_16x16x32_bf16 v[58:61], v[78:81], v[196:199], v[58:61]
	v_mfma_f32_16x16x32_bf16 v[46:49], v[70:73], v[204:207], v[46:49]
	v_mfma_f32_16x16x32_bf16 v[42:45], v[78:81], v[204:207], v[42:45]
	v_mfma_f32_16x16x32_bf16 v[30:33], v[70:73], v[212:215], v[30:33]
	v_mfma_f32_16x16x32_bf16 v[26:29], v[78:81], v[212:215], v[26:29]
	v_mfma_f32_16x16x32_bf16 v[14:17], v[70:73], v[220:223], v[14:17]
	v_mfma_f32_16x16x32_bf16 v[10:13], v[78:81], v[220:223], v[10:13]
	s_setprio 0
	s_setprio 1
	v_mfma_f32_16x16x32_bf16 v[54:57], v[162:165], v[192:195], 0
	v_mfma_f32_16x16x32_bf16 v[50:53], v[184:187], v[192:195], 0
	v_mfma_f32_16x16x32_bf16 v[38:41], v[162:165], v[200:203], 0
	v_mfma_f32_16x16x32_bf16 v[34:37], v[184:187], v[200:203], 0
	v_mfma_f32_16x16x32_bf16 v[22:25], v[162:165], v[208:211], 0
	v_mfma_f32_16x16x32_bf16 v[18:21], v[184:187], v[208:211], 0
	v_mfma_f32_16x16x32_bf16 v[6:9], v[162:165], v[216:219], 0
	v_mfma_f32_16x16x32_bf16 v[2:5], v[184:187], v[216:219], 0
	v_mfma_f32_16x16x32_bf16 v[54:57], v[180:183], v[196:199], v[54:57]
	v_mfma_f32_16x16x32_bf16 v[50:53], v[188:191], v[196:199], v[50:53]
	v_mfma_f32_16x16x32_bf16 v[38:41], v[180:183], v[204:207], v[38:41]
	v_mfma_f32_16x16x32_bf16 v[34:37], v[188:191], v[204:207], v[34:37]
	v_mfma_f32_16x16x32_bf16 v[22:25], v[180:183], v[212:215], v[22:25]
	v_mfma_f32_16x16x32_bf16 v[18:21], v[188:191], v[212:215], v[18:21]
	v_mfma_f32_16x16x32_bf16 v[6:9], v[180:183], v[220:223], v[6:9]
	v_mfma_f32_16x16x32_bf16 v[2:5], v[188:191], v[220:223], v[2:5]
	s_setprio 0
	s_barrier
	s_add_i32 s51, 0, 0x18000
	s_add_i32 s52, 0, 0x1c000
	v_add_u32_e32 v78, s51, v169
	v_add_u32_e32 v168, s52, v169
	ds_read_b128 v[66:69], v78
	ds_read_b128 v[70:73], v78 offset:1024
	ds_read_b128 v[74:77], v78 offset:2048
	ds_read_b128 v[78:81], v78 offset:3072
	ds_read_b128 v[162:165], v168
	ds_read_b128 v[180:183], v168 offset:1024
	ds_read_b128 v[184:187], v168 offset:2048
	ds_read_b128 v[188:191], v168 offset:3072
	s_add_u32 s40, s40, 0x80000
	s_addc_u32 s41, s41, 0
	s_mov_b32 m0, s31
	v_lshl_add_u64 v[230:231], s[40:41], 0, v[152:153]
	ds_read_b128 v[192:195], v175 offset:32768
	ds_read_b128 v[196:199], v175 offset:33792
	ds_read_b128 v[200:203], v175 offset:34816
	ds_read_b128 v[204:207], v175 offset:35840
	ds_read_b128 v[208:211], v175 offset:36864
	ds_read_b128 v[212:215], v175 offset:37888
	ds_read_b128 v[216:219], v175 offset:38912
	ds_read_b128 v[220:223], v175 offset:39936
	global_load_lds_dwordx4 v[230:231], off
	v_lshl_add_u64 v[230:231], s[40:41], 0, v[148:149]
	s_mov_b32 m0, s33
	s_nop 0
	global_load_lds_dwordx4 v[230:231], off
	s_waitcnt vmcnt(8)
	s_waitcnt lgkmcnt(0)
	s_barrier
	s_setprio 1
	s_waitcnt lgkmcnt(0)
	v_mfma_f32_16x16x32_bf16 v[142:145], v[66:69], v[192:195], v[142:145]
	v_mfma_f32_16x16x32_bf16 v[138:141], v[74:77], v[192:195], v[138:141]
	v_mfma_f32_16x16x32_bf16 v[126:129], v[66:69], v[200:203], v[126:129]
	v_mfma_f32_16x16x32_bf16 v[122:125], v[74:77], v[200:203], v[122:125]
	v_mfma_f32_16x16x32_bf16 v[110:113], v[66:69], v[208:211], v[110:113]
	v_mfma_f32_16x16x32_bf16 v[106:109], v[74:77], v[208:211], v[106:109]
	v_mfma_f32_16x16x32_bf16 v[94:97], v[66:69], v[216:219], v[94:97]
	v_mfma_f32_16x16x32_bf16 v[90:93], v[74:77], v[216:219], v[90:93]
	v_mfma_f32_16x16x32_bf16 v[142:145], v[70:73], v[196:199], v[142:145]
	v_mfma_f32_16x16x32_bf16 v[138:141], v[78:81], v[196:199], v[138:141]
	v_mfma_f32_16x16x32_bf16 v[126:129], v[70:73], v[204:207], v[126:129]
	v_mfma_f32_16x16x32_bf16 v[122:125], v[78:81], v[204:207], v[122:125]
	v_mfma_f32_16x16x32_bf16 v[110:113], v[70:73], v[212:215], v[110:113]
	v_mfma_f32_16x16x32_bf16 v[106:109], v[78:81], v[212:215], v[106:109]
	v_mfma_f32_16x16x32_bf16 v[94:97], v[70:73], v[220:223], v[94:97]
	v_mfma_f32_16x16x32_bf16 v[90:93], v[78:81], v[220:223], v[90:93]
	s_setprio 0
	s_setprio 1
	v_mfma_f32_16x16x32_bf16 v[134:137], v[162:165], v[192:195], v[134:137]
	v_mfma_f32_16x16x32_bf16 v[130:133], v[184:187], v[192:195], v[130:133]
	v_mfma_f32_16x16x32_bf16 v[118:121], v[162:165], v[200:203], v[118:121]
	v_mfma_f32_16x16x32_bf16 v[114:117], v[184:187], v[200:203], v[114:117]
	v_mfma_f32_16x16x32_bf16 v[102:105], v[162:165], v[208:211], v[102:105]
	v_mfma_f32_16x16x32_bf16 v[98:101], v[184:187], v[208:211], v[98:101]
	v_mfma_f32_16x16x32_bf16 v[86:89], v[162:165], v[216:219], v[86:89]
	v_mfma_f32_16x16x32_bf16 v[82:85], v[184:187], v[216:219], v[82:85]
	v_mfma_f32_16x16x32_bf16 v[134:137], v[180:183], v[196:199], v[134:137]
	v_mfma_f32_16x16x32_bf16 v[130:133], v[188:191], v[196:199], v[130:133]
	v_mfma_f32_16x16x32_bf16 v[118:121], v[180:183], v[204:207], v[118:121]
	v_mfma_f32_16x16x32_bf16 v[114:117], v[188:191], v[204:207], v[114:117]
	v_mfma_f32_16x16x32_bf16 v[102:105], v[180:183], v[212:215], v[102:105]
	v_mfma_f32_16x16x32_bf16 v[98:101], v[188:191], v[212:215], v[98:101]
	v_mfma_f32_16x16x32_bf16 v[86:89], v[180:183], v[220:223], v[86:89]
	v_mfma_f32_16x16x32_bf16 v[82:85], v[188:191], v[220:223], v[82:85]
	s_setprio 0
	s_barrier
; #define PG8_STAGE(bufoff, gbase, voff) do { _Pragma("unroll") for (int _i = 0; _i < 2; ++_i) \
;         __builtin_amdgcn_global_load_lds((const unsigned*)((const char*)(gbase) + (voff)[_i]), (LAS unsigned*)(lds + (bufoff) + ldsw + _i * 8192), 16, 0, 0); } while (0)
; #define PG8_LDA(dst, b, h) do { _Pragma("unroll") for (int m = 0; m < 4; ++m) _Pragma("unroll") for (int k = 0; k < 2; ++k) dst[m][k] = *(const LAS bf16x8*)(lds + PG8_SA(b, h) + aoff + m * 2048 + k * 1024); } while (0)
; #define PG8_MMA(ai, bj, At, Bt) do { __builtin_amdgcn_s_setprio(1); _Pragma("unroll") for (int m = 0; m < 4; ++m) _Pragma("unroll") for (int n = 0; n < 2; ++n) _Pragma("unroll") for (int k = 0; k < 2; ++k) \
;         acc[ai][bj][m][n] = __builtin_amdgcn_mfma_f32_16x16x32_bf16(Bt[n][k], At[m][k], acc[ai][bj][m][n], 0, 0, 0); __builtin_amdgcn_s_setprio(0); } while (0)
; #define PG8_WAIT_V(n) asm volatile("s_waitcnt vmcnt(" #n ")" ::: "memory")
; #define PG8_WAIT_L(n) asm volatile("s_waitcnt lgkmcnt(" #n ")" ::: "memory")
; #define PG8_BAR __builtin_amdgcn_s_barrier()
; #define PG8_SCHED __builtin_amdgcn_sched_barrier(0)
; template <class Epi, class Sched, bool ALIGN_EPI = false, bool SP2 = false>
; __device__ __forceinline__ void gemm_phase(LAS unsigned char* lds, const Gemm g, const Sched& S, const Epi& E) {
;     ...
;         for (int t = 0; t < nt; t += 2) {
;             const bool last = (t == nt - 2);
;     ...
;             PG8_LDA(At, 1, 1); PG8_STAGE(PG8_SB(1, 0), b3, voffB); PG8_STAGE(PG8_SB(1, 1), b3 + hstepB, voffB); PG8_STAGE(PG8_SA(1, 0), a3, voffA);
;             PG8_WAIT_V(8); PG8_WAIT_L(0); PG8_BAR; PG8_MMA(1, 0, At, B0); PG8_MMA(1, 1, At, B1); PG8_BAR; PG8_SCHED;
	s_add_i32 s40, s51, s26
	v_lshl_add_u64 v[166:167], v[166:167], 0, s[8:9]
	s_mov_b32 m0, s40
	ds_read_b128 v[192:195], v175 offset:49152
	ds_read_b128 v[196:199], v175 offset:50176
	ds_read_b128 v[200:203], v175 offset:51200
	ds_read_b128 v[204:207], v175 offset:52224
	ds_read_b128 v[208:211], v175 offset:53248
	ds_read_b128 v[212:215], v175 offset:54272
	ds_read_b128 v[216:219], v175 offset:55296
	ds_read_b128 v[220:223], v175 offset:56320
	global_load_lds_dwordx4 v[166:167], off
	s_add_i32 m0, s40, 0x2000
	s_add_u32 s22, s22, 0x80080
	v_lshl_add_u64 v[166:167], v[224:225], 0, s[8:9]
	s_addc_u32 s23, s23, 0
	s_add_i32 s40, s52, s26
	global_load_lds_dwordx4 v[166:167], off
	v_lshl_add_u64 v[166:167], s[22:23], 0, v[150:151]
	s_mov_b32 m0, s40
	s_nop 0
	global_load_lds_dwordx4 v[166:167], off
	v_lshl_add_u64 v[166:167], s[22:23], 0, v[146:147]
	s_add_i32 m0, s40, 0x2000
	s_nop 0
	global_load_lds_dwordx4 v[166:167], off
	v_lshl_add_u64 v[166:167], v[226:227], 0, s[8:9]
	s_mov_b32 m0, s42
	s_nop 0
	global_load_lds_dwordx4 v[166:167], off
	v_lshl_add_u64 v[166:167], v[228:229], 0, s[8:9]
	s_mov_b32 m0, s43
	s_nop 0
	global_load_lds_dwordx4 v[166:167], off
	s_waitcnt vmcnt(8)
	s_waitcnt lgkmcnt(0)
	s_barrier
	s_setprio 1
	s_waitcnt lgkmcnt(0)
	v_mfma_f32_16x16x32_bf16 v[62:65], v[66:69], v[192:195], v[62:65]
	v_mfma_f32_16x16x32_bf16 v[58:61], v[74:77], v[192:195], v[58:61]
	v_mfma_f32_16x16x32_bf16 v[46:49], v[66:69], v[200:203], v[46:49]
	v_mfma_f32_16x16x32_bf16 v[42:45], v[74:77], v[200:203], v[42:45]
	v_mfma_f32_16x16x32_bf16 v[30:33], v[66:69], v[208:211], v[30:33]
	v_mfma_f32_16x16x32_bf16 v[26:29], v[74:77], v[208:211], v[26:29]
	v_mfma_f32_16x16x32_bf16 v[14:17], v[66:69], v[216:219], v[14:17]
	v_mfma_f32_16x16x32_bf16 v[10:13], v[74:77], v[216:219], v[10:13]
	v_mfma_f32_16x16x32_bf16 v[62:65], v[70:73], v[196:199], v[62:65]
	v_mfma_f32_16x16x32_bf16 v[58:61], v[78:81], v[196:199], v[58:61]
	v_mfma_f32_16x16x32_bf16 v[46:49], v[70:73], v[204:207], v[46:49]
	v_mfma_f32_16x16x32_bf16 v[42:45], v[78:81], v[204:207], v[42:45]
	v_mfma_f32_16x16x32_bf16 v[30:33], v[70:73], v[212:215], v[30:33]
	v_mfma_f32_16x16x32_bf16 v[26:29], v[78:81], v[212:215], v[26:29]
	v_mfma_f32_16x16x32_bf16 v[14:17], v[70:73], v[220:223], v[14:17]
	v_mfma_f32_16x16x32_bf16 v[10:13], v[78:81], v[220:223], v[10:13]
	s_setprio 0
	s_setprio 1
	v_mfma_f32_16x16x32_bf16 v[54:57], v[162:165], v[192:195], v[54:57]
	v_mfma_f32_16x16x32_bf16 v[50:53], v[184:187], v[192:195], v[50:53]
	v_mfma_f32_16x16x32_bf16 v[38:41], v[162:165], v[200:203], v[38:41]
	v_mfma_f32_16x16x32_bf16 v[34:37], v[184:187], v[200:203], v[34:37]
	v_mfma_f32_16x16x32_bf16 v[22:25], v[162:165], v[208:211], v[22:25]
	v_mfma_f32_16x16x32_bf16 v[18:21], v[184:187], v[208:211], v[18:21]
	v_mfma_f32_16x16x32_bf16 v[6:9], v[162:165], v[216:219], v[6:9]
	v_mfma_f32_16x16x32_bf16 v[2:5], v[184:187], v[216:219], v[2:5]
	v_mfma_f32_16x16x32_bf16 v[54:57], v[180:183], v[196:199], v[54:57]
	v_mfma_f32_16x16x32_bf16 v[50:53], v[188:191], v[196:199], v[50:53]
	v_mfma_f32_16x16x32_bf16 v[38:41], v[180:183], v[204:207], v[38:41]
	v_mfma_f32_16x16x32_bf16 v[34:37], v[188:191], v[204:207], v[34:37]
	v_mfma_f32_16x16x32_bf16 v[22:25], v[180:183], v[212:215], v[22:25]
	v_mfma_f32_16x16x32_bf16 v[18:21], v[188:191], v[212:215], v[18:21]
	v_mfma_f32_16x16x32_bf16 v[6:9], v[180:183], v[220:223], v[6:9]
	v_mfma_f32_16x16x32_bf16 v[2:5], v[188:191], v[220:223], v[2:5]
	s_setprio 0
	s_barrier
	s_add_i32 s50, s50, 2
	s_add_u32 s25, s25, 0x100
	s_addc_u32 s49, s49, 0
	s_add_u32 s16, s16, 0x100
	s_addc_u32 s17, s17, 0
	s_cmp_lt_u32 s50, 30

; __device__ __forceinline__ unsigned cvt_pk_bf16(float lo, float hi) { unsigned r; asm volatile("v_cvt_pk_bf16_f32 %0, %1, %2" : "=v"(r) : "v"(lo), "v"(hi)); return r; }
; __device__ __forceinline__ float silu_mul(float a, float b) { return a * b * __builtin_amdgcn_rcpf(1.0f + __builtin_amdgcn_exp2f(-a * LOG2E)); }
; __device__ __forceinline__ float row_rstd(const float* ss, int row) { return 1.0f / sqrtf(ss[row] * (1.0f / DM) + 1e-6f); }
;     __device__ __forceinline__ void operator()(const f32x4 (&acc)[2][2][4][2], const Unit& u, int wr, int wc, int fr, int fq) const {
;     ...
;         const float rsl0 = row_rstd(ss, u.pm * BM + wr * 64 + lane), rsl1 = row_rstd(ss, u.pm * BM + HALF + wr * 64 + lane);
; #pragma unroll
;         for (int ai = 0; ai < 2; ++ai)
; #pragma unroll
;             for (int m = 0; m < 4; ++m) { const int row = row0 + ai * HALF + m * 16; const float rs = __shfl(ai ? rsl1 : rsl0, m * 16 + fr); bf16_t* rowp = O + (size_t)row * DFF + col0;
;                 const f32x4 a0 = acc[ai][0][m][0] * rs + ba0, a1 = acc[ai][0][m][1] * rs + ba1, b0 = acc[ai][1][m][0] * rs + bb0, b1 = acc[ai][1][m][1] * rs + bb1;
;                 u32x4 w; w.x = cvt_pk_bf16(silu_mul(a0[0], b0[0]), silu_mul(a0[1], b0[1])); w.y = cvt_pk_bf16(silu_mul(a0[2], b0[2]), silu_mul(a0[3], b0[3]));
;                 w.z = cvt_pk_bf16(silu_mul(a1[0], b1[0]), silu_mul(a1[1], b1[1])); w.w = cvt_pk_bf16(silu_mul(a1[2], b1[2]), silu_mul(a1[3], b1[3]));
;                 *(u32x4*)rowp = w; }
.LBB0_1827:
	s_lshl_b32 s2, s2, 8
	s_add_i32 s13, s2, s35
	s_lshl_b64 s[2:3], s[16:17], 2
	s_add_u32 s15, s36, s2
	s_addc_u32 s16, s37, s3
	s_lshl_b32 s2, s0, 8
	s_ashr_i32 s3, s2, 31
	s_lshl_b64 s[2:3], s[2:3], 2
	v_lshl_or_b32 v164, s0, 7, v172
	s_add_u32 s0, s15, s2
	s_addc_u32 s3, s16, s3
	v_or_b32_e32 v162, s13, v170
	s_add_u32 s2, s0, s47
	v_ashrrev_i32_e32 v163, 31, v162
	s_addc_u32 s3, s3, 0
	v_lshl_add_u64 v[162:163], v[162:163], 2, s[6:7]
	v_mov_b32_e32 v74, v234
	v_mov_b32_e32 v75, v235
	v_mov_b32_e32 v76, v236
	v_mov_b32_e32 v77, v237
	v_mov_b32_e32 v78, v238
	v_mov_b32_e32 v79, v239
	v_mov_b32_e32 v80, v240
	v_mov_b32_e32 v81, v241
	v_mov_b32_e32 v66, v242
	v_mov_b32_e32 v67, v243
	v_mov_b32_e32 v68, v244
	v_mov_b32_e32 v69, v245
	v_mov_b32_e32 v70, v246
	v_mov_b32_e32 v71, v247
	v_mov_b32_e32 v72, v248
	v_mov_b32_e32 v73, v249
	v_or_b32_e32 v180, s13, v1
	v_mov_b32_e32 v162, v250
	s_waitcnt vmcnt(0)
	v_fmamk_f32 v162, v162, 0x3a000000, v177
	v_cmp_gt_f32_e32 vcc, s48, v162
	v_mul_f32_e32 v163, 0x4f800000, v162
	s_nop 0
	v_cndmask_b32_e32 v162, v162, v163, vcc
	v_sqrt_f32_e32 v163, v162
	s_nop 0
	v_add_u32_e32 v165, -1, v163
	v_fma_f32 v166, -v165, v163, v162
	v_cmp_ge_f32_e64 s[2:3], 0, v166
	v_add_u32_e32 v166, 1, v163
	s_nop 0
	v_cndmask_b32_e64 v165, v163, v165, s[2:3]
	v_fma_f32 v163, -v166, v163, v162
	v_cmp_lt_f32_e64 s[2:3], 0, v163
	s_nop 1
	v_cndmask_b32_e64 v163, v165, v166, s[2:3]
	v_mul_f32_e32 v165, 0x37800000, v163
	v_cndmask_b32_e32 v163, v163, v165, vcc
	v_cmp_class_f32_e32 vcc, v162, v178
	s_nop 1
	v_cndmask_b32_e32 v166, v163, v162, vcc
	v_add_u32_e32 v162, s13, v171
	v_ashrrev_i32_e32 v163, 31, v162
	v_lshl_add_u64 v[162:163], v[162:163], 2, s[6:7]
	v_mov_b32_e32 v162, v251
	v_fmamk_f32 v162, v162, 0x3a000000, v177
	v_cmp_gt_f32_e32 vcc, s48, v162
	v_mul_f32_e32 v163, 0x4f800000, v162
	s_nop 0
	v_cndmask_b32_e32 v162, v162, v163, vcc
	v_sqrt_f32_e32 v163, v162
	s_nop 0
	v_add_u32_e32 v165, -1, v163
	v_fma_f32 v167, -v165, v163, v162
	v_cmp_ge_f32_e64 s[2:3], 0, v167
	v_add_u32_e32 v167, 1, v163
	s_nop 0
	v_cndmask_b32_e64 v165, v163, v165, s[2:3]
	v_fma_f32 v163, -v167, v163, v162
	v_cmp_lt_f32_e64 s[2:3], 0, v163
	s_nop 1
	v_cndmask_b32_e64 v163, v165, v167, s[2:3]
	v_mul_f32_e32 v165, 0x37800000, v163
	v_cndmask_b32_e32 v163, v163, v165, vcc
	v_cmp_class_f32_e32 vcc, v162, v178
	v_ashrrev_i32_e32 v165, 31, v164
	v_lshlrev_b64 v[164:165], 1, v[164:165]
	v_cndmask_b32_e32 v181, v163, v162, vcc
	v_div_scale_f32 v162, s[2:3], v166, v166, 1.0
	v_rcp_f32_e32 v163, v162
	s_nop 0
	v_fma_f32 v167, -v162, v163, 1.0
	v_fmac_f32_e32 v163, v167, v163
	v_div_scale_f32 v167, vcc, 1.0, v166, 1.0
	v_mul_f32_e32 v168, v167, v163
	v_fma_f32 v182, -v162, v168, v167
	v_fmac_f32_e32 v168, v182, v163
	v_fma_f32 v162, -v162, v168, v167
	v_div_fmas_f32 v162, v162, v163, v168
	v_div_fixup_f32 v182, v162, v166, 1.0
	ds_bpermute_b32 v168, v179, v182
	v_mov_b64_e32 v[162:163], s[96:97]
	v_mad_i64_i32 v[166:167], s[2:3], v180, s46, v[162:163]
	v_lshl_add_u64 v[166:167], v[166:167], 0, v[164:165]
	s_waitcnt lgkmcnt(0)
	v_pk_fma_f32 v[142:143], v[142:143], v[168:169], v[78:79] op_sel_hi:[1,0,1]
	v_pk_fma_f32 v[134:135], v[134:135], v[168:169], v[70:71] op_sel_hi:[1,0,1]
	v_pk_fma_f32 v[184:185], v[132:133], v[168:169], v[68:69] op_sel_hi:[1,0,1]
	v_pk_fma_f32 v[132:133], v[130:131], v[168:169], v[66:67] op_sel_hi:[1,0,1]
	v_mul_f32_e32 v131, 0xbfb8aa3b, v142
	v_mul_f32_e32 v130, v142, v134
	v_exp_f32_e32 v131, v131
	v_mul_f32_e32 v134, 0xbfb8aa3b, v143
	v_exp_f32_e32 v134, v134
	v_pk_fma_f32 v[144:145], v[144:145], v[168:169], v[80:81] op_sel_hi:[1,0,1]
	v_add_f32_e32 v131, 1.0, v131
	v_rcp_f32_e32 v131, v131
	v_add_f32_e32 v134, 1.0, v134
	v_rcp_f32_e32 v134, v134
	v_pk_fma_f32 v[136:137], v[136:137], v[168:169], v[72:73] op_sel_hi:[1,0,1]
	v_mul_f32_e32 v130, v130, v131
	v_mul_f32_e32 v131, v143, v135
	v_mul_f32_e32 v131, v131, v134
	v_mul_f32_e32 v134, 0xbfb8aa3b, v144
	v_exp_f32_e32 v134, v134
	v_mul_f32_e32 v135, 0xbfb8aa3b, v145
	v_exp_f32_e32 v135, v135
	v_cvt_pk_bf16_f32 v130, v130, v131
	v_add_f32_e32 v134, 1.0, v134
	v_rcp_f32_e32 v134, v134
	v_add_f32_e32 v135, 1.0, v135
	v_rcp_f32_e32 v135, v135
	v_mul_f32_e32 v131, v144, v136
	v_mul_f32_e32 v131, v131, v134
	v_mul_f32_e32 v134, v145, v137
	v_pk_fma_f32 v[138:139], v[138:139], v[168:169], v[74:75] op_sel_hi:[1,0,1]
	v_mul_f32_e32 v134, v134, v135
	v_cvt_pk_bf16_f32 v131, v131, v134
	v_mul_f32_e32 v134, 0xbfb8aa3b, v138
	v_exp_f32_e32 v134, v134
	v_mul_f32_e32 v132, v138, v132
	v_pk_fma_f32 v[140:141], v[140:141], v[168:169], v[76:77] op_sel_hi:[1,0,1]
	v_mul_f32_e32 v133, v139, v133
	v_add_f32_e32 v134, 1.0, v134
	v_rcp_f32_e32 v134, v134
	v_mul_f32_e32 v135, 0xbfb8aa3b, v141
	v_exp_f32_e32 v135, v135
	v_mul_f32_e32 v132, v132, v134
	v_mul_f32_e32 v134, 0xbfb8aa3b, v139
	v_exp_f32_e32 v134, v134
	v_add_f32_e32 v135, 1.0, v135
	v_rcp_f32_e32 v135, v135
	v_add_f32_e32 v134, 1.0, v134
	v_rcp_f32_e32 v134, v134
	s_nop 0
	v_mul_f32_e32 v133, v133, v134
	v_mul_f32_e32 v134, 0xbfb8aa3b, v140
	v_exp_f32_e32 v134, v134
	v_cvt_pk_bf16_f32 v132, v132, v133
	v_mul_f32_e32 v133, v140, v184
	v_add_f32_e32 v134, 1.0, v134
	v_rcp_f32_e32 v134, v134
	s_nop 0
	v_mul_f32_e32 v133, v133, v134
	v_mul_f32_e32 v134, v141, v185
	v_mul_f32_e32 v134, v134, v135
	v_cvt_pk_bf16_f32 v133, v133, v134
	global_store_dwordx4 v[166:167], v[130:133], off
	ds_bpermute_b32 v130, v179, v182 offset:64
	s_nop 0
	v_or_b32_e32 v131, 16, v180
	v_mad_i64_i32 v[132:133], s[2:3], v131, s46, v[162:163]
	s_waitcnt lgkmcnt(0)
; __device__ __forceinline__ unsigned cvt_pk_bf16(float lo, float hi) { unsigned r; asm volatile("v_cvt_pk_bf16_f32 %0, %1, %2" : "=v"(r) : "v"(lo), "v"(hi)); return r; }
; __device__ __forceinline__ float silu_mul(float a, float b) { return a * b * __builtin_amdgcn_rcpf(1.0f + __builtin_amdgcn_exp2f(-a * LOG2E)); }
;     __device__ __forceinline__ void operator()(const f32x4 (&acc)[2][2][4][2], const Unit& u, int wr, int wc, int fr, int fq) const {
;     ...
;             for (int m = 0; m < 4; ++m) { const int row = row0 + ai * HALF + m * 16; const float rs = __shfl(ai ? rsl1 : rsl0, m * 16 + fr); bf16_t* rowp = O + (size_t)row * DFF + col0;
;                 const f32x4 a0 = acc[ai][0][m][0] * rs + ba0, a1 = acc[ai][0][m][1] * rs + ba1, b0 = acc[ai][1][m][0] * rs + bb0, b1 = acc[ai][1][m][1] * rs + bb1;
;                 u32x4 w; w.x = cvt_pk_bf16(silu_mul(a0[0], b0[0]), silu_mul(a0[1], b0[1])); w.y = cvt_pk_bf16(silu_mul(a0[2], b0[2]), silu_mul(a0[3], b0[3]));
;                 w.z = cvt_pk_bf16(silu_mul(a1[0], b1[0]), silu_mul(a1[1], b1[1])); w.w = cvt_pk_bf16(silu_mul(a1[2], b1[2]), silu_mul(a1[3], b1[3]));
;                 *(u32x4*)rowp = w; }
	v_pk_fma_f32 v[126:127], v[126:127], v[130:131], v[78:79] op_sel_hi:[1,0,1]
	v_pk_fma_f32 v[118:119], v[118:119], v[130:131], v[70:71] op_sel_hi:[1,0,1]
	v_pk_fma_f32 v[134:135], v[116:117], v[130:131], v[68:69] op_sel_hi:[1,0,1]
	v_pk_fma_f32 v[116:117], v[114:115], v[130:131], v[66:67] op_sel_hi:[1,0,1]
	v_mul_f32_e32 v115, 0xbfb8aa3b, v126
	v_mul_f32_e32 v114, v126, v118
	v_exp_f32_e32 v115, v115
	v_mul_f32_e32 v118, 0xbfb8aa3b, v127
	v_exp_f32_e32 v118, v118
	v_pk_fma_f32 v[128:129], v[128:129], v[130:131], v[80:81] op_sel_hi:[1,0,1]
	v_add_f32_e32 v115, 1.0, v115
	v_rcp_f32_e32 v115, v115
	v_add_f32_e32 v118, 1.0, v118
	v_rcp_f32_e32 v118, v118
	v_pk_fma_f32 v[120:121], v[120:121], v[130:131], v[72:73] op_sel_hi:[1,0,1]
	v_mul_f32_e32 v114, v114, v115
	v_mul_f32_e32 v115, v127, v119
	v_mul_f32_e32 v115, v115, v118
	v_mul_f32_e32 v118, 0xbfb8aa3b, v128
	v_exp_f32_e32 v118, v118
	v_mul_f32_e32 v119, 0xbfb8aa3b, v129
	v_exp_f32_e32 v119, v119
	v_cvt_pk_bf16_f32 v114, v114, v115
	v_add_f32_e32 v118, 1.0, v118
	v_rcp_f32_e32 v118, v118
	v_add_f32_e32 v119, 1.0, v119
	v_rcp_f32_e32 v119, v119
	v_mul_f32_e32 v115, v128, v120
	v_mul_f32_e32 v115, v115, v118
	v_mul_f32_e32 v118, v129, v121
	v_pk_fma_f32 v[122:123], v[122:123], v[130:131], v[74:75] op_sel_hi:[1,0,1]
	v_mul_f32_e32 v118, v118, v119
	v_cvt_pk_bf16_f32 v115, v115, v118
	v_mul_f32_e32 v118, 0xbfb8aa3b, v122
	v_exp_f32_e32 v118, v118
	v_mul_f32_e32 v116, v122, v116
	v_pk_fma_f32 v[124:125], v[124:125], v[130:131], v[76:77] op_sel_hi:[1,0,1]
	v_mul_f32_e32 v117, v123, v117
	v_add_f32_e32 v118, 1.0, v118
	v_rcp_f32_e32 v118, v118
	v_mul_f32_e32 v119, 0xbfb8aa3b, v125
	v_exp_f32_e32 v119, v119
	v_lshl_add_u64 v[132:133], v[132:133], 0, v[164:165]
	v_mul_f32_e32 v116, v116, v118
	v_mul_f32_e32 v118, 0xbfb8aa3b, v123
	v_exp_f32_e32 v118, v118
	v_add_f32_e32 v119, 1.0, v119
	v_rcp_f32_e32 v119, v119
	v_add_f32_e32 v118, 1.0, v118
	v_rcp_f32_e32 v118, v118
	s_nop 0
	v_mul_f32_e32 v117, v117, v118
	v_mul_f32_e32 v118, 0xbfb8aa3b, v124
	v_exp_f32_e32 v118, v118
	v_cvt_pk_bf16_f32 v116, v116, v117
	v_mul_f32_e32 v117, v124, v134
	v_add_f32_e32 v118, 1.0, v118
	v_rcp_f32_e32 v118, v118
	s_nop 0
	v_mul_f32_e32 v117, v117, v118
	v_mul_f32_e32 v118, v125, v135
	v_mul_f32_e32 v118, v118, v119
	v_cvt_pk_bf16_f32 v117, v117, v118
	global_store_dwordx4 v[132:133], v[114:117], off
	ds_bpermute_b32 v114, v179, v182 offset:128
	s_nop 0
	v_or_b32_e32 v115, 32, v180
	v_mad_i64_i32 v[116:117], s[2:3], v115, s46, v[162:163]
	s_waitcnt lgkmcnt(0)
	v_pk_fma_f32 v[110:111], v[110:111], v[114:115], v[78:79] op_sel_hi:[1,0,1]
	v_pk_fma_f32 v[102:103], v[102:103], v[114:115], v[70:71] op_sel_hi:[1,0,1]
	v_pk_fma_f32 v[118:119], v[100:101], v[114:115], v[68:69] op_sel_hi:[1,0,1]
	v_pk_fma_f32 v[100:101], v[98:99], v[114:115], v[66:67] op_sel_hi:[1,0,1]
	v_mul_f32_e32 v99, 0xbfb8aa3b, v110
	v_mul_f32_e32 v98, v110, v102
	v_exp_f32_e32 v99, v99
	v_mul_f32_e32 v102, 0xbfb8aa3b, v111
	v_exp_f32_e32 v102, v102
	v_pk_fma_f32 v[112:113], v[112:113], v[114:115], v[80:81] op_sel_hi:[1,0,1]
	v_add_f32_e32 v99, 1.0, v99
	v_rcp_f32_e32 v99, v99
	v_add_f32_e32 v102, 1.0, v102
	v_rcp_f32_e32 v102, v102
	v_pk_fma_f32 v[104:105], v[104:105], v[114:115], v[72:73] op_sel_hi:[1,0,1]
	v_mul_f32_e32 v98, v98, v99
	v_mul_f32_e32 v99, v111, v103
	v_mul_f32_e32 v99, v99, v102
	v_mul_f32_e32 v102, 0xbfb8aa3b, v112
	v_exp_f32_e32 v102, v102
	v_mul_f32_e32 v103, 0xbfb8aa3b, v113
	v_exp_f32_e32 v103, v103
	v_cvt_pk_bf16_f32 v98, v98, v99
	v_add_f32_e32 v102, 1.0, v102
	v_rcp_f32_e32 v102, v102
	v_add_f32_e32 v103, 1.0, v103
	v_rcp_f32_e32 v103, v103
	v_mul_f32_e32 v99, v112, v104
	v_mul_f32_e32 v99, v99, v102
	v_mul_f32_e32 v102, v113, v105
	v_pk_fma_f32 v[106:107], v[106:107], v[114:115], v[74:75] op_sel_hi:[1,0,1]
	v_mul_f32_e32 v102, v102, v103
	v_cvt_pk_bf16_f32 v99, v99, v102
	v_mul_f32_e32 v102, 0xbfb8aa3b, v106
	v_exp_f32_e32 v102, v102
	v_mul_f32_e32 v100, v106, v100
	v_pk_fma_f32 v[108:109], v[108:109], v[114:115], v[76:77] op_sel_hi:[1,0,1]
	v_mul_f32_e32 v101, v107, v101
	v_add_f32_e32 v102, 1.0, v102
	v_rcp_f32_e32 v102, v102
	v_mul_f32_e32 v103, 0xbfb8aa3b, v109
	v_exp_f32_e32 v103, v103
	v_lshl_add_u64 v[116:117], v[116:117], 0, v[164:165]
	v_mul_f32_e32 v100, v100, v102
	v_mul_f32_e32 v102, 0xbfb8aa3b, v107
	v_exp_f32_e32 v102, v102
	v_add_f32_e32 v103, 1.0, v103
	v_rcp_f32_e32 v103, v103
	v_add_f32_e32 v102, 1.0, v102
	v_rcp_f32_e32 v102, v102
	s_nop 0
	v_mul_f32_e32 v101, v101, v102
	v_mul_f32_e32 v102, 0xbfb8aa3b, v108
	v_exp_f32_e32 v102, v102
	v_cvt_pk_bf16_f32 v100, v100, v101
	v_mul_f32_e32 v101, v108, v118
	v_add_f32_e32 v102, 1.0, v102
	v_rcp_f32_e32 v102, v102
	s_nop 0
	v_mul_f32_e32 v101, v101, v102
	v_mul_f32_e32 v102, v109, v119
	v_mul_f32_e32 v102, v102, v103
	v_cvt_pk_bf16_f32 v101, v101, v102
	global_store_dwordx4 v[116:117], v[98:101], off
	ds_bpermute_b32 v98, v179, v182 offset:192
	s_nop 0
	v_or_b32_e32 v99, 48, v180
	v_mad_i64_i32 v[100:101], s[2:3], v99, s46, v[162:163]
	s_waitcnt lgkmcnt(0)
; __device__ __forceinline__ unsigned cvt_pk_bf16(float lo, float hi) { unsigned r; asm volatile("v_cvt_pk_bf16_f32 %0, %1, %2" : "=v"(r) : "v"(lo), "v"(hi)); return r; }
; __device__ __forceinline__ float silu_mul(float a, float b) { return a * b * __builtin_amdgcn_rcpf(1.0f + __builtin_amdgcn_exp2f(-a * LOG2E)); }
; __device__ __forceinline__ float row_rstd(const float* ss, int row) { return 1.0f / sqrtf(ss[row] * (1.0f / DM) + 1e-6f); }
;     __device__ __forceinline__ void operator()(const f32x4 (&acc)[2][2][4][2], const Unit& u, int wr, int wc, int fr, int fq) const {
;     ...
;             for (int m = 0; m < 4; ++m) { const int row = row0 + ai * HALF + m * 16; const float rs = __shfl(ai ? rsl1 : rsl0, m * 16 + fr); bf16_t* rowp = O + (size_t)row * DFF + col0;
;                 const f32x4 a0 = acc[ai][0][m][0] * rs + ba0, a1 = acc[ai][0][m][1] * rs + ba1, b0 = acc[ai][1][m][0] * rs + bb0, b1 = acc[ai][1][m][1] * rs + bb1;
;                 u32x4 w; w.x = cvt_pk_bf16(silu_mul(a0[0], b0[0]), silu_mul(a0[1], b0[1])); w.y = cvt_pk_bf16(silu_mul(a0[2], b0[2]), silu_mul(a0[3], b0[3]));
;                 w.z = cvt_pk_bf16(silu_mul(a1[0], b1[0]), silu_mul(a1[1], b1[1])); w.w = cvt_pk_bf16(silu_mul(a1[2], b1[2]), silu_mul(a1[3], b1[3]));
;                 *(u32x4*)rowp = w; }
	v_pk_fma_f32 v[94:95], v[94:95], v[98:99], v[78:79] op_sel_hi:[1,0,1]
	v_pk_fma_f32 v[86:87], v[86:87], v[98:99], v[70:71] op_sel_hi:[1,0,1]
	v_pk_fma_f32 v[102:103], v[84:85], v[98:99], v[68:69] op_sel_hi:[1,0,1]
	v_pk_fma_f32 v[84:85], v[82:83], v[98:99], v[66:67] op_sel_hi:[1,0,1]
	v_mul_f32_e32 v83, 0xbfb8aa3b, v94
	v_mul_f32_e32 v82, v94, v86
	v_exp_f32_e32 v83, v83
	v_mul_f32_e32 v86, 0xbfb8aa3b, v95
	v_exp_f32_e32 v86, v86
	v_pk_fma_f32 v[96:97], v[96:97], v[98:99], v[80:81] op_sel_hi:[1,0,1]
	v_add_f32_e32 v83, 1.0, v83
	v_rcp_f32_e32 v83, v83
	v_add_f32_e32 v86, 1.0, v86
	v_rcp_f32_e32 v86, v86
	v_pk_fma_f32 v[88:89], v[88:89], v[98:99], v[72:73] op_sel_hi:[1,0,1]
	v_mul_f32_e32 v82, v82, v83
	v_mul_f32_e32 v83, v95, v87
	v_mul_f32_e32 v83, v83, v86
	v_mul_f32_e32 v86, 0xbfb8aa3b, v96
	v_exp_f32_e32 v86, v86
	v_mul_f32_e32 v87, 0xbfb8aa3b, v97
	v_exp_f32_e32 v87, v87
	v_cvt_pk_bf16_f32 v82, v82, v83
	v_add_f32_e32 v86, 1.0, v86
	v_rcp_f32_e32 v86, v86
	v_add_f32_e32 v87, 1.0, v87
	v_rcp_f32_e32 v87, v87
	v_mul_f32_e32 v83, v96, v88
	v_mul_f32_e32 v83, v83, v86
	v_mul_f32_e32 v86, v97, v89
	v_pk_fma_f32 v[90:91], v[90:91], v[98:99], v[74:75] op_sel_hi:[1,0,1]
	v_mul_f32_e32 v86, v86, v87
	v_cvt_pk_bf16_f32 v83, v83, v86
	v_mul_f32_e32 v86, 0xbfb8aa3b, v90
	v_exp_f32_e32 v86, v86
	v_mul_f32_e32 v84, v90, v84
	v_pk_fma_f32 v[92:93], v[92:93], v[98:99], v[76:77] op_sel_hi:[1,0,1]
	v_mul_f32_e32 v85, v91, v85
	v_add_f32_e32 v86, 1.0, v86
	v_rcp_f32_e32 v86, v86
	v_mul_f32_e32 v87, 0xbfb8aa3b, v93
	v_exp_f32_e32 v87, v87
	v_lshl_add_u64 v[100:101], v[100:101], 0, v[164:165]
	v_mul_f32_e32 v84, v84, v86
	v_mul_f32_e32 v86, 0xbfb8aa3b, v91
	v_exp_f32_e32 v86, v86
	v_add_f32_e32 v87, 1.0, v87
	v_rcp_f32_e32 v87, v87
	v_add_f32_e32 v86, 1.0, v86
	v_rcp_f32_e32 v86, v86
	s_nop 0
	v_mul_f32_e32 v85, v85, v86
	v_mul_f32_e32 v86, 0xbfb8aa3b, v92
	v_exp_f32_e32 v86, v86
	v_cvt_pk_bf16_f32 v84, v84, v85
	v_mul_f32_e32 v85, v92, v102
	v_add_f32_e32 v86, 1.0, v86
	v_rcp_f32_e32 v86, v86
	s_nop 0
	v_mul_f32_e32 v85, v85, v86
	v_mul_f32_e32 v86, v93, v103
	v_mul_f32_e32 v86, v86, v87
	v_cvt_pk_bf16_f32 v85, v85, v86
	global_store_dwordx4 v[100:101], v[82:85], off
	s_nop 1
	v_div_scale_f32 v82, s[2:3], v181, v181, 1.0
	v_rcp_f32_e32 v84, v82
	v_add_u32_e32 v83, 0x80, v180
	v_fma_f32 v85, -v82, v84, 1.0
	v_fmac_f32_e32 v84, v85, v84
	v_div_scale_f32 v85, vcc, 1.0, v181, 1.0
	v_mul_f32_e32 v86, v85, v84
	v_fma_f32 v87, -v82, v86, v85
	v_fmac_f32_e32 v86, v87, v84
	v_fma_f32 v82, -v82, v86, v85
	v_div_fmas_f32 v82, v82, v84, v86
	v_div_fixup_f32 v82, v82, v181, 1.0
	ds_bpermute_b32 v84, v179, v82
	v_mad_i64_i32 v[86:87], s[2:3], v83, s46, v[162:163]
	v_lshl_add_u64 v[86:87], v[86:87], 0, v[164:165]
	s_and_b64 vcc, s[38:39], exec
	s_waitcnt lgkmcnt(0)
	v_pk_fma_f32 v[62:63], v[62:63], v[84:85], v[78:79] op_sel_hi:[1,0,1]
	v_pk_fma_f32 v[54:55], v[54:55], v[84:85], v[70:71] op_sel_hi:[1,0,1]
	v_pk_fma_f32 v[88:89], v[52:53], v[84:85], v[68:69] op_sel_hi:[1,0,1]
	v_pk_fma_f32 v[52:53], v[50:51], v[84:85], v[66:67] op_sel_hi:[1,0,1]
	v_mul_f32_e32 v51, 0xbfb8aa3b, v62
	v_mul_f32_e32 v50, v62, v54
	v_exp_f32_e32 v51, v51
	v_mul_f32_e32 v54, 0xbfb8aa3b, v63
	v_exp_f32_e32 v54, v54
	v_pk_fma_f32 v[64:65], v[64:65], v[84:85], v[80:81] op_sel_hi:[1,0,1]
	v_add_f32_e32 v51, 1.0, v51
	v_rcp_f32_e32 v51, v51
	v_add_f32_e32 v54, 1.0, v54
	v_rcp_f32_e32 v54, v54
	v_pk_fma_f32 v[56:57], v[56:57], v[84:85], v[72:73] op_sel_hi:[1,0,1]
	v_mul_f32_e32 v50, v50, v51
	v_mul_f32_e32 v51, v63, v55
	v_mul_f32_e32 v51, v51, v54
	v_mul_f32_e32 v54, 0xbfb8aa3b, v64
	v_exp_f32_e32 v54, v54
	v_mul_f32_e32 v55, 0xbfb8aa3b, v65
	v_exp_f32_e32 v55, v55
	v_cvt_pk_bf16_f32 v50, v50, v51
	v_add_f32_e32 v54, 1.0, v54
	v_rcp_f32_e32 v54, v54
	v_add_f32_e32 v55, 1.0, v55
	v_rcp_f32_e32 v55, v55
	v_mul_f32_e32 v51, v64, v56
	v_mul_f32_e32 v51, v51, v54
	v_mul_f32_e32 v54, v65, v57
	v_pk_fma_f32 v[58:59], v[58:59], v[84:85], v[74:75] op_sel_hi:[1,0,1]
	v_mul_f32_e32 v54, v54, v55
	v_cvt_pk_bf16_f32 v51, v51, v54
	v_mul_f32_e32 v54, 0xbfb8aa3b, v58
	v_exp_f32_e32 v54, v54
	v_mul_f32_e32 v52, v58, v52
	v_pk_fma_f32 v[60:61], v[60:61], v[84:85], v[76:77] op_sel_hi:[1,0,1]
	v_mul_f32_e32 v53, v59, v53
	v_add_f32_e32 v54, 1.0, v54
	v_rcp_f32_e32 v54, v54
	v_mul_f32_e32 v55, 0xbfb8aa3b, v61
	v_exp_f32_e32 v55, v55
	v_mul_f32_e32 v52, v52, v54
	v_mul_f32_e32 v54, 0xbfb8aa3b, v59
	v_exp_f32_e32 v54, v54
	v_add_f32_e32 v55, 1.0, v55
	v_rcp_f32_e32 v55, v55
	v_add_f32_e32 v54, 1.0, v54
	v_rcp_f32_e32 v54, v54
	s_nop 0
	v_mul_f32_e32 v53, v53, v54
	v_mul_f32_e32 v54, 0xbfb8aa3b, v60
	v_exp_f32_e32 v54, v54
	v_cvt_pk_bf16_f32 v52, v52, v53
	v_mul_f32_e32 v53, v60, v88
	v_add_f32_e32 v54, 1.0, v54
	v_rcp_f32_e32 v54, v54
	s_nop 0
	v_mul_f32_e32 v53, v53, v54
	v_mul_f32_e32 v54, v61, v89
	v_mul_f32_e32 v54, v54, v55
	v_cvt_pk_bf16_f32 v53, v53, v54
	global_store_dwordx4 v[86:87], v[50:53], off
	ds_bpermute_b32 v50, v179, v82 offset:64
	s_nop 0
	v_add_u32_e32 v51, 0x90, v180
	v_mad_i64_i32 v[52:53], s[2:3], v51, s46, v[162:163]
	s_waitcnt lgkmcnt(0)
; __device__ __forceinline__ unsigned cvt_pk_bf16(float lo, float hi) { unsigned r; asm volatile("v_cvt_pk_bf16_f32 %0, %1, %2" : "=v"(r) : "v"(lo), "v"(hi)); return r; }
; __device__ __forceinline__ float silu_mul(float a, float b) { return a * b * __builtin_amdgcn_rcpf(1.0f + __builtin_amdgcn_exp2f(-a * LOG2E)); }
; #define PG8_BAR __builtin_amdgcn_s_barrier()
;     __device__ __forceinline__ void operator()(const f32x4 (&acc)[2][2][4][2], const Unit& u, int wr, int wc, int fr, int fq) const {
;     ...
;             for (int m = 0; m < 4; ++m) { const int row = row0 + ai * HALF + m * 16; const float rs = __shfl(ai ? rsl1 : rsl0, m * 16 + fr); bf16_t* rowp = O + (size_t)row * DFF + col0;
;                 const f32x4 a0 = acc[ai][0][m][0] * rs + ba0, a1 = acc[ai][0][m][1] * rs + ba1, b0 = acc[ai][1][m][0] * rs + bb0, b1 = acc[ai][1][m][1] * rs + bb1;
;                 u32x4 w; w.x = cvt_pk_bf16(silu_mul(a0[0], b0[0]), silu_mul(a0[1], b0[1])); w.y = cvt_pk_bf16(silu_mul(a0[2], b0[2]), silu_mul(a0[3], b0[3]));
;                 w.z = cvt_pk_bf16(silu_mul(a1[0], b1[0]), silu_mul(a1[1], b1[1])); w.w = cvt_pk_bf16(silu_mul(a1[2], b1[2]), silu_mul(a1[3], b1[3]));
;                 *(u32x4*)rowp = w; }
; template <class Epi, class Sched, bool ALIGN_EPI = false, bool SP2 = false>
; __device__ __forceinline__ void gemm_phase(LAS unsigned char* lds, const Gemm g, const Sched& S, const Epi& E) {
;     ...
;         if (!has_next) break;
; #pragma unroll
;         for (int a = 0; a < 2; ++a)
; #pragma unroll
;             for (int b = 0; b < 2; ++b)
; #pragma unroll
;                 for (int m = 0; m < 4; ++m)
; #pragma unroll
;                     for (int n = 0; n < 2; ++n) acc[a][b][m][n] = (f32x4){0.f, 0.f, 0.f, 0.f};
;         cur = nxt; cA = nA; cB = nB; ++ui;
;         if constexpr (ALIGN_EPI) { if (wr == 1) PG8_BAR; }
	v_pk_fma_f32 v[46:47], v[46:47], v[50:51], v[78:79] op_sel_hi:[1,0,1]
	v_pk_fma_f32 v[38:39], v[38:39], v[50:51], v[70:71] op_sel_hi:[1,0,1]
	v_pk_fma_f32 v[54:55], v[36:37], v[50:51], v[68:69] op_sel_hi:[1,0,1]
	v_pk_fma_f32 v[36:37], v[34:35], v[50:51], v[66:67] op_sel_hi:[1,0,1]
	v_mul_f32_e32 v35, 0xbfb8aa3b, v46
	v_mul_f32_e32 v34, v46, v38
	v_exp_f32_e32 v35, v35
	v_mul_f32_e32 v38, 0xbfb8aa3b, v47
	v_exp_f32_e32 v38, v38
	v_pk_fma_f32 v[48:49], v[48:49], v[50:51], v[80:81] op_sel_hi:[1,0,1]
	v_add_f32_e32 v35, 1.0, v35
	v_rcp_f32_e32 v35, v35
	v_add_f32_e32 v38, 1.0, v38
	v_rcp_f32_e32 v38, v38
	v_pk_fma_f32 v[40:41], v[40:41], v[50:51], v[72:73] op_sel_hi:[1,0,1]
	v_mul_f32_e32 v34, v34, v35
	v_mul_f32_e32 v35, v47, v39
	v_mul_f32_e32 v35, v35, v38
	v_mul_f32_e32 v38, 0xbfb8aa3b, v48
	v_exp_f32_e32 v38, v38
	v_mul_f32_e32 v39, 0xbfb8aa3b, v49
	v_exp_f32_e32 v39, v39
	v_cvt_pk_bf16_f32 v34, v34, v35
	v_add_f32_e32 v38, 1.0, v38
	v_rcp_f32_e32 v38, v38
	v_add_f32_e32 v39, 1.0, v39
	v_rcp_f32_e32 v39, v39
	v_mul_f32_e32 v35, v48, v40
	v_mul_f32_e32 v35, v35, v38
	v_mul_f32_e32 v38, v49, v41
	v_pk_fma_f32 v[42:43], v[42:43], v[50:51], v[74:75] op_sel_hi:[1,0,1]
	v_mul_f32_e32 v38, v38, v39
	v_cvt_pk_bf16_f32 v35, v35, v38
	v_mul_f32_e32 v38, 0xbfb8aa3b, v42
	v_exp_f32_e32 v38, v38
	v_mul_f32_e32 v36, v42, v36
	v_pk_fma_f32 v[44:45], v[44:45], v[50:51], v[76:77] op_sel_hi:[1,0,1]
	v_mul_f32_e32 v37, v43, v37
	v_add_f32_e32 v38, 1.0, v38
	v_rcp_f32_e32 v38, v38
	v_mul_f32_e32 v39, 0xbfb8aa3b, v45
	v_exp_f32_e32 v39, v39
	v_lshl_add_u64 v[52:53], v[52:53], 0, v[164:165]
	v_mul_f32_e32 v36, v36, v38
	v_mul_f32_e32 v38, 0xbfb8aa3b, v43
	v_exp_f32_e32 v38, v38
	v_add_f32_e32 v39, 1.0, v39
	v_rcp_f32_e32 v39, v39
	v_add_f32_e32 v38, 1.0, v38
	v_rcp_f32_e32 v38, v38
	s_nop 0
	v_mul_f32_e32 v37, v37, v38
	v_mul_f32_e32 v38, 0xbfb8aa3b, v44
	v_exp_f32_e32 v38, v38
	v_cvt_pk_bf16_f32 v36, v36, v37
	v_mul_f32_e32 v37, v44, v54
	v_add_f32_e32 v38, 1.0, v38
	v_rcp_f32_e32 v38, v38
	s_nop 0
	v_mul_f32_e32 v37, v37, v38
	v_mul_f32_e32 v38, v45, v55
	v_mul_f32_e32 v38, v38, v39
	v_cvt_pk_bf16_f32 v37, v37, v38
	global_store_dwordx4 v[52:53], v[34:37], off
	ds_bpermute_b32 v34, v179, v82 offset:128
	s_nop 0
	v_add_u32_e32 v35, 0xa0, v180
	v_mad_i64_i32 v[36:37], s[2:3], v35, s46, v[162:163]
	s_waitcnt lgkmcnt(0)
	v_pk_fma_f32 v[30:31], v[30:31], v[34:35], v[78:79] op_sel_hi:[1,0,1]
	v_pk_fma_f32 v[22:23], v[22:23], v[34:35], v[70:71] op_sel_hi:[1,0,1]
	v_pk_fma_f32 v[38:39], v[20:21], v[34:35], v[68:69] op_sel_hi:[1,0,1]
	v_pk_fma_f32 v[20:21], v[18:19], v[34:35], v[66:67] op_sel_hi:[1,0,1]
	v_mul_f32_e32 v19, 0xbfb8aa3b, v30
	v_mul_f32_e32 v18, v30, v22
	v_exp_f32_e32 v19, v19
	v_mul_f32_e32 v22, 0xbfb8aa3b, v31
	v_exp_f32_e32 v22, v22
	v_pk_fma_f32 v[32:33], v[32:33], v[34:35], v[80:81] op_sel_hi:[1,0,1]
	v_add_f32_e32 v19, 1.0, v19
	v_rcp_f32_e32 v19, v19
	v_add_f32_e32 v22, 1.0, v22
	v_rcp_f32_e32 v22, v22
	v_pk_fma_f32 v[24:25], v[24:25], v[34:35], v[72:73] op_sel_hi:[1,0,1]
	v_mul_f32_e32 v18, v18, v19
	v_mul_f32_e32 v19, v31, v23
	v_mul_f32_e32 v19, v19, v22
	v_mul_f32_e32 v22, 0xbfb8aa3b, v32
	v_exp_f32_e32 v22, v22
	v_mul_f32_e32 v23, 0xbfb8aa3b, v33
	v_exp_f32_e32 v23, v23
	v_cvt_pk_bf16_f32 v18, v18, v19
	v_add_f32_e32 v22, 1.0, v22
	v_rcp_f32_e32 v22, v22
	v_add_f32_e32 v23, 1.0, v23
	v_rcp_f32_e32 v23, v23
	v_mul_f32_e32 v19, v32, v24
	v_mul_f32_e32 v19, v19, v22
	v_mul_f32_e32 v22, v33, v25
	v_pk_fma_f32 v[26:27], v[26:27], v[34:35], v[74:75] op_sel_hi:[1,0,1]
	v_mul_f32_e32 v22, v22, v23
	v_cvt_pk_bf16_f32 v19, v19, v22
	v_mul_f32_e32 v22, 0xbfb8aa3b, v26
	v_exp_f32_e32 v22, v22
	v_mul_f32_e32 v20, v26, v20
	v_pk_fma_f32 v[28:29], v[28:29], v[34:35], v[76:77] op_sel_hi:[1,0,1]
	v_mul_f32_e32 v21, v27, v21
	v_add_f32_e32 v22, 1.0, v22
	v_rcp_f32_e32 v22, v22
	v_mul_f32_e32 v23, 0xbfb8aa3b, v29
	v_exp_f32_e32 v23, v23
	v_lshl_add_u64 v[36:37], v[36:37], 0, v[164:165]
	v_mul_f32_e32 v20, v20, v22
	v_mul_f32_e32 v22, 0xbfb8aa3b, v27
	v_exp_f32_e32 v22, v22
	v_add_f32_e32 v23, 1.0, v23
	v_rcp_f32_e32 v23, v23
	v_add_f32_e32 v22, 1.0, v22
	v_rcp_f32_e32 v22, v22
	s_nop 0
	v_mul_f32_e32 v21, v21, v22
	v_mul_f32_e32 v22, 0xbfb8aa3b, v28
	v_exp_f32_e32 v22, v22
	v_cvt_pk_bf16_f32 v20, v20, v21
	v_mul_f32_e32 v21, v28, v38
	v_add_f32_e32 v22, 1.0, v22
	v_rcp_f32_e32 v22, v22
	s_nop 0
	v_mul_f32_e32 v21, v21, v22
	v_mul_f32_e32 v22, v29, v39
	v_mul_f32_e32 v22, v22, v23
	v_cvt_pk_bf16_f32 v21, v21, v22
	global_store_dwordx4 v[36:37], v[18:21], off
	ds_bpermute_b32 v18, v179, v82 offset:192
	s_nop 0
	v_add_u32_e32 v19, 0xb0, v180
	v_mad_i64_i32 v[20:21], s[2:3], v19, s46, v[162:163]
	s_waitcnt lgkmcnt(0)
	v_pk_fma_f32 v[14:15], v[14:15], v[18:19], v[78:79] op_sel_hi:[1,0,1]
	v_pk_fma_f32 v[6:7], v[6:7], v[18:19], v[70:71] op_sel_hi:[1,0,1]
	v_pk_fma_f32 v[22:23], v[4:5], v[18:19], v[68:69] op_sel_hi:[1,0,1]
	v_pk_fma_f32 v[4:5], v[2:3], v[18:19], v[66:67] op_sel_hi:[1,0,1]
	v_mul_f32_e32 v3, 0xbfb8aa3b, v14
	v_mul_f32_e32 v2, v14, v6
	v_exp_f32_e32 v3, v3
	v_mul_f32_e32 v6, 0xbfb8aa3b, v15
	v_exp_f32_e32 v6, v6
	v_pk_fma_f32 v[16:17], v[16:17], v[18:19], v[80:81] op_sel_hi:[1,0,1]
	v_add_f32_e32 v3, 1.0, v3
	v_rcp_f32_e32 v3, v3
	v_add_f32_e32 v6, 1.0, v6
	v_rcp_f32_e32 v6, v6
	v_pk_fma_f32 v[8:9], v[8:9], v[18:19], v[72:73] op_sel_hi:[1,0,1]
	v_mul_f32_e32 v2, v2, v3
	v_mul_f32_e32 v3, v15, v7
	v_mul_f32_e32 v3, v3, v6
	v_mul_f32_e32 v6, 0xbfb8aa3b, v16
	v_exp_f32_e32 v6, v6
	v_mul_f32_e32 v7, 0xbfb8aa3b, v17
	v_exp_f32_e32 v7, v7
	v_cvt_pk_bf16_f32 v2, v2, v3
	v_add_f32_e32 v6, 1.0, v6
	v_rcp_f32_e32 v6, v6
	v_add_f32_e32 v7, 1.0, v7
	v_rcp_f32_e32 v7, v7
	v_mul_f32_e32 v3, v16, v8
	v_mul_f32_e32 v3, v3, v6
	v_mul_f32_e32 v6, v17, v9
	v_pk_fma_f32 v[10:11], v[10:11], v[18:19], v[74:75] op_sel_hi:[1,0,1]
	v_mul_f32_e32 v6, v6, v7
	v_cvt_pk_bf16_f32 v3, v3, v6
	v_mul_f32_e32 v6, 0xbfb8aa3b, v10
	v_exp_f32_e32 v6, v6
	v_mul_f32_e32 v4, v10, v4
	v_pk_fma_f32 v[12:13], v[12:13], v[18:19], v[76:77] op_sel_hi:[1,0,1]
	v_mul_f32_e32 v5, v11, v5
	v_add_f32_e32 v6, 1.0, v6
	v_rcp_f32_e32 v6, v6
	v_mul_f32_e32 v7, 0xbfb8aa3b, v13
	v_exp_f32_e32 v7, v7
	v_lshl_add_u64 v[20:21], v[20:21], 0, v[164:165]
	v_mul_f32_e32 v4, v4, v6
	v_mul_f32_e32 v6, 0xbfb8aa3b, v11
	v_exp_f32_e32 v6, v6
	v_add_f32_e32 v7, 1.0, v7
	v_rcp_f32_e32 v7, v7
	s_mov_b64 s[2:3], -1
	v_add_f32_e32 v6, 1.0, v6
	v_rcp_f32_e32 v6, v6
	s_nop 0
	v_mul_f32_e32 v5, v5, v6
	v_mul_f32_e32 v6, 0xbfb8aa3b, v12
	v_exp_f32_e32 v6, v6
	v_cvt_pk_bf16_f32 v4, v4, v5
	v_mul_f32_e32 v5, v12, v22
	v_add_f32_e32 v6, 1.0, v6
	v_rcp_f32_e32 v6, v6
	s_nop 0
	v_mul_f32_e32 v5, v5, v6
	v_mul_f32_e32 v6, v13, v23
	v_mul_f32_e32 v6, v6, v7
	v_cvt_pk_bf16_f32 v5, v5, v6
	global_store_dwordx4 v[20:21], v[2:5], off
	s_cbranch_vccz .LBB0_1818
	s_andn2_b64 vcc, exec, s[4:5]
	s_cbranch_vccnz .LBB0_1817
	s_barrier
	s_branch .LBB0_1817

;     __device__ bool next(int i, Unit& u) const { if (i != 0 || c >= 128) return false; const int t = c >> 2; u.pm = t & 3; u.pn = t >> 2; u.koff = koff_bytes; u.q = c & 3; return true; }
; #define PG8_STAGE(bufoff, gbase, voff) do { _Pragma("unroll") for (int _i = 0; _i < 2; ++_i) \
;         __builtin_amdgcn_global_load_lds((const unsigned*)((const char*)(gbase) + (voff)[_i]), (LAS unsigned*)(lds + (bufoff) + ldsw + _i * 8192), 16, 0, 0); } while (0)
; #define PG8_LDA(dst, b, h) do { _Pragma("unroll") for (int m = 0; m < 4; ++m) _Pragma("unroll") for (int k = 0; k < 2; ++k) dst[m][k] = *(const LAS bf16x8*)(lds + PG8_SA(b, h) + aoff + m * 2048 + k * 1024); } while (0)
; #define PG8_LDB(dst, b, h) do { _Pragma("unroll") for (int n = 0; n < 2; ++n) _Pragma("unroll") for (int k = 0; k < 2; ++k) dst[n][k] = *(const LAS bf16x8*)(lds + PG8_SB(b, h) + boff + n * 2048 + k * 1024); } while (0)
; template <class Epi, class Sched, bool ALIGN_EPI = false, bool SP2 = false>
; __device__ __forceinline__ void gemm_phase(LAS unsigned char* lds, const Gemm g, const Sched& S, const Epi& E) {
;     ...
;     Unit cur, nxt; int ui = 0;
;     if (!S.next(0, cur)) return;
;     f32x4 acc[2][2][4][2];
; #pragma unroll
;     for (int a = 0; a < 2; ++a)
; #pragma unroll
;         for (int b = 0; b < 2; ++b)
; #pragma unroll
;             for (int m = 0; m < 4; ++m)
; #pragma unroll
;                 for (int n = 0; n < 2; ++n) acc[a][b][m][n] = (f32x4){0.f, 0.f, 0.f, 0.f};
;     ...
;         const bool has_next = S.next(ui + 1, nxt);
;         const char* nA = has_next ? (const char*)g.A + (size_t)nxt.pm * tstep + nxt.koff : cA; const char* nB = has_next ? (const char*)g.Bt + (size_t)nxt.pn * tstep + nxt.koff : cB;
;         for (int t = 0; t < nt; t += 2) {
;             const bool last = (t == nt - 2);
;             const char* a1 = cA + (size_t)(t + 1) * kstep;
;             const char* a2 = last ? nA : cA + (size_t)(t + 2) * kstep; const char* b2 = last ? nB : cB + (size_t)(t + 2) * kstep;
;             const char* a3 = a2 + kstep; const char* b3 = b2 + kstep;
;             if (last && has_next) S.a_ready(nxt);
;             if constexpr (SP2) {
;             PG8_LDB(B0, 0, 0); PG8_LDB(B1, 0, 1); PG8_SCHED; PG8_LDA(At, 0, 0); PG8_STAGE(PG8_SA(1, 1), a1 + hstep, voffA);
;             PG8_WAIT_V(8); PG8_WAIT_L(0); PG8_BAR; PG8_MMA(0, 0, At, B0); PG8_MMA(0, 1, At, B1); PG8_BAR; PG8_SCHED;
.LBB0_1925:
	s_add_u32 s5, s20, 0x100
	s_addc_u32 s24, s21, 0
	s_mov_b32 s25, -2
	s_waitcnt vmcnt(0)
	ds_read_b128 v[130:133], v196
	ds_read_b128 v[134:137], v196 offset:1024
	ds_read_b128 v[138:141], v196 offset:2048
	ds_read_b128 v[142:145], v196 offset:3072
	ds_read_b128 v[166:169], v197
	ds_read_b128 v[170:173], v197 offset:1024
	ds_read_b128 v[174:177], v197 offset:2048
	ds_read_b128 v[178:181], v197 offset:3072
	s_add_u32 s20, s18, 0x100
	s_addc_u32 s21, s19, 0
	s_cmpk_eq_i32 s25, 0x54
	s_cselect_b32 s47, s17, s21
	s_cselect_b32 s46, s16, s20
	s_cselect_b32 s23, s3, s24
	s_cselect_b32 s22, s2, s5
	v_lshl_add_u64 v[190:191], s[18:19], 0, v[160:161]
	s_add_i32 m0, s27, 0xc000
	ds_read_b128 v[182:185], v198
	ds_read_b128 v[186:189], v198 offset:1024
	ds_read_b128 v[202:205], v198 offset:2048
	ds_read_b128 v[206:209], v198 offset:3072
	ds_read_b128 v[210:213], v198 offset:4096
	ds_read_b128 v[214:217], v198 offset:5120
	ds_read_b128 v[218:221], v198 offset:6144
	ds_read_b128 v[222:225], v198 offset:7168
	global_load_lds_dwordx4 v[190:191], off
	v_lshl_add_u64 v[190:191], s[18:19], 0, v[158:159]
	s_add_i32 m0, s27, 0xe000
	s_nop 0
	global_load_lds_dwordx4 v[190:191], off
	s_waitcnt lgkmcnt(0)
	s_barrier
	s_setprio 1
	s_waitcnt lgkmcnt(0)
	v_mfma_f32_16x16x32_bf16 v[126:129], v[130:133], v[182:185], 0
	v_mfma_f32_16x16x32_bf16 v[122:125], v[138:141], v[182:185], 0
	v_mfma_f32_16x16x32_bf16 v[110:113], v[130:133], v[202:205], 0
	v_mfma_f32_16x16x32_bf16 v[106:109], v[138:141], v[202:205], 0
	v_mfma_f32_16x16x32_bf16 v[94:97], v[130:133], v[210:213], 0
	v_mfma_f32_16x16x32_bf16 v[90:93], v[138:141], v[210:213], 0
	v_mfma_f32_16x16x32_bf16 v[78:81], v[130:133], v[218:221], 0
	v_mfma_f32_16x16x32_bf16 v[74:77], v[138:141], v[218:221], 0
	v_mfma_f32_16x16x32_bf16 v[126:129], v[134:137], v[186:189], v[126:129]
	v_mfma_f32_16x16x32_bf16 v[122:125], v[142:145], v[186:189], v[122:125]
	v_mfma_f32_16x16x32_bf16 v[110:113], v[134:137], v[206:209], v[110:113]
	v_mfma_f32_16x16x32_bf16 v[106:109], v[142:145], v[206:209], v[106:109]
	v_mfma_f32_16x16x32_bf16 v[94:97], v[134:137], v[214:217], v[94:97]
	v_mfma_f32_16x16x32_bf16 v[90:93], v[142:145], v[214:217], v[90:93]
	v_mfma_f32_16x16x32_bf16 v[78:81], v[134:137], v[222:225], v[78:81]
	v_mfma_f32_16x16x32_bf16 v[74:77], v[142:145], v[222:225], v[74:77]
	s_setprio 0
	s_setprio 1
	v_mfma_f32_16x16x32_bf16 v[118:121], v[166:169], v[182:185], 0
	v_mfma_f32_16x16x32_bf16 v[114:117], v[174:177], v[182:185], 0
	v_mfma_f32_16x16x32_bf16 v[102:105], v[166:169], v[202:205], 0
	v_mfma_f32_16x16x32_bf16 v[98:101], v[174:177], v[202:205], 0
	v_mfma_f32_16x16x32_bf16 v[86:89], v[166:169], v[210:213], 0
	v_mfma_f32_16x16x32_bf16 v[82:85], v[174:177], v[210:213], 0
	v_mfma_f32_16x16x32_bf16 v[70:73], v[166:169], v[218:221], 0
	v_mfma_f32_16x16x32_bf16 v[66:69], v[174:177], v[218:221], 0
	v_mfma_f32_16x16x32_bf16 v[118:121], v[170:173], v[186:189], v[118:121]
	v_mfma_f32_16x16x32_bf16 v[114:117], v[178:181], v[186:189], v[114:117]
	v_mfma_f32_16x16x32_bf16 v[102:105], v[170:173], v[206:209], v[102:105]
	v_mfma_f32_16x16x32_bf16 v[98:101], v[178:181], v[206:209], v[98:101]
	v_mfma_f32_16x16x32_bf16 v[86:89], v[170:173], v[214:217], v[86:89]
	v_mfma_f32_16x16x32_bf16 v[82:85], v[178:181], v[214:217], v[82:85]
	v_mfma_f32_16x16x32_bf16 v[70:73], v[170:173], v[222:225], v[70:73]
	v_mfma_f32_16x16x32_bf16 v[66:69], v[178:181], v[222:225], v[66:69]
	s_setprio 0
	s_barrier
	s_add_i32 s18, s50, s26
	v_lshl_add_u64 v[190:191], s[22:23], 0, v[148:149]
	s_mov_b32 m0, s18
	ds_read_b128 v[182:185], v198 offset:16384
	ds_read_b128 v[186:189], v198 offset:17408
	ds_read_b128 v[202:205], v198 offset:18432
	ds_read_b128 v[206:209], v198 offset:19456
	ds_read_b128 v[210:213], v198 offset:20480
	ds_read_b128 v[214:217], v198 offset:21504
	ds_read_b128 v[218:221], v198 offset:22528
	ds_read_b128 v[222:225], v198 offset:23552
	global_load_lds_dwordx4 v[190:191], off
	s_add_i32 m0, s18, 0x2000
	s_add_u32 s18, s22, 0x58000
	v_lshl_add_u64 v[226:227], s[22:23], 0, v[152:153]
	s_addc_u32 s19, s23, 0
	s_add_i32 s54, s51, s26
	global_load_lds_dwordx4 v[226:227], off
	v_lshl_add_u64 v[228:229], s[18:19], 0, v[148:149]
	s_mov_b32 m0, s54
	v_lshl_add_u64 v[230:231], s[46:47], 0, v[150:151]
	global_load_lds_dwordx4 v[228:229], off
	v_lshl_add_u64 v[228:229], s[18:19], 0, v[152:153]
	s_add_i32 m0, s54, 0x2000
	s_nop 0
	global_load_lds_dwordx4 v[228:229], off
	v_lshl_add_u64 v[228:229], s[46:47], 0, v[146:147]
	s_mov_b32 m0, s27
	s_nop 0
	global_load_lds_dwordx4 v[228:229], off
	s_mov_b32 m0, s28
	s_nop 0
	global_load_lds_dwordx4 v[230:231], off
	s_waitcnt vmcnt(8)
	s_waitcnt lgkmcnt(0)
	s_barrier
; #define PG8_STAGE(bufoff, gbase, voff) do { _Pragma("unroll") for (int _i = 0; _i < 2; ++_i) \
;         __builtin_amdgcn_global_load_lds((const unsigned*)((const char*)(gbase) + (voff)[_i]), (LAS unsigned*)(lds + (bufoff) + ldsw + _i * 8192), 16, 0, 0); } while (0)
; #define PG8_LDA(dst, b, h) do { _Pragma("unroll") for (int m = 0; m < 4; ++m) _Pragma("unroll") for (int k = 0; k < 2; ++k) dst[m][k] = *(const LAS bf16x8*)(lds + PG8_SA(b, h) + aoff + m * 2048 + k * 1024); } while (0)
; #define PG8_LDB(dst, b, h) do { _Pragma("unroll") for (int n = 0; n < 2; ++n) _Pragma("unroll") for (int k = 0; k < 2; ++k) dst[n][k] = *(const LAS bf16x8*)(lds + PG8_SB(b, h) + boff + n * 2048 + k * 1024); } while (0)
; #define PG8_MMA(ai, bj, At, Bt) do { __builtin_amdgcn_s_setprio(1); _Pragma("unroll") for (int m = 0; m < 4; ++m) _Pragma("unroll") for (int n = 0; n < 2; ++n) _Pragma("unroll") for (int k = 0; k < 2; ++k) \
;         acc[ai][bj][m][n] = __builtin_amdgcn_mfma_f32_16x16x32_bf16(Bt[n][k], At[m][k], acc[ai][bj][m][n], 0, 0, 0); __builtin_amdgcn_s_setprio(0); } while (0)
; #define PG8_WAIT_V(n) asm volatile("s_waitcnt vmcnt(" #n ")" ::: "memory")
; #define PG8_WAIT_L(n) asm volatile("s_waitcnt lgkmcnt(" #n ")" ::: "memory")
; #define PG8_BAR __builtin_amdgcn_s_barrier()
; #define PG8_SCHED __builtin_amdgcn_sched_barrier(0)
; template <class Epi, class Sched, bool ALIGN_EPI = false, bool SP2 = false>
; __device__ __forceinline__ void gemm_phase(LAS unsigned char* lds, const Gemm g, const Sched& S, const Epi& E) {
;     ...
;             PG8_WAIT_V(8); PG8_WAIT_L(0); PG8_BAR; PG8_MMA(1, 0, At, B0); PG8_MMA(1, 1, At, B1); PG8_BAR; PG8_SCHED;
;             PG8_LDB(B0, 1, 0); PG8_LDB(B1, 1, 1); PG8_SCHED; PG8_LDA(At, 1, 0); PG8_STAGE(PG8_SA(0, 1), a2 + hstep, voffA);
;             PG8_WAIT_V(8); PG8_WAIT_L(0); PG8_BAR; PG8_MMA(0, 0, At, B0); PG8_MMA(0, 1, At, B1); PG8_BAR; PG8_SCHED;
	s_setprio 1
	s_waitcnt lgkmcnt(0)
	v_mfma_f32_16x16x32_bf16 v[62:65], v[130:133], v[182:185], 0
	v_mfma_f32_16x16x32_bf16 v[58:61], v[138:141], v[182:185], 0
	v_mfma_f32_16x16x32_bf16 v[46:49], v[130:133], v[202:205], 0
	v_mfma_f32_16x16x32_bf16 v[42:45], v[138:141], v[202:205], 0
	v_mfma_f32_16x16x32_bf16 v[30:33], v[130:133], v[210:213], 0
	v_mfma_f32_16x16x32_bf16 v[26:29], v[138:141], v[210:213], 0
	v_mfma_f32_16x16x32_bf16 v[14:17], v[130:133], v[218:221], 0
	v_mfma_f32_16x16x32_bf16 v[10:13], v[138:141], v[218:221], 0
	v_mfma_f32_16x16x32_bf16 v[62:65], v[134:137], v[186:189], v[62:65]
	v_mfma_f32_16x16x32_bf16 v[58:61], v[142:145], v[186:189], v[58:61]
	v_mfma_f32_16x16x32_bf16 v[46:49], v[134:137], v[206:209], v[46:49]
	v_mfma_f32_16x16x32_bf16 v[42:45], v[142:145], v[206:209], v[42:45]
	v_mfma_f32_16x16x32_bf16 v[30:33], v[134:137], v[214:217], v[30:33]
	v_mfma_f32_16x16x32_bf16 v[26:29], v[142:145], v[214:217], v[26:29]
	v_mfma_f32_16x16x32_bf16 v[14:17], v[134:137], v[222:225], v[14:17]
	v_mfma_f32_16x16x32_bf16 v[10:13], v[142:145], v[222:225], v[10:13]
	s_setprio 0
	s_setprio 1
	v_mfma_f32_16x16x32_bf16 v[54:57], v[166:169], v[182:185], 0
	v_mfma_f32_16x16x32_bf16 v[50:53], v[174:177], v[182:185], 0
	v_mfma_f32_16x16x32_bf16 v[38:41], v[166:169], v[202:205], 0
	v_mfma_f32_16x16x32_bf16 v[34:37], v[174:177], v[202:205], 0
	v_mfma_f32_16x16x32_bf16 v[22:25], v[166:169], v[210:213], 0
	v_mfma_f32_16x16x32_bf16 v[18:21], v[174:177], v[210:213], 0
	v_mfma_f32_16x16x32_bf16 v[6:9], v[166:169], v[218:221], 0
	v_mfma_f32_16x16x32_bf16 v[2:5], v[174:177], v[218:221], 0
	v_mfma_f32_16x16x32_bf16 v[54:57], v[170:173], v[186:189], v[54:57]
	v_mfma_f32_16x16x32_bf16 v[50:53], v[178:181], v[186:189], v[50:53]
	v_mfma_f32_16x16x32_bf16 v[38:41], v[170:173], v[206:209], v[38:41]
	v_mfma_f32_16x16x32_bf16 v[34:37], v[178:181], v[206:209], v[34:37]
	v_mfma_f32_16x16x32_bf16 v[22:25], v[170:173], v[214:217], v[22:25]
	v_mfma_f32_16x16x32_bf16 v[18:21], v[178:181], v[214:217], v[18:21]
	v_mfma_f32_16x16x32_bf16 v[6:9], v[170:173], v[222:225], v[6:9]
	v_mfma_f32_16x16x32_bf16 v[2:5], v[178:181], v[222:225], v[2:5]
	s_setprio 0
	s_barrier
	s_add_i32 s54, 0, 0x18000
	s_add_i32 s55, 0, 0x1c000
	v_add_u32_e32 v142, s54, v1
	v_add_u32_e32 v154, s55, v1
	ds_read_b128 v[130:133], v142
	ds_read_b128 v[134:137], v142 offset:1024
	ds_read_b128 v[138:141], v142 offset:2048
	ds_read_b128 v[142:145], v142 offset:3072
	ds_read_b128 v[166:169], v154
	ds_read_b128 v[170:173], v154 offset:1024
	ds_read_b128 v[174:177], v154 offset:2048
	ds_read_b128 v[178:181], v154 offset:3072
	s_add_u32 s18, s46, 0x160000
	s_addc_u32 s19, s47, 0
	s_mov_b32 m0, s29
	v_lshl_add_u64 v[232:233], s[18:19], 0, v[146:147]
	ds_read_b128 v[182:185], v198 offset:32768
	ds_read_b128 v[186:189], v198 offset:33792
	ds_read_b128 v[202:205], v198 offset:34816
	ds_read_b128 v[206:209], v198 offset:35840
	ds_read_b128 v[210:213], v198 offset:36864
	ds_read_b128 v[214:217], v198 offset:37888
	ds_read_b128 v[218:221], v198 offset:38912
	ds_read_b128 v[222:225], v198 offset:39936
	global_load_lds_dwordx4 v[232:233], off
	v_lshl_add_u64 v[232:233], s[18:19], 0, v[150:151]
	s_mov_b32 m0, s30
	s_nop 0
	global_load_lds_dwordx4 v[232:233], off
	s_waitcnt vmcnt(8)
	s_waitcnt lgkmcnt(0)
	s_barrier
	s_setprio 1
	s_waitcnt lgkmcnt(0)
	v_mfma_f32_16x16x32_bf16 v[126:129], v[130:133], v[182:185], v[126:129]
	v_mfma_f32_16x16x32_bf16 v[122:125], v[138:141], v[182:185], v[122:125]
	v_mfma_f32_16x16x32_bf16 v[110:113], v[130:133], v[202:205], v[110:113]
	v_mfma_f32_16x16x32_bf16 v[106:109], v[138:141], v[202:205], v[106:109]
	v_mfma_f32_16x16x32_bf16 v[94:97], v[130:133], v[210:213], v[94:97]
	v_mfma_f32_16x16x32_bf16 v[90:93], v[138:141], v[210:213], v[90:93]
	v_mfma_f32_16x16x32_bf16 v[78:81], v[130:133], v[218:221], v[78:81]
	v_mfma_f32_16x16x32_bf16 v[74:77], v[138:141], v[218:221], v[74:77]
	v_mfma_f32_16x16x32_bf16 v[126:129], v[134:137], v[186:189], v[126:129]
	v_mfma_f32_16x16x32_bf16 v[122:125], v[142:145], v[186:189], v[122:125]
	v_mfma_f32_16x16x32_bf16 v[110:113], v[134:137], v[206:209], v[110:113]
	v_mfma_f32_16x16x32_bf16 v[106:109], v[142:145], v[206:209], v[106:109]
	v_mfma_f32_16x16x32_bf16 v[94:97], v[134:137], v[214:217], v[94:97]
	v_mfma_f32_16x16x32_bf16 v[90:93], v[142:145], v[214:217], v[90:93]
	v_mfma_f32_16x16x32_bf16 v[78:81], v[134:137], v[222:225], v[78:81]
	v_mfma_f32_16x16x32_bf16 v[74:77], v[142:145], v[222:225], v[74:77]
	s_setprio 0
	s_setprio 1
	v_mfma_f32_16x16x32_bf16 v[118:121], v[166:169], v[182:185], v[118:121]
	v_mfma_f32_16x16x32_bf16 v[114:117], v[174:177], v[182:185], v[114:117]
	v_mfma_f32_16x16x32_bf16 v[102:105], v[166:169], v[202:205], v[102:105]
	v_mfma_f32_16x16x32_bf16 v[98:101], v[174:177], v[202:205], v[98:101]
	v_mfma_f32_16x16x32_bf16 v[86:89], v[166:169], v[210:213], v[86:89]
	v_mfma_f32_16x16x32_bf16 v[82:85], v[174:177], v[210:213], v[82:85]
	v_mfma_f32_16x16x32_bf16 v[70:73], v[166:169], v[218:221], v[70:73]
	v_mfma_f32_16x16x32_bf16 v[66:69], v[174:177], v[218:221], v[66:69]
	v_mfma_f32_16x16x32_bf16 v[118:121], v[170:173], v[186:189], v[118:121]
	v_mfma_f32_16x16x32_bf16 v[114:117], v[178:181], v[186:189], v[114:117]
	v_mfma_f32_16x16x32_bf16 v[102:105], v[170:173], v[206:209], v[102:105]
	v_mfma_f32_16x16x32_bf16 v[98:101], v[178:181], v[206:209], v[98:101]
	v_mfma_f32_16x16x32_bf16 v[86:89], v[170:173], v[214:217], v[86:89]
	v_mfma_f32_16x16x32_bf16 v[82:85], v[178:181], v[214:217], v[82:85]
	v_mfma_f32_16x16x32_bf16 v[70:73], v[170:173], v[222:225], v[70:73]
	v_mfma_f32_16x16x32_bf16 v[66:69], v[178:181], v[222:225], v[66:69]
	s_setprio 0
	s_barrier
; #define PG8_STAGE(bufoff, gbase, voff) do { _Pragma("unroll") for (int _i = 0; _i < 2; ++_i) \
;         __builtin_amdgcn_global_load_lds((const unsigned*)((const char*)(gbase) + (voff)[_i]), (LAS unsigned*)(lds + (bufoff) + ldsw + _i * 8192), 16, 0, 0); } while (0)
; #define PG8_LDA(dst, b, h) do { _Pragma("unroll") for (int m = 0; m < 4; ++m) _Pragma("unroll") for (int k = 0; k < 2; ++k) dst[m][k] = *(const LAS bf16x8*)(lds + PG8_SA(b, h) + aoff + m * 2048 + k * 1024); } while (0)
; #define PG8_MMA(ai, bj, At, Bt) do { __builtin_amdgcn_s_setprio(1); _Pragma("unroll") for (int m = 0; m < 4; ++m) _Pragma("unroll") for (int n = 0; n < 2; ++n) _Pragma("unroll") for (int k = 0; k < 2; ++k) \
;         acc[ai][bj][m][n] = __builtin_amdgcn_mfma_f32_16x16x32_bf16(Bt[n][k], At[m][k], acc[ai][bj][m][n], 0, 0, 0); __builtin_amdgcn_s_setprio(0); } while (0)
; #define PG8_WAIT_V(n) asm volatile("s_waitcnt vmcnt(" #n ")" ::: "memory")
; #define PG8_WAIT_L(n) asm volatile("s_waitcnt lgkmcnt(" #n ")" ::: "memory")
; #define PG8_BAR __builtin_amdgcn_s_barrier()
; #define PG8_SCHED __builtin_amdgcn_sched_barrier(0)
; template <class Epi, class Sched, bool ALIGN_EPI = false, bool SP2 = false>
; __device__ __forceinline__ void gemm_phase(LAS unsigned char* lds, const Gemm g, const Sched& S, const Epi& E) {
;     ...
;         for (int t = 0; t < nt; t += 2) {
;             const bool last = (t == nt - 2);
;     ...
;             PG8_LDA(At, 1, 1); PG8_STAGE(PG8_SB(1, 0), b3, voffB); PG8_STAGE(PG8_SB(1, 1), b3 + hstepB, voffB); PG8_STAGE(PG8_SA(1, 0), a3, voffA);
;             PG8_WAIT_V(8); PG8_WAIT_L(0); PG8_BAR; PG8_MMA(1, 0, At, B0); PG8_MMA(1, 1, At, B1); PG8_BAR; PG8_SCHED;
	s_add_i32 s18, s54, s26
	v_lshl_add_u64 v[190:191], v[190:191], 0, s[12:13]
	s_mov_b32 m0, s18
	ds_read_b128 v[182:185], v198 offset:49152
	ds_read_b128 v[186:189], v198 offset:50176
	ds_read_b128 v[202:205], v198 offset:51200
	ds_read_b128 v[206:209], v198 offset:52224
	ds_read_b128 v[210:213], v198 offset:53248
	ds_read_b128 v[214:217], v198 offset:54272
	ds_read_b128 v[218:221], v198 offset:55296
	ds_read_b128 v[222:225], v198 offset:56320
	global_load_lds_dwordx4 v[190:191], off
	s_add_i32 m0, s18, 0x2000
	s_add_u32 s18, s22, 0x58080
	v_lshl_add_u64 v[190:191], v[226:227], 0, s[12:13]
	s_addc_u32 s19, s23, 0
	s_add_i32 s22, s55, s26
	global_load_lds_dwordx4 v[190:191], off
	v_lshl_add_u64 v[190:191], s[18:19], 0, v[148:149]
	s_mov_b32 m0, s22
	s_nop 0
	global_load_lds_dwordx4 v[190:191], off
	v_lshl_add_u64 v[190:191], s[18:19], 0, v[152:153]
	s_add_i32 m0, s22, 0x2000
	s_nop 0
	global_load_lds_dwordx4 v[190:191], off
	v_lshl_add_u64 v[190:191], v[228:229], 0, s[12:13]
	s_mov_b32 m0, s37
	s_nop 0
	global_load_lds_dwordx4 v[190:191], off
	v_lshl_add_u64 v[190:191], v[230:231], 0, s[12:13]
	s_mov_b32 m0, s48
	s_nop 0
	global_load_lds_dwordx4 v[190:191], off
	s_waitcnt vmcnt(8)
	s_waitcnt lgkmcnt(0)
	s_barrier
	s_setprio 1
	s_waitcnt lgkmcnt(0)
	v_mfma_f32_16x16x32_bf16 v[62:65], v[130:133], v[182:185], v[62:65]
	v_mfma_f32_16x16x32_bf16 v[58:61], v[138:141], v[182:185], v[58:61]
	v_mfma_f32_16x16x32_bf16 v[46:49], v[130:133], v[202:205], v[46:49]
	v_mfma_f32_16x16x32_bf16 v[42:45], v[138:141], v[202:205], v[42:45]
	v_mfma_f32_16x16x32_bf16 v[30:33], v[130:133], v[210:213], v[30:33]
	v_mfma_f32_16x16x32_bf16 v[26:29], v[138:141], v[210:213], v[26:29]
	v_mfma_f32_16x16x32_bf16 v[14:17], v[130:133], v[218:221], v[14:17]
	v_mfma_f32_16x16x32_bf16 v[10:13], v[138:141], v[218:221], v[10:13]
	v_mfma_f32_16x16x32_bf16 v[62:65], v[134:137], v[186:189], v[62:65]
	v_mfma_f32_16x16x32_bf16 v[58:61], v[142:145], v[186:189], v[58:61]
	v_mfma_f32_16x16x32_bf16 v[46:49], v[134:137], v[206:209], v[46:49]
	v_mfma_f32_16x16x32_bf16 v[42:45], v[142:145], v[206:209], v[42:45]
	v_mfma_f32_16x16x32_bf16 v[30:33], v[134:137], v[214:217], v[30:33]
	v_mfma_f32_16x16x32_bf16 v[26:29], v[142:145], v[214:217], v[26:29]
	v_mfma_f32_16x16x32_bf16 v[14:17], v[134:137], v[222:225], v[14:17]
	v_mfma_f32_16x16x32_bf16 v[10:13], v[142:145], v[222:225], v[10:13]
	s_setprio 0
	s_setprio 1
	v_mfma_f32_16x16x32_bf16 v[54:57], v[166:169], v[182:185], v[54:57]
	v_mfma_f32_16x16x32_bf16 v[50:53], v[174:177], v[182:185], v[50:53]
	v_mfma_f32_16x16x32_bf16 v[38:41], v[166:169], v[202:205], v[38:41]
	v_mfma_f32_16x16x32_bf16 v[34:37], v[174:177], v[202:205], v[34:37]
	v_mfma_f32_16x16x32_bf16 v[22:25], v[166:169], v[210:213], v[22:25]
	v_mfma_f32_16x16x32_bf16 v[18:21], v[174:177], v[210:213], v[18:21]
	v_mfma_f32_16x16x32_bf16 v[6:9], v[166:169], v[218:221], v[6:9]
	v_mfma_f32_16x16x32_bf16 v[2:5], v[174:177], v[218:221], v[2:5]
	v_mfma_f32_16x16x32_bf16 v[54:57], v[170:173], v[186:189], v[54:57]
	v_mfma_f32_16x16x32_bf16 v[50:53], v[178:181], v[186:189], v[50:53]
	v_mfma_f32_16x16x32_bf16 v[38:41], v[170:173], v[206:209], v[38:41]
	v_mfma_f32_16x16x32_bf16 v[34:37], v[178:181], v[206:209], v[34:37]
	v_mfma_f32_16x16x32_bf16 v[22:25], v[170:173], v[214:217], v[22:25]
	v_mfma_f32_16x16x32_bf16 v[18:21], v[178:181], v[214:217], v[18:21]
	v_mfma_f32_16x16x32_bf16 v[6:9], v[170:173], v[222:225], v[6:9]
	v_mfma_f32_16x16x32_bf16 v[2:5], v[178:181], v[222:225], v[2:5]
	s_setprio 0
	s_barrier
	s_add_i32 s25, s25, 2
	s_add_u32 s5, s5, 0x100
	s_addc_u32 s24, s24, 0
	s_cmpk_lt_u32 s25, 0x56
	s_mov_b64 s[18:19], s[20:21]

;     __device__ bool next(int i, Unit& u) const { if (i != 0 || c >= 128) return false; const int t = c >> 2; u.pm = t & 3; u.pn = t >> 2; u.koff = koff_bytes; u.q = c & 3; return true; }
; #define PG8_STAGE(bufoff, gbase, voff) do { _Pragma("unroll") for (int _i = 0; _i < 2; ++_i) \
;         __builtin_amdgcn_global_load_lds((const unsigned*)((const char*)(gbase) + (voff)[_i]), (LAS unsigned*)(lds + (bufoff) + ldsw + _i * 8192), 16, 0, 0); } while (0)
; #define PG8_LDA(dst, b, h) do { _Pragma("unroll") for (int m = 0; m < 4; ++m) _Pragma("unroll") for (int k = 0; k < 2; ++k) dst[m][k] = *(const LAS bf16x8*)(lds + PG8_SA(b, h) + aoff + m * 2048 + k * 1024); } while (0)
; #define PG8_LDB(dst, b, h) do { _Pragma("unroll") for (int n = 0; n < 2; ++n) _Pragma("unroll") for (int k = 0; k < 2; ++k) dst[n][k] = *(const LAS bf16x8*)(lds + PG8_SB(b, h) + boff + n * 2048 + k * 1024); } while (0)
; template <class Epi, class Sched, bool ALIGN_EPI = false, bool SP2 = false>
; __device__ __forceinline__ void gemm_phase(LAS unsigned char* lds, const Gemm g, const Sched& S, const Epi& E) {
;     ...
;     Unit cur, nxt; int ui = 0;
;     if (!S.next(0, cur)) return;
;     f32x4 acc[2][2][4][2];
; #pragma unroll
;     for (int a = 0; a < 2; ++a)
; #pragma unroll
;         for (int b = 0; b < 2; ++b)
; #pragma unroll
;             for (int m = 0; m < 4; ++m)
; #pragma unroll
;                 for (int n = 0; n < 2; ++n) acc[a][b][m][n] = (f32x4){0.f, 0.f, 0.f, 0.f};
;     ...
;         const bool has_next = S.next(ui + 1, nxt);
;         const char* nA = has_next ? (const char*)g.A + (size_t)nxt.pm * tstep + nxt.koff : cA; const char* nB = has_next ? (const char*)g.Bt + (size_t)nxt.pn * tstep + nxt.koff : cB;
;         for (int t = 0; t < nt; t += 2) {
;             const bool last = (t == nt - 2);
;             const char* a1 = cA + (size_t)(t + 1) * kstep;
;             const char* a2 = last ? nA : cA + (size_t)(t + 2) * kstep; const char* b2 = last ? nB : cB + (size_t)(t + 2) * kstep;
;             const char* a3 = a2 + kstep; const char* b3 = b2 + kstep;
;             if (last && has_next) S.a_ready(nxt);
;             if constexpr (SP2) {
;             PG8_LDB(B0, 0, 0); PG8_LDB(B1, 0, 1); PG8_SCHED; PG8_LDA(At, 0, 0); PG8_STAGE(PG8_SA(1, 1), a1 + hstep, voffA);
;             PG8_WAIT_V(8); PG8_WAIT_L(0); PG8_BAR; PG8_MMA(0, 0, At, B0); PG8_MMA(0, 1, At, B1); PG8_BAR; PG8_SCHED;
.LBB0_2142:
	s_ashr_i32 s13, s12, 31
	v_cmp_lt_i64_e64 s[44:45], s[14:15], v[176:177]
	s_lshl_b64 s[14:15], s[12:13], 20
	s_add_u32 s14, s93, s14
	s_addc_u32 s15, s92, s15
	s_and_b64 s[16:17], s[44:45], exec
	s_cselect_b32 s3, s15, s23
	s_cselect_b32 s13, s14, s22
	s_ashr_i32 s11, s10, 31
	s_lshl_b64 s[16:17], s[10:11], 20
	v_readlane_b32 s24, v254, 58
	v_readlane_b32 s25, v254, 59
	s_add_u32 s16, s24, s16
	s_addc_u32 s17, s25, s17
	s_and_b64 s[24:25], s[44:45], exec
	s_cselect_b32 s11, s17, s21
	s_cselect_b32 s19, s16, s20
	s_add_u32 s24, s20, 0x100
	s_addc_u32 s25, s21, 0
	s_add_u32 s20, s22, 0x80080
	s_addc_u32 s21, s23, 0
	s_mov_b32 s34, -2
	s_waitcnt vmcnt(0)
	ds_read_b128 v[34:37], v202
	ds_read_b128 v[38:41], v202 offset:1024
	ds_read_b128 v[42:45], v202 offset:2048
	ds_read_b128 v[46:49], v202 offset:3072
	ds_read_b128 v[98:101], v203
	ds_read_b128 v[102:105], v203 offset:1024
	ds_read_b128 v[106:109], v203 offset:2048
	ds_read_b128 v[110:113], v203 offset:3072
	s_add_u32 s22, s20, 0xfff80080
	s_addc_u32 s23, s21, -1
	s_cmp_eq_u32 s34, 28
	s_cselect_b32 s37, s3, s23
	s_cselect_b32 s36, s13, s22
	s_cselect_b32 s23, s11, s25
	s_cselect_b32 s22, s19, s24
	v_lshl_add_u64 v[182:183], s[20:21], 0, v[174:175]
	s_add_i32 m0, s28, 0xc000
	ds_read_b128 v[210:213], v204
	ds_read_b128 v[214:217], v204 offset:1024
	ds_read_b128 v[218:221], v204 offset:2048
	ds_read_b128 v[222:225], v204 offset:3072
	ds_read_b128 v[226:229], v204 offset:4096
	ds_read_b128 v[230:233], v204 offset:5120
	ds_read_b128 v[234:237], v204 offset:6144
	ds_read_b128 v[238:241], v204 offset:7168
	global_load_lds_dwordx4 v[182:183], off
	v_lshl_add_u64 v[182:183], s[20:21], 0, v[172:173]
	s_add_i32 m0, s28, 0xe000
	s_nop 0
	global_load_lds_dwordx4 v[182:183], off
	s_waitcnt lgkmcnt(0)
	s_barrier
	s_setprio 1
	s_waitcnt lgkmcnt(0)
	v_mfma_f32_16x16x32_bf16 v[158:161], v[34:37], v[210:213], 0
	v_mfma_f32_16x16x32_bf16 v[154:157], v[42:45], v[210:213], 0
	v_mfma_f32_16x16x32_bf16 v[142:145], v[34:37], v[218:221], 0
	v_mfma_f32_16x16x32_bf16 v[138:141], v[42:45], v[218:221], 0
	v_mfma_f32_16x16x32_bf16 v[126:129], v[34:37], v[226:229], 0
	v_mfma_f32_16x16x32_bf16 v[122:125], v[42:45], v[226:229], 0
	v_mfma_f32_16x16x32_bf16 v[94:97], v[34:37], v[234:237], 0
	v_mfma_f32_16x16x32_bf16 v[90:93], v[42:45], v[234:237], 0
	v_mfma_f32_16x16x32_bf16 v[158:161], v[38:41], v[214:217], v[158:161]
	v_mfma_f32_16x16x32_bf16 v[154:157], v[46:49], v[214:217], v[154:157]
	v_mfma_f32_16x16x32_bf16 v[142:145], v[38:41], v[222:225], v[142:145]
	v_mfma_f32_16x16x32_bf16 v[138:141], v[46:49], v[222:225], v[138:141]
	v_mfma_f32_16x16x32_bf16 v[126:129], v[38:41], v[230:233], v[126:129]
	v_mfma_f32_16x16x32_bf16 v[122:125], v[46:49], v[230:233], v[122:125]
	v_mfma_f32_16x16x32_bf16 v[94:97], v[38:41], v[238:241], v[94:97]
	v_mfma_f32_16x16x32_bf16 v[90:93], v[46:49], v[238:241], v[90:93]
	s_setprio 0
	s_setprio 1
	v_mfma_f32_16x16x32_bf16 v[150:153], v[98:101], v[210:213], 0
	v_mfma_f32_16x16x32_bf16 v[146:149], v[106:109], v[210:213], 0
	v_mfma_f32_16x16x32_bf16 v[134:137], v[98:101], v[218:221], 0
	v_mfma_f32_16x16x32_bf16 v[130:133], v[106:109], v[218:221], 0
	v_mfma_f32_16x16x32_bf16 v[118:121], v[98:101], v[226:229], 0
	v_mfma_f32_16x16x32_bf16 v[114:117], v[106:109], v[226:229], 0
	v_mfma_f32_16x16x32_bf16 v[86:89], v[98:101], v[234:237], 0
	v_mfma_f32_16x16x32_bf16 v[82:85], v[106:109], v[234:237], 0
	v_mfma_f32_16x16x32_bf16 v[150:153], v[102:105], v[214:217], v[150:153]
	v_mfma_f32_16x16x32_bf16 v[146:149], v[110:113], v[214:217], v[146:149]
	v_mfma_f32_16x16x32_bf16 v[134:137], v[102:105], v[222:225], v[134:137]
	v_mfma_f32_16x16x32_bf16 v[130:133], v[110:113], v[222:225], v[130:133]
	v_mfma_f32_16x16x32_bf16 v[118:121], v[102:105], v[230:233], v[118:121]
	v_mfma_f32_16x16x32_bf16 v[114:117], v[110:113], v[230:233], v[114:117]
	v_mfma_f32_16x16x32_bf16 v[86:89], v[102:105], v[238:241], v[86:89]
	v_mfma_f32_16x16x32_bf16 v[82:85], v[110:113], v[238:241], v[82:85]
	s_setprio 0
	s_barrier
	s_add_i32 s35, s56, s27
	v_lshl_add_u64 v[182:183], s[22:23], 0, v[164:165]
	s_mov_b32 m0, s35
	ds_read_b128 v[210:213], v204 offset:16384
	ds_read_b128 v[214:217], v204 offset:17408
	ds_read_b128 v[218:221], v204 offset:18432
	ds_read_b128 v[222:225], v204 offset:19456
	ds_read_b128 v[226:229], v204 offset:20480
	ds_read_b128 v[230:233], v204 offset:21504
	ds_read_b128 v[234:237], v204 offset:22528
	ds_read_b128 v[238:241], v204 offset:23552
	global_load_lds_dwordx4 v[182:183], off
	s_add_i32 m0, s35, 0x2000
	s_add_u32 s46, s22, 0x20000
	v_lshl_add_u64 v[242:243], s[22:23], 0, v[168:169]
	s_addc_u32 s47, s23, 0
	s_add_i32 s35, s57, s27
	global_load_lds_dwordx4 v[242:243], off
	v_lshl_add_u64 v[244:245], s[46:47], 0, v[164:165]
	s_mov_b32 m0, s35
	v_lshl_add_u64 v[246:247], s[36:37], 0, v[166:167]
	global_load_lds_dwordx4 v[244:245], off
	v_lshl_add_u64 v[244:245], s[46:47], 0, v[168:169]
	s_add_i32 m0, s35, 0x2000
	s_nop 0
	global_load_lds_dwordx4 v[244:245], off
	v_lshl_add_u64 v[244:245], s[36:37], 0, v[162:163]
	s_mov_b32 m0, s28
	s_nop 0
	global_load_lds_dwordx4 v[244:245], off
	s_mov_b32 m0, s29
	s_nop 0
	global_load_lds_dwordx4 v[246:247], off
	s_waitcnt vmcnt(8)
	s_waitcnt lgkmcnt(0)
	s_barrier
; #define PG8_STAGE(bufoff, gbase, voff) do { _Pragma("unroll") for (int _i = 0; _i < 2; ++_i) \
;         __builtin_amdgcn_global_load_lds((const unsigned*)((const char*)(gbase) + (voff)[_i]), (LAS unsigned*)(lds + (bufoff) + ldsw + _i * 8192), 16, 0, 0); } while (0)
; #define PG8_LDA(dst, b, h) do { _Pragma("unroll") for (int m = 0; m < 4; ++m) _Pragma("unroll") for (int k = 0; k < 2; ++k) dst[m][k] = *(const LAS bf16x8*)(lds + PG8_SA(b, h) + aoff + m * 2048 + k * 1024); } while (0)
; #define PG8_LDB(dst, b, h) do { _Pragma("unroll") for (int n = 0; n < 2; ++n) _Pragma("unroll") for (int k = 0; k < 2; ++k) dst[n][k] = *(const LAS bf16x8*)(lds + PG8_SB(b, h) + boff + n * 2048 + k * 1024); } while (0)
; #define PG8_MMA(ai, bj, At, Bt) do { __builtin_amdgcn_s_setprio(1); _Pragma("unroll") for (int m = 0; m < 4; ++m) _Pragma("unroll") for (int n = 0; n < 2; ++n) _Pragma("unroll") for (int k = 0; k < 2; ++k) \
;         acc[ai][bj][m][n] = __builtin_amdgcn_mfma_f32_16x16x32_bf16(Bt[n][k], At[m][k], acc[ai][bj][m][n], 0, 0, 0); __builtin_amdgcn_s_setprio(0); } while (0)
; #define PG8_WAIT_V(n) asm volatile("s_waitcnt vmcnt(" #n ")" ::: "memory")
; #define PG8_WAIT_L(n) asm volatile("s_waitcnt lgkmcnt(" #n ")" ::: "memory")
; #define PG8_BAR __builtin_amdgcn_s_barrier()
; #define PG8_SCHED __builtin_amdgcn_sched_barrier(0)
; template <class Epi, class Sched, bool ALIGN_EPI = false, bool SP2 = false>
; __device__ __forceinline__ void gemm_phase(LAS unsigned char* lds, const Gemm g, const Sched& S, const Epi& E) {
;     ...
;             PG8_WAIT_V(8); PG8_WAIT_L(0); PG8_BAR; PG8_MMA(1, 0, At, B0); PG8_MMA(1, 1, At, B1); PG8_BAR; PG8_SCHED;
;             PG8_LDB(B0, 1, 0); PG8_LDB(B1, 1, 1); PG8_SCHED; PG8_LDA(At, 1, 0); PG8_STAGE(PG8_SA(0, 1), a2 + hstep, voffA);
;             PG8_WAIT_V(8); PG8_WAIT_L(0); PG8_BAR; PG8_MMA(0, 0, At, B0); PG8_MMA(0, 1, At, B1); PG8_BAR; PG8_SCHED;
	s_setprio 1
	s_waitcnt lgkmcnt(0)
	v_mfma_f32_16x16x32_bf16 v[78:81], v[34:37], v[210:213], 0
	v_mfma_f32_16x16x32_bf16 v[74:77], v[42:45], v[210:213], 0
	v_mfma_f32_16x16x32_bf16 v[62:65], v[34:37], v[218:221], 0
	v_mfma_f32_16x16x32_bf16 v[58:61], v[42:45], v[218:221], 0
	v_mfma_f32_16x16x32_bf16 v[30:33], v[34:37], v[226:229], 0
	v_mfma_f32_16x16x32_bf16 v[26:29], v[42:45], v[226:229], 0
	v_mfma_f32_16x16x32_bf16 v[14:17], v[34:37], v[234:237], 0
	v_mfma_f32_16x16x32_bf16 v[10:13], v[42:45], v[234:237], 0
	v_mfma_f32_16x16x32_bf16 v[78:81], v[38:41], v[214:217], v[78:81]
	v_mfma_f32_16x16x32_bf16 v[74:77], v[46:49], v[214:217], v[74:77]
	v_mfma_f32_16x16x32_bf16 v[62:65], v[38:41], v[222:225], v[62:65]
	v_mfma_f32_16x16x32_bf16 v[58:61], v[46:49], v[222:225], v[58:61]
	v_mfma_f32_16x16x32_bf16 v[30:33], v[38:41], v[230:233], v[30:33]
	v_mfma_f32_16x16x32_bf16 v[26:29], v[46:49], v[230:233], v[26:29]
	v_mfma_f32_16x16x32_bf16 v[14:17], v[38:41], v[238:241], v[14:17]
	v_mfma_f32_16x16x32_bf16 v[10:13], v[46:49], v[238:241], v[10:13]
	s_setprio 0
	s_setprio 1
	v_mfma_f32_16x16x32_bf16 v[22:25], v[98:101], v[226:229], 0
	v_mfma_f32_16x16x32_bf16 v[18:21], v[106:109], v[226:229], 0
	v_mfma_f32_16x16x32_bf16 v[6:9], v[98:101], v[234:237], 0
	v_mfma_f32_16x16x32_bf16 v[2:5], v[106:109], v[234:237], 0
	v_mfma_f32_16x16x32_bf16 v[34:37], v[98:101], v[210:213], 0
	v_mfma_f32_16x16x32_bf16 v[38:41], v[106:109], v[210:213], 0
	v_mfma_f32_16x16x32_bf16 v[42:45], v[98:101], v[218:221], 0
	v_mfma_f32_16x16x32_bf16 v[46:49], v[106:109], v[218:221], 0
	v_mfma_f32_16x16x32_bf16 v[22:25], v[102:105], v[230:233], v[22:25]
	v_mfma_f32_16x16x32_bf16 v[18:21], v[110:113], v[230:233], v[18:21]
	v_mfma_f32_16x16x32_bf16 v[6:9], v[102:105], v[238:241], v[6:9]
	v_mfma_f32_16x16x32_bf16 v[2:5], v[110:113], v[238:241], v[2:5]
	v_mfma_f32_16x16x32_bf16 v[34:37], v[102:105], v[214:217], v[34:37]
	v_mfma_f32_16x16x32_bf16 v[38:41], v[110:113], v[214:217], v[38:41]
	v_mfma_f32_16x16x32_bf16 v[42:45], v[102:105], v[222:225], v[42:45]
	v_mfma_f32_16x16x32_bf16 v[46:49], v[110:113], v[222:225], v[46:49]
	s_setprio 0
	s_barrier
	s_add_i32 s35, 0, 0x18000
	s_add_i32 s46, 0, 0x1c000
	v_add_u32_e32 v70, s35, v185
	v_add_u32_e32 v110, s46, v185
	ds_read_b128 v[50:53], v70
	ds_read_b128 v[54:57], v70 offset:1024
	ds_read_b128 v[66:69], v70 offset:2048
	ds_read_b128 v[70:73], v70 offset:3072
	ds_read_b128 v[98:101], v110
	ds_read_b128 v[102:105], v110 offset:1024
	ds_read_b128 v[106:109], v110 offset:2048
	ds_read_b128 v[110:113], v110 offset:3072
	s_add_u32 s36, s36, 0x80000
	s_addc_u32 s37, s37, 0
	s_mov_b32 m0, s30
	v_lshl_add_u64 v[248:249], s[36:37], 0, v[162:163]
	ds_read_b128 v[210:213], v204 offset:32768
	ds_read_b128 v[214:217], v204 offset:33792
	ds_read_b128 v[218:221], v204 offset:34816
	ds_read_b128 v[222:225], v204 offset:35840
	ds_read_b128 v[226:229], v204 offset:36864
	ds_read_b128 v[230:233], v204 offset:37888
	ds_read_b128 v[234:237], v204 offset:38912
	ds_read_b128 v[238:241], v204 offset:39936
	global_load_lds_dwordx4 v[248:249], off
	v_lshl_add_u64 v[248:249], s[36:37], 0, v[166:167]
	s_mov_b32 m0, s31
	s_nop 0
	global_load_lds_dwordx4 v[248:249], off
	s_waitcnt vmcnt(8)
	s_waitcnt lgkmcnt(0)
	s_barrier
	s_setprio 1
	s_waitcnt lgkmcnt(0)
	v_mfma_f32_16x16x32_bf16 v[158:161], v[50:53], v[210:213], v[158:161]
	v_mfma_f32_16x16x32_bf16 v[154:157], v[66:69], v[210:213], v[154:157]
	v_mfma_f32_16x16x32_bf16 v[142:145], v[50:53], v[218:221], v[142:145]
	v_mfma_f32_16x16x32_bf16 v[138:141], v[66:69], v[218:221], v[138:141]
	v_mfma_f32_16x16x32_bf16 v[126:129], v[50:53], v[226:229], v[126:129]
	v_mfma_f32_16x16x32_bf16 v[122:125], v[66:69], v[226:229], v[122:125]
	v_mfma_f32_16x16x32_bf16 v[94:97], v[50:53], v[234:237], v[94:97]
	v_mfma_f32_16x16x32_bf16 v[90:93], v[66:69], v[234:237], v[90:93]
	v_mfma_f32_16x16x32_bf16 v[158:161], v[54:57], v[214:217], v[158:161]
	v_mfma_f32_16x16x32_bf16 v[154:157], v[70:73], v[214:217], v[154:157]
	v_mfma_f32_16x16x32_bf16 v[142:145], v[54:57], v[222:225], v[142:145]
	v_mfma_f32_16x16x32_bf16 v[138:141], v[70:73], v[222:225], v[138:141]
	v_mfma_f32_16x16x32_bf16 v[126:129], v[54:57], v[230:233], v[126:129]
	v_mfma_f32_16x16x32_bf16 v[122:125], v[70:73], v[230:233], v[122:125]
	v_mfma_f32_16x16x32_bf16 v[94:97], v[54:57], v[238:241], v[94:97]
	v_mfma_f32_16x16x32_bf16 v[90:93], v[70:73], v[238:241], v[90:93]
	s_setprio 0
	s_setprio 1
	v_mfma_f32_16x16x32_bf16 v[150:153], v[98:101], v[210:213], v[150:153]
	v_mfma_f32_16x16x32_bf16 v[146:149], v[106:109], v[210:213], v[146:149]
	v_mfma_f32_16x16x32_bf16 v[134:137], v[98:101], v[218:221], v[134:137]
	v_mfma_f32_16x16x32_bf16 v[130:133], v[106:109], v[218:221], v[130:133]
	v_mfma_f32_16x16x32_bf16 v[118:121], v[98:101], v[226:229], v[118:121]
	v_mfma_f32_16x16x32_bf16 v[114:117], v[106:109], v[226:229], v[114:117]
	v_mfma_f32_16x16x32_bf16 v[86:89], v[98:101], v[234:237], v[86:89]
	v_mfma_f32_16x16x32_bf16 v[82:85], v[106:109], v[234:237], v[82:85]
	v_mfma_f32_16x16x32_bf16 v[150:153], v[102:105], v[214:217], v[150:153]
	v_mfma_f32_16x16x32_bf16 v[146:149], v[110:113], v[214:217], v[146:149]
	v_mfma_f32_16x16x32_bf16 v[134:137], v[102:105], v[222:225], v[134:137]
	v_mfma_f32_16x16x32_bf16 v[130:133], v[110:113], v[222:225], v[130:133]
	v_mfma_f32_16x16x32_bf16 v[118:121], v[102:105], v[230:233], v[118:121]
	v_mfma_f32_16x16x32_bf16 v[114:117], v[110:113], v[230:233], v[114:117]
	v_mfma_f32_16x16x32_bf16 v[86:89], v[102:105], v[238:241], v[86:89]
	v_mfma_f32_16x16x32_bf16 v[82:85], v[110:113], v[238:241], v[82:85]
	s_setprio 0
	s_barrier
; #define PG8_STAGE(bufoff, gbase, voff) do { _Pragma("unroll") for (int _i = 0; _i < 2; ++_i) \
;         __builtin_amdgcn_global_load_lds((const unsigned*)((const char*)(gbase) + (voff)[_i]), (LAS unsigned*)(lds + (bufoff) + ldsw + _i * 8192), 16, 0, 0); } while (0)
; #define PG8_LDA(dst, b, h) do { _Pragma("unroll") for (int m = 0; m < 4; ++m) _Pragma("unroll") for (int k = 0; k < 2; ++k) dst[m][k] = *(const LAS bf16x8*)(lds + PG8_SA(b, h) + aoff + m * 2048 + k * 1024); } while (0)
; #define PG8_MMA(ai, bj, At, Bt) do { __builtin_amdgcn_s_setprio(1); _Pragma("unroll") for (int m = 0; m < 4; ++m) _Pragma("unroll") for (int n = 0; n < 2; ++n) _Pragma("unroll") for (int k = 0; k < 2; ++k) \
;         acc[ai][bj][m][n] = __builtin_amdgcn_mfma_f32_16x16x32_bf16(Bt[n][k], At[m][k], acc[ai][bj][m][n], 0, 0, 0); __builtin_amdgcn_s_setprio(0); } while (0)
; #define PG8_WAIT_V(n) asm volatile("s_waitcnt vmcnt(" #n ")" ::: "memory")
; #define PG8_WAIT_L(n) asm volatile("s_waitcnt lgkmcnt(" #n ")" ::: "memory")
; #define PG8_BAR __builtin_amdgcn_s_barrier()
; #define PG8_SCHED __builtin_amdgcn_sched_barrier(0)
; template <class Epi, class Sched, bool ALIGN_EPI = false, bool SP2 = false>
; __device__ __forceinline__ void gemm_phase(LAS unsigned char* lds, const Gemm g, const Sched& S, const Epi& E) {
;     ...
;         for (int t = 0; t < nt; t += 2) {
;             const bool last = (t == nt - 2);
;     ...
;             PG8_LDA(At, 1, 1); PG8_STAGE(PG8_SB(1, 0), b3, voffB); PG8_STAGE(PG8_SB(1, 1), b3 + hstepB, voffB); PG8_STAGE(PG8_SA(1, 0), a3, voffA);
;             PG8_WAIT_V(8); PG8_WAIT_L(0); PG8_BAR; PG8_MMA(1, 0, At, B0); PG8_MMA(1, 1, At, B1); PG8_BAR; PG8_SCHED;
	s_add_i32 s35, s35, s27
	v_lshl_add_u64 v[182:183], v[182:183], 0, s[4:5]
	s_mov_b32 m0, s35
	ds_read_b128 v[210:213], v204 offset:49152
	ds_read_b128 v[214:217], v204 offset:50176
	ds_read_b128 v[218:221], v204 offset:51200
	ds_read_b128 v[222:225], v204 offset:52224
	ds_read_b128 v[226:229], v204 offset:53248
	ds_read_b128 v[230:233], v204 offset:54272
	ds_read_b128 v[234:237], v204 offset:55296
	ds_read_b128 v[238:241], v204 offset:56320
	global_load_lds_dwordx4 v[182:183], off
	s_add_i32 m0, s35, 0x2000
	s_add_u32 s22, s22, 0x20080
	v_lshl_add_u64 v[182:183], v[242:243], 0, s[4:5]
	s_addc_u32 s23, s23, 0
	s_add_i32 s35, s46, s27
	global_load_lds_dwordx4 v[182:183], off
	v_lshl_add_u64 v[182:183], s[22:23], 0, v[164:165]
	s_mov_b32 m0, s35
	s_nop 0
	global_load_lds_dwordx4 v[182:183], off
	v_lshl_add_u64 v[182:183], s[22:23], 0, v[168:169]
	s_add_i32 m0, s35, 0x2000
	s_nop 0
	global_load_lds_dwordx4 v[182:183], off
	v_lshl_add_u64 v[182:183], v[244:245], 0, s[4:5]
	s_mov_b32 m0, s53
	s_nop 0
	global_load_lds_dwordx4 v[182:183], off
	v_lshl_add_u64 v[182:183], v[246:247], 0, s[4:5]
	s_mov_b32 m0, s54
	s_nop 0
	global_load_lds_dwordx4 v[182:183], off
	s_waitcnt vmcnt(8)
	s_waitcnt lgkmcnt(0)
	s_barrier
	s_setprio 1
	s_waitcnt lgkmcnt(0)
	v_mfma_f32_16x16x32_bf16 v[78:81], v[50:53], v[210:213], v[78:81]
	v_mfma_f32_16x16x32_bf16 v[74:77], v[66:69], v[210:213], v[74:77]
	v_mfma_f32_16x16x32_bf16 v[62:65], v[50:53], v[218:221], v[62:65]
	v_mfma_f32_16x16x32_bf16 v[58:61], v[66:69], v[218:221], v[58:61]
	v_mfma_f32_16x16x32_bf16 v[30:33], v[50:53], v[226:229], v[30:33]
	v_mfma_f32_16x16x32_bf16 v[26:29], v[66:69], v[226:229], v[26:29]
	v_mfma_f32_16x16x32_bf16 v[14:17], v[50:53], v[234:237], v[14:17]
	v_mfma_f32_16x16x32_bf16 v[10:13], v[66:69], v[234:237], v[10:13]
	v_mfma_f32_16x16x32_bf16 v[78:81], v[54:57], v[214:217], v[78:81]
	v_mfma_f32_16x16x32_bf16 v[74:77], v[70:73], v[214:217], v[74:77]
	v_mfma_f32_16x16x32_bf16 v[62:65], v[54:57], v[222:225], v[62:65]
	v_mfma_f32_16x16x32_bf16 v[58:61], v[70:73], v[222:225], v[58:61]
	v_mfma_f32_16x16x32_bf16 v[30:33], v[54:57], v[230:233], v[30:33]
	v_mfma_f32_16x16x32_bf16 v[26:29], v[70:73], v[230:233], v[26:29]
	v_mfma_f32_16x16x32_bf16 v[14:17], v[54:57], v[238:241], v[14:17]
	v_mfma_f32_16x16x32_bf16 v[10:13], v[70:73], v[238:241], v[10:13]
	s_setprio 0
	s_setprio 1
	v_mfma_f32_16x16x32_bf16 v[34:37], v[98:101], v[210:213], v[34:37]
	v_mfma_f32_16x16x32_bf16 v[70:73], v[102:105], v[214:217], v[34:37]
	v_mfma_f32_16x16x32_bf16 v[34:37], v[106:109], v[210:213], v[38:41]
	v_mfma_f32_16x16x32_bf16 v[66:69], v[110:113], v[214:217], v[34:37]
	v_mfma_f32_16x16x32_bf16 v[34:37], v[98:101], v[218:221], v[42:45]
	v_mfma_f32_16x16x32_bf16 v[54:57], v[102:105], v[222:225], v[34:37]
	v_mfma_f32_16x16x32_bf16 v[34:37], v[106:109], v[218:221], v[46:49]
	v_mfma_f32_16x16x32_bf16 v[22:25], v[98:101], v[226:229], v[22:25]
	v_mfma_f32_16x16x32_bf16 v[18:21], v[106:109], v[226:229], v[18:21]
	v_mfma_f32_16x16x32_bf16 v[6:9], v[98:101], v[234:237], v[6:9]
	v_mfma_f32_16x16x32_bf16 v[2:5], v[106:109], v[234:237], v[2:5]
	v_mfma_f32_16x16x32_bf16 v[50:53], v[110:113], v[222:225], v[34:37]
	v_mfma_f32_16x16x32_bf16 v[22:25], v[102:105], v[230:233], v[22:25]
	v_mfma_f32_16x16x32_bf16 v[18:21], v[110:113], v[230:233], v[18:21]
	v_mfma_f32_16x16x32_bf16 v[6:9], v[102:105], v[238:241], v[6:9]
	v_mfma_f32_16x16x32_bf16 v[2:5], v[110:113], v[238:241], v[2:5]
	s_setprio 0
	s_barrier
	s_add_i32 s34, s34, 2
	s_add_u32 s24, s24, 0x100
	s_addc_u32 s25, s25, 0
	s_add_u32 s20, s20, 0x100
	s_addc_u32 s21, s21, 0
	s_cmp_lt_u32 s34, 30

;     __device__ bool next(int i, Unit& u) const { if (i != 0 || c >= 128) return false; const int t = c >> 2; u.pm = t & 3; u.pn = t >> 2; u.koff = koff_bytes; u.q = c & 3; return true; }
; #define PG8_STAGE(bufoff, gbase, voff) do { _Pragma("unroll") for (int _i = 0; _i < 2; ++_i) \
;         __builtin_amdgcn_global_load_lds((const unsigned*)((const char*)(gbase) + (voff)[_i]), (LAS unsigned*)(lds + (bufoff) + ldsw + _i * 8192), 16, 0, 0); } while (0)
; #define PG8_LDA(dst, b, h) do { _Pragma("unroll") for (int m = 0; m < 4; ++m) _Pragma("unroll") for (int k = 0; k < 2; ++k) dst[m][k] = *(const LAS bf16x8*)(lds + PG8_SA(b, h) + aoff + m * 2048 + k * 1024); } while (0)
; #define PG8_LDB(dst, b, h) do { _Pragma("unroll") for (int n = 0; n < 2; ++n) _Pragma("unroll") for (int k = 0; k < 2; ++k) dst[n][k] = *(const LAS bf16x8*)(lds + PG8_SB(b, h) + boff + n * 2048 + k * 1024); } while (0)
; template <class Epi, class Sched, bool ALIGN_EPI = false, bool SP2 = false>
; __device__ __forceinline__ void gemm_phase(LAS unsigned char* lds, const Gemm g, const Sched& S, const Epi& E) {
;     ...
;     Unit cur, nxt; int ui = 0;
;     if (!S.next(0, cur)) return;
;     f32x4 acc[2][2][4][2];
; #pragma unroll
;     for (int a = 0; a < 2; ++a)
; #pragma unroll
;         for (int b = 0; b < 2; ++b)
; #pragma unroll
;             for (int m = 0; m < 4; ++m)
; #pragma unroll
;                 for (int n = 0; n < 2; ++n) acc[a][b][m][n] = (f32x4){0.f, 0.f, 0.f, 0.f};
;     ...
;         const bool has_next = S.next(ui + 1, nxt);
;         const char* nA = has_next ? (const char*)g.A + (size_t)nxt.pm * tstep + nxt.koff : cA; const char* nB = has_next ? (const char*)g.Bt + (size_t)nxt.pn * tstep + nxt.koff : cB;
;         for (int t = 0; t < nt; t += 2) {
;             const bool last = (t == nt - 2);
;             const char* a1 = cA + (size_t)(t + 1) * kstep;
;             const char* a2 = last ? nA : cA + (size_t)(t + 2) * kstep; const char* b2 = last ? nB : cB + (size_t)(t + 2) * kstep;
;             const char* a3 = a2 + kstep; const char* b3 = b2 + kstep;
;             if (last && has_next) S.a_ready(nxt);
;             if constexpr (SP2) {
;             PG8_LDB(B0, 0, 0); PG8_LDB(B1, 0, 1); PG8_SCHED; PG8_LDA(At, 0, 0); PG8_STAGE(PG8_SA(1, 1), a1 + hstep, voffA);
;             PG8_WAIT_V(8); PG8_WAIT_L(0); PG8_BAR; PG8_MMA(0, 0, At, B0); PG8_MMA(0, 1, At, B1); PG8_BAR; PG8_SCHED;
.LBB0_2765:
	s_ashr_i32 s15, s14, 31
	v_cmp_lt_i64_e64 s[42:43], s[16:17], v[170:171]
	s_lshl_b64 s[16:17], s[14:15], 20
	v_readlane_b32 s3, v252, 25
	s_add_u32 s16, s3, s16
	v_readlane_b32 s3, v252, 26
	s_addc_u32 s17, s3, s17
	s_and_b64 s[18:19], s[42:43], exec
	s_cselect_b32 s3, s17, s35
	s_cselect_b32 s15, s16, s34
	s_ashr_i32 s13, s12, 31
	s_lshl_b64 s[18:19], s[12:13], 20
	v_readlane_b32 s4, v254, 56
	v_readlane_b32 s5, v254, 57
	s_add_u32 s18, s4, s18
	s_addc_u32 s19, s5, s19
	s_and_b64 s[24:25], s[42:43], exec
	s_cselect_b32 s13, s19, s23
	s_cselect_b32 s21, s18, s22
	s_add_u32 s53, s22, 0x100
	s_addc_u32 s54, s23, 0
	s_add_u32 s22, s34, 0x80080
	s_mov_b64 s[70:71], s[58:59]
	s_addc_u32 s23, s35, 0
	s_mov_b32 s55, -2
	s_waitcnt vmcnt(0)
	ds_read_b128 v[50:53], v196
	ds_read_b128 v[54:57], v196 offset:1024
	ds_read_b128 v[138:141], v196 offset:2048
	ds_read_b128 v[142:145], v196 offset:3072
	ds_read_b128 v[146:149], v197
	ds_read_b128 v[150:153], v197 offset:1024
	ds_read_b128 v[174:177], v197 offset:2048
	ds_read_b128 v[178:181], v197 offset:3072
	s_add_u32 s24, s22, 0xfff80080
	s_addc_u32 s25, s23, -1
	s_cmp_eq_u32 s55, 28
	s_cselect_b32 s35, s3, s25
	s_cselect_b32 s34, s15, s24
	s_cselect_b32 s25, s13, s54
	s_cselect_b32 s24, s21, s53
	v_lshl_add_u64 v[190:191], s[22:23], 0, v[168:169]
	s_add_i32 m0, s28, 0xc000
	ds_read_b128 v[182:185], v198
	ds_read_b128 v[186:189], v198 offset:1024
	ds_read_b128 v[202:205], v198 offset:2048
	ds_read_b128 v[206:209], v198 offset:3072
	ds_read_b128 v[210:213], v198 offset:4096
	ds_read_b128 v[214:217], v198 offset:5120
	ds_read_b128 v[218:221], v198 offset:6144
	ds_read_b128 v[222:225], v198 offset:7168
	global_load_lds_dwordx4 v[190:191], off
	v_lshl_add_u64 v[190:191], s[22:23], 0, v[166:167]
	s_add_i32 m0, s28, 0xe000
	s_nop 0
	global_load_lds_dwordx4 v[190:191], off
	s_waitcnt lgkmcnt(0)
	s_barrier
	s_setprio 1
	s_waitcnt lgkmcnt(0)
	v_mfma_f32_16x16x32_bf16 v[134:137], v[50:53], v[182:185], 0
	v_mfma_f32_16x16x32_bf16 v[130:133], v[138:141], v[182:185], 0
	v_mfma_f32_16x16x32_bf16 v[118:121], v[50:53], v[202:205], 0
	v_mfma_f32_16x16x32_bf16 v[114:117], v[138:141], v[202:205], 0
	v_mfma_f32_16x16x32_bf16 v[102:105], v[50:53], v[210:213], 0
	v_mfma_f32_16x16x32_bf16 v[98:101], v[138:141], v[210:213], 0
	v_mfma_f32_16x16x32_bf16 v[86:89], v[50:53], v[218:221], 0
	v_mfma_f32_16x16x32_bf16 v[82:85], v[138:141], v[218:221], 0
	v_mfma_f32_16x16x32_bf16 v[134:137], v[54:57], v[186:189], v[134:137]
	v_mfma_f32_16x16x32_bf16 v[130:133], v[142:145], v[186:189], v[130:133]
	v_mfma_f32_16x16x32_bf16 v[118:121], v[54:57], v[206:209], v[118:121]
	v_mfma_f32_16x16x32_bf16 v[114:117], v[142:145], v[206:209], v[114:117]
	v_mfma_f32_16x16x32_bf16 v[102:105], v[54:57], v[214:217], v[102:105]
	v_mfma_f32_16x16x32_bf16 v[98:101], v[142:145], v[214:217], v[98:101]
	v_mfma_f32_16x16x32_bf16 v[86:89], v[54:57], v[222:225], v[86:89]
	v_mfma_f32_16x16x32_bf16 v[82:85], v[142:145], v[222:225], v[82:85]
	s_setprio 0
	s_setprio 1
	v_mfma_f32_16x16x32_bf16 v[126:129], v[146:149], v[182:185], 0
	v_mfma_f32_16x16x32_bf16 v[122:125], v[174:177], v[182:185], 0
	v_mfma_f32_16x16x32_bf16 v[110:113], v[146:149], v[202:205], 0
	v_mfma_f32_16x16x32_bf16 v[106:109], v[174:177], v[202:205], 0
	v_mfma_f32_16x16x32_bf16 v[94:97], v[146:149], v[210:213], 0
	v_mfma_f32_16x16x32_bf16 v[90:93], v[174:177], v[210:213], 0
	v_mfma_f32_16x16x32_bf16 v[78:81], v[146:149], v[218:221], 0
	v_mfma_f32_16x16x32_bf16 v[74:77], v[174:177], v[218:221], 0
	v_mfma_f32_16x16x32_bf16 v[126:129], v[150:153], v[186:189], v[126:129]
	v_mfma_f32_16x16x32_bf16 v[122:125], v[178:181], v[186:189], v[122:125]
	v_mfma_f32_16x16x32_bf16 v[110:113], v[150:153], v[206:209], v[110:113]
	v_mfma_f32_16x16x32_bf16 v[106:109], v[178:181], v[206:209], v[106:109]
	v_mfma_f32_16x16x32_bf16 v[94:97], v[150:153], v[214:217], v[94:97]
	v_mfma_f32_16x16x32_bf16 v[90:93], v[178:181], v[214:217], v[90:93]
	v_mfma_f32_16x16x32_bf16 v[78:81], v[150:153], v[222:225], v[78:81]
	v_mfma_f32_16x16x32_bf16 v[74:77], v[178:181], v[222:225], v[74:77]
	s_setprio 0
	s_barrier
	s_add_i32 s56, s51, s27
	v_lshl_add_u64 v[190:191], s[24:25], 0, v[156:157]
	s_mov_b32 m0, s56
	ds_read_b128 v[182:185], v198 offset:16384
	ds_read_b128 v[186:189], v198 offset:17408
	ds_read_b128 v[202:205], v198 offset:18432
	ds_read_b128 v[206:209], v198 offset:19456
	ds_read_b128 v[210:213], v198 offset:20480
	ds_read_b128 v[214:217], v198 offset:21504
	ds_read_b128 v[218:221], v198 offset:22528
	ds_read_b128 v[222:225], v198 offset:23552
	global_load_lds_dwordx4 v[190:191], off
	s_add_i32 m0, s56, 0x2000
	s_add_u32 s56, s24, 0x20000
	v_lshl_add_u64 v[226:227], s[24:25], 0, v[160:161]
	s_addc_u32 s57, s25, 0
	s_add_i32 s58, s52, s27
	global_load_lds_dwordx4 v[226:227], off
	v_lshl_add_u64 v[228:229], s[56:57], 0, v[156:157]
	s_mov_b32 m0, s58
	v_lshl_add_u64 v[230:231], s[34:35], 0, v[158:159]
	global_load_lds_dwordx4 v[228:229], off
	v_lshl_add_u64 v[228:229], s[56:57], 0, v[160:161]
	s_add_i32 m0, s58, 0x2000
	s_nop 0
	global_load_lds_dwordx4 v[228:229], off
	v_lshl_add_u64 v[228:229], s[34:35], 0, v[154:155]
	s_mov_b32 m0, s28
	s_nop 0
	global_load_lds_dwordx4 v[228:229], off
	s_mov_b32 m0, s29
	s_nop 0
	global_load_lds_dwordx4 v[230:231], off
	s_waitcnt vmcnt(8)
	s_waitcnt lgkmcnt(0)
	s_barrier
; #define PG8_STAGE(bufoff, gbase, voff) do { _Pragma("unroll") for (int _i = 0; _i < 2; ++_i) \
;         __builtin_amdgcn_global_load_lds((const unsigned*)((const char*)(gbase) + (voff)[_i]), (LAS unsigned*)(lds + (bufoff) + ldsw + _i * 8192), 16, 0, 0); } while (0)
; #define PG8_LDA(dst, b, h) do { _Pragma("unroll") for (int m = 0; m < 4; ++m) _Pragma("unroll") for (int k = 0; k < 2; ++k) dst[m][k] = *(const LAS bf16x8*)(lds + PG8_SA(b, h) + aoff + m * 2048 + k * 1024); } while (0)
; #define PG8_LDB(dst, b, h) do { _Pragma("unroll") for (int n = 0; n < 2; ++n) _Pragma("unroll") for (int k = 0; k < 2; ++k) dst[n][k] = *(const LAS bf16x8*)(lds + PG8_SB(b, h) + boff + n * 2048 + k * 1024); } while (0)
; #define PG8_MMA(ai, bj, At, Bt) do { __builtin_amdgcn_s_setprio(1); _Pragma("unroll") for (int m = 0; m < 4; ++m) _Pragma("unroll") for (int n = 0; n < 2; ++n) _Pragma("unroll") for (int k = 0; k < 2; ++k) \
;         acc[ai][bj][m][n] = __builtin_amdgcn_mfma_f32_16x16x32_bf16(Bt[n][k], At[m][k], acc[ai][bj][m][n], 0, 0, 0); __builtin_amdgcn_s_setprio(0); } while (0)
; #define PG8_WAIT_V(n) asm volatile("s_waitcnt vmcnt(" #n ")" ::: "memory")
; #define PG8_WAIT_L(n) asm volatile("s_waitcnt lgkmcnt(" #n ")" ::: "memory")
; #define PG8_BAR __builtin_amdgcn_s_barrier()
; #define PG8_SCHED __builtin_amdgcn_sched_barrier(0)
; template <class Epi, class Sched, bool ALIGN_EPI = false, bool SP2 = false>
; __device__ __forceinline__ void gemm_phase(LAS unsigned char* lds, const Gemm g, const Sched& S, const Epi& E) {
;     ...
;             PG8_WAIT_V(8); PG8_WAIT_L(0); PG8_BAR; PG8_MMA(1, 0, At, B0); PG8_MMA(1, 1, At, B1); PG8_BAR; PG8_SCHED;
;             PG8_LDB(B0, 1, 0); PG8_LDB(B1, 1, 1); PG8_SCHED; PG8_LDA(At, 1, 0); PG8_STAGE(PG8_SA(0, 1), a2 + hstep, voffA);
;             PG8_WAIT_V(8); PG8_WAIT_L(0); PG8_BAR; PG8_MMA(0, 0, At, B0); PG8_MMA(0, 1, At, B1); PG8_BAR; PG8_SCHED;
	s_setprio 1
	s_waitcnt lgkmcnt(0)
	v_mfma_f32_16x16x32_bf16 v[70:73], v[50:53], v[182:185], 0
	v_mfma_f32_16x16x32_bf16 v[66:69], v[138:141], v[182:185], 0
	v_mfma_f32_16x16x32_bf16 v[46:49], v[50:53], v[202:205], 0
	v_mfma_f32_16x16x32_bf16 v[42:45], v[138:141], v[202:205], 0
	v_mfma_f32_16x16x32_bf16 v[30:33], v[50:53], v[210:213], 0
	v_mfma_f32_16x16x32_bf16 v[26:29], v[138:141], v[210:213], 0
	v_mfma_f32_16x16x32_bf16 v[14:17], v[50:53], v[218:221], 0
	v_mfma_f32_16x16x32_bf16 v[10:13], v[138:141], v[218:221], 0
	v_mfma_f32_16x16x32_bf16 v[70:73], v[54:57], v[186:189], v[70:73]
	v_mfma_f32_16x16x32_bf16 v[66:69], v[142:145], v[186:189], v[66:69]
	v_mfma_f32_16x16x32_bf16 v[46:49], v[54:57], v[206:209], v[46:49]
	v_mfma_f32_16x16x32_bf16 v[42:45], v[142:145], v[206:209], v[42:45]
	v_mfma_f32_16x16x32_bf16 v[30:33], v[54:57], v[214:217], v[30:33]
	v_mfma_f32_16x16x32_bf16 v[26:29], v[142:145], v[214:217], v[26:29]
	v_mfma_f32_16x16x32_bf16 v[14:17], v[54:57], v[222:225], v[14:17]
	v_mfma_f32_16x16x32_bf16 v[10:13], v[142:145], v[222:225], v[10:13]
	s_setprio 0
	s_setprio 1
	v_mfma_f32_16x16x32_bf16 v[38:41], v[146:149], v[202:205], 0
	v_mfma_f32_16x16x32_bf16 v[34:37], v[174:177], v[202:205], 0
	v_mfma_f32_16x16x32_bf16 v[22:25], v[146:149], v[210:213], 0
	v_mfma_f32_16x16x32_bf16 v[18:21], v[174:177], v[210:213], 0
	v_mfma_f32_16x16x32_bf16 v[6:9], v[146:149], v[218:221], 0
	v_mfma_f32_16x16x32_bf16 v[2:5], v[174:177], v[218:221], 0
	v_mfma_f32_16x16x32_bf16 v[50:53], v[146:149], v[182:185], 0
	v_mfma_f32_16x16x32_bf16 v[54:57], v[174:177], v[182:185], 0
	v_mfma_f32_16x16x32_bf16 v[38:41], v[150:153], v[206:209], v[38:41]
	v_mfma_f32_16x16x32_bf16 v[34:37], v[178:181], v[206:209], v[34:37]
	v_mfma_f32_16x16x32_bf16 v[22:25], v[150:153], v[214:217], v[22:25]
	v_mfma_f32_16x16x32_bf16 v[18:21], v[178:181], v[214:217], v[18:21]
	v_mfma_f32_16x16x32_bf16 v[6:9], v[150:153], v[222:225], v[6:9]
	v_mfma_f32_16x16x32_bf16 v[2:5], v[178:181], v[222:225], v[2:5]
	v_mfma_f32_16x16x32_bf16 v[50:53], v[150:153], v[186:189], v[50:53]
	v_mfma_f32_16x16x32_bf16 v[54:57], v[178:181], v[186:189], v[54:57]
	s_setprio 0
	s_barrier
	s_add_i32 s56, 0, 0x18000
	s_add_i32 s57, 0, 0x1c000
	v_add_u32_e32 v142, s56, v1
	v_add_u32_e32 v162, s57, v1
	ds_read_b128 v[58:61], v142
	ds_read_b128 v[62:65], v142 offset:1024
	ds_read_b128 v[138:141], v142 offset:2048
	ds_read_b128 v[142:145], v142 offset:3072
	ds_read_b128 v[146:149], v162
	ds_read_b128 v[150:153], v162 offset:1024
	ds_read_b128 v[174:177], v162 offset:2048
	ds_read_b128 v[178:181], v162 offset:3072
	s_add_u32 s34, s34, 0x80000
	s_addc_u32 s35, s35, 0
	s_mov_b32 m0, s30
	v_lshl_add_u64 v[232:233], s[34:35], 0, v[154:155]
	ds_read_b128 v[182:185], v198 offset:32768
	ds_read_b128 v[186:189], v198 offset:33792
	ds_read_b128 v[202:205], v198 offset:34816
	ds_read_b128 v[206:209], v198 offset:35840
	ds_read_b128 v[210:213], v198 offset:36864
	ds_read_b128 v[214:217], v198 offset:37888
	ds_read_b128 v[218:221], v198 offset:38912
	ds_read_b128 v[222:225], v198 offset:39936
	global_load_lds_dwordx4 v[232:233], off
	v_lshl_add_u64 v[232:233], s[34:35], 0, v[158:159]
	s_mov_b32 m0, s31
	s_nop 0
	global_load_lds_dwordx4 v[232:233], off
	s_waitcnt vmcnt(8)
	s_waitcnt lgkmcnt(0)
	s_barrier
	s_setprio 1
	s_waitcnt lgkmcnt(0)
	v_mfma_f32_16x16x32_bf16 v[134:137], v[58:61], v[182:185], v[134:137]
	v_mfma_f32_16x16x32_bf16 v[130:133], v[138:141], v[182:185], v[130:133]
	v_mfma_f32_16x16x32_bf16 v[118:121], v[58:61], v[202:205], v[118:121]
	v_mfma_f32_16x16x32_bf16 v[114:117], v[138:141], v[202:205], v[114:117]
	v_mfma_f32_16x16x32_bf16 v[102:105], v[58:61], v[210:213], v[102:105]
	v_mfma_f32_16x16x32_bf16 v[98:101], v[138:141], v[210:213], v[98:101]
	v_mfma_f32_16x16x32_bf16 v[86:89], v[58:61], v[218:221], v[86:89]
	v_mfma_f32_16x16x32_bf16 v[82:85], v[138:141], v[218:221], v[82:85]
	v_mfma_f32_16x16x32_bf16 v[134:137], v[62:65], v[186:189], v[134:137]
	v_mfma_f32_16x16x32_bf16 v[130:133], v[142:145], v[186:189], v[130:133]
	v_mfma_f32_16x16x32_bf16 v[118:121], v[62:65], v[206:209], v[118:121]
	v_mfma_f32_16x16x32_bf16 v[114:117], v[142:145], v[206:209], v[114:117]
	v_mfma_f32_16x16x32_bf16 v[102:105], v[62:65], v[214:217], v[102:105]
	v_mfma_f32_16x16x32_bf16 v[98:101], v[142:145], v[214:217], v[98:101]
	v_mfma_f32_16x16x32_bf16 v[86:89], v[62:65], v[222:225], v[86:89]
	v_mfma_f32_16x16x32_bf16 v[82:85], v[142:145], v[222:225], v[82:85]
	s_setprio 0
	s_setprio 1
	v_mfma_f32_16x16x32_bf16 v[126:129], v[146:149], v[182:185], v[126:129]
	v_mfma_f32_16x16x32_bf16 v[122:125], v[174:177], v[182:185], v[122:125]
	v_mfma_f32_16x16x32_bf16 v[110:113], v[146:149], v[202:205], v[110:113]
	v_mfma_f32_16x16x32_bf16 v[106:109], v[174:177], v[202:205], v[106:109]
	v_mfma_f32_16x16x32_bf16 v[94:97], v[146:149], v[210:213], v[94:97]
	v_mfma_f32_16x16x32_bf16 v[90:93], v[174:177], v[210:213], v[90:93]
	v_mfma_f32_16x16x32_bf16 v[78:81], v[146:149], v[218:221], v[78:81]
	v_mfma_f32_16x16x32_bf16 v[74:77], v[174:177], v[218:221], v[74:77]
	v_mfma_f32_16x16x32_bf16 v[126:129], v[150:153], v[186:189], v[126:129]
	v_mfma_f32_16x16x32_bf16 v[122:125], v[178:181], v[186:189], v[122:125]
	v_mfma_f32_16x16x32_bf16 v[110:113], v[150:153], v[206:209], v[110:113]
	v_mfma_f32_16x16x32_bf16 v[106:109], v[178:181], v[206:209], v[106:109]
	v_mfma_f32_16x16x32_bf16 v[94:97], v[150:153], v[214:217], v[94:97]
	v_mfma_f32_16x16x32_bf16 v[90:93], v[178:181], v[214:217], v[90:93]
	v_mfma_f32_16x16x32_bf16 v[78:81], v[150:153], v[222:225], v[78:81]
	v_mfma_f32_16x16x32_bf16 v[74:77], v[178:181], v[222:225], v[74:77]
	s_setprio 0
	s_barrier
; #define PG8_STAGE(bufoff, gbase, voff) do { _Pragma("unroll") for (int _i = 0; _i < 2; ++_i) \
;         __builtin_amdgcn_global_load_lds((const unsigned*)((const char*)(gbase) + (voff)[_i]), (LAS unsigned*)(lds + (bufoff) + ldsw + _i * 8192), 16, 0, 0); } while (0)
; #define PG8_LDA(dst, b, h) do { _Pragma("unroll") for (int m = 0; m < 4; ++m) _Pragma("unroll") for (int k = 0; k < 2; ++k) dst[m][k] = *(const LAS bf16x8*)(lds + PG8_SA(b, h) + aoff + m * 2048 + k * 1024); } while (0)
; #define PG8_MMA(ai, bj, At, Bt) do { __builtin_amdgcn_s_setprio(1); _Pragma("unroll") for (int m = 0; m < 4; ++m) _Pragma("unroll") for (int n = 0; n < 2; ++n) _Pragma("unroll") for (int k = 0; k < 2; ++k) \
;         acc[ai][bj][m][n] = __builtin_amdgcn_mfma_f32_16x16x32_bf16(Bt[n][k], At[m][k], acc[ai][bj][m][n], 0, 0, 0); __builtin_amdgcn_s_setprio(0); } while (0)
; #define PG8_WAIT_V(n) asm volatile("s_waitcnt vmcnt(" #n ")" ::: "memory")
; #define PG8_WAIT_L(n) asm volatile("s_waitcnt lgkmcnt(" #n ")" ::: "memory")
; #define PG8_BAR __builtin_amdgcn_s_barrier()
; #define PG8_SCHED __builtin_amdgcn_sched_barrier(0)
; template <class Epi, class Sched, bool ALIGN_EPI = false, bool SP2 = false>
; __device__ __forceinline__ void gemm_phase(LAS unsigned char* lds, const Gemm g, const Sched& S, const Epi& E) {
;     ...
;         for (int t = 0; t < nt; t += 2) {
;             const bool last = (t == nt - 2);
;     ...
;             PG8_LDA(At, 1, 1); PG8_STAGE(PG8_SB(1, 0), b3, voffB); PG8_STAGE(PG8_SB(1, 1), b3 + hstepB, voffB); PG8_STAGE(PG8_SA(1, 0), a3, voffA);
;             PG8_WAIT_V(8); PG8_WAIT_L(0); PG8_BAR; PG8_MMA(1, 0, At, B0); PG8_MMA(1, 1, At, B1); PG8_BAR; PG8_SCHED;
	s_add_i32 s34, s56, s27
	v_lshl_add_u64 v[190:191], v[190:191], 0, s[8:9]
	s_mov_b32 m0, s34
	ds_read_b128 v[182:185], v198 offset:49152
	ds_read_b128 v[186:189], v198 offset:50176
	ds_read_b128 v[202:205], v198 offset:51200
	ds_read_b128 v[206:209], v198 offset:52224
	ds_read_b128 v[210:213], v198 offset:53248
	ds_read_b128 v[214:217], v198 offset:54272
	ds_read_b128 v[218:221], v198 offset:55296
	ds_read_b128 v[222:225], v198 offset:56320
	global_load_lds_dwordx4 v[190:191], off
	s_add_i32 m0, s34, 0x2000
	s_add_u32 s24, s24, 0x20080
	v_lshl_add_u64 v[190:191], v[226:227], 0, s[8:9]
	s_addc_u32 s25, s25, 0
	s_add_i32 s34, s57, s27
	global_load_lds_dwordx4 v[190:191], off
	v_lshl_add_u64 v[190:191], s[24:25], 0, v[156:157]
	s_mov_b32 m0, s34
	s_nop 0
	global_load_lds_dwordx4 v[190:191], off
	v_lshl_add_u64 v[190:191], s[24:25], 0, v[160:161]
	s_add_i32 m0, s34, 0x2000
	s_nop 0
	global_load_lds_dwordx4 v[190:191], off
	v_lshl_add_u64 v[190:191], v[228:229], 0, s[8:9]
	s_mov_b32 m0, s48
	s_nop 0
	global_load_lds_dwordx4 v[190:191], off
	v_lshl_add_u64 v[190:191], v[230:231], 0, s[8:9]
	s_mov_b32 m0, s49
	s_nop 0
	global_load_lds_dwordx4 v[190:191], off
	s_waitcnt vmcnt(8)
	s_waitcnt lgkmcnt(0)
	s_barrier
	s_setprio 1
	s_waitcnt lgkmcnt(0)
	v_mfma_f32_16x16x32_bf16 v[70:73], v[58:61], v[182:185], v[70:73]
	v_mfma_f32_16x16x32_bf16 v[66:69], v[138:141], v[182:185], v[66:69]
	v_mfma_f32_16x16x32_bf16 v[46:49], v[58:61], v[202:205], v[46:49]
	v_mfma_f32_16x16x32_bf16 v[42:45], v[138:141], v[202:205], v[42:45]
	v_mfma_f32_16x16x32_bf16 v[30:33], v[58:61], v[210:213], v[30:33]
	v_mfma_f32_16x16x32_bf16 v[26:29], v[138:141], v[210:213], v[26:29]
	v_mfma_f32_16x16x32_bf16 v[14:17], v[58:61], v[218:221], v[14:17]
	v_mfma_f32_16x16x32_bf16 v[10:13], v[138:141], v[218:221], v[10:13]
	v_mfma_f32_16x16x32_bf16 v[70:73], v[62:65], v[186:189], v[70:73]
	v_mfma_f32_16x16x32_bf16 v[66:69], v[142:145], v[186:189], v[66:69]
	v_mfma_f32_16x16x32_bf16 v[46:49], v[62:65], v[206:209], v[46:49]
	v_mfma_f32_16x16x32_bf16 v[42:45], v[142:145], v[206:209], v[42:45]
	v_mfma_f32_16x16x32_bf16 v[30:33], v[62:65], v[214:217], v[30:33]
	v_mfma_f32_16x16x32_bf16 v[26:29], v[142:145], v[214:217], v[26:29]
	v_mfma_f32_16x16x32_bf16 v[14:17], v[62:65], v[222:225], v[14:17]
	v_mfma_f32_16x16x32_bf16 v[10:13], v[142:145], v[222:225], v[10:13]
	s_setprio 0
	s_setprio 1
	v_mfma_f32_16x16x32_bf16 v[50:53], v[146:149], v[182:185], v[50:53]
	v_mfma_f32_16x16x32_bf16 v[62:65], v[150:153], v[186:189], v[50:53]
	v_mfma_f32_16x16x32_bf16 v[50:53], v[174:177], v[182:185], v[54:57]
	v_mfma_f32_16x16x32_bf16 v[38:41], v[146:149], v[202:205], v[38:41]
	v_mfma_f32_16x16x32_bf16 v[34:37], v[174:177], v[202:205], v[34:37]
	v_mfma_f32_16x16x32_bf16 v[22:25], v[146:149], v[210:213], v[22:25]
	v_mfma_f32_16x16x32_bf16 v[18:21], v[174:177], v[210:213], v[18:21]
	v_mfma_f32_16x16x32_bf16 v[6:9], v[146:149], v[218:221], v[6:9]
	v_mfma_f32_16x16x32_bf16 v[2:5], v[174:177], v[218:221], v[2:5]
	v_mfma_f32_16x16x32_bf16 v[58:61], v[178:181], v[186:189], v[50:53]
	v_mfma_f32_16x16x32_bf16 v[38:41], v[150:153], v[206:209], v[38:41]
	v_mfma_f32_16x16x32_bf16 v[34:37], v[178:181], v[206:209], v[34:37]
	v_mfma_f32_16x16x32_bf16 v[22:25], v[150:153], v[214:217], v[22:25]
	v_mfma_f32_16x16x32_bf16 v[18:21], v[178:181], v[214:217], v[18:21]
	v_mfma_f32_16x16x32_bf16 v[6:9], v[150:153], v[222:225], v[6:9]
	v_mfma_f32_16x16x32_bf16 v[2:5], v[178:181], v[222:225], v[2:5]
	s_setprio 0
	s_barrier
	s_add_i32 s55, s55, 2
	s_add_u32 s53, s53, 0x100
	s_addc_u32 s54, s54, 0
	s_add_u32 s22, s22, 0x100
	s_addc_u32 s23, s23, 0
	s_cmp_lt_u32 s55, 30

; __device__ __forceinline__ float row_rstd(const float* ss, int row) { return 1.0f / sqrtf(ss[row] * (1.0f / DM) + 1e-6f); }
; #define PG8_WAIT_V(n) asm volatile("s_waitcnt vmcnt(" #n ")" ::: "memory")
; #define PG8_WAIT_L(n) asm volatile("s_waitcnt lgkmcnt(" #n ")" ::: "memory")
;     __device__ __forceinline__ void operator()(const f32x4 (&acc)[2][2][4][2], const Unit& u, int wr, int wc, int fr, int fq) const {
;     ...
;         const int s = (u.pm < ML / BM) ? (u.pm >> 5) : 4;
;         const float* bp = bias + (size_t)s * BIAS_N + u.pn * BM + wc * 32 + 8 * fq;
;         const f32x4 ba0 = *(const f32x4*)bp, ba1 = *(const f32x4*)(bp + 4), bb0 = *(const f32x4*)(bp + HALF), bb1 = *(const f32x4*)(bp + HALF + 4);
;         const int lane = fq * 16 + fr;
;         const float rsl0 = row_rstd(ss, u.pm * BM + wr * 64 + lane), rsl1 = row_rstd(ss, u.pm * BM + HALF + wr * 64 + lane);
; template <class Epi, class Sched, bool ALIGN_EPI = false, bool SP2 = false>
; __device__ __forceinline__ void gemm_phase(LAS unsigned char* lds, const Gemm g, const Sched& S, const Epi& E) {
;     ...
;     Unit cur, nxt; int ui = 0;
;     if (!S.next(0, cur)) return;
;     f32x4 acc[2][2][4][2];
; #pragma unroll
;     for (int a = 0; a < 2; ++a)
; #pragma unroll
;         for (int b = 0; b < 2; ++b)
; #pragma unroll
;             for (int m = 0; m < 4; ++m)
; #pragma unroll
;                 for (int n = 0; n < 2; ++n) acc[a][b][m][n] = (f32x4){0.f, 0.f, 0.f, 0.f};
;     ...
;         const bool has_next = S.next(ui + 1, nxt);
;         const char* nA = has_next ? (const char*)g.A + (size_t)nxt.pm * tstep + nxt.koff : cA; const char* nB = has_next ? (const char*)g.Bt + (size_t)nxt.pn * tstep + nxt.koff : cB;
;         for (int t = 0; t < nt; t += 2) {
;             const bool last = (t == nt - 2);
;             const char* a1 = cA + (size_t)(t + 1) * kstep;
;             const char* a2 = last ? nA : cA + (size_t)(t + 2) * kstep; const char* b2 = last ? nB : cB + (size_t)(t + 2) * kstep;
;             const char* a3 = a2 + kstep; const char* b3 = b2 + kstep;
;             if (last && has_next) S.a_ready(nxt);
;             if constexpr (SP2) {
;             PG8_LDB(B0, 0, 0); PG8_LDB(B1, 0, 1); PG8_SCHED; PG8_LDA(At, 0, 0); PG8_STAGE(PG8_SA(1, 1), a1 + hstep, voffA);
;             PG8_WAIT_V(8); PG8_WAIT_L(0); PG8_BAR; PG8_MMA(0, 0, At, B0); PG8_MMA(0, 1, At, B1); PG8_BAR; PG8_SCHED;
.LBB0_2915:
	s_ashr_i32 s13, s12, 31
	v_cmp_lt_i64_e64 s[36:37], s[14:15], v[158:159]
	s_lshl_b64 s[14:15], s[12:13], 20
	s_add_u32 s14, s93, s14
	s_addc_u32 s15, s92, s15
	s_and_b64 s[16:17], s[36:37], exec
	s_cselect_b32 s13, s15, s21
	s_cselect_b32 s46, s14, s20
	s_ashr_i32 s11, s10, 31
	s_lshl_b64 s[16:17], s[10:11], 20
	s_add_u32 s16, s78, s16
	s_addc_u32 s17, s79, s17
	s_and_b64 s[22:23], s[36:37], exec
	s_cselect_b32 s11, s17, s19
	s_cselect_b32 s47, s16, s18
	s_add_u32 s48, s18, 0x100
	s_addc_u32 s49, s19, 0
	s_add_u32 s18, s20, 0x80080
	s_addc_u32 s19, s21, 0
	s_mov_b32 s50, -2
	s_waitcnt vmcnt(0)
	s_cmpk_gt_i32 s2, 0x7f
	s_mov_b64 s[98:99], 0xb000
	s_cbranch_scc1 .Lpre_up2l1
	s_ashr_i32 s100, s2, 5
	s_mul_hi_i32 s99, s100, 0x2c00
	s_mul_i32 s98, s100, 0x2c00
.Lpre_up2l1:
	s_lshl_b64 s[98:99], s[98:99], 2
	s_add_u32 s98, s35, s98
	s_addc_u32 s99, s38, s99
	s_lshl_b32 s100, s3, 8
	s_ashr_i32 s101, s100, 31
	s_lshl_b64 s[100:101], s[100:101], 2
	s_add_u32 s98, s98, s100
	s_addc_u32 s99, s99, s101
	s_add_u32 s98, s98, s44
	s_addc_u32 s99, s99, 0
	s_lshl_b32 s100, s2, 8
	s_add_i32 s100, s100, s34
	v_or_b32_e32 v162, s100, v170
	v_ashrrev_i32_e32 v163, 31, v162
	v_lshl_add_u64 v[162:163], v[162:163], 2, s[0:1]
	v_add_u32_e32 v164, s100, v171
	v_ashrrev_i32_e32 v165, 31, v164
	v_lshl_add_u64 v[164:165], v[164:165], 2, s[0:1]
	global_load_dwordx4 v[234:237], v176, s[98:99] offset:16
	global_load_dwordx4 v[238:241], v176, s[98:99]
	global_load_dwordx4 v[242:245], v176, s[98:99] offset:528
	global_load_dwordx4 v[246:249], v176, s[98:99] offset:512
	global_load_dword v250, v[162:163], off
	global_load_dword v251, v[164:165], off
	ds_read_b128 v[66:69], v173
	ds_read_b128 v[70:73], v173 offset:1024
	ds_read_b128 v[74:77], v173 offset:2048
	ds_read_b128 v[78:81], v173 offset:3072
	ds_read_b128 v[162:165], v174
	ds_read_b128 v[180:183], v174 offset:1024
	ds_read_b128 v[184:187], v174 offset:2048
	ds_read_b128 v[188:191], v174 offset:3072
	s_add_u32 s20, s18, 0xfff80080
	s_addc_u32 s21, s19, -1
	s_cmp_eq_u32 s50, 28
	s_cselect_b32 s23, s13, s21
	s_cselect_b32 s22, s46, s20
	s_cselect_b32 s21, s11, s49
	s_cselect_b32 s20, s47, s48
	v_lshl_add_u64 v[166:167], s[18:19], 0, v[156:157]
	s_add_i32 m0, s28, 0xc000
	ds_read_b128 v[192:195], v175
	ds_read_b128 v[196:199], v175 offset:1024
	ds_read_b128 v[200:203], v175 offset:2048
	ds_read_b128 v[204:207], v175 offset:3072
	ds_read_b128 v[208:211], v175 offset:4096
	ds_read_b128 v[212:215], v175 offset:5120
	ds_read_b128 v[216:219], v175 offset:6144
	ds_read_b128 v[220:223], v175 offset:7168
	global_load_lds_dwordx4 v[166:167], off
	v_lshl_add_u64 v[166:167], s[18:19], 0, v[154:155]
	s_add_i32 m0, s28, 0xe000
	s_nop 0
	global_load_lds_dwordx4 v[166:167], off
	s_waitcnt lgkmcnt(0)
	s_barrier
	s_setprio 1
	s_waitcnt lgkmcnt(0)
	v_mfma_f32_16x16x32_bf16 v[142:145], v[66:69], v[192:195], 0
	v_mfma_f32_16x16x32_bf16 v[138:141], v[74:77], v[192:195], 0
	v_mfma_f32_16x16x32_bf16 v[126:129], v[66:69], v[200:203], 0
	v_mfma_f32_16x16x32_bf16 v[122:125], v[74:77], v[200:203], 0
	v_mfma_f32_16x16x32_bf16 v[110:113], v[66:69], v[208:211], 0
	v_mfma_f32_16x16x32_bf16 v[106:109], v[74:77], v[208:211], 0
	v_mfma_f32_16x16x32_bf16 v[94:97], v[66:69], v[216:219], 0
	v_mfma_f32_16x16x32_bf16 v[90:93], v[74:77], v[216:219], 0
	v_mfma_f32_16x16x32_bf16 v[142:145], v[70:73], v[196:199], v[142:145]
	v_mfma_f32_16x16x32_bf16 v[138:141], v[78:81], v[196:199], v[138:141]
	v_mfma_f32_16x16x32_bf16 v[126:129], v[70:73], v[204:207], v[126:129]
	v_mfma_f32_16x16x32_bf16 v[122:125], v[78:81], v[204:207], v[122:125]
	v_mfma_f32_16x16x32_bf16 v[110:113], v[70:73], v[212:215], v[110:113]
	v_mfma_f32_16x16x32_bf16 v[106:109], v[78:81], v[212:215], v[106:109]
	v_mfma_f32_16x16x32_bf16 v[94:97], v[70:73], v[220:223], v[94:97]
	v_mfma_f32_16x16x32_bf16 v[90:93], v[78:81], v[220:223], v[90:93]
	s_setprio 0
	s_setprio 1
	v_mfma_f32_16x16x32_bf16 v[134:137], v[162:165], v[192:195], 0
	v_mfma_f32_16x16x32_bf16 v[130:133], v[184:187], v[192:195], 0
	v_mfma_f32_16x16x32_bf16 v[118:121], v[162:165], v[200:203], 0
	v_mfma_f32_16x16x32_bf16 v[114:117], v[184:187], v[200:203], 0
	v_mfma_f32_16x16x32_bf16 v[102:105], v[162:165], v[208:211], 0
	v_mfma_f32_16x16x32_bf16 v[98:101], v[184:187], v[208:211], 0
	v_mfma_f32_16x16x32_bf16 v[86:89], v[162:165], v[216:219], 0
	v_mfma_f32_16x16x32_bf16 v[82:85], v[184:187], v[216:219], 0
	v_mfma_f32_16x16x32_bf16 v[134:137], v[180:183], v[196:199], v[134:137]
	v_mfma_f32_16x16x32_bf16 v[130:133], v[188:191], v[196:199], v[130:133]
	v_mfma_f32_16x16x32_bf16 v[118:121], v[180:183], v[204:207], v[118:121]
	v_mfma_f32_16x16x32_bf16 v[114:117], v[188:191], v[204:207], v[114:117]
	v_mfma_f32_16x16x32_bf16 v[102:105], v[180:183], v[212:215], v[102:105]
	v_mfma_f32_16x16x32_bf16 v[98:101], v[188:191], v[212:215], v[98:101]
	v_mfma_f32_16x16x32_bf16 v[86:89], v[180:183], v[220:223], v[86:89]
	v_mfma_f32_16x16x32_bf16 v[82:85], v[188:191], v[220:223], v[82:85]
	s_setprio 0
	s_barrier
	s_add_i32 s51, s41, s25
	v_lshl_add_u64 v[166:167], s[20:21], 0, v[150:151]
	s_mov_b32 m0, s51
	ds_read_b128 v[192:195], v175 offset:16384
	ds_read_b128 v[196:199], v175 offset:17408
	ds_read_b128 v[200:203], v175 offset:18432
	ds_read_b128 v[204:207], v175 offset:19456
	ds_read_b128 v[208:211], v175 offset:20480
	ds_read_b128 v[212:215], v175 offset:21504
	ds_read_b128 v[216:219], v175 offset:22528
	ds_read_b128 v[220:223], v175 offset:23552
	global_load_lds_dwordx4 v[166:167], off
	s_add_i32 m0, s51, 0x2000
	s_add_u32 s52, s20, 0x80000
	v_lshl_add_u64 v[224:225], s[20:21], 0, v[146:147]
	s_addc_u32 s53, s21, 0
	s_add_i32 s51, s42, s25
	global_load_lds_dwordx4 v[224:225], off
	v_lshl_add_u64 v[226:227], s[52:53], 0, v[150:151]
	s_mov_b32 m0, s51
	v_lshl_add_u64 v[228:229], s[22:23], 0, v[148:149]
	global_load_lds_dwordx4 v[226:227], off
	v_lshl_add_u64 v[226:227], s[52:53], 0, v[146:147]
	s_add_i32 m0, s51, 0x2000
	s_nop 0
	global_load_lds_dwordx4 v[226:227], off
	v_lshl_add_u64 v[226:227], s[22:23], 0, v[152:153]
	s_mov_b32 m0, s28
	s_nop 0
	global_load_lds_dwordx4 v[226:227], off
	s_mov_b32 m0, s29
	s_nop 0
	global_load_lds_dwordx4 v[228:229], off
	s_waitcnt vmcnt(8)
	s_waitcnt lgkmcnt(0)
	s_barrier
; #define PG8_STAGE(bufoff, gbase, voff) do { _Pragma("unroll") for (int _i = 0; _i < 2; ++_i) \
;         __builtin_amdgcn_global_load_lds((const unsigned*)((const char*)(gbase) + (voff)[_i]), (LAS unsigned*)(lds + (bufoff) + ldsw + _i * 8192), 16, 0, 0); } while (0)
; #define PG8_LDA(dst, b, h) do { _Pragma("unroll") for (int m = 0; m < 4; ++m) _Pragma("unroll") for (int k = 0; k < 2; ++k) dst[m][k] = *(const LAS bf16x8*)(lds + PG8_SA(b, h) + aoff + m * 2048 + k * 1024); } while (0)
; #define PG8_LDB(dst, b, h) do { _Pragma("unroll") for (int n = 0; n < 2; ++n) _Pragma("unroll") for (int k = 0; k < 2; ++k) dst[n][k] = *(const LAS bf16x8*)(lds + PG8_SB(b, h) + boff + n * 2048 + k * 1024); } while (0)
; #define PG8_MMA(ai, bj, At, Bt) do { __builtin_amdgcn_s_setprio(1); _Pragma("unroll") for (int m = 0; m < 4; ++m) _Pragma("unroll") for (int n = 0; n < 2; ++n) _Pragma("unroll") for (int k = 0; k < 2; ++k) \
;         acc[ai][bj][m][n] = __builtin_amdgcn_mfma_f32_16x16x32_bf16(Bt[n][k], At[m][k], acc[ai][bj][m][n], 0, 0, 0); __builtin_amdgcn_s_setprio(0); } while (0)
; #define PG8_WAIT_V(n) asm volatile("s_waitcnt vmcnt(" #n ")" ::: "memory")
; #define PG8_WAIT_L(n) asm volatile("s_waitcnt lgkmcnt(" #n ")" ::: "memory")
; #define PG8_BAR __builtin_amdgcn_s_barrier()
; #define PG8_SCHED __builtin_amdgcn_sched_barrier(0)
; template <class Epi, class Sched, bool ALIGN_EPI = false, bool SP2 = false>
; __device__ __forceinline__ void gemm_phase(LAS unsigned char* lds, const Gemm g, const Sched& S, const Epi& E) {
;     ...
;             PG8_WAIT_V(8); PG8_WAIT_L(0); PG8_BAR; PG8_MMA(0, 0, At, B0); PG8_MMA(0, 1, At, B1); PG8_BAR; PG8_SCHED;
;             PG8_LDA(At, 0, 1); PG8_STAGE(PG8_SB(0, 0), b2, voffB); PG8_STAGE(PG8_SB(0, 1), b2 + hstepB, voffB); PG8_STAGE(PG8_SA(0, 0), a2, voffA);
;             PG8_WAIT_V(8); PG8_WAIT_L(0); PG8_BAR; PG8_MMA(1, 0, At, B0); PG8_MMA(1, 1, At, B1); PG8_BAR; PG8_SCHED;
;             PG8_LDB(B0, 1, 0); PG8_LDB(B1, 1, 1); PG8_SCHED; PG8_LDA(At, 1, 0); PG8_STAGE(PG8_SA(0, 1), a2 + hstep, voffA);
;             PG8_WAIT_V(8); PG8_WAIT_L(0); PG8_BAR; PG8_MMA(0, 0, At, B0); PG8_MMA(0, 1, At, B1); PG8_BAR; PG8_SCHED;
	s_setprio 1
	s_waitcnt lgkmcnt(0)
	v_mfma_f32_16x16x32_bf16 v[62:65], v[66:69], v[192:195], 0
	v_mfma_f32_16x16x32_bf16 v[58:61], v[74:77], v[192:195], 0
	v_mfma_f32_16x16x32_bf16 v[46:49], v[66:69], v[200:203], 0
	v_mfma_f32_16x16x32_bf16 v[42:45], v[74:77], v[200:203], 0
	v_mfma_f32_16x16x32_bf16 v[30:33], v[66:69], v[208:211], 0
	v_mfma_f32_16x16x32_bf16 v[26:29], v[74:77], v[208:211], 0
	v_mfma_f32_16x16x32_bf16 v[14:17], v[66:69], v[216:219], 0
	v_mfma_f32_16x16x32_bf16 v[10:13], v[74:77], v[216:219], 0
	v_mfma_f32_16x16x32_bf16 v[62:65], v[70:73], v[196:199], v[62:65]
	v_mfma_f32_16x16x32_bf16 v[58:61], v[78:81], v[196:199], v[58:61]
	v_mfma_f32_16x16x32_bf16 v[46:49], v[70:73], v[204:207], v[46:49]
	v_mfma_f32_16x16x32_bf16 v[42:45], v[78:81], v[204:207], v[42:45]
	v_mfma_f32_16x16x32_bf16 v[30:33], v[70:73], v[212:215], v[30:33]
	v_mfma_f32_16x16x32_bf16 v[26:29], v[78:81], v[212:215], v[26:29]
	v_mfma_f32_16x16x32_bf16 v[14:17], v[70:73], v[220:223], v[14:17]
	v_mfma_f32_16x16x32_bf16 v[10:13], v[78:81], v[220:223], v[10:13]
	s_setprio 0
	s_setprio 1
	v_mfma_f32_16x16x32_bf16 v[54:57], v[162:165], v[192:195], 0
	v_mfma_f32_16x16x32_bf16 v[50:53], v[184:187], v[192:195], 0
	v_mfma_f32_16x16x32_bf16 v[38:41], v[162:165], v[200:203], 0
	v_mfma_f32_16x16x32_bf16 v[34:37], v[184:187], v[200:203], 0
	v_mfma_f32_16x16x32_bf16 v[22:25], v[162:165], v[208:211], 0
	v_mfma_f32_16x16x32_bf16 v[18:21], v[184:187], v[208:211], 0
	v_mfma_f32_16x16x32_bf16 v[6:9], v[162:165], v[216:219], 0
	v_mfma_f32_16x16x32_bf16 v[2:5], v[184:187], v[216:219], 0
	v_mfma_f32_16x16x32_bf16 v[54:57], v[180:183], v[196:199], v[54:57]
	v_mfma_f32_16x16x32_bf16 v[50:53], v[188:191], v[196:199], v[50:53]
	v_mfma_f32_16x16x32_bf16 v[38:41], v[180:183], v[204:207], v[38:41]
	v_mfma_f32_16x16x32_bf16 v[34:37], v[188:191], v[204:207], v[34:37]
	v_mfma_f32_16x16x32_bf16 v[22:25], v[180:183], v[212:215], v[22:25]
	v_mfma_f32_16x16x32_bf16 v[18:21], v[188:191], v[212:215], v[18:21]
	v_mfma_f32_16x16x32_bf16 v[6:9], v[180:183], v[220:223], v[6:9]
	v_mfma_f32_16x16x32_bf16 v[2:5], v[188:191], v[220:223], v[2:5]
	s_setprio 0
	s_barrier
	s_add_i32 s51, 0, 0x18000
	s_add_i32 s52, 0, 0x1c000
	v_add_u32_e32 v78, s51, v169
	v_add_u32_e32 v168, s52, v169
	ds_read_b128 v[66:69], v78
	ds_read_b128 v[70:73], v78 offset:1024
	ds_read_b128 v[74:77], v78 offset:2048
	ds_read_b128 v[78:81], v78 offset:3072
	ds_read_b128 v[162:165], v168
	ds_read_b128 v[180:183], v168 offset:1024
	ds_read_b128 v[184:187], v168 offset:2048
	ds_read_b128 v[188:191], v168 offset:3072
	s_add_u32 s22, s22, 0x80000
	s_addc_u32 s23, s23, 0
	s_mov_b32 m0, s30
	v_lshl_add_u64 v[230:231], s[22:23], 0, v[152:153]
	ds_read_b128 v[192:195], v175 offset:32768
	ds_read_b128 v[196:199], v175 offset:33792
	ds_read_b128 v[200:203], v175 offset:34816
	ds_read_b128 v[204:207], v175 offset:35840
	ds_read_b128 v[208:211], v175 offset:36864
	ds_read_b128 v[212:215], v175 offset:37888
	ds_read_b128 v[216:219], v175 offset:38912
	ds_read_b128 v[220:223], v175 offset:39936
	global_load_lds_dwordx4 v[230:231], off
	v_lshl_add_u64 v[230:231], s[22:23], 0, v[148:149]
	s_mov_b32 m0, s31
	s_nop 0
	global_load_lds_dwordx4 v[230:231], off
	s_waitcnt vmcnt(8)
	s_waitcnt lgkmcnt(0)
	s_barrier
	s_setprio 1
	s_waitcnt lgkmcnt(0)
	v_mfma_f32_16x16x32_bf16 v[142:145], v[66:69], v[192:195], v[142:145]
	v_mfma_f32_16x16x32_bf16 v[138:141], v[74:77], v[192:195], v[138:141]
	v_mfma_f32_16x16x32_bf16 v[126:129], v[66:69], v[200:203], v[126:129]
	v_mfma_f32_16x16x32_bf16 v[122:125], v[74:77], v[200:203], v[122:125]
	v_mfma_f32_16x16x32_bf16 v[110:113], v[66:69], v[208:211], v[110:113]
	v_mfma_f32_16x16x32_bf16 v[106:109], v[74:77], v[208:211], v[106:109]
	v_mfma_f32_16x16x32_bf16 v[94:97], v[66:69], v[216:219], v[94:97]
	v_mfma_f32_16x16x32_bf16 v[90:93], v[74:77], v[216:219], v[90:93]
	v_mfma_f32_16x16x32_bf16 v[142:145], v[70:73], v[196:199], v[142:145]
	v_mfma_f32_16x16x32_bf16 v[138:141], v[78:81], v[196:199], v[138:141]
	v_mfma_f32_16x16x32_bf16 v[126:129], v[70:73], v[204:207], v[126:129]
	v_mfma_f32_16x16x32_bf16 v[122:125], v[78:81], v[204:207], v[122:125]
	v_mfma_f32_16x16x32_bf16 v[110:113], v[70:73], v[212:215], v[110:113]
	v_mfma_f32_16x16x32_bf16 v[106:109], v[78:81], v[212:215], v[106:109]
	v_mfma_f32_16x16x32_bf16 v[94:97], v[70:73], v[220:223], v[94:97]
	v_mfma_f32_16x16x32_bf16 v[90:93], v[78:81], v[220:223], v[90:93]
	s_setprio 0
	s_setprio 1
	v_mfma_f32_16x16x32_bf16 v[134:137], v[162:165], v[192:195], v[134:137]
	v_mfma_f32_16x16x32_bf16 v[130:133], v[184:187], v[192:195], v[130:133]
	v_mfma_f32_16x16x32_bf16 v[118:121], v[162:165], v[200:203], v[118:121]
	v_mfma_f32_16x16x32_bf16 v[114:117], v[184:187], v[200:203], v[114:117]
	v_mfma_f32_16x16x32_bf16 v[102:105], v[162:165], v[208:211], v[102:105]
	v_mfma_f32_16x16x32_bf16 v[98:101], v[184:187], v[208:211], v[98:101]
	v_mfma_f32_16x16x32_bf16 v[86:89], v[162:165], v[216:219], v[86:89]
	v_mfma_f32_16x16x32_bf16 v[82:85], v[184:187], v[216:219], v[82:85]
	v_mfma_f32_16x16x32_bf16 v[134:137], v[180:183], v[196:199], v[134:137]
	v_mfma_f32_16x16x32_bf16 v[130:133], v[188:191], v[196:199], v[130:133]
	v_mfma_f32_16x16x32_bf16 v[118:121], v[180:183], v[204:207], v[118:121]
	v_mfma_f32_16x16x32_bf16 v[114:117], v[188:191], v[204:207], v[114:117]
	v_mfma_f32_16x16x32_bf16 v[102:105], v[180:183], v[212:215], v[102:105]
	v_mfma_f32_16x16x32_bf16 v[98:101], v[188:191], v[212:215], v[98:101]
	v_mfma_f32_16x16x32_bf16 v[86:89], v[180:183], v[220:223], v[86:89]
	v_mfma_f32_16x16x32_bf16 v[82:85], v[188:191], v[220:223], v[82:85]
	s_setprio 0
	s_barrier
; #define PG8_STAGE(bufoff, gbase, voff) do { _Pragma("unroll") for (int _i = 0; _i < 2; ++_i) \
;         __builtin_amdgcn_global_load_lds((const unsigned*)((const char*)(gbase) + (voff)[_i]), (LAS unsigned*)(lds + (bufoff) + ldsw + _i * 8192), 16, 0, 0); } while (0)
; #define PG8_LDA(dst, b, h) do { _Pragma("unroll") for (int m = 0; m < 4; ++m) _Pragma("unroll") for (int k = 0; k < 2; ++k) dst[m][k] = *(const LAS bf16x8*)(lds + PG8_SA(b, h) + aoff + m * 2048 + k * 1024); } while (0)
; #define PG8_LDB(dst, b, h) do { _Pragma("unroll") for (int n = 0; n < 2; ++n) _Pragma("unroll") for (int k = 0; k < 2; ++k) dst[n][k] = *(const LAS bf16x8*)(lds + PG8_SB(b, h) + boff + n * 2048 + k * 1024); } while (0)
; template <class Epi, class Sched, bool ALIGN_EPI = false, bool SP2 = false>
; __device__ __forceinline__ void gemm_phase(LAS unsigned char* lds, const Gemm g, const Sched& S, const Epi& E) {
;     ...
;         for (int t = 0; t < nt; t += 2) {
;             const bool last = (t == nt - 2);
;             const char* a1 = cA + (size_t)(t + 1) * kstep;
;             const char* a2 = last ? nA : cA + (size_t)(t + 2) * kstep; const char* b2 = last ? nB : cB + (size_t)(t + 2) * kstep;
;             const char* a3 = a2 + kstep; const char* b3 = b2 + kstep;
;             if (last && has_next) S.a_ready(nxt);
;             if constexpr (SP2) {
;             PG8_LDB(B0, 0, 0); PG8_LDB(B1, 0, 1); PG8_SCHED; PG8_LDA(At, 0, 0); PG8_STAGE(PG8_SA(1, 1), a1 + hstep, voffA);
;             PG8_WAIT_V(8); PG8_WAIT_L(0); PG8_BAR; PG8_MMA(0, 0, At, B0); PG8_MMA(0, 1, At, B1); PG8_BAR; PG8_SCHED;
;             PG8_LDA(At, 0, 1); PG8_STAGE(PG8_SB(0, 0), b2, voffB); PG8_STAGE(PG8_SB(0, 1), b2 + hstepB, voffB); PG8_STAGE(PG8_SA(0, 0), a2, voffA);
;             PG8_WAIT_V(8); PG8_WAIT_L(0); PG8_BAR; PG8_MMA(1, 0, At, B0); PG8_MMA(1, 1, At, B1); PG8_BAR; PG8_SCHED;
;             PG8_LDB(B0, 1, 0); PG8_LDB(B1, 1, 1); PG8_SCHED; PG8_LDA(At, 1, 0); PG8_STAGE(PG8_SA(0, 1), a2 + hstep, voffA);
;             PG8_WAIT_V(8); PG8_WAIT_L(0); PG8_BAR; PG8_MMA(0, 0, At, B0); PG8_MMA(0, 1, At, B1); PG8_BAR; PG8_SCHED;
;             PG8_LDA(At, 1, 1); PG8_STAGE(PG8_SB(1, 0), b3, voffB); PG8_STAGE(PG8_SB(1, 1), b3 + hstepB, voffB); PG8_STAGE(PG8_SA(1, 0), a3, voffA);
;             PG8_WAIT_V(8); PG8_WAIT_L(0); PG8_BAR; PG8_MMA(1, 0, At, B0); PG8_MMA(1, 1, At, B1); PG8_BAR; PG8_SCHED;
	s_add_i32 s22, s51, s25
	v_lshl_add_u64 v[166:167], v[166:167], 0, s[6:7]
	s_mov_b32 m0, s22
	ds_read_b128 v[192:195], v175 offset:49152
	ds_read_b128 v[196:199], v175 offset:50176
	ds_read_b128 v[200:203], v175 offset:51200
	ds_read_b128 v[204:207], v175 offset:52224
	ds_read_b128 v[208:211], v175 offset:53248
	ds_read_b128 v[212:215], v175 offset:54272
	ds_read_b128 v[216:219], v175 offset:55296
	ds_read_b128 v[220:223], v175 offset:56320
	global_load_lds_dwordx4 v[166:167], off
	s_add_i32 m0, s22, 0x2000
	s_add_u32 s20, s20, 0x80080
	v_lshl_add_u64 v[166:167], v[224:225], 0, s[6:7]
	s_addc_u32 s21, s21, 0
	s_add_i32 s22, s52, s25
	global_load_lds_dwordx4 v[166:167], off
	v_lshl_add_u64 v[166:167], s[20:21], 0, v[150:151]
	s_mov_b32 m0, s22
	s_nop 0
	global_load_lds_dwordx4 v[166:167], off
	v_lshl_add_u64 v[166:167], s[20:21], 0, v[146:147]
	s_add_i32 m0, s22, 0x2000
	s_nop 0
	global_load_lds_dwordx4 v[166:167], off
	v_lshl_add_u64 v[166:167], v[226:227], 0, s[6:7]
	s_mov_b32 m0, s39
	s_nop 0
	global_load_lds_dwordx4 v[166:167], off
	v_lshl_add_u64 v[166:167], v[228:229], 0, s[6:7]
	s_mov_b32 m0, s40
	s_nop 0
	global_load_lds_dwordx4 v[166:167], off
	s_waitcnt vmcnt(8)
	s_waitcnt lgkmcnt(0)
	s_barrier
	s_setprio 1
	s_waitcnt lgkmcnt(0)
	v_mfma_f32_16x16x32_bf16 v[62:65], v[66:69], v[192:195], v[62:65]
	v_mfma_f32_16x16x32_bf16 v[58:61], v[74:77], v[192:195], v[58:61]
	v_mfma_f32_16x16x32_bf16 v[46:49], v[66:69], v[200:203], v[46:49]
	v_mfma_f32_16x16x32_bf16 v[42:45], v[74:77], v[200:203], v[42:45]
	v_mfma_f32_16x16x32_bf16 v[30:33], v[66:69], v[208:211], v[30:33]
	v_mfma_f32_16x16x32_bf16 v[26:29], v[74:77], v[208:211], v[26:29]
	v_mfma_f32_16x16x32_bf16 v[14:17], v[66:69], v[216:219], v[14:17]
	v_mfma_f32_16x16x32_bf16 v[10:13], v[74:77], v[216:219], v[10:13]
	v_mfma_f32_16x16x32_bf16 v[62:65], v[70:73], v[196:199], v[62:65]
	v_mfma_f32_16x16x32_bf16 v[58:61], v[78:81], v[196:199], v[58:61]
	v_mfma_f32_16x16x32_bf16 v[46:49], v[70:73], v[204:207], v[46:49]
	v_mfma_f32_16x16x32_bf16 v[42:45], v[78:81], v[204:207], v[42:45]
	v_mfma_f32_16x16x32_bf16 v[30:33], v[70:73], v[212:215], v[30:33]
	v_mfma_f32_16x16x32_bf16 v[26:29], v[78:81], v[212:215], v[26:29]
	v_mfma_f32_16x16x32_bf16 v[14:17], v[70:73], v[220:223], v[14:17]
	v_mfma_f32_16x16x32_bf16 v[10:13], v[78:81], v[220:223], v[10:13]
	s_setprio 0
	s_setprio 1
	v_mfma_f32_16x16x32_bf16 v[54:57], v[162:165], v[192:195], v[54:57]
	v_mfma_f32_16x16x32_bf16 v[50:53], v[184:187], v[192:195], v[50:53]
	v_mfma_f32_16x16x32_bf16 v[38:41], v[162:165], v[200:203], v[38:41]
	v_mfma_f32_16x16x32_bf16 v[34:37], v[184:187], v[200:203], v[34:37]
	v_mfma_f32_16x16x32_bf16 v[22:25], v[162:165], v[208:211], v[22:25]
	v_mfma_f32_16x16x32_bf16 v[18:21], v[184:187], v[208:211], v[18:21]
	v_mfma_f32_16x16x32_bf16 v[6:9], v[162:165], v[216:219], v[6:9]
	v_mfma_f32_16x16x32_bf16 v[2:5], v[184:187], v[216:219], v[2:5]
	v_mfma_f32_16x16x32_bf16 v[54:57], v[180:183], v[196:199], v[54:57]
	v_mfma_f32_16x16x32_bf16 v[50:53], v[188:191], v[196:199], v[50:53]
	v_mfma_f32_16x16x32_bf16 v[38:41], v[180:183], v[204:207], v[38:41]
	v_mfma_f32_16x16x32_bf16 v[34:37], v[188:191], v[204:207], v[34:37]
	v_mfma_f32_16x16x32_bf16 v[22:25], v[180:183], v[212:215], v[22:25]
	v_mfma_f32_16x16x32_bf16 v[18:21], v[188:191], v[212:215], v[18:21]
	v_mfma_f32_16x16x32_bf16 v[6:9], v[180:183], v[220:223], v[6:9]
	v_mfma_f32_16x16x32_bf16 v[2:5], v[188:191], v[220:223], v[2:5]
	s_setprio 0
	s_barrier
	s_add_i32 s50, s50, 2
	s_add_u32 s48, s48, 0x100
	s_addc_u32 s49, s49, 0
	s_add_u32 s18, s18, 0x100
	s_addc_u32 s19, s19, 0
	s_cmp_lt_u32 s50, 30

; __device__ __forceinline__ unsigned cvt_pk_bf16(float lo, float hi) { unsigned r; asm volatile("v_cvt_pk_bf16_f32 %0, %1, %2" : "=v"(r) : "v"(lo), "v"(hi)); return r; }
; __device__ __forceinline__ float silu_mul(float a, float b) { return a * b * __builtin_amdgcn_rcpf(1.0f + __builtin_amdgcn_exp2f(-a * LOG2E)); }
; __device__ __forceinline__ float row_rstd(const float* ss, int row) { return 1.0f / sqrtf(ss[row] * (1.0f / DM) + 1e-6f); }
;     __device__ __forceinline__ void operator()(const f32x4 (&acc)[2][2][4][2], const Unit& u, int wr, int wc, int fr, int fq) const {
;         const int row0 = u.pm * BM + wr * 64 + fr, col0 = u.pn * HALF + wc * 32 + 8 * fq;
;         const int s = (u.pm < ML / BM) ? (u.pm >> 5) : 4;
;         const float* bp = bias + (size_t)s * BIAS_N + u.pn * BM + wc * 32 + 8 * fq;
;         const f32x4 ba0 = *(const f32x4*)bp, ba1 = *(const f32x4*)(bp + 4), bb0 = *(const f32x4*)(bp + HALF), bb1 = *(const f32x4*)(bp + HALF + 4);
;         const int lane = fq * 16 + fr;
;         const float rsl0 = row_rstd(ss, u.pm * BM + wr * 64 + lane), rsl1 = row_rstd(ss, u.pm * BM + HALF + wr * 64 + lane);
; #pragma unroll
;         for (int ai = 0; ai < 2; ++ai)
; #pragma unroll
;             for (int m = 0; m < 4; ++m) { const int row = row0 + ai * HALF + m * 16; const float rs = __shfl(ai ? rsl1 : rsl0, m * 16 + fr); bf16_t* rowp = O + (size_t)row * DFF + col0;
;                 const f32x4 a0 = acc[ai][0][m][0] * rs + ba0, a1 = acc[ai][0][m][1] * rs + ba1, b0 = acc[ai][1][m][0] * rs + bb0, b1 = acc[ai][1][m][1] * rs + bb1;
;                 u32x4 w; w.x = cvt_pk_bf16(silu_mul(a0[0], b0[0]), silu_mul(a0[1], b0[1])); w.y = cvt_pk_bf16(silu_mul(a0[2], b0[2]), silu_mul(a0[3], b0[3]));
;                 w.z = cvt_pk_bf16(silu_mul(a1[0], b1[0]), silu_mul(a1[1], b1[1])); w.w = cvt_pk_bf16(silu_mul(a1[2], b1[2]), silu_mul(a1[3], b1[3]));
;                 *(u32x4*)rowp = w; }
.LBB0_2921:
	s_lshl_b32 s2, s2, 8
	s_add_i32 s11, s2, s34
	s_lshl_b64 s[18:19], s[18:19], 2
	s_add_u32 s13, s35, s18
	s_addc_u32 s18, s38, s19
	s_lshl_b32 s2, s3, 8
	v_lshl_or_b32 v164, s3, 7, v172
	s_ashr_i32 s3, s2, 31
	s_lshl_b64 s[2:3], s[2:3], 2
	s_add_u32 s2, s13, s2
	s_addc_u32 s3, s18, s3
	v_or_b32_e32 v162, s11, v170
	s_add_u32 s2, s2, s44
	v_ashrrev_i32_e32 v163, 31, v162
	s_addc_u32 s3, s3, 0
	v_lshl_add_u64 v[162:163], v[162:163], 2, s[0:1]
	v_mov_b32_e32 v74, v234
	v_mov_b32_e32 v75, v235
	v_mov_b32_e32 v76, v236
	v_mov_b32_e32 v77, v237
	v_mov_b32_e32 v78, v238
	v_mov_b32_e32 v79, v239
	v_mov_b32_e32 v80, v240
	v_mov_b32_e32 v81, v241
	v_mov_b32_e32 v66, v242
	v_mov_b32_e32 v67, v243
	v_mov_b32_e32 v68, v244
	v_mov_b32_e32 v69, v245
	v_mov_b32_e32 v70, v246
	v_mov_b32_e32 v71, v247
	v_mov_b32_e32 v72, v248
	v_mov_b32_e32 v73, v249
	v_or_b32_e32 v180, s11, v1
	v_mov_b32_e32 v162, v250
	s_waitcnt vmcnt(0)
	v_fmamk_f32 v162, v162, 0x3a000000, v177
	v_cmp_gt_f32_e32 vcc, s45, v162
	v_mul_f32_e32 v163, 0x4f800000, v162
	s_nop 0
	v_cndmask_b32_e32 v162, v162, v163, vcc
	v_sqrt_f32_e32 v163, v162
	s_nop 0
	v_add_u32_e32 v165, -1, v163
	v_fma_f32 v166, -v165, v163, v162
	v_cmp_ge_f32_e64 s[2:3], 0, v166
	v_add_u32_e32 v166, 1, v163
	s_nop 0
	v_cndmask_b32_e64 v165, v163, v165, s[2:3]
	v_fma_f32 v163, -v166, v163, v162
	v_cmp_lt_f32_e64 s[2:3], 0, v163
	s_nop 1
	v_cndmask_b32_e64 v163, v165, v166, s[2:3]
	v_mul_f32_e32 v165, 0x37800000, v163
	v_cndmask_b32_e32 v163, v163, v165, vcc
	v_cmp_class_f32_e32 vcc, v162, v178
	s_nop 1
	v_cndmask_b32_e32 v166, v163, v162, vcc
	v_add_u32_e32 v162, s11, v171
	v_ashrrev_i32_e32 v163, 31, v162
	v_lshl_add_u64 v[162:163], v[162:163], 2, s[0:1]
	v_mov_b32_e32 v162, v251
	v_fmamk_f32 v162, v162, 0x3a000000, v177
	v_cmp_gt_f32_e32 vcc, s45, v162
	v_mul_f32_e32 v163, 0x4f800000, v162
	s_nop 0
	v_cndmask_b32_e32 v162, v162, v163, vcc
	v_sqrt_f32_e32 v163, v162
	s_nop 0
	v_add_u32_e32 v165, -1, v163
	v_fma_f32 v167, -v165, v163, v162
	v_cmp_ge_f32_e64 s[2:3], 0, v167
	v_add_u32_e32 v167, 1, v163
	s_nop 0
	v_cndmask_b32_e64 v165, v163, v165, s[2:3]
	v_fma_f32 v163, -v167, v163, v162
	v_cmp_lt_f32_e64 s[2:3], 0, v163
	s_nop 1
	v_cndmask_b32_e64 v163, v165, v167, s[2:3]
	v_mul_f32_e32 v165, 0x37800000, v163
	v_cndmask_b32_e32 v163, v163, v165, vcc
	v_cmp_class_f32_e32 vcc, v162, v178
	v_ashrrev_i32_e32 v165, 31, v164
	v_lshlrev_b64 v[164:165], 1, v[164:165]
	v_cndmask_b32_e32 v181, v163, v162, vcc
	v_div_scale_f32 v162, s[2:3], v166, v166, 1.0
	v_rcp_f32_e32 v163, v162
	s_nop 0
	v_fma_f32 v167, -v162, v163, 1.0
	v_fmac_f32_e32 v163, v167, v163
	v_div_scale_f32 v167, vcc, 1.0, v166, 1.0
	v_mul_f32_e32 v168, v167, v163
	v_fma_f32 v182, -v162, v168, v167
	v_fmac_f32_e32 v168, v182, v163
	v_fma_f32 v162, -v162, v168, v167
	v_div_fmas_f32 v162, v162, v163, v168
	v_div_fixup_f32 v182, v162, v166, 1.0
	ds_bpermute_b32 v168, v179, v182
	v_mov_b64_e32 v[162:163], s[96:97]
	v_mad_i64_i32 v[166:167], s[2:3], v180, s43, v[162:163]
	v_lshl_add_u64 v[166:167], v[166:167], 0, v[164:165]
	s_waitcnt lgkmcnt(0)
	v_pk_fma_f32 v[142:143], v[142:143], v[168:169], v[78:79] op_sel_hi:[1,0,1]
	v_pk_fma_f32 v[134:135], v[134:135], v[168:169], v[70:71] op_sel_hi:[1,0,1]
	v_pk_fma_f32 v[184:185], v[132:133], v[168:169], v[68:69] op_sel_hi:[1,0,1]
	v_pk_fma_f32 v[132:133], v[130:131], v[168:169], v[66:67] op_sel_hi:[1,0,1]
	v_mul_f32_e32 v131, 0xbfb8aa3b, v142
	v_mul_f32_e32 v130, v142, v134
	v_exp_f32_e32 v131, v131
	v_mul_f32_e32 v134, 0xbfb8aa3b, v143
	v_exp_f32_e32 v134, v134
	v_pk_fma_f32 v[144:145], v[144:145], v[168:169], v[80:81] op_sel_hi:[1,0,1]
	v_add_f32_e32 v131, 1.0, v131
	v_rcp_f32_e32 v131, v131
	v_add_f32_e32 v134, 1.0, v134
	v_rcp_f32_e32 v134, v134
	v_pk_fma_f32 v[136:137], v[136:137], v[168:169], v[72:73] op_sel_hi:[1,0,1]
	v_mul_f32_e32 v130, v130, v131
	v_mul_f32_e32 v131, v143, v135
	v_mul_f32_e32 v131, v131, v134
	v_mul_f32_e32 v134, 0xbfb8aa3b, v144
	v_exp_f32_e32 v134, v134
	v_mul_f32_e32 v135, 0xbfb8aa3b, v145
	v_exp_f32_e32 v135, v135
	v_cvt_pk_bf16_f32 v130, v130, v131
	v_add_f32_e32 v134, 1.0, v134
	v_rcp_f32_e32 v134, v134
	v_add_f32_e32 v135, 1.0, v135
	v_rcp_f32_e32 v135, v135
	v_mul_f32_e32 v131, v144, v136
	v_mul_f32_e32 v131, v131, v134
	v_mul_f32_e32 v134, v145, v137
	v_pk_fma_f32 v[138:139], v[138:139], v[168:169], v[74:75] op_sel_hi:[1,0,1]
	v_mul_f32_e32 v134, v134, v135
	v_cvt_pk_bf16_f32 v131, v131, v134
	v_mul_f32_e32 v134, 0xbfb8aa3b, v138
	v_exp_f32_e32 v134, v134
	v_mul_f32_e32 v132, v138, v132
	v_pk_fma_f32 v[140:141], v[140:141], v[168:169], v[76:77] op_sel_hi:[1,0,1]
	v_mul_f32_e32 v133, v139, v133
	v_add_f32_e32 v134, 1.0, v134
	v_rcp_f32_e32 v134, v134
	v_mul_f32_e32 v135, 0xbfb8aa3b, v141
	v_exp_f32_e32 v135, v135
	v_mul_f32_e32 v132, v132, v134
	v_mul_f32_e32 v134, 0xbfb8aa3b, v139
	v_exp_f32_e32 v134, v134
	v_add_f32_e32 v135, 1.0, v135
	v_rcp_f32_e32 v135, v135
	v_add_f32_e32 v134, 1.0, v134
	v_rcp_f32_e32 v134, v134
	s_nop 0
	v_mul_f32_e32 v133, v133, v134
	v_mul_f32_e32 v134, 0xbfb8aa3b, v140
	v_exp_f32_e32 v134, v134
	v_cvt_pk_bf16_f32 v132, v132, v133
	v_mul_f32_e32 v133, v140, v184
	v_add_f32_e32 v134, 1.0, v134
	v_rcp_f32_e32 v134, v134
	s_nop 0
	v_mul_f32_e32 v133, v133, v134
	v_mul_f32_e32 v134, v141, v185
	v_mul_f32_e32 v134, v134, v135
	v_cvt_pk_bf16_f32 v133, v133, v134
	global_store_dwordx4 v[166:167], v[130:133], off
	ds_bpermute_b32 v130, v179, v182 offset:64
	s_nop 0
	v_or_b32_e32 v131, 16, v180
	v_mad_i64_i32 v[132:133], s[2:3], v131, s43, v[162:163]
	s_waitcnt lgkmcnt(0)
; __device__ __forceinline__ unsigned cvt_pk_bf16(float lo, float hi) { unsigned r; asm volatile("v_cvt_pk_bf16_f32 %0, %1, %2" : "=v"(r) : "v"(lo), "v"(hi)); return r; }
; __device__ __forceinline__ float silu_mul(float a, float b) { return a * b * __builtin_amdgcn_rcpf(1.0f + __builtin_amdgcn_exp2f(-a * LOG2E)); }
;     __device__ __forceinline__ void operator()(const f32x4 (&acc)[2][2][4][2], const Unit& u, int wr, int wc, int fr, int fq) const {
;     ...
;             for (int m = 0; m < 4; ++m) { const int row = row0 + ai * HALF + m * 16; const float rs = __shfl(ai ? rsl1 : rsl0, m * 16 + fr); bf16_t* rowp = O + (size_t)row * DFF + col0;
;                 const f32x4 a0 = acc[ai][0][m][0] * rs + ba0, a1 = acc[ai][0][m][1] * rs + ba1, b0 = acc[ai][1][m][0] * rs + bb0, b1 = acc[ai][1][m][1] * rs + bb1;
;                 u32x4 w; w.x = cvt_pk_bf16(silu_mul(a0[0], b0[0]), silu_mul(a0[1], b0[1])); w.y = cvt_pk_bf16(silu_mul(a0[2], b0[2]), silu_mul(a0[3], b0[3]));
;                 w.z = cvt_pk_bf16(silu_mul(a1[0], b1[0]), silu_mul(a1[1], b1[1])); w.w = cvt_pk_bf16(silu_mul(a1[2], b1[2]), silu_mul(a1[3], b1[3]));
;                 *(u32x4*)rowp = w; }
	v_pk_fma_f32 v[126:127], v[126:127], v[130:131], v[78:79] op_sel_hi:[1,0,1]
	v_pk_fma_f32 v[118:119], v[118:119], v[130:131], v[70:71] op_sel_hi:[1,0,1]
	v_pk_fma_f32 v[134:135], v[116:117], v[130:131], v[68:69] op_sel_hi:[1,0,1]
	v_pk_fma_f32 v[116:117], v[114:115], v[130:131], v[66:67] op_sel_hi:[1,0,1]
	v_mul_f32_e32 v115, 0xbfb8aa3b, v126
	v_mul_f32_e32 v114, v126, v118
	v_exp_f32_e32 v115, v115
	v_mul_f32_e32 v118, 0xbfb8aa3b, v127
	v_exp_f32_e32 v118, v118
	v_pk_fma_f32 v[128:129], v[128:129], v[130:131], v[80:81] op_sel_hi:[1,0,1]
	v_add_f32_e32 v115, 1.0, v115
	v_rcp_f32_e32 v115, v115
	v_add_f32_e32 v118, 1.0, v118
	v_rcp_f32_e32 v118, v118
	v_pk_fma_f32 v[120:121], v[120:121], v[130:131], v[72:73] op_sel_hi:[1,0,1]
	v_mul_f32_e32 v114, v114, v115
	v_mul_f32_e32 v115, v127, v119
	v_mul_f32_e32 v115, v115, v118
	v_mul_f32_e32 v118, 0xbfb8aa3b, v128
	v_exp_f32_e32 v118, v118
	v_mul_f32_e32 v119, 0xbfb8aa3b, v129
	v_exp_f32_e32 v119, v119
	v_cvt_pk_bf16_f32 v114, v114, v115
	v_add_f32_e32 v118, 1.0, v118
	v_rcp_f32_e32 v118, v118
	v_add_f32_e32 v119, 1.0, v119
	v_rcp_f32_e32 v119, v119
	v_mul_f32_e32 v115, v128, v120
	v_mul_f32_e32 v115, v115, v118
	v_mul_f32_e32 v118, v129, v121
	v_pk_fma_f32 v[122:123], v[122:123], v[130:131], v[74:75] op_sel_hi:[1,0,1]
	v_mul_f32_e32 v118, v118, v119
	v_cvt_pk_bf16_f32 v115, v115, v118
	v_mul_f32_e32 v118, 0xbfb8aa3b, v122
	v_exp_f32_e32 v118, v118
	v_mul_f32_e32 v116, v122, v116
	v_pk_fma_f32 v[124:125], v[124:125], v[130:131], v[76:77] op_sel_hi:[1,0,1]
	v_mul_f32_e32 v117, v123, v117
	v_add_f32_e32 v118, 1.0, v118
	v_rcp_f32_e32 v118, v118
	v_mul_f32_e32 v119, 0xbfb8aa3b, v125
	v_exp_f32_e32 v119, v119
	v_lshl_add_u64 v[132:133], v[132:133], 0, v[164:165]
	v_mul_f32_e32 v116, v116, v118
	v_mul_f32_e32 v118, 0xbfb8aa3b, v123
	v_exp_f32_e32 v118, v118
	v_add_f32_e32 v119, 1.0, v119
	v_rcp_f32_e32 v119, v119
	v_add_f32_e32 v118, 1.0, v118
	v_rcp_f32_e32 v118, v118
	s_nop 0
	v_mul_f32_e32 v117, v117, v118
	v_mul_f32_e32 v118, 0xbfb8aa3b, v124
	v_exp_f32_e32 v118, v118
	v_cvt_pk_bf16_f32 v116, v116, v117
	v_mul_f32_e32 v117, v124, v134
	v_add_f32_e32 v118, 1.0, v118
	v_rcp_f32_e32 v118, v118
	s_nop 0
	v_mul_f32_e32 v117, v117, v118
	v_mul_f32_e32 v118, v125, v135
	v_mul_f32_e32 v118, v118, v119
	v_cvt_pk_bf16_f32 v117, v117, v118
	global_store_dwordx4 v[132:133], v[114:117], off
	ds_bpermute_b32 v114, v179, v182 offset:128
	s_nop 0
	v_or_b32_e32 v115, 32, v180
	v_mad_i64_i32 v[116:117], s[2:3], v115, s43, v[162:163]
	s_waitcnt lgkmcnt(0)
	v_pk_fma_f32 v[110:111], v[110:111], v[114:115], v[78:79] op_sel_hi:[1,0,1]
	v_pk_fma_f32 v[102:103], v[102:103], v[114:115], v[70:71] op_sel_hi:[1,0,1]
	v_pk_fma_f32 v[118:119], v[100:101], v[114:115], v[68:69] op_sel_hi:[1,0,1]
	v_pk_fma_f32 v[100:101], v[98:99], v[114:115], v[66:67] op_sel_hi:[1,0,1]
	v_mul_f32_e32 v99, 0xbfb8aa3b, v110
	v_mul_f32_e32 v98, v110, v102
	v_exp_f32_e32 v99, v99
	v_mul_f32_e32 v102, 0xbfb8aa3b, v111
	v_exp_f32_e32 v102, v102
	v_pk_fma_f32 v[112:113], v[112:113], v[114:115], v[80:81] op_sel_hi:[1,0,1]
	v_add_f32_e32 v99, 1.0, v99
	v_rcp_f32_e32 v99, v99
	v_add_f32_e32 v102, 1.0, v102
	v_rcp_f32_e32 v102, v102
	v_pk_fma_f32 v[104:105], v[104:105], v[114:115], v[72:73] op_sel_hi:[1,0,1]
	v_mul_f32_e32 v98, v98, v99
	v_mul_f32_e32 v99, v111, v103
	v_mul_f32_e32 v99, v99, v102
	v_mul_f32_e32 v102, 0xbfb8aa3b, v112
	v_exp_f32_e32 v102, v102
	v_mul_f32_e32 v103, 0xbfb8aa3b, v113
	v_exp_f32_e32 v103, v103
	v_cvt_pk_bf16_f32 v98, v98, v99
	v_add_f32_e32 v102, 1.0, v102
	v_rcp_f32_e32 v102, v102
	v_add_f32_e32 v103, 1.0, v103
	v_rcp_f32_e32 v103, v103
	v_mul_f32_e32 v99, v112, v104
	v_mul_f32_e32 v99, v99, v102
	v_mul_f32_e32 v102, v113, v105
	v_pk_fma_f32 v[106:107], v[106:107], v[114:115], v[74:75] op_sel_hi:[1,0,1]
	v_mul_f32_e32 v102, v102, v103
	v_cvt_pk_bf16_f32 v99, v99, v102
	v_mul_f32_e32 v102, 0xbfb8aa3b, v106
	v_exp_f32_e32 v102, v102
	v_mul_f32_e32 v100, v106, v100
	v_pk_fma_f32 v[108:109], v[108:109], v[114:115], v[76:77] op_sel_hi:[1,0,1]
	v_mul_f32_e32 v101, v107, v101
	v_add_f32_e32 v102, 1.0, v102
	v_rcp_f32_e32 v102, v102
	v_mul_f32_e32 v103, 0xbfb8aa3b, v109
	v_exp_f32_e32 v103, v103
	v_lshl_add_u64 v[116:117], v[116:117], 0, v[164:165]
	v_mul_f32_e32 v100, v100, v102
	v_mul_f32_e32 v102, 0xbfb8aa3b, v107
	v_exp_f32_e32 v102, v102
	v_add_f32_e32 v103, 1.0, v103
	v_rcp_f32_e32 v103, v103
	v_add_f32_e32 v102, 1.0, v102
	v_rcp_f32_e32 v102, v102
	s_nop 0
	v_mul_f32_e32 v101, v101, v102
	v_mul_f32_e32 v102, 0xbfb8aa3b, v108
	v_exp_f32_e32 v102, v102
	v_cvt_pk_bf16_f32 v100, v100, v101
	v_mul_f32_e32 v101, v108, v118
	v_add_f32_e32 v102, 1.0, v102
	v_rcp_f32_e32 v102, v102
	s_nop 0
	v_mul_f32_e32 v101, v101, v102
	v_mul_f32_e32 v102, v109, v119
	v_mul_f32_e32 v102, v102, v103
	v_cvt_pk_bf16_f32 v101, v101, v102
	global_store_dwordx4 v[116:117], v[98:101], off
	ds_bpermute_b32 v98, v179, v182 offset:192
	s_nop 0
	v_or_b32_e32 v99, 48, v180
	v_mad_i64_i32 v[100:101], s[2:3], v99, s43, v[162:163]
	s_waitcnt lgkmcnt(0)
; __device__ __forceinline__ unsigned cvt_pk_bf16(float lo, float hi) { unsigned r; asm volatile("v_cvt_pk_bf16_f32 %0, %1, %2" : "=v"(r) : "v"(lo), "v"(hi)); return r; }
; __device__ __forceinline__ float row_rstd(const float* ss, int row) { return 1.0f / sqrtf(ss[row] * (1.0f / DM) + 1e-6f); }
; __device__ __forceinline__ float silu_mul(float a, float b) { return a * b * __builtin_amdgcn_rcpf(1.0f + __builtin_amdgcn_exp2f(-a * LOG2E)); }
;     __device__ __forceinline__ void operator()(const f32x4 (&acc)[2][2][4][2], const Unit& u, int wr, int wc, int fr, int fq) const {
;     ...
;         const float rsl0 = row_rstd(ss, u.pm * BM + wr * 64 + lane), rsl1 = row_rstd(ss, u.pm * BM + HALF + wr * 64 + lane);
; #pragma unroll
;         for (int ai = 0; ai < 2; ++ai)
; #pragma unroll
;             for (int m = 0; m < 4; ++m) { const int row = row0 + ai * HALF + m * 16; const float rs = __shfl(ai ? rsl1 : rsl0, m * 16 + fr); bf16_t* rowp = O + (size_t)row * DFF + col0;
;                 const f32x4 a0 = acc[ai][0][m][0] * rs + ba0, a1 = acc[ai][0][m][1] * rs + ba1, b0 = acc[ai][1][m][0] * rs + bb0, b1 = acc[ai][1][m][1] * rs + bb1;
;                 u32x4 w; w.x = cvt_pk_bf16(silu_mul(a0[0], b0[0]), silu_mul(a0[1], b0[1])); w.y = cvt_pk_bf16(silu_mul(a0[2], b0[2]), silu_mul(a0[3], b0[3]));
;                 w.z = cvt_pk_bf16(silu_mul(a1[0], b1[0]), silu_mul(a1[1], b1[1])); w.w = cvt_pk_bf16(silu_mul(a1[2], b1[2]), silu_mul(a1[3], b1[3]));
;                 *(u32x4*)rowp = w; }
	v_pk_fma_f32 v[94:95], v[94:95], v[98:99], v[78:79] op_sel_hi:[1,0,1]
	v_pk_fma_f32 v[86:87], v[86:87], v[98:99], v[70:71] op_sel_hi:[1,0,1]
	v_pk_fma_f32 v[102:103], v[84:85], v[98:99], v[68:69] op_sel_hi:[1,0,1]
	v_pk_fma_f32 v[84:85], v[82:83], v[98:99], v[66:67] op_sel_hi:[1,0,1]
	v_mul_f32_e32 v83, 0xbfb8aa3b, v94
	v_mul_f32_e32 v82, v94, v86
	v_exp_f32_e32 v83, v83
	v_mul_f32_e32 v86, 0xbfb8aa3b, v95
	v_exp_f32_e32 v86, v86
	v_pk_fma_f32 v[96:97], v[96:97], v[98:99], v[80:81] op_sel_hi:[1,0,1]
	v_add_f32_e32 v83, 1.0, v83
	v_rcp_f32_e32 v83, v83
	v_add_f32_e32 v86, 1.0, v86
	v_rcp_f32_e32 v86, v86
	v_pk_fma_f32 v[88:89], v[88:89], v[98:99], v[72:73] op_sel_hi:[1,0,1]
	v_mul_f32_e32 v82, v82, v83
	v_mul_f32_e32 v83, v95, v87
	v_mul_f32_e32 v83, v83, v86
	v_mul_f32_e32 v86, 0xbfb8aa3b, v96
	v_exp_f32_e32 v86, v86
	v_mul_f32_e32 v87, 0xbfb8aa3b, v97
	v_exp_f32_e32 v87, v87
	v_cvt_pk_bf16_f32 v82, v82, v83
	v_add_f32_e32 v86, 1.0, v86
	v_rcp_f32_e32 v86, v86
	v_add_f32_e32 v87, 1.0, v87
	v_rcp_f32_e32 v87, v87
	v_mul_f32_e32 v83, v96, v88
	v_mul_f32_e32 v83, v83, v86
	v_mul_f32_e32 v86, v97, v89
	v_pk_fma_f32 v[90:91], v[90:91], v[98:99], v[74:75] op_sel_hi:[1,0,1]
	v_mul_f32_e32 v86, v86, v87
	v_cvt_pk_bf16_f32 v83, v83, v86
	v_mul_f32_e32 v86, 0xbfb8aa3b, v90
	v_exp_f32_e32 v86, v86
	v_mul_f32_e32 v84, v90, v84
	v_pk_fma_f32 v[92:93], v[92:93], v[98:99], v[76:77] op_sel_hi:[1,0,1]
	v_mul_f32_e32 v85, v91, v85
	v_add_f32_e32 v86, 1.0, v86
	v_rcp_f32_e32 v86, v86
	v_mul_f32_e32 v87, 0xbfb8aa3b, v93
	v_exp_f32_e32 v87, v87
	v_lshl_add_u64 v[100:101], v[100:101], 0, v[164:165]
	v_mul_f32_e32 v84, v84, v86
	v_mul_f32_e32 v86, 0xbfb8aa3b, v91
	v_exp_f32_e32 v86, v86
	v_add_f32_e32 v87, 1.0, v87
	v_rcp_f32_e32 v87, v87
	v_add_f32_e32 v86, 1.0, v86
	v_rcp_f32_e32 v86, v86
	s_nop 0
	v_mul_f32_e32 v85, v85, v86
	v_mul_f32_e32 v86, 0xbfb8aa3b, v92
	v_exp_f32_e32 v86, v86
	v_cvt_pk_bf16_f32 v84, v84, v85
	v_mul_f32_e32 v85, v92, v102
	v_add_f32_e32 v86, 1.0, v86
	v_rcp_f32_e32 v86, v86
	s_nop 0
	v_mul_f32_e32 v85, v85, v86
	v_mul_f32_e32 v86, v93, v103
	v_mul_f32_e32 v86, v86, v87
	v_cvt_pk_bf16_f32 v85, v85, v86
	global_store_dwordx4 v[100:101], v[82:85], off
	s_nop 1
	v_div_scale_f32 v82, s[2:3], v181, v181, 1.0
	v_rcp_f32_e32 v84, v82
	v_add_u32_e32 v83, 0x80, v180
	v_fma_f32 v85, -v82, v84, 1.0
	v_fmac_f32_e32 v84, v85, v84
	v_div_scale_f32 v85, vcc, 1.0, v181, 1.0
	v_mul_f32_e32 v86, v85, v84
	v_fma_f32 v87, -v82, v86, v85
	v_fmac_f32_e32 v86, v87, v84
	v_fma_f32 v82, -v82, v86, v85
	v_div_fmas_f32 v82, v82, v84, v86
	v_div_fixup_f32 v82, v82, v181, 1.0
	ds_bpermute_b32 v84, v179, v82
	v_mad_i64_i32 v[86:87], s[2:3], v83, s43, v[162:163]
	v_lshl_add_u64 v[86:87], v[86:87], 0, v[164:165]
	s_and_b64 vcc, s[36:37], exec
	s_waitcnt lgkmcnt(0)
	v_pk_fma_f32 v[62:63], v[62:63], v[84:85], v[78:79] op_sel_hi:[1,0,1]
	v_pk_fma_f32 v[54:55], v[54:55], v[84:85], v[70:71] op_sel_hi:[1,0,1]
	v_pk_fma_f32 v[88:89], v[52:53], v[84:85], v[68:69] op_sel_hi:[1,0,1]
	v_pk_fma_f32 v[52:53], v[50:51], v[84:85], v[66:67] op_sel_hi:[1,0,1]
	v_mul_f32_e32 v51, 0xbfb8aa3b, v62
	v_mul_f32_e32 v50, v62, v54
	v_exp_f32_e32 v51, v51
	v_mul_f32_e32 v54, 0xbfb8aa3b, v63
	v_exp_f32_e32 v54, v54
	v_pk_fma_f32 v[64:65], v[64:65], v[84:85], v[80:81] op_sel_hi:[1,0,1]
	v_add_f32_e32 v51, 1.0, v51
	v_rcp_f32_e32 v51, v51
	v_add_f32_e32 v54, 1.0, v54
	v_rcp_f32_e32 v54, v54
	v_pk_fma_f32 v[56:57], v[56:57], v[84:85], v[72:73] op_sel_hi:[1,0,1]
	v_mul_f32_e32 v50, v50, v51
	v_mul_f32_e32 v51, v63, v55
	v_mul_f32_e32 v51, v51, v54
	v_mul_f32_e32 v54, 0xbfb8aa3b, v64
	v_exp_f32_e32 v54, v54
	v_mul_f32_e32 v55, 0xbfb8aa3b, v65
	v_exp_f32_e32 v55, v55
	v_cvt_pk_bf16_f32 v50, v50, v51
	v_add_f32_e32 v54, 1.0, v54
	v_rcp_f32_e32 v54, v54
	v_add_f32_e32 v55, 1.0, v55
	v_rcp_f32_e32 v55, v55
	v_mul_f32_e32 v51, v64, v56
	v_mul_f32_e32 v51, v51, v54
	v_mul_f32_e32 v54, v65, v57
	v_pk_fma_f32 v[58:59], v[58:59], v[84:85], v[74:75] op_sel_hi:[1,0,1]
	v_mul_f32_e32 v54, v54, v55
	v_cvt_pk_bf16_f32 v51, v51, v54
	v_mul_f32_e32 v54, 0xbfb8aa3b, v58
	v_exp_f32_e32 v54, v54
	v_mul_f32_e32 v52, v58, v52
	v_pk_fma_f32 v[60:61], v[60:61], v[84:85], v[76:77] op_sel_hi:[1,0,1]
	v_mul_f32_e32 v53, v59, v53
	v_add_f32_e32 v54, 1.0, v54
	v_rcp_f32_e32 v54, v54
	v_mul_f32_e32 v55, 0xbfb8aa3b, v61
	v_exp_f32_e32 v55, v55
	v_mul_f32_e32 v52, v52, v54
	v_mul_f32_e32 v54, 0xbfb8aa3b, v59
	v_exp_f32_e32 v54, v54
	v_add_f32_e32 v55, 1.0, v55
	v_rcp_f32_e32 v55, v55
	v_add_f32_e32 v54, 1.0, v54
	v_rcp_f32_e32 v54, v54
	s_nop 0
	v_mul_f32_e32 v53, v53, v54
	v_mul_f32_e32 v54, 0xbfb8aa3b, v60
	v_exp_f32_e32 v54, v54
	v_cvt_pk_bf16_f32 v52, v52, v53
	v_mul_f32_e32 v53, v60, v88
	v_add_f32_e32 v54, 1.0, v54
	v_rcp_f32_e32 v54, v54
	s_nop 0
	v_mul_f32_e32 v53, v53, v54
	v_mul_f32_e32 v54, v61, v89
	v_mul_f32_e32 v54, v54, v55
	v_cvt_pk_bf16_f32 v53, v53, v54
	global_store_dwordx4 v[86:87], v[50:53], off
	ds_bpermute_b32 v50, v179, v82 offset:64
	s_nop 0
	v_add_u32_e32 v51, 0x90, v180
	v_mad_i64_i32 v[52:53], s[2:3], v51, s43, v[162:163]
	s_waitcnt lgkmcnt(0)
; __device__ __forceinline__ unsigned cvt_pk_bf16(float lo, float hi) { unsigned r; asm volatile("v_cvt_pk_bf16_f32 %0, %1, %2" : "=v"(r) : "v"(lo), "v"(hi)); return r; }
; __device__ __forceinline__ float silu_mul(float a, float b) { return a * b * __builtin_amdgcn_rcpf(1.0f + __builtin_amdgcn_exp2f(-a * LOG2E)); }
; #define PG8_BAR __builtin_amdgcn_s_barrier()
;     __device__ __forceinline__ void operator()(const f32x4 (&acc)[2][2][4][2], const Unit& u, int wr, int wc, int fr, int fq) const {
;     ...
;             for (int m = 0; m < 4; ++m) { const int row = row0 + ai * HALF + m * 16; const float rs = __shfl(ai ? rsl1 : rsl0, m * 16 + fr); bf16_t* rowp = O + (size_t)row * DFF + col0;
;                 const f32x4 a0 = acc[ai][0][m][0] * rs + ba0, a1 = acc[ai][0][m][1] * rs + ba1, b0 = acc[ai][1][m][0] * rs + bb0, b1 = acc[ai][1][m][1] * rs + bb1;
;                 u32x4 w; w.x = cvt_pk_bf16(silu_mul(a0[0], b0[0]), silu_mul(a0[1], b0[1])); w.y = cvt_pk_bf16(silu_mul(a0[2], b0[2]), silu_mul(a0[3], b0[3]));
;                 w.z = cvt_pk_bf16(silu_mul(a1[0], b1[0]), silu_mul(a1[1], b1[1])); w.w = cvt_pk_bf16(silu_mul(a1[2], b1[2]), silu_mul(a1[3], b1[3]));
;                 *(u32x4*)rowp = w; }
; template <class Epi, class Sched, bool ALIGN_EPI = false, bool SP2 = false>
; __device__ __forceinline__ void gemm_phase(LAS unsigned char* lds, const Gemm g, const Sched& S, const Epi& E) {
;     ...
;         if constexpr (!Epi::AFTER_DRAIN) { E(acc, cur, wr, wc, fr, fq); S.done(cur); }
;         if (!has_next) break;
; #pragma unroll
;         for (int a = 0; a < 2; ++a)
; #pragma unroll
;             for (int b = 0; b < 2; ++b)
; #pragma unroll
;                 for (int m = 0; m < 4; ++m)
; #pragma unroll
;                     for (int n = 0; n < 2; ++n) acc[a][b][m][n] = (f32x4){0.f, 0.f, 0.f, 0.f};
;         cur = nxt; cA = nA; cB = nB; ++ui;
;         if constexpr (ALIGN_EPI) { if (wr == 1) PG8_BAR; }
	v_pk_fma_f32 v[46:47], v[46:47], v[50:51], v[78:79] op_sel_hi:[1,0,1]
	v_pk_fma_f32 v[38:39], v[38:39], v[50:51], v[70:71] op_sel_hi:[1,0,1]
	v_pk_fma_f32 v[54:55], v[36:37], v[50:51], v[68:69] op_sel_hi:[1,0,1]
	v_pk_fma_f32 v[36:37], v[34:35], v[50:51], v[66:67] op_sel_hi:[1,0,1]
	v_mul_f32_e32 v35, 0xbfb8aa3b, v46
	v_mul_f32_e32 v34, v46, v38
	v_exp_f32_e32 v35, v35
	v_mul_f32_e32 v38, 0xbfb8aa3b, v47
	v_exp_f32_e32 v38, v38
	v_pk_fma_f32 v[48:49], v[48:49], v[50:51], v[80:81] op_sel_hi:[1,0,1]
	v_add_f32_e32 v35, 1.0, v35
	v_rcp_f32_e32 v35, v35
	v_add_f32_e32 v38, 1.0, v38
	v_rcp_f32_e32 v38, v38
	v_pk_fma_f32 v[40:41], v[40:41], v[50:51], v[72:73] op_sel_hi:[1,0,1]
	v_mul_f32_e32 v34, v34, v35
	v_mul_f32_e32 v35, v47, v39
	v_mul_f32_e32 v35, v35, v38
	v_mul_f32_e32 v38, 0xbfb8aa3b, v48
	v_exp_f32_e32 v38, v38
	v_mul_f32_e32 v39, 0xbfb8aa3b, v49
	v_exp_f32_e32 v39, v39
	v_cvt_pk_bf16_f32 v34, v34, v35
	v_add_f32_e32 v38, 1.0, v38
	v_rcp_f32_e32 v38, v38
	v_add_f32_e32 v39, 1.0, v39
	v_rcp_f32_e32 v39, v39
	v_mul_f32_e32 v35, v48, v40
	v_mul_f32_e32 v35, v35, v38
	v_mul_f32_e32 v38, v49, v41
	v_pk_fma_f32 v[42:43], v[42:43], v[50:51], v[74:75] op_sel_hi:[1,0,1]
	v_mul_f32_e32 v38, v38, v39
	v_cvt_pk_bf16_f32 v35, v35, v38
	v_mul_f32_e32 v38, 0xbfb8aa3b, v42
	v_exp_f32_e32 v38, v38
	v_mul_f32_e32 v36, v42, v36
	v_pk_fma_f32 v[44:45], v[44:45], v[50:51], v[76:77] op_sel_hi:[1,0,1]
	v_mul_f32_e32 v37, v43, v37
	v_add_f32_e32 v38, 1.0, v38
	v_rcp_f32_e32 v38, v38
	v_mul_f32_e32 v39, 0xbfb8aa3b, v45
	v_exp_f32_e32 v39, v39
	v_lshl_add_u64 v[52:53], v[52:53], 0, v[164:165]
	v_mul_f32_e32 v36, v36, v38
	v_mul_f32_e32 v38, 0xbfb8aa3b, v43
	v_exp_f32_e32 v38, v38
	v_add_f32_e32 v39, 1.0, v39
	v_rcp_f32_e32 v39, v39
	v_add_f32_e32 v38, 1.0, v38
	v_rcp_f32_e32 v38, v38
	s_nop 0
	v_mul_f32_e32 v37, v37, v38
	v_mul_f32_e32 v38, 0xbfb8aa3b, v44
	v_exp_f32_e32 v38, v38
	v_cvt_pk_bf16_f32 v36, v36, v37
	v_mul_f32_e32 v37, v44, v54
	v_add_f32_e32 v38, 1.0, v38
	v_rcp_f32_e32 v38, v38
	s_nop 0
	v_mul_f32_e32 v37, v37, v38
	v_mul_f32_e32 v38, v45, v55
	v_mul_f32_e32 v38, v38, v39
	v_cvt_pk_bf16_f32 v37, v37, v38
	global_store_dwordx4 v[52:53], v[34:37], off
	ds_bpermute_b32 v34, v179, v82 offset:128
	s_nop 0
	v_add_u32_e32 v35, 0xa0, v180
	v_mad_i64_i32 v[36:37], s[2:3], v35, s43, v[162:163]
	s_waitcnt lgkmcnt(0)
	v_pk_fma_f32 v[30:31], v[30:31], v[34:35], v[78:79] op_sel_hi:[1,0,1]
	v_pk_fma_f32 v[22:23], v[22:23], v[34:35], v[70:71] op_sel_hi:[1,0,1]
	v_pk_fma_f32 v[38:39], v[20:21], v[34:35], v[68:69] op_sel_hi:[1,0,1]
	v_pk_fma_f32 v[20:21], v[18:19], v[34:35], v[66:67] op_sel_hi:[1,0,1]
	v_mul_f32_e32 v19, 0xbfb8aa3b, v30
	v_mul_f32_e32 v18, v30, v22
	v_exp_f32_e32 v19, v19
	v_mul_f32_e32 v22, 0xbfb8aa3b, v31
	v_exp_f32_e32 v22, v22
	v_pk_fma_f32 v[32:33], v[32:33], v[34:35], v[80:81] op_sel_hi:[1,0,1]
	v_add_f32_e32 v19, 1.0, v19
	v_rcp_f32_e32 v19, v19
	v_add_f32_e32 v22, 1.0, v22
	v_rcp_f32_e32 v22, v22
	v_pk_fma_f32 v[24:25], v[24:25], v[34:35], v[72:73] op_sel_hi:[1,0,1]
	v_mul_f32_e32 v18, v18, v19
	v_mul_f32_e32 v19, v31, v23
	v_mul_f32_e32 v19, v19, v22
	v_mul_f32_e32 v22, 0xbfb8aa3b, v32
	v_exp_f32_e32 v22, v22
	v_mul_f32_e32 v23, 0xbfb8aa3b, v33
	v_exp_f32_e32 v23, v23
	v_cvt_pk_bf16_f32 v18, v18, v19
	v_add_f32_e32 v22, 1.0, v22
	v_rcp_f32_e32 v22, v22
	v_add_f32_e32 v23, 1.0, v23
	v_rcp_f32_e32 v23, v23
	v_mul_f32_e32 v19, v32, v24
	v_mul_f32_e32 v19, v19, v22
	v_mul_f32_e32 v22, v33, v25
	v_pk_fma_f32 v[26:27], v[26:27], v[34:35], v[74:75] op_sel_hi:[1,0,1]
	v_mul_f32_e32 v22, v22, v23
	v_cvt_pk_bf16_f32 v19, v19, v22
	v_mul_f32_e32 v22, 0xbfb8aa3b, v26
	v_exp_f32_e32 v22, v22
	v_mul_f32_e32 v20, v26, v20
	v_pk_fma_f32 v[28:29], v[28:29], v[34:35], v[76:77] op_sel_hi:[1,0,1]
	v_mul_f32_e32 v21, v27, v21
	v_add_f32_e32 v22, 1.0, v22
	v_rcp_f32_e32 v22, v22
	v_mul_f32_e32 v23, 0xbfb8aa3b, v29
	v_exp_f32_e32 v23, v23
	v_lshl_add_u64 v[36:37], v[36:37], 0, v[164:165]
	v_mul_f32_e32 v20, v20, v22
	v_mul_f32_e32 v22, 0xbfb8aa3b, v27
	v_exp_f32_e32 v22, v22
	v_add_f32_e32 v23, 1.0, v23
	v_rcp_f32_e32 v23, v23
	v_add_f32_e32 v22, 1.0, v22
	v_rcp_f32_e32 v22, v22
	s_nop 0
	v_mul_f32_e32 v21, v21, v22
	v_mul_f32_e32 v22, 0xbfb8aa3b, v28
	v_exp_f32_e32 v22, v22
	v_cvt_pk_bf16_f32 v20, v20, v21
	v_mul_f32_e32 v21, v28, v38
	v_add_f32_e32 v22, 1.0, v22
	v_rcp_f32_e32 v22, v22
	s_nop 0
	v_mul_f32_e32 v21, v21, v22
	v_mul_f32_e32 v22, v29, v39
	v_mul_f32_e32 v22, v22, v23
	v_cvt_pk_bf16_f32 v21, v21, v22
	global_store_dwordx4 v[36:37], v[18:21], off
	ds_bpermute_b32 v18, v179, v82 offset:192
	s_nop 0
	v_add_u32_e32 v19, 0xb0, v180
	v_mad_i64_i32 v[20:21], s[2:3], v19, s43, v[162:163]
	s_waitcnt lgkmcnt(0)
	v_pk_fma_f32 v[14:15], v[14:15], v[18:19], v[78:79] op_sel_hi:[1,0,1]
	v_pk_fma_f32 v[6:7], v[6:7], v[18:19], v[70:71] op_sel_hi:[1,0,1]
	v_pk_fma_f32 v[22:23], v[4:5], v[18:19], v[68:69] op_sel_hi:[1,0,1]
	v_pk_fma_f32 v[4:5], v[2:3], v[18:19], v[66:67] op_sel_hi:[1,0,1]
	v_mul_f32_e32 v3, 0xbfb8aa3b, v14
	v_mul_f32_e32 v2, v14, v6
	v_exp_f32_e32 v3, v3
	v_mul_f32_e32 v6, 0xbfb8aa3b, v15
	v_exp_f32_e32 v6, v6
	v_pk_fma_f32 v[16:17], v[16:17], v[18:19], v[80:81] op_sel_hi:[1,0,1]
	v_add_f32_e32 v3, 1.0, v3
	v_rcp_f32_e32 v3, v3
	v_add_f32_e32 v6, 1.0, v6
	v_rcp_f32_e32 v6, v6
	v_pk_fma_f32 v[8:9], v[8:9], v[18:19], v[72:73] op_sel_hi:[1,0,1]
	v_mul_f32_e32 v2, v2, v3
	v_mul_f32_e32 v3, v15, v7
	v_mul_f32_e32 v3, v3, v6
	v_mul_f32_e32 v6, 0xbfb8aa3b, v16
	v_exp_f32_e32 v6, v6
	v_mul_f32_e32 v7, 0xbfb8aa3b, v17
	v_exp_f32_e32 v7, v7
	v_cvt_pk_bf16_f32 v2, v2, v3
	v_add_f32_e32 v6, 1.0, v6
	v_rcp_f32_e32 v6, v6
	v_add_f32_e32 v7, 1.0, v7
	v_rcp_f32_e32 v7, v7
	v_mul_f32_e32 v3, v16, v8
	v_mul_f32_e32 v3, v3, v6
	v_mul_f32_e32 v6, v17, v9
	v_pk_fma_f32 v[10:11], v[10:11], v[18:19], v[74:75] op_sel_hi:[1,0,1]
	v_mul_f32_e32 v6, v6, v7
	v_cvt_pk_bf16_f32 v3, v3, v6
	v_mul_f32_e32 v6, 0xbfb8aa3b, v10
	v_exp_f32_e32 v6, v6
	v_mul_f32_e32 v4, v10, v4
	v_pk_fma_f32 v[12:13], v[12:13], v[18:19], v[76:77] op_sel_hi:[1,0,1]
	v_mul_f32_e32 v5, v11, v5
	v_add_f32_e32 v6, 1.0, v6
	v_rcp_f32_e32 v6, v6
	v_mul_f32_e32 v7, 0xbfb8aa3b, v13
	v_exp_f32_e32 v7, v7
	v_lshl_add_u64 v[20:21], v[20:21], 0, v[164:165]
	v_mul_f32_e32 v4, v4, v6
	v_mul_f32_e32 v6, 0xbfb8aa3b, v11
	v_exp_f32_e32 v6, v6
	v_add_f32_e32 v7, 1.0, v7
	v_rcp_f32_e32 v7, v7
	s_mov_b64 s[2:3], -1
	v_add_f32_e32 v6, 1.0, v6
	v_rcp_f32_e32 v6, v6
	s_nop 0
	v_mul_f32_e32 v5, v5, v6
	v_mul_f32_e32 v6, 0xbfb8aa3b, v12
	v_exp_f32_e32 v6, v6
	v_cvt_pk_bf16_f32 v4, v4, v5
	v_mul_f32_e32 v5, v12, v22
	v_add_f32_e32 v6, 1.0, v6
	v_rcp_f32_e32 v6, v6
	s_nop 0
	v_mul_f32_e32 v5, v5, v6
	v_mul_f32_e32 v6, v13, v23
	v_mul_f32_e32 v6, v6, v7
	v_cvt_pk_bf16_f32 v5, v5, v6
	global_store_dwordx4 v[20:21], v[2:5], off
	s_cbranch_vccz .LBB0_2912
	s_andn2_b64 vcc, exec, s[4:5]
	s_cbranch_vccnz .LBB0_2911
	s_barrier
	s_branch .LBB0_2911

; #define PG8_WAIT_V(n) asm volatile("s_waitcnt vmcnt(" #n ")" ::: "memory")
; template <class Epi, class Sched, bool ALIGN_EPI = false, bool SP2 = false>
; __device__ __forceinline__ void gemm_phase(LAS unsigned char* lds, const Gemm g, const Sched& S, const Epi& E) {
;     ...
;     f32x4 acc[2][2][4][2];
; #pragma unroll
;     for (int a = 0; a < 2; ++a)
; #pragma unroll
;         for (int b = 0; b < 2; ++b)
; #pragma unroll
;             for (int m = 0; m < 4; ++m)
; #pragma unroll
;                 for (int n = 0; n < 2; ++n) acc[a][b][m][n] = (f32x4){0.f, 0.f, 0.f, 0.f};
;     bf16x8 At[4][2], B0[2][2], B1[2][2];
;     const char* cA = (const char*)g.A + (size_t)cur.pm * tstep + cur.koff; const char* cB = (const char*)g.Bt + (size_t)cur.pn * tstep + cur.koff;
;     S.a_ready(cur);
;     if constexpr (SP2) {
;         PG8_STAGE(PG8_SB(0, 0), cB, voffB); PG8_STAGE(PG8_SB(0, 1), cB + hstepB, voffB); PG8_STAGE(PG8_SA(0, 0), cA, voffA); PG8_STAGE(PG8_SA(0, 1), cA + hstep, voffA);
;         if (wr == 1) PG8_BAR;
;         PG8_WAIT_V(2); PG8_BAR;
;         PG8_STAGE(PG8_SB(1, 0), cB + kstep, voffB); PG8_STAGE(PG8_SA(1, 0), cA + kstep, voffA); PG8_STAGE(PG8_SB(1, 1), cB + hstepB + kstep, voffB);
;         PG8_WAIT_V(6); PG8_BAR;
;     } else {
;         PG8_STAGE(PG8_SB(0, 0), cB, voffB); PG8_STAGE(PG8_SA(0, 0), cA, voffA); PG8_STAGE(PG8_SB(0, 1), cB + hstepB, voffB); PG8_STAGE(PG8_SA(0, 1), cA + hstep, voffA);
;         if (wr == 1) PG8_BAR;
;         PG8_WAIT_V(4); PG8_BAR;
;         PG8_STAGE(PG8_SB(1, 0), cB + kstep, voffB); PG8_STAGE(PG8_SA(1, 0), cA + kstep, voffA); PG8_STAGE(PG8_SB(1, 1), cB + hstepB + kstep, voffB);
;         PG8_WAIT_V(6); PG8_BAR;
;     }
;     for (;;) {
;         const bool has_next = S.next(ui + 1, nxt);
;         const char* nA = has_next ? (const char*)g.A + (size_t)nxt.pm * tstep + nxt.koff : cA; const char* nB = has_next ? (const char*)g.Bt + (size_t)nxt.pn * tstep + nxt.koff : cB;
;         for (int t = 0; t < nt; t += 2) {
;             const bool last = (t == nt - 2);
;             const char* a1 = cA + (size_t)(t + 1) * kstep;
;             const char* a2 = last ? nA : cA + (size_t)(t + 2) * kstep; const char* b2 = last ? nB : cB + (size_t)(t + 2) * kstep;
;             const char* a3 = a2 + kstep; const char* b3 = b2 + kstep;
;             if (last && has_next) S.a_ready(nxt);
;             if constexpr (SP2) {
.LBB0_3001:
	s_add_u32 s13, s16, 0x100
	s_addc_u32 s39, s17, 0
	s_mov_b32 s40, -2
	s_waitcnt vmcnt(0)
	ds_read_b128 v[152:155], v147
	ds_read_b128 v[156:159], v147 offset:1024
	ds_read_b128 v[160:163], v147 offset:2048
	ds_read_b128 v[164:167], v147 offset:3072
	ds_read_b128 v[168:171], v148
	ds_read_b128 v[172:175], v148 offset:1024
	ds_read_b128 v[176:179], v148 offset:2048
	ds_read_b128 v[180:183], v148 offset:3072
	s_add_u32 s16, s14, 0x100
	s_addc_u32 s17, s15, 0
	s_cmpk_eq_i32 s40, 0x54
	s_cselect_b32 s21, s11, s17
	s_cselect_b32 s20, s10, s16
	s_cselect_b32 s19, s3, s39
	s_cselect_b32 s18, s2, s13
	v_lshl_add_u64 v[216:217], s[14:15], 0, v[138:139]
	s_add_i32 m0, s24, 0xc000
	ds_read_b128 v[184:187], v149
	ds_read_b128 v[188:191], v149 offset:1024
	ds_read_b128 v[192:195], v149 offset:2048
	ds_read_b128 v[196:199], v149 offset:3072
	ds_read_b128 v[200:203], v149 offset:4096
	ds_read_b128 v[204:207], v149 offset:5120
	ds_read_b128 v[208:211], v149 offset:6144
	ds_read_b128 v[212:215], v149 offset:7168
	global_load_lds_dwordx4 v[216:217], off
	v_lshl_add_u64 v[216:217], s[14:15], 0, v[136:137]
	s_add_i32 m0, s24, 0xe000
	s_nop 0
	global_load_lds_dwordx4 v[216:217], off
	s_waitcnt lgkmcnt(0)
	s_barrier
	s_setprio 1
	s_waitcnt lgkmcnt(0)
	v_mfma_f32_16x16x32_bf16 v[124:127], v[152:155], v[184:187], 0
	v_mfma_f32_16x16x32_bf16 v[120:123], v[160:163], v[184:187], 0
	v_mfma_f32_16x16x32_bf16 v[112:115], v[152:155], v[192:195], 0
	v_mfma_f32_16x16x32_bf16 v[104:107], v[160:163], v[192:195], 0
	v_mfma_f32_16x16x32_bf16 v[92:95], v[152:155], v[200:203], 0
	v_mfma_f32_16x16x32_bf16 v[88:91], v[160:163], v[200:203], 0
	v_mfma_f32_16x16x32_bf16 v[76:79], v[152:155], v[208:211], 0
	v_mfma_f32_16x16x32_bf16 v[72:75], v[160:163], v[208:211], 0
	v_mfma_f32_16x16x32_bf16 v[124:127], v[156:159], v[188:191], v[124:127]
	v_mfma_f32_16x16x32_bf16 v[120:123], v[164:167], v[188:191], v[120:123]
	v_mfma_f32_16x16x32_bf16 v[112:115], v[156:159], v[196:199], v[112:115]
	v_mfma_f32_16x16x32_bf16 v[104:107], v[164:167], v[196:199], v[104:107]
	v_mfma_f32_16x16x32_bf16 v[92:95], v[156:159], v[204:207], v[92:95]
	v_mfma_f32_16x16x32_bf16 v[88:91], v[164:167], v[204:207], v[88:91]
	v_mfma_f32_16x16x32_bf16 v[76:79], v[156:159], v[212:215], v[76:79]
	v_mfma_f32_16x16x32_bf16 v[72:75], v[164:167], v[212:215], v[72:75]
	s_setprio 0
	s_setprio 1
	v_mfma_f32_16x16x32_bf16 v[116:119], v[168:171], v[184:187], 0
	v_mfma_f32_16x16x32_bf16 v[108:111], v[176:179], v[184:187], 0
	v_mfma_f32_16x16x32_bf16 v[100:103], v[168:171], v[192:195], 0
	v_mfma_f32_16x16x32_bf16 v[96:99], v[176:179], v[192:195], 0
	v_mfma_f32_16x16x32_bf16 v[84:87], v[168:171], v[200:203], 0
	v_mfma_f32_16x16x32_bf16 v[80:83], v[176:179], v[200:203], 0
	v_mfma_f32_16x16x32_bf16 v[68:71], v[168:171], v[208:211], 0
	v_mfma_f32_16x16x32_bf16 v[64:67], v[176:179], v[208:211], 0
	v_mfma_f32_16x16x32_bf16 v[116:119], v[172:175], v[188:191], v[116:119]
	v_mfma_f32_16x16x32_bf16 v[108:111], v[180:183], v[188:191], v[108:111]
	v_mfma_f32_16x16x32_bf16 v[100:103], v[172:175], v[196:199], v[100:103]
	v_mfma_f32_16x16x32_bf16 v[96:99], v[180:183], v[196:199], v[96:99]
	v_mfma_f32_16x16x32_bf16 v[84:87], v[172:175], v[204:207], v[84:87]
	v_mfma_f32_16x16x32_bf16 v[80:83], v[180:183], v[204:207], v[80:83]
	v_mfma_f32_16x16x32_bf16 v[68:71], v[172:175], v[212:215], v[68:71]
	v_mfma_f32_16x16x32_bf16 v[64:67], v[180:183], v[212:215], v[64:67]
	s_setprio 0
	s_barrier
	s_add_i32 s14, s34, s23
	v_lshl_add_u64 v[216:217], s[18:19], 0, v[130:131]
	s_mov_b32 m0, s14
	ds_read_b128 v[184:187], v149 offset:16384
	ds_read_b128 v[188:191], v149 offset:17408
	ds_read_b128 v[192:195], v149 offset:18432
	ds_read_b128 v[196:199], v149 offset:19456
	ds_read_b128 v[200:203], v149 offset:20480
	ds_read_b128 v[204:207], v149 offset:21504
	ds_read_b128 v[208:211], v149 offset:22528
	ds_read_b128 v[212:215], v149 offset:23552
	global_load_lds_dwordx4 v[216:217], off
	s_add_i32 m0, s14, 0x2000
	s_add_u32 s14, s18, 0x58000
	v_lshl_add_u64 v[218:219], s[18:19], 0, v[134:135]
	s_addc_u32 s15, s19, 0
	s_add_i32 s41, s35, s23
	global_load_lds_dwordx4 v[218:219], off
	v_lshl_add_u64 v[220:221], s[14:15], 0, v[130:131]
	s_mov_b32 m0, s41
	v_lshl_add_u64 v[222:223], s[20:21], 0, v[132:133]
	global_load_lds_dwordx4 v[220:221], off
	v_lshl_add_u64 v[220:221], s[14:15], 0, v[134:135]
	s_add_i32 m0, s41, 0x2000
	s_nop 0
	global_load_lds_dwordx4 v[220:221], off
	v_lshl_add_u64 v[220:221], s[20:21], 0, v[128:129]
	s_mov_b32 m0, s24
	s_nop 0
	global_load_lds_dwordx4 v[220:221], off
	s_mov_b32 m0, s25
	s_nop 0
	global_load_lds_dwordx4 v[222:223], off
	s_waitcnt vmcnt(8)
	s_waitcnt lgkmcnt(0)
	s_barrier
; #define PG8_STAGE(bufoff, gbase, voff) do { _Pragma("unroll") for (int _i = 0; _i < 2; ++_i) \
;         __builtin_amdgcn_global_load_lds((const unsigned*)((const char*)(gbase) + (voff)[_i]), (LAS unsigned*)(lds + (bufoff) + ldsw + _i * 8192), 16, 0, 0); } while (0)
; #define PG8_LDA(dst, b, h) do { _Pragma("unroll") for (int m = 0; m < 4; ++m) _Pragma("unroll") for (int k = 0; k < 2; ++k) dst[m][k] = *(const LAS bf16x8*)(lds + PG8_SA(b, h) + aoff + m * 2048 + k * 1024); } while (0)
; #define PG8_LDB(dst, b, h) do { _Pragma("unroll") for (int n = 0; n < 2; ++n) _Pragma("unroll") for (int k = 0; k < 2; ++k) dst[n][k] = *(const LAS bf16x8*)(lds + PG8_SB(b, h) + boff + n * 2048 + k * 1024); } while (0)
; #define PG8_MMA(ai, bj, At, Bt) do { __builtin_amdgcn_s_setprio(1); _Pragma("unroll") for (int m = 0; m < 4; ++m) _Pragma("unroll") for (int n = 0; n < 2; ++n) _Pragma("unroll") for (int k = 0; k < 2; ++k) \
;         acc[ai][bj][m][n] = __builtin_amdgcn_mfma_f32_16x16x32_bf16(Bt[n][k], At[m][k], acc[ai][bj][m][n], 0, 0, 0); __builtin_amdgcn_s_setprio(0); } while (0)
; #define PG8_WAIT_V(n) asm volatile("s_waitcnt vmcnt(" #n ")" ::: "memory")
; #define PG8_WAIT_L(n) asm volatile("s_waitcnt lgkmcnt(" #n ")" ::: "memory")
; #define PG8_BAR __builtin_amdgcn_s_barrier()
; #define PG8_SCHED __builtin_amdgcn_sched_barrier(0)
; template <class Epi, class Sched, bool ALIGN_EPI = false, bool SP2 = false>
; __device__ __forceinline__ void gemm_phase(LAS unsigned char* lds, const Gemm g, const Sched& S, const Epi& E) {
;     ...
;             PG8_WAIT_V(8); PG8_WAIT_L(0); PG8_BAR; PG8_MMA(1, 0, At, B0); PG8_MMA(1, 1, At, B1); PG8_BAR; PG8_SCHED;
;             PG8_LDB(B0, 1, 0); PG8_LDB(B1, 1, 1); PG8_SCHED; PG8_LDA(At, 1, 0); PG8_STAGE(PG8_SA(0, 1), a2 + hstep, voffA);
;             PG8_WAIT_V(8); PG8_WAIT_L(0); PG8_BAR; PG8_MMA(0, 0, At, B0); PG8_MMA(0, 1, At, B1); PG8_BAR; PG8_SCHED;
	s_setprio 1
	s_waitcnt lgkmcnt(0)
	v_mfma_f32_16x16x32_bf16 v[60:63], v[152:155], v[184:187], 0
	v_mfma_f32_16x16x32_bf16 v[56:59], v[160:163], v[184:187], 0
	v_mfma_f32_16x16x32_bf16 v[44:47], v[152:155], v[192:195], 0
	v_mfma_f32_16x16x32_bf16 v[40:43], v[160:163], v[192:195], 0
	v_mfma_f32_16x16x32_bf16 v[28:31], v[152:155], v[200:203], 0
	v_mfma_f32_16x16x32_bf16 v[24:27], v[160:163], v[200:203], 0
	v_mfma_f32_16x16x32_bf16 v[12:15], v[152:155], v[208:211], 0
	v_mfma_f32_16x16x32_bf16 v[8:11], v[160:163], v[208:211], 0
	v_mfma_f32_16x16x32_bf16 v[60:63], v[156:159], v[188:191], v[60:63]
	v_mfma_f32_16x16x32_bf16 v[56:59], v[164:167], v[188:191], v[56:59]
	v_mfma_f32_16x16x32_bf16 v[44:47], v[156:159], v[196:199], v[44:47]
	v_mfma_f32_16x16x32_bf16 v[40:43], v[164:167], v[196:199], v[40:43]
	v_mfma_f32_16x16x32_bf16 v[28:31], v[156:159], v[204:207], v[28:31]
	v_mfma_f32_16x16x32_bf16 v[24:27], v[164:167], v[204:207], v[24:27]
	v_mfma_f32_16x16x32_bf16 v[12:15], v[156:159], v[212:215], v[12:15]
	v_mfma_f32_16x16x32_bf16 v[8:11], v[164:167], v[212:215], v[8:11]
	s_setprio 0
	s_setprio 1
	v_mfma_f32_16x16x32_bf16 v[52:55], v[168:171], v[184:187], 0
	v_mfma_f32_16x16x32_bf16 v[48:51], v[176:179], v[184:187], 0
	v_mfma_f32_16x16x32_bf16 v[36:39], v[168:171], v[192:195], 0
	v_mfma_f32_16x16x32_bf16 v[32:35], v[176:179], v[192:195], 0
	v_mfma_f32_16x16x32_bf16 v[20:23], v[168:171], v[200:203], 0
	v_mfma_f32_16x16x32_bf16 v[16:19], v[176:179], v[200:203], 0
	v_mfma_f32_16x16x32_bf16 v[4:7], v[168:171], v[208:211], 0
	v_mfma_f32_16x16x32_bf16 v[0:3], v[176:179], v[208:211], 0
	v_mfma_f32_16x16x32_bf16 v[52:55], v[172:175], v[188:191], v[52:55]
	v_mfma_f32_16x16x32_bf16 v[48:51], v[180:183], v[188:191], v[48:51]
	v_mfma_f32_16x16x32_bf16 v[36:39], v[172:175], v[196:199], v[36:39]
	v_mfma_f32_16x16x32_bf16 v[32:35], v[180:183], v[196:199], v[32:35]
	v_mfma_f32_16x16x32_bf16 v[20:23], v[172:175], v[204:207], v[20:23]
	v_mfma_f32_16x16x32_bf16 v[16:19], v[180:183], v[204:207], v[16:19]
	v_mfma_f32_16x16x32_bf16 v[4:7], v[172:175], v[212:215], v[4:7]
	v_mfma_f32_16x16x32_bf16 v[0:3], v[180:183], v[212:215], v[0:3]
	s_setprio 0
	s_barrier
	s_add_i32 s41, 0, 0x18000
	s_add_i32 s42, 0, 0x1c000
	v_add_u32_e32 v164, s41, v144
	v_add_u32_e32 v180, s42, v144
	ds_read_b128 v[152:155], v164
	ds_read_b128 v[156:159], v164 offset:1024
	ds_read_b128 v[160:163], v164 offset:2048
	ds_read_b128 v[164:167], v164 offset:3072
	ds_read_b128 v[168:171], v180
	ds_read_b128 v[172:175], v180 offset:1024
	ds_read_b128 v[176:179], v180 offset:2048
	ds_read_b128 v[180:183], v180 offset:3072
	s_add_u32 s14, s20, 0x160000
	s_addc_u32 s15, s21, 0
	s_mov_b32 m0, s26
	v_lshl_add_u64 v[224:225], s[14:15], 0, v[128:129]
	ds_read_b128 v[184:187], v149 offset:32768
	ds_read_b128 v[188:191], v149 offset:33792
	ds_read_b128 v[192:195], v149 offset:34816
	ds_read_b128 v[196:199], v149 offset:35840
	ds_read_b128 v[200:203], v149 offset:36864
	ds_read_b128 v[204:207], v149 offset:37888
	ds_read_b128 v[208:211], v149 offset:38912
	ds_read_b128 v[212:215], v149 offset:39936
	global_load_lds_dwordx4 v[224:225], off
	v_lshl_add_u64 v[224:225], s[14:15], 0, v[132:133]
	s_mov_b32 m0, s27
	s_nop 0
	global_load_lds_dwordx4 v[224:225], off
	s_waitcnt vmcnt(8)
	s_waitcnt lgkmcnt(0)
	s_barrier
	s_setprio 1
	s_waitcnt lgkmcnt(0)
	v_mfma_f32_16x16x32_bf16 v[124:127], v[152:155], v[184:187], v[124:127]
	v_mfma_f32_16x16x32_bf16 v[120:123], v[160:163], v[184:187], v[120:123]
	v_mfma_f32_16x16x32_bf16 v[112:115], v[152:155], v[192:195], v[112:115]
	v_mfma_f32_16x16x32_bf16 v[104:107], v[160:163], v[192:195], v[104:107]
	v_mfma_f32_16x16x32_bf16 v[92:95], v[152:155], v[200:203], v[92:95]
	v_mfma_f32_16x16x32_bf16 v[88:91], v[160:163], v[200:203], v[88:91]
	v_mfma_f32_16x16x32_bf16 v[76:79], v[152:155], v[208:211], v[76:79]
	v_mfma_f32_16x16x32_bf16 v[72:75], v[160:163], v[208:211], v[72:75]
	v_mfma_f32_16x16x32_bf16 v[124:127], v[156:159], v[188:191], v[124:127]
	v_mfma_f32_16x16x32_bf16 v[120:123], v[164:167], v[188:191], v[120:123]
	v_mfma_f32_16x16x32_bf16 v[112:115], v[156:159], v[196:199], v[112:115]
	v_mfma_f32_16x16x32_bf16 v[104:107], v[164:167], v[196:199], v[104:107]
	v_mfma_f32_16x16x32_bf16 v[92:95], v[156:159], v[204:207], v[92:95]
	v_mfma_f32_16x16x32_bf16 v[88:91], v[164:167], v[204:207], v[88:91]
	v_mfma_f32_16x16x32_bf16 v[76:79], v[156:159], v[212:215], v[76:79]
	v_mfma_f32_16x16x32_bf16 v[72:75], v[164:167], v[212:215], v[72:75]
	s_setprio 0
	s_setprio 1
	v_mfma_f32_16x16x32_bf16 v[116:119], v[168:171], v[184:187], v[116:119]
	v_mfma_f32_16x16x32_bf16 v[108:111], v[176:179], v[184:187], v[108:111]
	v_mfma_f32_16x16x32_bf16 v[100:103], v[168:171], v[192:195], v[100:103]
	v_mfma_f32_16x16x32_bf16 v[96:99], v[176:179], v[192:195], v[96:99]
	v_mfma_f32_16x16x32_bf16 v[84:87], v[168:171], v[200:203], v[84:87]
	v_mfma_f32_16x16x32_bf16 v[80:83], v[176:179], v[200:203], v[80:83]
	v_mfma_f32_16x16x32_bf16 v[68:71], v[168:171], v[208:211], v[68:71]
	v_mfma_f32_16x16x32_bf16 v[64:67], v[176:179], v[208:211], v[64:67]
	v_mfma_f32_16x16x32_bf16 v[116:119], v[172:175], v[188:191], v[116:119]
	v_mfma_f32_16x16x32_bf16 v[108:111], v[180:183], v[188:191], v[108:111]
	v_mfma_f32_16x16x32_bf16 v[100:103], v[172:175], v[196:199], v[100:103]
	v_mfma_f32_16x16x32_bf16 v[96:99], v[180:183], v[196:199], v[96:99]
	v_mfma_f32_16x16x32_bf16 v[84:87], v[172:175], v[204:207], v[84:87]
	v_mfma_f32_16x16x32_bf16 v[80:83], v[180:183], v[204:207], v[80:83]
	v_mfma_f32_16x16x32_bf16 v[68:71], v[172:175], v[212:215], v[68:71]
	v_mfma_f32_16x16x32_bf16 v[64:67], v[180:183], v[212:215], v[64:67]
	s_setprio 0
	s_barrier
; #define PG8_STAGE(bufoff, gbase, voff) do { _Pragma("unroll") for (int _i = 0; _i < 2; ++_i) \
;         __builtin_amdgcn_global_load_lds((const unsigned*)((const char*)(gbase) + (voff)[_i]), (LAS unsigned*)(lds + (bufoff) + ldsw + _i * 8192), 16, 0, 0); } while (0)
; #define PG8_LDA(dst, b, h) do { _Pragma("unroll") for (int m = 0; m < 4; ++m) _Pragma("unroll") for (int k = 0; k < 2; ++k) dst[m][k] = *(const LAS bf16x8*)(lds + PG8_SA(b, h) + aoff + m * 2048 + k * 1024); } while (0)
; #define PG8_LDB(dst, b, h) do { _Pragma("unroll") for (int n = 0; n < 2; ++n) _Pragma("unroll") for (int k = 0; k < 2; ++k) dst[n][k] = *(const LAS bf16x8*)(lds + PG8_SB(b, h) + boff + n * 2048 + k * 1024); } while (0)
; template <class Epi, class Sched, bool ALIGN_EPI = false, bool SP2 = false>
; __device__ __forceinline__ void gemm_phase(LAS unsigned char* lds, const Gemm g, const Sched& S, const Epi& E) {
;     ...
;         for (int t = 0; t < nt; t += 2) {
;             const bool last = (t == nt - 2);
;             const char* a1 = cA + (size_t)(t + 1) * kstep;
;             const char* a2 = last ? nA : cA + (size_t)(t + 2) * kstep; const char* b2 = last ? nB : cB + (size_t)(t + 2) * kstep;
;             const char* a3 = a2 + kstep; const char* b3 = b2 + kstep;
;             if (last && has_next) S.a_ready(nxt);
;             if constexpr (SP2) {
;             PG8_LDB(B0, 0, 0); PG8_LDB(B1, 0, 1); PG8_SCHED; PG8_LDA(At, 0, 0); PG8_STAGE(PG8_SA(1, 1), a1 + hstep, voffA);
;             PG8_WAIT_V(8); PG8_WAIT_L(0); PG8_BAR; PG8_MMA(0, 0, At, B0); PG8_MMA(0, 1, At, B1); PG8_BAR; PG8_SCHED;
;             PG8_LDA(At, 0, 1); PG8_STAGE(PG8_SB(0, 0), b2, voffB); PG8_STAGE(PG8_SB(0, 1), b2 + hstepB, voffB); PG8_STAGE(PG8_SA(0, 0), a2, voffA);
;             PG8_WAIT_V(8); PG8_WAIT_L(0); PG8_BAR; PG8_MMA(1, 0, At, B0); PG8_MMA(1, 1, At, B1); PG8_BAR; PG8_SCHED;
;             PG8_LDB(B0, 1, 0); PG8_LDB(B1, 1, 1); PG8_SCHED; PG8_LDA(At, 1, 0); PG8_STAGE(PG8_SA(0, 1), a2 + hstep, voffA);
;             PG8_WAIT_V(8); PG8_WAIT_L(0); PG8_BAR; PG8_MMA(0, 0, At, B0); PG8_MMA(0, 1, At, B1); PG8_BAR; PG8_SCHED;
;             PG8_LDA(At, 1, 1); PG8_STAGE(PG8_SB(1, 0), b3, voffB); PG8_STAGE(PG8_SB(1, 1), b3 + hstepB, voffB); PG8_STAGE(PG8_SA(1, 0), a3, voffA);
;             PG8_WAIT_V(8); PG8_WAIT_L(0); PG8_BAR; PG8_MMA(1, 0, At, B0); PG8_MMA(1, 1, At, B1); PG8_BAR; PG8_SCHED;
	s_add_i32 s14, s41, s23
	v_lshl_add_u64 v[216:217], v[216:217], 0, s[6:7]
	s_mov_b32 m0, s14
	ds_read_b128 v[184:187], v149 offset:49152
	ds_read_b128 v[188:191], v149 offset:50176
	ds_read_b128 v[192:195], v149 offset:51200
	ds_read_b128 v[196:199], v149 offset:52224
	ds_read_b128 v[200:203], v149 offset:53248
	ds_read_b128 v[204:207], v149 offset:54272
	ds_read_b128 v[208:211], v149 offset:55296
	ds_read_b128 v[212:215], v149 offset:56320
	global_load_lds_dwordx4 v[216:217], off
	s_add_i32 m0, s14, 0x2000
	s_add_u32 s14, s18, 0x58080
	v_lshl_add_u64 v[216:217], v[218:219], 0, s[6:7]
	s_addc_u32 s15, s19, 0
	s_add_i32 s18, s42, s23
	global_load_lds_dwordx4 v[216:217], off
	v_lshl_add_u64 v[216:217], s[14:15], 0, v[130:131]
	s_mov_b32 m0, s18
	s_nop 0
	global_load_lds_dwordx4 v[216:217], off
	v_lshl_add_u64 v[216:217], s[14:15], 0, v[134:135]
	s_add_i32 m0, s18, 0x2000
	s_nop 0
	global_load_lds_dwordx4 v[216:217], off
	v_lshl_add_u64 v[216:217], v[220:221], 0, s[6:7]
	s_mov_b32 m0, s31
	s_nop 0
	global_load_lds_dwordx4 v[216:217], off
	v_lshl_add_u64 v[216:217], v[222:223], 0, s[6:7]
	s_mov_b32 m0, s33
	s_nop 0
	global_load_lds_dwordx4 v[216:217], off
	s_waitcnt vmcnt(8)
	s_waitcnt lgkmcnt(0)
	s_barrier
	s_setprio 1
	s_waitcnt lgkmcnt(0)
	v_mfma_f32_16x16x32_bf16 v[60:63], v[152:155], v[184:187], v[60:63]
	v_mfma_f32_16x16x32_bf16 v[56:59], v[160:163], v[184:187], v[56:59]
	v_mfma_f32_16x16x32_bf16 v[44:47], v[152:155], v[192:195], v[44:47]
	v_mfma_f32_16x16x32_bf16 v[40:43], v[160:163], v[192:195], v[40:43]
	v_mfma_f32_16x16x32_bf16 v[28:31], v[152:155], v[200:203], v[28:31]
	v_mfma_f32_16x16x32_bf16 v[24:27], v[160:163], v[200:203], v[24:27]
	v_mfma_f32_16x16x32_bf16 v[12:15], v[152:155], v[208:211], v[12:15]
	v_mfma_f32_16x16x32_bf16 v[8:11], v[160:163], v[208:211], v[8:11]
	v_mfma_f32_16x16x32_bf16 v[60:63], v[156:159], v[188:191], v[60:63]
	v_mfma_f32_16x16x32_bf16 v[56:59], v[164:167], v[188:191], v[56:59]
	v_mfma_f32_16x16x32_bf16 v[44:47], v[156:159], v[196:199], v[44:47]
	v_mfma_f32_16x16x32_bf16 v[40:43], v[164:167], v[196:199], v[40:43]
	v_mfma_f32_16x16x32_bf16 v[28:31], v[156:159], v[204:207], v[28:31]
	v_mfma_f32_16x16x32_bf16 v[24:27], v[164:167], v[204:207], v[24:27]
	v_mfma_f32_16x16x32_bf16 v[12:15], v[156:159], v[212:215], v[12:15]
	v_mfma_f32_16x16x32_bf16 v[8:11], v[164:167], v[212:215], v[8:11]
	s_setprio 0
	s_setprio 1
	v_mfma_f32_16x16x32_bf16 v[52:55], v[168:171], v[184:187], v[52:55]
	v_mfma_f32_16x16x32_bf16 v[48:51], v[176:179], v[184:187], v[48:51]
	v_mfma_f32_16x16x32_bf16 v[36:39], v[168:171], v[192:195], v[36:39]
	v_mfma_f32_16x16x32_bf16 v[32:35], v[176:179], v[192:195], v[32:35]
	v_mfma_f32_16x16x32_bf16 v[20:23], v[168:171], v[200:203], v[20:23]
	v_mfma_f32_16x16x32_bf16 v[16:19], v[176:179], v[200:203], v[16:19]
	v_mfma_f32_16x16x32_bf16 v[4:7], v[168:171], v[208:211], v[4:7]
	v_mfma_f32_16x16x32_bf16 v[0:3], v[176:179], v[208:211], v[0:3]
	v_mfma_f32_16x16x32_bf16 v[52:55], v[172:175], v[188:191], v[52:55]
	v_mfma_f32_16x16x32_bf16 v[48:51], v[180:183], v[188:191], v[48:51]
	v_mfma_f32_16x16x32_bf16 v[36:39], v[172:175], v[196:199], v[36:39]
	v_mfma_f32_16x16x32_bf16 v[32:35], v[180:183], v[196:199], v[32:35]
	v_mfma_f32_16x16x32_bf16 v[20:23], v[172:175], v[204:207], v[20:23]
	v_mfma_f32_16x16x32_bf16 v[16:19], v[180:183], v[204:207], v[16:19]
	v_mfma_f32_16x16x32_bf16 v[4:7], v[172:175], v[212:215], v[4:7]
	v_mfma_f32_16x16x32_bf16 v[0:3], v[180:183], v[212:215], v[0:3]
	s_setprio 0
	s_barrier
	s_add_i32 s40, s40, 2
	s_add_u32 s13, s13, 0x100
	s_addc_u32 s39, s39, 0
	s_cmpk_lt_u32 s40, 0x56
	s_mov_b64 s[14:15], s[16:17]
